# scan fast paths v3: 8-byte instruction alignment, one LDS wait per step, clustered LDS reads, partial operand double buffering, swizzled B/C and q/k LDS reads
# speedup vs baseline: 1.1200x; 1.0267x over previous
; __device__ __forceinline__ void scan_gdn(const Params& p, int l, int seq, int h, int qt, char* smem, const unsigned* wflags, unsigned wexpect) {
;     ...
;     prefetch(Pfree, min(c + 2, nch - 1));
;     const int nsteps = min(16, T - c * 16);
;     const float* vb = vec + cur * 16 * 288;
;     const float* sb = scb + cur * 64;
;     GdRegs RA, RB;
;     float* ydummy = yb + 16 * 32 + tid;
;     gd_load(RA, vb, sb, 0, k0, cl);
.LBB0_188:
	s_or_b64 exec, exec, s[50:51]
	s_lshl_b32 s52, s14, 4
	s_sub_i32 s51, s18, s52
	s_min_i32 s50, s51, 16
	s_cmp_lt_i32 s51, 1
	s_cbranch_scc1 .LBB0_193
	s_cmp_lg_u32 s50, 16
	s_cbranch_scc1 .Lgdf_slow0
	v_add_u32_e32 v166, 0x9200, v2
	v_lshrrev_b32_e32 v167, 4, v151
	v_and_b32_e32 v167, 16, v167
	v_add_u32_e32 v161, v151, v167
	v_sub_u32_e32 v162, v151, v167
	v_mov_b32_e32 v163, v150
	v_mov_b32_e32 v164, 0
	v_cndmask_b32_e64 v166, v149, v166, s[44:45]
	s_mov_b32 s51, 0
	s_branch .Lgdf_body

; __device__ __forceinline__ void scan_gdn(const Params& p, int l, int seq, int h, int qt, char* smem, const unsigned* wflags, unsigned wexpect) {
;     ...
;     prefetch(Pfree, min(c + 2, nch - 1));
;     const int nsteps = min(16, T - c * 16);
;     const float* vb = vec + cur * 16 * 288;
;     const float* sb = scb + cur * 64;
;     GdRegs RA, RB;
;     float* ydummy = yb + 16 * 32 + tid;
;     gd_load(RA, vb, sb, 0, k0, cl);
.LBB0_224:
	s_or_b64 exec, exec, s[50:51]
	s_lshl_b32 s14, s58, 4
	s_sub_i32 s51, s18, s14
	s_min_i32 s50, s51, 16
	s_cmp_lt_i32 s51, 1
	s_cbranch_scc1 .LBB0_229
	s_cmp_lg_u32 s50, 16
	s_cbranch_scc1 .Lgdf_slow1
	v_add_u32_e32 v166, 0x9200, v2
	v_lshrrev_b32_e32 v167, 4, v151
	v_and_b32_e32 v167, 16, v167
	s_movk_i32 s51, 0x4800
	v_add3_u32 v161, v151, v167, s51
	v_sub_u32_e32 v162, v151, v167
	v_add_u32_e32 v162, 0x4800, v162
	v_add_u32_e32 v163, 0x4800, v150
	v_mov_b32_e32 v164, 0x100
	v_cndmask_b32_e64 v166, v149, v166, s[44:45]
	s_mov_b32 s51, 1
	s_branch .Lgdf_body

; __device__ __forceinline__ void scan_rwkv(const Params& p, int l, int seq, int h, char* smem, const unsigned* wflags, unsigned wexpect) {
;     ...
;     prefetch(Pfree, min(c + 2, nch - 1));
;     const int nsteps = min(16, T - c * 16);
;     const float* vb = vec + cur * 16 * 384;
;     const float* sb = scb + cur * 64;
;     RwRegs RA, RB;
;     float* ydummy = yb + 16 * 64 + tid * 2;
;     rw_load(RA, vb, sb, 0, k0, vrow0);
.LBB0_278:
	s_or_b64 exec, exec, s[38:39]
	s_lshl_b32 s27, s14, 4
	s_sub_i32 s39, s18, s27
	s_min_i32 s38, s39, 16
	s_cmp_lt_i32 s39, 1
	s_cbranch_scc1 .LBB0_283
	s_cmp_lg_u32 s38, 16
	s_cbranch_scc1 .Lrwf_slow0
	v_add_u32_e32 v208, 0xc200, v198
	v_mov_b32_e32 v205, v152
	v_mov_b32_e32 v206, v195
	v_mov_b32_e32 v207, 0
	v_cndmask_b32_e64 v208, v194, v208, s[44:45]
	s_mov_b32 s39, 0
	s_branch .Lrwf_body

; __device__ __forceinline__ void scan_rwkv(const Params& p, int l, int seq, int h, char* smem, const unsigned* wflags, unsigned wexpect) {
;     ...
;     prefetch(Pfree, min(c + 2, nch - 1));
;     const int nsteps = min(16, T - c * 16);
;     const float* vb = vec + cur * 16 * 384;
;     const float* sb = scb + cur * 64;
;     RwRegs RA, RB;
;     float* ydummy = yb + 16 * 64 + tid * 2;
;     rw_load(RA, vb, sb, 0, k0, vrow0);
.LBB0_296:
	s_or_b64 exec, exec, s[38:39]
	s_lshl_b32 s14, s27, 4
	s_sub_i32 s38, s18, s14
	s_min_i32 s27, s38, 16
	s_cmp_lt_i32 s38, 1
	s_cbranch_scc1 .LBB0_301
	s_cmp_lg_u32 s27, 16
	s_cbranch_scc1 .Lrwf_slow1
	v_add_u32_e32 v208, 0xc200, v198
	v_add_u32_e32 v205, 0x6000, v152
	v_add_u32_e32 v206, 0x6000, v195
	v_mov_b32_e32 v207, 0x100
	v_cndmask_b32_e64 v208, v194, v208, s[44:45]
	s_mov_b32 s39, 1
	s_branch .Lrwf_body

; __device__ __forceinline__ void scan_ssm(const Params& p, int l, int seq, int h, char* smem, const unsigned* wflags, unsigned wexpect) {
;     ...
;     prefetch(Pfree, min(c + 2, nch - 1));
;     const int nsteps = min(16, T - c * 16);
;     const float* vb = vec + cur * 16 * 320;
;     const float* sb = scb + cur * 32;
;     SsRegs RA, RB;
;     float* ydummy = yb + 16 * 64 + tid * 2;
;     ss_load(RA, vb, sb, 0, n0, prow0);
.LBB0_643:
	s_or_b64 exec, exec, s[50:51]
	s_lshl_b32 s26, s14, 4
	s_sub_i32 s50, s18, s26
	s_min_i32 s27, s50, 16
	s_cmp_lt_i32 s50, 1
	s_cbranch_scc1 .LBB0_648
	s_cmp_lg_u32 s27, 16
	s_cbranch_scc1 .Lssf_slow0
	v_add_u32_e32 v154, 0xa100, v2
	v_lshrrev_b32_e32 v155, 4, v126
	v_and_b32_e32 v155, 16, v155
	v_add_u32_e32 v150, v126, v155
	v_sub_u32_e32 v151, v126, v155
	v_mov_b32_e32 v152, v165
	v_mov_b32_e32 v153, 0
	v_cndmask_b32_e64 v154, v164, v154, s[44:45]
	s_mov_b32 s50, 0
	s_branch .Lssf_body

; __device__ __forceinline__ void scan_ssm(const Params& p, int l, int seq, int h, char* smem, const unsigned* wflags, unsigned wexpect) {
;     ...
;     prefetch(Pfree, min(c + 2, nch - 1));
;     const int nsteps = min(16, T - c * 16);
;     const float* vb = vec + cur * 16 * 320;
;     const float* sb = scb + cur * 32;
;     SsRegs RA, RB;
;     float* ydummy = yb + 16 * 64 + tid * 2;
;     ss_load(RA, vb, sb, 0, n0, prow0);
.LBB0_679:
	s_or_b64 exec, exec, s[50:51]
	s_lshl_b32 s14, s26, 4
	s_sub_i32 s27, s18, s14
	s_min_i32 s26, s27, 16
	s_cmp_lt_i32 s27, 1
	s_cbranch_scc1 .LBB0_684
	s_cmp_lg_u32 s26, 16
	s_cbranch_scc1 .Lssf_slow1
	v_add_u32_e32 v154, 0xa100, v2
	v_lshrrev_b32_e32 v155, 4, v126
	v_and_b32_e32 v155, 16, v155
	s_movk_i32 s50, 0x5000
	v_add3_u32 v150, v126, v155, s50
	v_sub_u32_e32 v151, v126, v155
	v_add_u32_e32 v151, 0x5000, v151
	v_add_u32_e32 v152, 0x5000, v165
	v_mov_b32_e32 v153, 0x80
	v_cndmask_b32_e64 v154, v164, v154, s[44:45]
	s_mov_b32 s50, 1
	s_branch .Lssf_body

; __device__ __forceinline__ float red8(float v) { v = red4(v); v += dppf<0x141>(v); return v; }
; __device__ __forceinline__ f32x2 lo2(const f32x4& v) { return __builtin_shufflevector(v, v, 0, 1); }
; __device__ __forceinline__ f32x2 hi2(const f32x4& v) { return __builtin_shufflevector(v, v, 2, 3); }
; __device__ __forceinline__ f32x2 splat2(float x) { return (f32x2){x, x}; }
; __device__ __forceinline__ void gd_load(GdRegs& R, const float* vb, const float* sb, int t, int k0, int cl) {
;   const float* vt = vb + t * 288;
; #pragma unroll
;   for (int q = 0; q < 4; ++q) {
;     R.q[q] = *(const f32x4*)(vt + k0 + q * 4);
;     R.k[q] = *(const f32x4*)(vt + 128 + k0 + q * 4);
;   }
;   R.v = vt[256 + cl];
;   R.sc = *(const f32x4*)(sb + t * 4);
; }
; __device__ __forceinline__ float gd_step(f32x2 (&S)[8], const GdRegs& R) {
;   f32x2 k0a = splat2(0.f), k1a = splat2(0.f), q0a = splat2(0.f), q1a = splat2(0.f);
; #pragma unroll
;   for (int q = 0; q < 4; ++q) {
;     k0a += S[2 * q] * lo2(R.k[q]);
;     k1a += S[2 * q + 1] * hi2(R.k[q]);
;     q0a += S[2 * q] * lo2(R.q[q]);
;     q1a += S[2 * q + 1] * hi2(R.q[q]);
;   }
;   k0a += k1a; q0a += q1a;
;   const float dK = red8(k0a.x + k0a.y), dQ = red8(q0a.x + q0a.y);
;   const float vn = R.sc.y * (R.v - R.sc.x * dK);
;   const float o = R.sc.x * dQ + R.sc.z * vn;
;   const f32x2 al2 = splat2(R.sc.x), vn2 = splat2(vn);
; #pragma unroll
;   for (int q = 0; q < 4; ++q) {
;     S[2 * q] = S[2 * q] * al2 + lo2(R.k[q]) * vn2;
;     S[2 * q + 1] = S[2 * q + 1] * al2 + hi2(R.k[q]) * vn2;
;   }
;   return o;
; }
.LBB0_907:
	s_endpgm
	.p2align 3
.Lgdf_body:
	s_mov_b32 exec_lo, 0xf0f0f0f0
	s_mov_b32 exec_hi, 0xf0f0f0f0
	v_swap_b32 v120, v124
	v_swap_b32 v121, v125
	v_swap_b32 v122, v126
	v_swap_b32 v123, v127
	v_swap_b32 v128, v132
	v_swap_b32 v129, v133
	v_swap_b32 v130, v134
	v_swap_b32 v131, v135
	s_mov_b64 exec, -1
	s_nop 0
	ds_read_b32 v100, v163 offset:1024
	ds_read_b128 v[92:95], v164 offset:36864
	ds_read_b128 v[60:63], v161 offset:512
	ds_read_b128 v[36:39], v161 offset:0
	ds_read_b128 v[64:67], v162 offset:528
	ds_read_b128 v[40:43], v162 offset:16
	ds_read_b128 v[68:71], v161 offset:544
	ds_read_b128 v[44:47], v161 offset:32
	ds_read_b128 v[72:75], v162 offset:560
	ds_read_b128 v[48:51], v162 offset:48
	s_waitcnt lgkmcnt(0)
	s_nop 0
	ds_read_b128 v[76:79], v161 offset:1664
	ds_read_b128 v[80:83], v162 offset:1680
	ds_read_b128 v[84:87], v161 offset:1696
	ds_read_b128 v[88:91], v162 offset:1712
	ds_read_b32 v101, v163 offset:2176
	ds_read_b128 v[96:99], v164 offset:36880
	ds_read_b128 v[52:55], v161 offset:1184
	ds_read_b128 v[56:59], v162 offset:1200
	v_pk_mul_f32 v[102:103], v[120:121], v[60:61]
	v_pk_mul_f32 v[104:105], v[120:121], v[36:37]
	v_pk_fma_f32 v[102:103], v[122:123], v[62:63], v[102:103]
	v_pk_fma_f32 v[104:105], v[122:123], v[38:39], v[104:105]
	v_pk_mul_f32 v[120:121], v[120:121], v[92:93] op_sel_hi:[1,0]
	v_pk_fma_f32 v[102:103], v[124:125], v[64:65], v[102:103]
	v_pk_fma_f32 v[104:105], v[124:125], v[40:41], v[104:105]
	v_pk_mul_f32 v[122:123], v[122:123], v[92:93] op_sel_hi:[1,0]
	v_pk_fma_f32 v[102:103], v[126:127], v[66:67], v[102:103]
	v_pk_fma_f32 v[104:105], v[126:127], v[42:43], v[104:105]
	v_pk_mul_f32 v[124:125], v[124:125], v[92:93] op_sel_hi:[1,0]
	v_pk_fma_f32 v[102:103], v[128:129], v[68:69], v[102:103]
	v_pk_fma_f32 v[104:105], v[128:129], v[44:45], v[104:105]
	v_pk_mul_f32 v[126:127], v[126:127], v[92:93] op_sel_hi:[1,0]
	v_pk_fma_f32 v[102:103], v[130:131], v[70:71], v[102:103]
	v_pk_fma_f32 v[104:105], v[130:131], v[46:47], v[104:105]
	v_pk_mul_f32 v[128:129], v[128:129], v[92:93] op_sel_hi:[1,0]
	v_pk_fma_f32 v[102:103], v[132:133], v[72:73], v[102:103]
	v_pk_fma_f32 v[104:105], v[132:133], v[48:49], v[104:105]
	v_pk_fma_f32 v[102:103], v[134:135], v[74:75], v[102:103]
	v_pk_fma_f32 v[104:105], v[134:135], v[50:51], v[104:105]
	v_add_f32_e64 v102, v102, v103
	v_add_f32_e64 v104, v104, v105
	ds_read_b128 v[36:39], v161 offset:1152
	ds_read_b128 v[40:43], v162 offset:1168
	v_add_f32_dpp v102, v102, v102 quad_perm:[1,0,3,2] row_mask:0xf bank_mask:0xf bound_ctrl:1
	v_add_f32_dpp v104, v104, v104 quad_perm:[1,0,3,2] row_mask:0xf bank_mask:0xf bound_ctrl:1
	v_pk_mul_f32 v[130:131], v[130:131], v[92:93] op_sel_hi:[1,0]
	v_add_f32_dpp v102, v102, v102 quad_perm:[2,3,0,1] row_mask:0xf bank_mask:0xf bound_ctrl:1
	v_add_f32_dpp v104, v104, v104 quad_perm:[2,3,0,1] row_mask:0xf bank_mask:0xf bound_ctrl:1
	v_pk_mul_f32 v[132:133], v[132:133], v[92:93] op_sel_hi:[1,0]
	v_add_f32_dpp v102, v102, v102 row_half_mirror row_mask:0xf bank_mask:0xf bound_ctrl:1
	v_add_f32_dpp v104, v104, v104 row_half_mirror row_mask:0xf bank_mask:0xf bound_ctrl:1
	v_fma_f32 v105, -v92, v102, v100
	v_pk_mul_f32 v[106:107], v[92:93], v[104:105]
	v_pk_mul_f32 v[134:135], v[134:135], v[92:93] op_sel_hi:[1,0]
	v_pk_fma_f32 v[120:121], v[60:61], v[106:107], v[120:121] op_sel:[0,1,0]
	v_pk_fma_f32 v[122:123], v[62:63], v[106:107], v[122:123] op_sel:[0,1,0]
	v_fma_f32 v106, v94, v107, v106
	v_pk_fma_f32 v[124:125], v[64:65], v[106:107], v[124:125] op_sel:[0,1,0]
	v_pk_fma_f32 v[126:127], v[66:67], v[106:107], v[126:127] op_sel:[0,1,0]
	v_pk_fma_f32 v[128:129], v[68:69], v[106:107], v[128:129] op_sel:[0,1,0]
	v_pk_fma_f32 v[130:131], v[70:71], v[106:107], v[130:131] op_sel:[0,1,0]
	v_pk_fma_f32 v[132:133], v[72:73], v[106:107], v[132:133] op_sel:[0,1,0]
	v_pk_fma_f32 v[134:135], v[74:75], v[106:107], v[134:135] op_sel:[0,1,0]
	ds_write_b32 v166, v106 offset:0
	s_waitcnt lgkmcnt(1)
	s_nop 0
	ds_read_b128 v[60:63], v161 offset:2816
	ds_read_b128 v[64:67], v162 offset:2832
	ds_read_b128 v[68:71], v161 offset:2848
	ds_read_b128 v[72:75], v162 offset:2864
	ds_read_b32 v100, v163 offset:3328
	ds_read_b128 v[92:95], v164 offset:36896
	ds_read_b128 v[44:47], v161 offset:2336
	ds_read_b128 v[48:51], v162 offset:2352
	v_pk_mul_f32 v[102:103], v[120:121], v[76:77]
	v_pk_mul_f32 v[104:105], v[120:121], v[36:37]
	v_pk_fma_f32 v[102:103], v[122:123], v[78:79], v[102:103]
	v_pk_fma_f32 v[104:105], v[122:123], v[38:39], v[104:105]
	v_pk_mul_f32 v[120:121], v[120:121], v[96:97] op_sel_hi:[1,0]
	v_pk_fma_f32 v[102:103], v[124:125], v[80:81], v[102:103]
	v_pk_fma_f32 v[104:105], v[124:125], v[40:41], v[104:105]
	v_pk_mul_f32 v[122:123], v[122:123], v[96:97] op_sel_hi:[1,0]
	v_pk_fma_f32 v[102:103], v[126:127], v[82:83], v[102:103]
	v_pk_fma_f32 v[104:105], v[126:127], v[42:43], v[104:105]
	v_pk_mul_f32 v[124:125], v[124:125], v[96:97] op_sel_hi:[1,0]
	v_pk_fma_f32 v[102:103], v[128:129], v[84:85], v[102:103]
	v_pk_fma_f32 v[104:105], v[128:129], v[52:53], v[104:105]
	v_pk_mul_f32 v[126:127], v[126:127], v[96:97] op_sel_hi:[1,0]
	v_pk_fma_f32 v[102:103], v[130:131], v[86:87], v[102:103]
	v_pk_fma_f32 v[104:105], v[130:131], v[54:55], v[104:105]
	v_pk_mul_f32 v[128:129], v[128:129], v[96:97] op_sel_hi:[1,0]
	v_pk_fma_f32 v[102:103], v[132:133], v[88:89], v[102:103]
	v_pk_fma_f32 v[104:105], v[132:133], v[56:57], v[104:105]
	v_pk_fma_f32 v[102:103], v[134:135], v[90:91], v[102:103]
	v_pk_fma_f32 v[104:105], v[134:135], v[58:59], v[104:105]
	v_add_f32_e64 v102, v102, v103
	v_add_f32_e64 v104, v104, v105
	ds_read_b128 v[36:39], v161 offset:2304
	ds_read_b128 v[40:43], v162 offset:2320
; __device__ __forceinline__ float red8(float v) { v = red4(v); v += dppf<0x141>(v); return v; }
; __device__ __forceinline__ f32x2 lo2(const f32x4& v) { return __builtin_shufflevector(v, v, 0, 1); }
; __device__ __forceinline__ f32x2 hi2(const f32x4& v) { return __builtin_shufflevector(v, v, 2, 3); }
; __device__ __forceinline__ f32x2 splat2(float x) { return (f32x2){x, x}; }
; __device__ __forceinline__ void gd_load(GdRegs& R, const float* vb, const float* sb, int t, int k0, int cl) {
;   const float* vt = vb + t * 288;
; #pragma unroll
;   for (int q = 0; q < 4; ++q) {
;     R.q[q] = *(const f32x4*)(vt + k0 + q * 4);
;     R.k[q] = *(const f32x4*)(vt + 128 + k0 + q * 4);
;   }
;   R.v = vt[256 + cl];
;   R.sc = *(const f32x4*)(sb + t * 4);
; }
; __device__ __forceinline__ float gd_step(f32x2 (&S)[8], const GdRegs& R) {
;   f32x2 k0a = splat2(0.f), k1a = splat2(0.f), q0a = splat2(0.f), q1a = splat2(0.f);
; #pragma unroll
;   for (int q = 0; q < 4; ++q) {
;     k0a += S[2 * q] * lo2(R.k[q]);
;     k1a += S[2 * q + 1] * hi2(R.k[q]);
;     q0a += S[2 * q] * lo2(R.q[q]);
;     q1a += S[2 * q + 1] * hi2(R.q[q]);
;   }
;   k0a += k1a; q0a += q1a;
;   const float dK = red8(k0a.x + k0a.y), dQ = red8(q0a.x + q0a.y);
;   const float vn = R.sc.y * (R.v - R.sc.x * dK);
;   const float o = R.sc.x * dQ + R.sc.z * vn;
;   const f32x2 al2 = splat2(R.sc.x), vn2 = splat2(vn);
; #pragma unroll
;   for (int q = 0; q < 4; ++q) {
;     S[2 * q] = S[2 * q] * al2 + lo2(R.k[q]) * vn2;
;     S[2 * q + 1] = S[2 * q + 1] * al2 + hi2(R.k[q]) * vn2;
;   }
;   return o;
; }
	v_add_f32_dpp v102, v102, v102 quad_perm:[1,0,3,2] row_mask:0xf bank_mask:0xf bound_ctrl:1
	v_add_f32_dpp v104, v104, v104 quad_perm:[1,0,3,2] row_mask:0xf bank_mask:0xf bound_ctrl:1
	v_pk_mul_f32 v[130:131], v[130:131], v[96:97] op_sel_hi:[1,0]
	v_add_f32_dpp v102, v102, v102 quad_perm:[2,3,0,1] row_mask:0xf bank_mask:0xf bound_ctrl:1
	v_add_f32_dpp v104, v104, v104 quad_perm:[2,3,0,1] row_mask:0xf bank_mask:0xf bound_ctrl:1
	v_pk_mul_f32 v[132:133], v[132:133], v[96:97] op_sel_hi:[1,0]
	v_add_f32_dpp v102, v102, v102 row_half_mirror row_mask:0xf bank_mask:0xf bound_ctrl:1
	v_add_f32_dpp v104, v104, v104 row_half_mirror row_mask:0xf bank_mask:0xf bound_ctrl:1
	v_fma_f32 v105, -v96, v102, v101
	v_pk_mul_f32 v[106:107], v[96:97], v[104:105]
	v_pk_mul_f32 v[134:135], v[134:135], v[96:97] op_sel_hi:[1,0]
	v_pk_fma_f32 v[120:121], v[76:77], v[106:107], v[120:121] op_sel:[0,1,0]
	v_pk_fma_f32 v[122:123], v[78:79], v[106:107], v[122:123] op_sel:[0,1,0]
	v_fma_f32 v106, v98, v107, v106
	v_pk_fma_f32 v[124:125], v[80:81], v[106:107], v[124:125] op_sel:[0,1,0]
	v_pk_fma_f32 v[126:127], v[82:83], v[106:107], v[126:127] op_sel:[0,1,0]
	v_pk_fma_f32 v[128:129], v[84:85], v[106:107], v[128:129] op_sel:[0,1,0]
	v_pk_fma_f32 v[130:131], v[86:87], v[106:107], v[130:131] op_sel:[0,1,0]
	v_pk_fma_f32 v[132:133], v[88:89], v[106:107], v[132:133] op_sel:[0,1,0]
	v_pk_fma_f32 v[134:135], v[90:91], v[106:107], v[134:135] op_sel:[0,1,0]
	ds_write_b32 v166, v106 offset:128
	s_waitcnt lgkmcnt(1)
	s_nop 0
	ds_read_b128 v[76:79], v161 offset:3968
	ds_read_b128 v[80:83], v162 offset:3984
	ds_read_b128 v[84:87], v161 offset:4000
	ds_read_b128 v[88:91], v162 offset:4016
	ds_read_b32 v101, v163 offset:4480
	ds_read_b128 v[96:99], v164 offset:36912
	ds_read_b128 v[52:55], v161 offset:3488
	ds_read_b128 v[56:59], v162 offset:3504
	v_pk_mul_f32 v[102:103], v[120:121], v[60:61]
	v_pk_mul_f32 v[104:105], v[120:121], v[36:37]
	v_pk_fma_f32 v[102:103], v[122:123], v[62:63], v[102:103]
	v_pk_fma_f32 v[104:105], v[122:123], v[38:39], v[104:105]
	v_pk_mul_f32 v[120:121], v[120:121], v[92:93] op_sel_hi:[1,0]
	v_pk_fma_f32 v[102:103], v[124:125], v[64:65], v[102:103]
	v_pk_fma_f32 v[104:105], v[124:125], v[40:41], v[104:105]
	v_pk_mul_f32 v[122:123], v[122:123], v[92:93] op_sel_hi:[1,0]
	v_pk_fma_f32 v[102:103], v[126:127], v[66:67], v[102:103]
	v_pk_fma_f32 v[104:105], v[126:127], v[42:43], v[104:105]
	v_pk_mul_f32 v[124:125], v[124:125], v[92:93] op_sel_hi:[1,0]
	v_pk_fma_f32 v[102:103], v[128:129], v[68:69], v[102:103]
	v_pk_fma_f32 v[104:105], v[128:129], v[44:45], v[104:105]
	v_pk_mul_f32 v[126:127], v[126:127], v[92:93] op_sel_hi:[1,0]
	v_pk_fma_f32 v[102:103], v[130:131], v[70:71], v[102:103]
	v_pk_fma_f32 v[104:105], v[130:131], v[46:47], v[104:105]
	v_pk_mul_f32 v[128:129], v[128:129], v[92:93] op_sel_hi:[1,0]
	v_pk_fma_f32 v[102:103], v[132:133], v[72:73], v[102:103]
	v_pk_fma_f32 v[104:105], v[132:133], v[48:49], v[104:105]
	v_pk_fma_f32 v[102:103], v[134:135], v[74:75], v[102:103]
	v_pk_fma_f32 v[104:105], v[134:135], v[50:51], v[104:105]
	v_add_f32_e64 v102, v102, v103
	v_add_f32_e64 v104, v104, v105
	ds_read_b128 v[36:39], v161 offset:3456
	ds_read_b128 v[40:43], v162 offset:3472
	v_add_f32_dpp v102, v102, v102 quad_perm:[1,0,3,2] row_mask:0xf bank_mask:0xf bound_ctrl:1
	v_add_f32_dpp v104, v104, v104 quad_perm:[1,0,3,2] row_mask:0xf bank_mask:0xf bound_ctrl:1
	v_pk_mul_f32 v[130:131], v[130:131], v[92:93] op_sel_hi:[1,0]
	v_add_f32_dpp v102, v102, v102 quad_perm:[2,3,0,1] row_mask:0xf bank_mask:0xf bound_ctrl:1
	v_add_f32_dpp v104, v104, v104 quad_perm:[2,3,0,1] row_mask:0xf bank_mask:0xf bound_ctrl:1
	v_pk_mul_f32 v[132:133], v[132:133], v[92:93] op_sel_hi:[1,0]
	v_add_f32_dpp v102, v102, v102 row_half_mirror row_mask:0xf bank_mask:0xf bound_ctrl:1
	v_add_f32_dpp v104, v104, v104 row_half_mirror row_mask:0xf bank_mask:0xf bound_ctrl:1
	v_fma_f32 v105, -v92, v102, v100
	v_pk_mul_f32 v[106:107], v[92:93], v[104:105]
	v_pk_mul_f32 v[134:135], v[134:135], v[92:93] op_sel_hi:[1,0]
	v_pk_fma_f32 v[120:121], v[60:61], v[106:107], v[120:121] op_sel:[0,1,0]
	v_pk_fma_f32 v[122:123], v[62:63], v[106:107], v[122:123] op_sel:[0,1,0]
	v_fma_f32 v106, v94, v107, v106
	v_pk_fma_f32 v[124:125], v[64:65], v[106:107], v[124:125] op_sel:[0,1,0]
	v_pk_fma_f32 v[126:127], v[66:67], v[106:107], v[126:127] op_sel:[0,1,0]
	v_pk_fma_f32 v[128:129], v[68:69], v[106:107], v[128:129] op_sel:[0,1,0]
	v_pk_fma_f32 v[130:131], v[70:71], v[106:107], v[130:131] op_sel:[0,1,0]
	v_pk_fma_f32 v[132:133], v[72:73], v[106:107], v[132:133] op_sel:[0,1,0]
	v_pk_fma_f32 v[134:135], v[74:75], v[106:107], v[134:135] op_sel:[0,1,0]
	ds_write_b32 v166, v106 offset:256
	s_waitcnt lgkmcnt(1)
; __device__ __forceinline__ float red8(float v) { v = red4(v); v += dppf<0x141>(v); return v; }
; __device__ __forceinline__ f32x2 lo2(const f32x4& v) { return __builtin_shufflevector(v, v, 0, 1); }
; __device__ __forceinline__ f32x2 hi2(const f32x4& v) { return __builtin_shufflevector(v, v, 2, 3); }
; __device__ __forceinline__ f32x2 splat2(float x) { return (f32x2){x, x}; }
; __device__ __forceinline__ void gd_load(GdRegs& R, const float* vb, const float* sb, int t, int k0, int cl) {
;   const float* vt = vb + t * 288;
; #pragma unroll
;   for (int q = 0; q < 4; ++q) {
;     R.q[q] = *(const f32x4*)(vt + k0 + q * 4);
;     R.k[q] = *(const f32x4*)(vt + 128 + k0 + q * 4);
;   }
;   R.v = vt[256 + cl];
;   R.sc = *(const f32x4*)(sb + t * 4);
; }
; __device__ __forceinline__ float gd_step(f32x2 (&S)[8], const GdRegs& R) {
;   f32x2 k0a = splat2(0.f), k1a = splat2(0.f), q0a = splat2(0.f), q1a = splat2(0.f);
; #pragma unroll
;   for (int q = 0; q < 4; ++q) {
;     k0a += S[2 * q] * lo2(R.k[q]);
;     k1a += S[2 * q + 1] * hi2(R.k[q]);
;     q0a += S[2 * q] * lo2(R.q[q]);
;     q1a += S[2 * q + 1] * hi2(R.q[q]);
;   }
;   k0a += k1a; q0a += q1a;
;   const float dK = red8(k0a.x + k0a.y), dQ = red8(q0a.x + q0a.y);
;   const float vn = R.sc.y * (R.v - R.sc.x * dK);
;   const float o = R.sc.x * dQ + R.sc.z * vn;
;   const f32x2 al2 = splat2(R.sc.x), vn2 = splat2(vn);
; #pragma unroll
;   for (int q = 0; q < 4; ++q) {
;     S[2 * q] = S[2 * q] * al2 + lo2(R.k[q]) * vn2;
;     S[2 * q + 1] = S[2 * q + 1] * al2 + hi2(R.k[q]) * vn2;
;   }
;   return o;
; }
	s_nop 0
	ds_read_b128 v[60:63], v161 offset:5120
	ds_read_b128 v[64:67], v162 offset:5136
	ds_read_b128 v[68:71], v161 offset:5152
	ds_read_b128 v[72:75], v162 offset:5168
	ds_read_b32 v100, v163 offset:5632
	ds_read_b128 v[92:95], v164 offset:36928
	ds_read_b128 v[44:47], v161 offset:4640
	ds_read_b128 v[48:51], v162 offset:4656
	v_pk_mul_f32 v[102:103], v[120:121], v[76:77]
	v_pk_mul_f32 v[104:105], v[120:121], v[36:37]
	v_pk_fma_f32 v[102:103], v[122:123], v[78:79], v[102:103]
	v_pk_fma_f32 v[104:105], v[122:123], v[38:39], v[104:105]
	v_pk_mul_f32 v[120:121], v[120:121], v[96:97] op_sel_hi:[1,0]
	v_pk_fma_f32 v[102:103], v[124:125], v[80:81], v[102:103]
	v_pk_fma_f32 v[104:105], v[124:125], v[40:41], v[104:105]
	v_pk_mul_f32 v[122:123], v[122:123], v[96:97] op_sel_hi:[1,0]
	v_pk_fma_f32 v[102:103], v[126:127], v[82:83], v[102:103]
	v_pk_fma_f32 v[104:105], v[126:127], v[42:43], v[104:105]
	v_pk_mul_f32 v[124:125], v[124:125], v[96:97] op_sel_hi:[1,0]
	v_pk_fma_f32 v[102:103], v[128:129], v[84:85], v[102:103]
	v_pk_fma_f32 v[104:105], v[128:129], v[52:53], v[104:105]
	v_pk_mul_f32 v[126:127], v[126:127], v[96:97] op_sel_hi:[1,0]
	v_pk_fma_f32 v[102:103], v[130:131], v[86:87], v[102:103]
	v_pk_fma_f32 v[104:105], v[130:131], v[54:55], v[104:105]
	v_pk_mul_f32 v[128:129], v[128:129], v[96:97] op_sel_hi:[1,0]
	v_pk_fma_f32 v[102:103], v[132:133], v[88:89], v[102:103]
	v_pk_fma_f32 v[104:105], v[132:133], v[56:57], v[104:105]
	v_pk_fma_f32 v[102:103], v[134:135], v[90:91], v[102:103]
	v_pk_fma_f32 v[104:105], v[134:135], v[58:59], v[104:105]
	v_add_f32_e64 v102, v102, v103
	v_add_f32_e64 v104, v104, v105
	ds_read_b128 v[36:39], v161 offset:4608
	ds_read_b128 v[40:43], v162 offset:4624
	v_add_f32_dpp v102, v102, v102 quad_perm:[1,0,3,2] row_mask:0xf bank_mask:0xf bound_ctrl:1
	v_add_f32_dpp v104, v104, v104 quad_perm:[1,0,3,2] row_mask:0xf bank_mask:0xf bound_ctrl:1
	v_pk_mul_f32 v[130:131], v[130:131], v[96:97] op_sel_hi:[1,0]
	v_add_f32_dpp v102, v102, v102 quad_perm:[2,3,0,1] row_mask:0xf bank_mask:0xf bound_ctrl:1
	v_add_f32_dpp v104, v104, v104 quad_perm:[2,3,0,1] row_mask:0xf bank_mask:0xf bound_ctrl:1
	v_pk_mul_f32 v[132:133], v[132:133], v[96:97] op_sel_hi:[1,0]
	v_add_f32_dpp v102, v102, v102 row_half_mirror row_mask:0xf bank_mask:0xf bound_ctrl:1
	v_add_f32_dpp v104, v104, v104 row_half_mirror row_mask:0xf bank_mask:0xf bound_ctrl:1
	v_fma_f32 v105, -v96, v102, v101
	v_pk_mul_f32 v[106:107], v[96:97], v[104:105]
	v_pk_mul_f32 v[134:135], v[134:135], v[96:97] op_sel_hi:[1,0]
	v_pk_fma_f32 v[120:121], v[76:77], v[106:107], v[120:121] op_sel:[0,1,0]
	v_pk_fma_f32 v[122:123], v[78:79], v[106:107], v[122:123] op_sel:[0,1,0]
	v_fma_f32 v106, v98, v107, v106
	v_pk_fma_f32 v[124:125], v[80:81], v[106:107], v[124:125] op_sel:[0,1,0]
	v_pk_fma_f32 v[126:127], v[82:83], v[106:107], v[126:127] op_sel:[0,1,0]
	v_pk_fma_f32 v[128:129], v[84:85], v[106:107], v[128:129] op_sel:[0,1,0]
	v_pk_fma_f32 v[130:131], v[86:87], v[106:107], v[130:131] op_sel:[0,1,0]
	v_pk_fma_f32 v[132:133], v[88:89], v[106:107], v[132:133] op_sel:[0,1,0]
	v_pk_fma_f32 v[134:135], v[90:91], v[106:107], v[134:135] op_sel:[0,1,0]
	ds_write_b32 v166, v106 offset:384
	s_waitcnt lgkmcnt(1)
	s_nop 0
	ds_read_b128 v[76:79], v161 offset:6272
	ds_read_b128 v[80:83], v162 offset:6288
	ds_read_b128 v[84:87], v161 offset:6304
	ds_read_b128 v[88:91], v162 offset:6320
	ds_read_b32 v101, v163 offset:6784
	ds_read_b128 v[96:99], v164 offset:36944
	ds_read_b128 v[52:55], v161 offset:5792
	ds_read_b128 v[56:59], v162 offset:5808
	v_pk_mul_f32 v[102:103], v[120:121], v[60:61]
	v_pk_mul_f32 v[104:105], v[120:121], v[36:37]
	v_pk_fma_f32 v[102:103], v[122:123], v[62:63], v[102:103]
	v_pk_fma_f32 v[104:105], v[122:123], v[38:39], v[104:105]
	v_pk_mul_f32 v[120:121], v[120:121], v[92:93] op_sel_hi:[1,0]
	v_pk_fma_f32 v[102:103], v[124:125], v[64:65], v[102:103]
	v_pk_fma_f32 v[104:105], v[124:125], v[40:41], v[104:105]
	v_pk_mul_f32 v[122:123], v[122:123], v[92:93] op_sel_hi:[1,0]
	v_pk_fma_f32 v[102:103], v[126:127], v[66:67], v[102:103]
	v_pk_fma_f32 v[104:105], v[126:127], v[42:43], v[104:105]
	v_pk_mul_f32 v[124:125], v[124:125], v[92:93] op_sel_hi:[1,0]
	v_pk_fma_f32 v[102:103], v[128:129], v[68:69], v[102:103]
	v_pk_fma_f32 v[104:105], v[128:129], v[44:45], v[104:105]
	v_pk_mul_f32 v[126:127], v[126:127], v[92:93] op_sel_hi:[1,0]
	v_pk_fma_f32 v[102:103], v[130:131], v[70:71], v[102:103]
	v_pk_fma_f32 v[104:105], v[130:131], v[46:47], v[104:105]
	v_pk_mul_f32 v[128:129], v[128:129], v[92:93] op_sel_hi:[1,0]
	v_pk_fma_f32 v[102:103], v[132:133], v[72:73], v[102:103]
	v_pk_fma_f32 v[104:105], v[132:133], v[48:49], v[104:105]
	v_pk_fma_f32 v[102:103], v[134:135], v[74:75], v[102:103]
	v_pk_fma_f32 v[104:105], v[134:135], v[50:51], v[104:105]
	v_add_f32_e64 v102, v102, v103
	v_add_f32_e64 v104, v104, v105
	ds_read_b128 v[36:39], v161 offset:5760
	ds_read_b128 v[40:43], v162 offset:5776
	v_add_f32_dpp v102, v102, v102 quad_perm:[1,0,3,2] row_mask:0xf bank_mask:0xf bound_ctrl:1
	v_add_f32_dpp v104, v104, v104 quad_perm:[1,0,3,2] row_mask:0xf bank_mask:0xf bound_ctrl:1
	v_pk_mul_f32 v[130:131], v[130:131], v[92:93] op_sel_hi:[1,0]
	v_add_f32_dpp v102, v102, v102 quad_perm:[2,3,0,1] row_mask:0xf bank_mask:0xf bound_ctrl:1
	v_add_f32_dpp v104, v104, v104 quad_perm:[2,3,0,1] row_mask:0xf bank_mask:0xf bound_ctrl:1
	v_pk_mul_f32 v[132:133], v[132:133], v[92:93] op_sel_hi:[1,0]
	v_add_f32_dpp v102, v102, v102 row_half_mirror row_mask:0xf bank_mask:0xf bound_ctrl:1
	v_add_f32_dpp v104, v104, v104 row_half_mirror row_mask:0xf bank_mask:0xf bound_ctrl:1
	v_fma_f32 v105, -v92, v102, v100
	v_pk_mul_f32 v[106:107], v[92:93], v[104:105]
	v_pk_mul_f32 v[134:135], v[134:135], v[92:93] op_sel_hi:[1,0]
	v_pk_fma_f32 v[120:121], v[60:61], v[106:107], v[120:121] op_sel:[0,1,0]
	v_pk_fma_f32 v[122:123], v[62:63], v[106:107], v[122:123] op_sel:[0,1,0]
	v_fma_f32 v106, v94, v107, v106
	v_pk_fma_f32 v[124:125], v[64:65], v[106:107], v[124:125] op_sel:[0,1,0]
	v_pk_fma_f32 v[126:127], v[66:67], v[106:107], v[126:127] op_sel:[0,1,0]
	v_pk_fma_f32 v[128:129], v[68:69], v[106:107], v[128:129] op_sel:[0,1,0]
	v_pk_fma_f32 v[130:131], v[70:71], v[106:107], v[130:131] op_sel:[0,1,0]
	v_pk_fma_f32 v[132:133], v[72:73], v[106:107], v[132:133] op_sel:[0,1,0]
	v_pk_fma_f32 v[134:135], v[74:75], v[106:107], v[134:135] op_sel:[0,1,0]
	ds_write_b32 v166, v106 offset:512
	s_waitcnt lgkmcnt(1)
; __device__ __forceinline__ float red8(float v) { v = red4(v); v += dppf<0x141>(v); return v; }
; __device__ __forceinline__ f32x2 lo2(const f32x4& v) { return __builtin_shufflevector(v, v, 0, 1); }
; __device__ __forceinline__ f32x2 hi2(const f32x4& v) { return __builtin_shufflevector(v, v, 2, 3); }
; __device__ __forceinline__ f32x2 splat2(float x) { return (f32x2){x, x}; }
; __device__ __forceinline__ void gd_load(GdRegs& R, const float* vb, const float* sb, int t, int k0, int cl) {
;   const float* vt = vb + t * 288;
; #pragma unroll
;   for (int q = 0; q < 4; ++q) {
;     R.q[q] = *(const f32x4*)(vt + k0 + q * 4);
;     R.k[q] = *(const f32x4*)(vt + 128 + k0 + q * 4);
;   }
;   R.v = vt[256 + cl];
;   R.sc = *(const f32x4*)(sb + t * 4);
; }
; __device__ __forceinline__ float gd_step(f32x2 (&S)[8], const GdRegs& R) {
;   f32x2 k0a = splat2(0.f), k1a = splat2(0.f), q0a = splat2(0.f), q1a = splat2(0.f);
; #pragma unroll
;   for (int q = 0; q < 4; ++q) {
;     k0a += S[2 * q] * lo2(R.k[q]);
;     k1a += S[2 * q + 1] * hi2(R.k[q]);
;     q0a += S[2 * q] * lo2(R.q[q]);
;     q1a += S[2 * q + 1] * hi2(R.q[q]);
;   }
;   k0a += k1a; q0a += q1a;
;   const float dK = red8(k0a.x + k0a.y), dQ = red8(q0a.x + q0a.y);
;   const float vn = R.sc.y * (R.v - R.sc.x * dK);
;   const float o = R.sc.x * dQ + R.sc.z * vn;
;   const f32x2 al2 = splat2(R.sc.x), vn2 = splat2(vn);
; #pragma unroll
;   for (int q = 0; q < 4; ++q) {
;     S[2 * q] = S[2 * q] * al2 + lo2(R.k[q]) * vn2;
;     S[2 * q + 1] = S[2 * q + 1] * al2 + hi2(R.k[q]) * vn2;
;   }
;   return o;
; }
	s_nop 0
	ds_read_b128 v[60:63], v161 offset:7424
	ds_read_b128 v[64:67], v162 offset:7440
	ds_read_b128 v[68:71], v161 offset:7456
	ds_read_b128 v[72:75], v162 offset:7472
	ds_read_b32 v100, v163 offset:7936
	ds_read_b128 v[92:95], v164 offset:36960
	ds_read_b128 v[44:47], v161 offset:6944
	ds_read_b128 v[48:51], v162 offset:6960
	v_pk_mul_f32 v[102:103], v[120:121], v[76:77]
	v_pk_mul_f32 v[104:105], v[120:121], v[36:37]
	v_pk_fma_f32 v[102:103], v[122:123], v[78:79], v[102:103]
	v_pk_fma_f32 v[104:105], v[122:123], v[38:39], v[104:105]
	v_pk_mul_f32 v[120:121], v[120:121], v[96:97] op_sel_hi:[1,0]
	v_pk_fma_f32 v[102:103], v[124:125], v[80:81], v[102:103]
	v_pk_fma_f32 v[104:105], v[124:125], v[40:41], v[104:105]
	v_pk_mul_f32 v[122:123], v[122:123], v[96:97] op_sel_hi:[1,0]
	v_pk_fma_f32 v[102:103], v[126:127], v[82:83], v[102:103]
	v_pk_fma_f32 v[104:105], v[126:127], v[42:43], v[104:105]
	v_pk_mul_f32 v[124:125], v[124:125], v[96:97] op_sel_hi:[1,0]
	v_pk_fma_f32 v[102:103], v[128:129], v[84:85], v[102:103]
	v_pk_fma_f32 v[104:105], v[128:129], v[52:53], v[104:105]
	v_pk_mul_f32 v[126:127], v[126:127], v[96:97] op_sel_hi:[1,0]
	v_pk_fma_f32 v[102:103], v[130:131], v[86:87], v[102:103]
	v_pk_fma_f32 v[104:105], v[130:131], v[54:55], v[104:105]
	v_pk_mul_f32 v[128:129], v[128:129], v[96:97] op_sel_hi:[1,0]
	v_pk_fma_f32 v[102:103], v[132:133], v[88:89], v[102:103]
	v_pk_fma_f32 v[104:105], v[132:133], v[56:57], v[104:105]
	v_pk_fma_f32 v[102:103], v[134:135], v[90:91], v[102:103]
	v_pk_fma_f32 v[104:105], v[134:135], v[58:59], v[104:105]
	v_add_f32_e64 v102, v102, v103
	v_add_f32_e64 v104, v104, v105
	ds_read_b128 v[36:39], v161 offset:6912
	ds_read_b128 v[40:43], v162 offset:6928
	v_add_f32_dpp v102, v102, v102 quad_perm:[1,0,3,2] row_mask:0xf bank_mask:0xf bound_ctrl:1
	v_add_f32_dpp v104, v104, v104 quad_perm:[1,0,3,2] row_mask:0xf bank_mask:0xf bound_ctrl:1
	v_pk_mul_f32 v[130:131], v[130:131], v[96:97] op_sel_hi:[1,0]
	v_add_f32_dpp v102, v102, v102 quad_perm:[2,3,0,1] row_mask:0xf bank_mask:0xf bound_ctrl:1
	v_add_f32_dpp v104, v104, v104 quad_perm:[2,3,0,1] row_mask:0xf bank_mask:0xf bound_ctrl:1
	v_pk_mul_f32 v[132:133], v[132:133], v[96:97] op_sel_hi:[1,0]
	v_add_f32_dpp v102, v102, v102 row_half_mirror row_mask:0xf bank_mask:0xf bound_ctrl:1
	v_add_f32_dpp v104, v104, v104 row_half_mirror row_mask:0xf bank_mask:0xf bound_ctrl:1
	v_fma_f32 v105, -v96, v102, v101
	v_pk_mul_f32 v[106:107], v[96:97], v[104:105]
	v_pk_mul_f32 v[134:135], v[134:135], v[96:97] op_sel_hi:[1,0]
	v_pk_fma_f32 v[120:121], v[76:77], v[106:107], v[120:121] op_sel:[0,1,0]
	v_pk_fma_f32 v[122:123], v[78:79], v[106:107], v[122:123] op_sel:[0,1,0]
	v_fma_f32 v106, v98, v107, v106
	v_pk_fma_f32 v[124:125], v[80:81], v[106:107], v[124:125] op_sel:[0,1,0]
	v_pk_fma_f32 v[126:127], v[82:83], v[106:107], v[126:127] op_sel:[0,1,0]
	v_pk_fma_f32 v[128:129], v[84:85], v[106:107], v[128:129] op_sel:[0,1,0]
	v_pk_fma_f32 v[130:131], v[86:87], v[106:107], v[130:131] op_sel:[0,1,0]
	v_pk_fma_f32 v[132:133], v[88:89], v[106:107], v[132:133] op_sel:[0,1,0]
	v_pk_fma_f32 v[134:135], v[90:91], v[106:107], v[134:135] op_sel:[0,1,0]
	ds_write_b32 v166, v106 offset:640
	s_waitcnt lgkmcnt(1)
	s_nop 0
	ds_read_b128 v[76:79], v161 offset:8576
	ds_read_b128 v[80:83], v162 offset:8592
	ds_read_b128 v[84:87], v161 offset:8608
	ds_read_b128 v[88:91], v162 offset:8624
	ds_read_b32 v101, v163 offset:9088
	ds_read_b128 v[96:99], v164 offset:36976
	ds_read_b128 v[52:55], v161 offset:8096
	ds_read_b128 v[56:59], v162 offset:8112
	v_pk_mul_f32 v[102:103], v[120:121], v[60:61]
	v_pk_mul_f32 v[104:105], v[120:121], v[36:37]
	v_pk_fma_f32 v[102:103], v[122:123], v[62:63], v[102:103]
	v_pk_fma_f32 v[104:105], v[122:123], v[38:39], v[104:105]
	v_pk_mul_f32 v[120:121], v[120:121], v[92:93] op_sel_hi:[1,0]
	v_pk_fma_f32 v[102:103], v[124:125], v[64:65], v[102:103]
	v_pk_fma_f32 v[104:105], v[124:125], v[40:41], v[104:105]
	v_pk_mul_f32 v[122:123], v[122:123], v[92:93] op_sel_hi:[1,0]
	v_pk_fma_f32 v[102:103], v[126:127], v[66:67], v[102:103]
	v_pk_fma_f32 v[104:105], v[126:127], v[42:43], v[104:105]
	v_pk_mul_f32 v[124:125], v[124:125], v[92:93] op_sel_hi:[1,0]
	v_pk_fma_f32 v[102:103], v[128:129], v[68:69], v[102:103]
	v_pk_fma_f32 v[104:105], v[128:129], v[44:45], v[104:105]
	v_pk_mul_f32 v[126:127], v[126:127], v[92:93] op_sel_hi:[1,0]
	v_pk_fma_f32 v[102:103], v[130:131], v[70:71], v[102:103]
	v_pk_fma_f32 v[104:105], v[130:131], v[46:47], v[104:105]
	v_pk_mul_f32 v[128:129], v[128:129], v[92:93] op_sel_hi:[1,0]
	v_pk_fma_f32 v[102:103], v[132:133], v[72:73], v[102:103]
	v_pk_fma_f32 v[104:105], v[132:133], v[48:49], v[104:105]
	v_pk_fma_f32 v[102:103], v[134:135], v[74:75], v[102:103]
	v_pk_fma_f32 v[104:105], v[134:135], v[50:51], v[104:105]
	v_add_f32_e64 v102, v102, v103
	v_add_f32_e64 v104, v104, v105
	ds_read_b128 v[36:39], v161 offset:8064
	ds_read_b128 v[40:43], v162 offset:8080
	v_add_f32_dpp v102, v102, v102 quad_perm:[1,0,3,2] row_mask:0xf bank_mask:0xf bound_ctrl:1
	v_add_f32_dpp v104, v104, v104 quad_perm:[1,0,3,2] row_mask:0xf bank_mask:0xf bound_ctrl:1
	v_pk_mul_f32 v[130:131], v[130:131], v[92:93] op_sel_hi:[1,0]
	v_add_f32_dpp v102, v102, v102 quad_perm:[2,3,0,1] row_mask:0xf bank_mask:0xf bound_ctrl:1
	v_add_f32_dpp v104, v104, v104 quad_perm:[2,3,0,1] row_mask:0xf bank_mask:0xf bound_ctrl:1
	v_pk_mul_f32 v[132:133], v[132:133], v[92:93] op_sel_hi:[1,0]
	v_add_f32_dpp v102, v102, v102 row_half_mirror row_mask:0xf bank_mask:0xf bound_ctrl:1
	v_add_f32_dpp v104, v104, v104 row_half_mirror row_mask:0xf bank_mask:0xf bound_ctrl:1
	v_fma_f32 v105, -v92, v102, v100
	v_pk_mul_f32 v[106:107], v[92:93], v[104:105]
	v_pk_mul_f32 v[134:135], v[134:135], v[92:93] op_sel_hi:[1,0]
	v_pk_fma_f32 v[120:121], v[60:61], v[106:107], v[120:121] op_sel:[0,1,0]
	v_pk_fma_f32 v[122:123], v[62:63], v[106:107], v[122:123] op_sel:[0,1,0]
	v_fma_f32 v106, v94, v107, v106
	v_pk_fma_f32 v[124:125], v[64:65], v[106:107], v[124:125] op_sel:[0,1,0]
	v_pk_fma_f32 v[126:127], v[66:67], v[106:107], v[126:127] op_sel:[0,1,0]
	v_pk_fma_f32 v[128:129], v[68:69], v[106:107], v[128:129] op_sel:[0,1,0]
	v_pk_fma_f32 v[130:131], v[70:71], v[106:107], v[130:131] op_sel:[0,1,0]
	v_pk_fma_f32 v[132:133], v[72:73], v[106:107], v[132:133] op_sel:[0,1,0]
	v_pk_fma_f32 v[134:135], v[74:75], v[106:107], v[134:135] op_sel:[0,1,0]
	ds_write_b32 v166, v106 offset:768
	s_waitcnt lgkmcnt(1)
; __device__ __forceinline__ float red8(float v) { v = red4(v); v += dppf<0x141>(v); return v; }
; __device__ __forceinline__ f32x2 lo2(const f32x4& v) { return __builtin_shufflevector(v, v, 0, 1); }
; __device__ __forceinline__ f32x2 hi2(const f32x4& v) { return __builtin_shufflevector(v, v, 2, 3); }
; __device__ __forceinline__ f32x2 splat2(float x) { return (f32x2){x, x}; }
; __device__ __forceinline__ void gd_load(GdRegs& R, const float* vb, const float* sb, int t, int k0, int cl) {
;   const float* vt = vb + t * 288;
; #pragma unroll
;   for (int q = 0; q < 4; ++q) {
;     R.q[q] = *(const f32x4*)(vt + k0 + q * 4);
;     R.k[q] = *(const f32x4*)(vt + 128 + k0 + q * 4);
;   }
;   R.v = vt[256 + cl];
;   R.sc = *(const f32x4*)(sb + t * 4);
; }
; __device__ __forceinline__ float gd_step(f32x2 (&S)[8], const GdRegs& R) {
;   f32x2 k0a = splat2(0.f), k1a = splat2(0.f), q0a = splat2(0.f), q1a = splat2(0.f);
; #pragma unroll
;   for (int q = 0; q < 4; ++q) {
;     k0a += S[2 * q] * lo2(R.k[q]);
;     k1a += S[2 * q + 1] * hi2(R.k[q]);
;     q0a += S[2 * q] * lo2(R.q[q]);
;     q1a += S[2 * q + 1] * hi2(R.q[q]);
;   }
;   k0a += k1a; q0a += q1a;
;   const float dK = red8(k0a.x + k0a.y), dQ = red8(q0a.x + q0a.y);
;   const float vn = R.sc.y * (R.v - R.sc.x * dK);
;   const float o = R.sc.x * dQ + R.sc.z * vn;
;   const f32x2 al2 = splat2(R.sc.x), vn2 = splat2(vn);
; #pragma unroll
;   for (int q = 0; q < 4; ++q) {
;     S[2 * q] = S[2 * q] * al2 + lo2(R.k[q]) * vn2;
;     S[2 * q + 1] = S[2 * q + 1] * al2 + hi2(R.k[q]) * vn2;
;   }
;   return o;
; }
	s_nop 0
	ds_read_b128 v[60:63], v161 offset:9728
	ds_read_b128 v[64:67], v162 offset:9744
	ds_read_b128 v[68:71], v161 offset:9760
	ds_read_b128 v[72:75], v162 offset:9776
	ds_read_b32 v100, v163 offset:10240
	ds_read_b128 v[92:95], v164 offset:36992
	ds_read_b128 v[44:47], v161 offset:9248
	ds_read_b128 v[48:51], v162 offset:9264
	v_pk_mul_f32 v[102:103], v[120:121], v[76:77]
	v_pk_mul_f32 v[104:105], v[120:121], v[36:37]
	v_pk_fma_f32 v[102:103], v[122:123], v[78:79], v[102:103]
	v_pk_fma_f32 v[104:105], v[122:123], v[38:39], v[104:105]
	v_pk_mul_f32 v[120:121], v[120:121], v[96:97] op_sel_hi:[1,0]
	v_pk_fma_f32 v[102:103], v[124:125], v[80:81], v[102:103]
	v_pk_fma_f32 v[104:105], v[124:125], v[40:41], v[104:105]
	v_pk_mul_f32 v[122:123], v[122:123], v[96:97] op_sel_hi:[1,0]
	v_pk_fma_f32 v[102:103], v[126:127], v[82:83], v[102:103]
	v_pk_fma_f32 v[104:105], v[126:127], v[42:43], v[104:105]
	v_pk_mul_f32 v[124:125], v[124:125], v[96:97] op_sel_hi:[1,0]
	v_pk_fma_f32 v[102:103], v[128:129], v[84:85], v[102:103]
	v_pk_fma_f32 v[104:105], v[128:129], v[52:53], v[104:105]
	v_pk_mul_f32 v[126:127], v[126:127], v[96:97] op_sel_hi:[1,0]
	v_pk_fma_f32 v[102:103], v[130:131], v[86:87], v[102:103]
	v_pk_fma_f32 v[104:105], v[130:131], v[54:55], v[104:105]
	v_pk_mul_f32 v[128:129], v[128:129], v[96:97] op_sel_hi:[1,0]
	v_pk_fma_f32 v[102:103], v[132:133], v[88:89], v[102:103]
	v_pk_fma_f32 v[104:105], v[132:133], v[56:57], v[104:105]
	v_pk_fma_f32 v[102:103], v[134:135], v[90:91], v[102:103]
	v_pk_fma_f32 v[104:105], v[134:135], v[58:59], v[104:105]
	v_add_f32_e64 v102, v102, v103
	v_add_f32_e64 v104, v104, v105
	ds_read_b128 v[36:39], v161 offset:9216
	ds_read_b128 v[40:43], v162 offset:9232
	v_add_f32_dpp v102, v102, v102 quad_perm:[1,0,3,2] row_mask:0xf bank_mask:0xf bound_ctrl:1
	v_add_f32_dpp v104, v104, v104 quad_perm:[1,0,3,2] row_mask:0xf bank_mask:0xf bound_ctrl:1
	v_pk_mul_f32 v[130:131], v[130:131], v[96:97] op_sel_hi:[1,0]
	v_add_f32_dpp v102, v102, v102 quad_perm:[2,3,0,1] row_mask:0xf bank_mask:0xf bound_ctrl:1
	v_add_f32_dpp v104, v104, v104 quad_perm:[2,3,0,1] row_mask:0xf bank_mask:0xf bound_ctrl:1
	v_pk_mul_f32 v[132:133], v[132:133], v[96:97] op_sel_hi:[1,0]
	v_add_f32_dpp v102, v102, v102 row_half_mirror row_mask:0xf bank_mask:0xf bound_ctrl:1
	v_add_f32_dpp v104, v104, v104 row_half_mirror row_mask:0xf bank_mask:0xf bound_ctrl:1
	v_fma_f32 v105, -v96, v102, v101
	v_pk_mul_f32 v[106:107], v[96:97], v[104:105]
	v_pk_mul_f32 v[134:135], v[134:135], v[96:97] op_sel_hi:[1,0]
	v_pk_fma_f32 v[120:121], v[76:77], v[106:107], v[120:121] op_sel:[0,1,0]
	v_pk_fma_f32 v[122:123], v[78:79], v[106:107], v[122:123] op_sel:[0,1,0]
	v_fma_f32 v106, v98, v107, v106
	v_pk_fma_f32 v[124:125], v[80:81], v[106:107], v[124:125] op_sel:[0,1,0]
	v_pk_fma_f32 v[126:127], v[82:83], v[106:107], v[126:127] op_sel:[0,1,0]
	v_pk_fma_f32 v[128:129], v[84:85], v[106:107], v[128:129] op_sel:[0,1,0]
	v_pk_fma_f32 v[130:131], v[86:87], v[106:107], v[130:131] op_sel:[0,1,0]
	v_pk_fma_f32 v[132:133], v[88:89], v[106:107], v[132:133] op_sel:[0,1,0]
	v_pk_fma_f32 v[134:135], v[90:91], v[106:107], v[134:135] op_sel:[0,1,0]
	ds_write_b32 v166, v106 offset:896
	s_waitcnt lgkmcnt(1)
	s_nop 0
	ds_read_b128 v[76:79], v161 offset:10880
	ds_read_b128 v[80:83], v162 offset:10896
	ds_read_b128 v[84:87], v161 offset:10912
	ds_read_b128 v[88:91], v162 offset:10928
	ds_read_b32 v101, v163 offset:11392
	ds_read_b128 v[96:99], v164 offset:37008
	ds_read_b128 v[52:55], v161 offset:10400
	ds_read_b128 v[56:59], v162 offset:10416
	v_pk_mul_f32 v[102:103], v[120:121], v[60:61]
	v_pk_mul_f32 v[104:105], v[120:121], v[36:37]
	v_pk_fma_f32 v[102:103], v[122:123], v[62:63], v[102:103]
	v_pk_fma_f32 v[104:105], v[122:123], v[38:39], v[104:105]
	v_pk_mul_f32 v[120:121], v[120:121], v[92:93] op_sel_hi:[1,0]
	v_pk_fma_f32 v[102:103], v[124:125], v[64:65], v[102:103]
	v_pk_fma_f32 v[104:105], v[124:125], v[40:41], v[104:105]
	v_pk_mul_f32 v[122:123], v[122:123], v[92:93] op_sel_hi:[1,0]
	v_pk_fma_f32 v[102:103], v[126:127], v[66:67], v[102:103]
	v_pk_fma_f32 v[104:105], v[126:127], v[42:43], v[104:105]
	v_pk_mul_f32 v[124:125], v[124:125], v[92:93] op_sel_hi:[1,0]
	v_pk_fma_f32 v[102:103], v[128:129], v[68:69], v[102:103]
	v_pk_fma_f32 v[104:105], v[128:129], v[44:45], v[104:105]
	v_pk_mul_f32 v[126:127], v[126:127], v[92:93] op_sel_hi:[1,0]
	v_pk_fma_f32 v[102:103], v[130:131], v[70:71], v[102:103]
	v_pk_fma_f32 v[104:105], v[130:131], v[46:47], v[104:105]
	v_pk_mul_f32 v[128:129], v[128:129], v[92:93] op_sel_hi:[1,0]
	v_pk_fma_f32 v[102:103], v[132:133], v[72:73], v[102:103]
	v_pk_fma_f32 v[104:105], v[132:133], v[48:49], v[104:105]
	v_pk_fma_f32 v[102:103], v[134:135], v[74:75], v[102:103]
	v_pk_fma_f32 v[104:105], v[134:135], v[50:51], v[104:105]
	v_add_f32_e64 v102, v102, v103
	v_add_f32_e64 v104, v104, v105
	ds_read_b128 v[36:39], v161 offset:10368
	ds_read_b128 v[40:43], v162 offset:10384
	v_add_f32_dpp v102, v102, v102 quad_perm:[1,0,3,2] row_mask:0xf bank_mask:0xf bound_ctrl:1
	v_add_f32_dpp v104, v104, v104 quad_perm:[1,0,3,2] row_mask:0xf bank_mask:0xf bound_ctrl:1
	v_pk_mul_f32 v[130:131], v[130:131], v[92:93] op_sel_hi:[1,0]
	v_add_f32_dpp v102, v102, v102 quad_perm:[2,3,0,1] row_mask:0xf bank_mask:0xf bound_ctrl:1
	v_add_f32_dpp v104, v104, v104 quad_perm:[2,3,0,1] row_mask:0xf bank_mask:0xf bound_ctrl:1
	v_pk_mul_f32 v[132:133], v[132:133], v[92:93] op_sel_hi:[1,0]
	v_add_f32_dpp v102, v102, v102 row_half_mirror row_mask:0xf bank_mask:0xf bound_ctrl:1
	v_add_f32_dpp v104, v104, v104 row_half_mirror row_mask:0xf bank_mask:0xf bound_ctrl:1
	v_fma_f32 v105, -v92, v102, v100
	v_pk_mul_f32 v[106:107], v[92:93], v[104:105]
	v_pk_mul_f32 v[134:135], v[134:135], v[92:93] op_sel_hi:[1,0]
	v_pk_fma_f32 v[120:121], v[60:61], v[106:107], v[120:121] op_sel:[0,1,0]
	v_pk_fma_f32 v[122:123], v[62:63], v[106:107], v[122:123] op_sel:[0,1,0]
	v_fma_f32 v106, v94, v107, v106
	v_pk_fma_f32 v[124:125], v[64:65], v[106:107], v[124:125] op_sel:[0,1,0]
	v_pk_fma_f32 v[126:127], v[66:67], v[106:107], v[126:127] op_sel:[0,1,0]
	v_pk_fma_f32 v[128:129], v[68:69], v[106:107], v[128:129] op_sel:[0,1,0]
	v_pk_fma_f32 v[130:131], v[70:71], v[106:107], v[130:131] op_sel:[0,1,0]
	v_pk_fma_f32 v[132:133], v[72:73], v[106:107], v[132:133] op_sel:[0,1,0]
	v_pk_fma_f32 v[134:135], v[74:75], v[106:107], v[134:135] op_sel:[0,1,0]
	ds_write_b32 v166, v106 offset:1024
	s_waitcnt lgkmcnt(1)
; __device__ __forceinline__ float red8(float v) { v = red4(v); v += dppf<0x141>(v); return v; }
; __device__ __forceinline__ f32x2 lo2(const f32x4& v) { return __builtin_shufflevector(v, v, 0, 1); }
; __device__ __forceinline__ f32x2 hi2(const f32x4& v) { return __builtin_shufflevector(v, v, 2, 3); }
; __device__ __forceinline__ f32x2 splat2(float x) { return (f32x2){x, x}; }
; __device__ __forceinline__ void gd_load(GdRegs& R, const float* vb, const float* sb, int t, int k0, int cl) {
;   const float* vt = vb + t * 288;
; #pragma unroll
;   for (int q = 0; q < 4; ++q) {
;     R.q[q] = *(const f32x4*)(vt + k0 + q * 4);
;     R.k[q] = *(const f32x4*)(vt + 128 + k0 + q * 4);
;   }
;   R.v = vt[256 + cl];
;   R.sc = *(const f32x4*)(sb + t * 4);
; }
; __device__ __forceinline__ float gd_step(f32x2 (&S)[8], const GdRegs& R) {
;   f32x2 k0a = splat2(0.f), k1a = splat2(0.f), q0a = splat2(0.f), q1a = splat2(0.f);
; #pragma unroll
;   for (int q = 0; q < 4; ++q) {
;     k0a += S[2 * q] * lo2(R.k[q]);
;     k1a += S[2 * q + 1] * hi2(R.k[q]);
;     q0a += S[2 * q] * lo2(R.q[q]);
;     q1a += S[2 * q + 1] * hi2(R.q[q]);
;   }
;   k0a += k1a; q0a += q1a;
;   const float dK = red8(k0a.x + k0a.y), dQ = red8(q0a.x + q0a.y);
;   const float vn = R.sc.y * (R.v - R.sc.x * dK);
;   const float o = R.sc.x * dQ + R.sc.z * vn;
;   const f32x2 al2 = splat2(R.sc.x), vn2 = splat2(vn);
; #pragma unroll
;   for (int q = 0; q < 4; ++q) {
;     S[2 * q] = S[2 * q] * al2 + lo2(R.k[q]) * vn2;
;     S[2 * q + 1] = S[2 * q + 1] * al2 + hi2(R.k[q]) * vn2;
;   }
;   return o;
; }
	s_nop 0
	ds_read_b128 v[60:63], v161 offset:12032
	ds_read_b128 v[64:67], v162 offset:12048
	ds_read_b128 v[68:71], v161 offset:12064
	ds_read_b128 v[72:75], v162 offset:12080
	ds_read_b32 v100, v163 offset:12544
	ds_read_b128 v[92:95], v164 offset:37024
	ds_read_b128 v[44:47], v161 offset:11552
	ds_read_b128 v[48:51], v162 offset:11568
	v_pk_mul_f32 v[102:103], v[120:121], v[76:77]
	v_pk_mul_f32 v[104:105], v[120:121], v[36:37]
	v_pk_fma_f32 v[102:103], v[122:123], v[78:79], v[102:103]
	v_pk_fma_f32 v[104:105], v[122:123], v[38:39], v[104:105]
	v_pk_mul_f32 v[120:121], v[120:121], v[96:97] op_sel_hi:[1,0]
	v_pk_fma_f32 v[102:103], v[124:125], v[80:81], v[102:103]
	v_pk_fma_f32 v[104:105], v[124:125], v[40:41], v[104:105]
	v_pk_mul_f32 v[122:123], v[122:123], v[96:97] op_sel_hi:[1,0]
	v_pk_fma_f32 v[102:103], v[126:127], v[82:83], v[102:103]
	v_pk_fma_f32 v[104:105], v[126:127], v[42:43], v[104:105]
	v_pk_mul_f32 v[124:125], v[124:125], v[96:97] op_sel_hi:[1,0]
	v_pk_fma_f32 v[102:103], v[128:129], v[84:85], v[102:103]
	v_pk_fma_f32 v[104:105], v[128:129], v[52:53], v[104:105]
	v_pk_mul_f32 v[126:127], v[126:127], v[96:97] op_sel_hi:[1,0]
	v_pk_fma_f32 v[102:103], v[130:131], v[86:87], v[102:103]
	v_pk_fma_f32 v[104:105], v[130:131], v[54:55], v[104:105]
	v_pk_mul_f32 v[128:129], v[128:129], v[96:97] op_sel_hi:[1,0]
	v_pk_fma_f32 v[102:103], v[132:133], v[88:89], v[102:103]
	v_pk_fma_f32 v[104:105], v[132:133], v[56:57], v[104:105]
	v_pk_fma_f32 v[102:103], v[134:135], v[90:91], v[102:103]
	v_pk_fma_f32 v[104:105], v[134:135], v[58:59], v[104:105]
	v_add_f32_e64 v102, v102, v103
	v_add_f32_e64 v104, v104, v105
	ds_read_b128 v[36:39], v161 offset:11520
	ds_read_b128 v[40:43], v162 offset:11536
	v_add_f32_dpp v102, v102, v102 quad_perm:[1,0,3,2] row_mask:0xf bank_mask:0xf bound_ctrl:1
	v_add_f32_dpp v104, v104, v104 quad_perm:[1,0,3,2] row_mask:0xf bank_mask:0xf bound_ctrl:1
	v_pk_mul_f32 v[130:131], v[130:131], v[96:97] op_sel_hi:[1,0]
	v_add_f32_dpp v102, v102, v102 quad_perm:[2,3,0,1] row_mask:0xf bank_mask:0xf bound_ctrl:1
	v_add_f32_dpp v104, v104, v104 quad_perm:[2,3,0,1] row_mask:0xf bank_mask:0xf bound_ctrl:1
	v_pk_mul_f32 v[132:133], v[132:133], v[96:97] op_sel_hi:[1,0]
	v_add_f32_dpp v102, v102, v102 row_half_mirror row_mask:0xf bank_mask:0xf bound_ctrl:1
	v_add_f32_dpp v104, v104, v104 row_half_mirror row_mask:0xf bank_mask:0xf bound_ctrl:1
	v_fma_f32 v105, -v96, v102, v101
	v_pk_mul_f32 v[106:107], v[96:97], v[104:105]
	v_pk_mul_f32 v[134:135], v[134:135], v[96:97] op_sel_hi:[1,0]
	v_pk_fma_f32 v[120:121], v[76:77], v[106:107], v[120:121] op_sel:[0,1,0]
	v_pk_fma_f32 v[122:123], v[78:79], v[106:107], v[122:123] op_sel:[0,1,0]
	v_fma_f32 v106, v98, v107, v106
	v_pk_fma_f32 v[124:125], v[80:81], v[106:107], v[124:125] op_sel:[0,1,0]
	v_pk_fma_f32 v[126:127], v[82:83], v[106:107], v[126:127] op_sel:[0,1,0]
	v_pk_fma_f32 v[128:129], v[84:85], v[106:107], v[128:129] op_sel:[0,1,0]
	v_pk_fma_f32 v[130:131], v[86:87], v[106:107], v[130:131] op_sel:[0,1,0]
	v_pk_fma_f32 v[132:133], v[88:89], v[106:107], v[132:133] op_sel:[0,1,0]
	v_pk_fma_f32 v[134:135], v[90:91], v[106:107], v[134:135] op_sel:[0,1,0]
	ds_write_b32 v166, v106 offset:1152
	s_waitcnt lgkmcnt(1)
	s_nop 0
	ds_read_b128 v[76:79], v161 offset:13184
	ds_read_b128 v[80:83], v162 offset:13200
	ds_read_b128 v[84:87], v161 offset:13216
	ds_read_b128 v[88:91], v162 offset:13232
	ds_read_b32 v101, v163 offset:13696
	ds_read_b128 v[96:99], v164 offset:37040
	ds_read_b128 v[52:55], v161 offset:12704
	ds_read_b128 v[56:59], v162 offset:12720
	v_pk_mul_f32 v[102:103], v[120:121], v[60:61]
	v_pk_mul_f32 v[104:105], v[120:121], v[36:37]
	v_pk_fma_f32 v[102:103], v[122:123], v[62:63], v[102:103]
	v_pk_fma_f32 v[104:105], v[122:123], v[38:39], v[104:105]
	v_pk_mul_f32 v[120:121], v[120:121], v[92:93] op_sel_hi:[1,0]
	v_pk_fma_f32 v[102:103], v[124:125], v[64:65], v[102:103]
	v_pk_fma_f32 v[104:105], v[124:125], v[40:41], v[104:105]
	v_pk_mul_f32 v[122:123], v[122:123], v[92:93] op_sel_hi:[1,0]
	v_pk_fma_f32 v[102:103], v[126:127], v[66:67], v[102:103]
	v_pk_fma_f32 v[104:105], v[126:127], v[42:43], v[104:105]
	v_pk_mul_f32 v[124:125], v[124:125], v[92:93] op_sel_hi:[1,0]
	v_pk_fma_f32 v[102:103], v[128:129], v[68:69], v[102:103]
	v_pk_fma_f32 v[104:105], v[128:129], v[44:45], v[104:105]
	v_pk_mul_f32 v[126:127], v[126:127], v[92:93] op_sel_hi:[1,0]
	v_pk_fma_f32 v[102:103], v[130:131], v[70:71], v[102:103]
	v_pk_fma_f32 v[104:105], v[130:131], v[46:47], v[104:105]
	v_pk_mul_f32 v[128:129], v[128:129], v[92:93] op_sel_hi:[1,0]
	v_pk_fma_f32 v[102:103], v[132:133], v[72:73], v[102:103]
	v_pk_fma_f32 v[104:105], v[132:133], v[48:49], v[104:105]
	v_pk_fma_f32 v[102:103], v[134:135], v[74:75], v[102:103]
	v_pk_fma_f32 v[104:105], v[134:135], v[50:51], v[104:105]
	v_add_f32_e64 v102, v102, v103
	v_add_f32_e64 v104, v104, v105
	ds_read_b128 v[36:39], v161 offset:12672
	ds_read_b128 v[40:43], v162 offset:12688
	v_add_f32_dpp v102, v102, v102 quad_perm:[1,0,3,2] row_mask:0xf bank_mask:0xf bound_ctrl:1
	v_add_f32_dpp v104, v104, v104 quad_perm:[1,0,3,2] row_mask:0xf bank_mask:0xf bound_ctrl:1
	v_pk_mul_f32 v[130:131], v[130:131], v[92:93] op_sel_hi:[1,0]
	v_add_f32_dpp v102, v102, v102 quad_perm:[2,3,0,1] row_mask:0xf bank_mask:0xf bound_ctrl:1
	v_add_f32_dpp v104, v104, v104 quad_perm:[2,3,0,1] row_mask:0xf bank_mask:0xf bound_ctrl:1
	v_pk_mul_f32 v[132:133], v[132:133], v[92:93] op_sel_hi:[1,0]
	v_add_f32_dpp v102, v102, v102 row_half_mirror row_mask:0xf bank_mask:0xf bound_ctrl:1
	v_add_f32_dpp v104, v104, v104 row_half_mirror row_mask:0xf bank_mask:0xf bound_ctrl:1
	v_fma_f32 v105, -v92, v102, v100
	v_pk_mul_f32 v[106:107], v[92:93], v[104:105]
	v_pk_mul_f32 v[134:135], v[134:135], v[92:93] op_sel_hi:[1,0]
	v_pk_fma_f32 v[120:121], v[60:61], v[106:107], v[120:121] op_sel:[0,1,0]
	v_pk_fma_f32 v[122:123], v[62:63], v[106:107], v[122:123] op_sel:[0,1,0]
	v_fma_f32 v106, v94, v107, v106
	v_pk_fma_f32 v[124:125], v[64:65], v[106:107], v[124:125] op_sel:[0,1,0]
	v_pk_fma_f32 v[126:127], v[66:67], v[106:107], v[126:127] op_sel:[0,1,0]
	v_pk_fma_f32 v[128:129], v[68:69], v[106:107], v[128:129] op_sel:[0,1,0]
	v_pk_fma_f32 v[130:131], v[70:71], v[106:107], v[130:131] op_sel:[0,1,0]
	v_pk_fma_f32 v[132:133], v[72:73], v[106:107], v[132:133] op_sel:[0,1,0]
	v_pk_fma_f32 v[134:135], v[74:75], v[106:107], v[134:135] op_sel:[0,1,0]
	ds_write_b32 v166, v106 offset:1280
	s_waitcnt lgkmcnt(1)
; __device__ __forceinline__ float red8(float v) { v = red4(v); v += dppf<0x141>(v); return v; }
; __device__ __forceinline__ f32x2 lo2(const f32x4& v) { return __builtin_shufflevector(v, v, 0, 1); }
; __device__ __forceinline__ f32x2 hi2(const f32x4& v) { return __builtin_shufflevector(v, v, 2, 3); }
; __device__ __forceinline__ f32x2 splat2(float x) { return (f32x2){x, x}; }
; __device__ __forceinline__ void gd_load(GdRegs& R, const float* vb, const float* sb, int t, int k0, int cl) {
;   const float* vt = vb + t * 288;
; #pragma unroll
;   for (int q = 0; q < 4; ++q) {
;     R.q[q] = *(const f32x4*)(vt + k0 + q * 4);
;     R.k[q] = *(const f32x4*)(vt + 128 + k0 + q * 4);
;   }
;   R.v = vt[256 + cl];
;   R.sc = *(const f32x4*)(sb + t * 4);
; }
; __device__ __forceinline__ float gd_step(f32x2 (&S)[8], const GdRegs& R) {
;   f32x2 k0a = splat2(0.f), k1a = splat2(0.f), q0a = splat2(0.f), q1a = splat2(0.f);
; #pragma unroll
;   for (int q = 0; q < 4; ++q) {
;     k0a += S[2 * q] * lo2(R.k[q]);
;     k1a += S[2 * q + 1] * hi2(R.k[q]);
;     q0a += S[2 * q] * lo2(R.q[q]);
;     q1a += S[2 * q + 1] * hi2(R.q[q]);
;   }
;   k0a += k1a; q0a += q1a;
;   const float dK = red8(k0a.x + k0a.y), dQ = red8(q0a.x + q0a.y);
;   const float vn = R.sc.y * (R.v - R.sc.x * dK);
;   const float o = R.sc.x * dQ + R.sc.z * vn;
;   const f32x2 al2 = splat2(R.sc.x), vn2 = splat2(vn);
; #pragma unroll
;   for (int q = 0; q < 4; ++q) {
;     S[2 * q] = S[2 * q] * al2 + lo2(R.k[q]) * vn2;
;     S[2 * q + 1] = S[2 * q + 1] * al2 + hi2(R.k[q]) * vn2;
;   }
;   return o;
; }
	s_nop 0
	ds_read_b128 v[60:63], v161 offset:14336
	ds_read_b128 v[64:67], v162 offset:14352
	ds_read_b128 v[68:71], v161 offset:14368
	ds_read_b128 v[72:75], v162 offset:14384
	ds_read_b32 v100, v163 offset:14848
	ds_read_b128 v[92:95], v164 offset:37056
	ds_read_b128 v[44:47], v161 offset:13856
	ds_read_b128 v[48:51], v162 offset:13872
	v_pk_mul_f32 v[102:103], v[120:121], v[76:77]
	v_pk_mul_f32 v[104:105], v[120:121], v[36:37]
	v_pk_fma_f32 v[102:103], v[122:123], v[78:79], v[102:103]
	v_pk_fma_f32 v[104:105], v[122:123], v[38:39], v[104:105]
	v_pk_mul_f32 v[120:121], v[120:121], v[96:97] op_sel_hi:[1,0]
	v_pk_fma_f32 v[102:103], v[124:125], v[80:81], v[102:103]
	v_pk_fma_f32 v[104:105], v[124:125], v[40:41], v[104:105]
	v_pk_mul_f32 v[122:123], v[122:123], v[96:97] op_sel_hi:[1,0]
	v_pk_fma_f32 v[102:103], v[126:127], v[82:83], v[102:103]
	v_pk_fma_f32 v[104:105], v[126:127], v[42:43], v[104:105]
	v_pk_mul_f32 v[124:125], v[124:125], v[96:97] op_sel_hi:[1,0]
	v_pk_fma_f32 v[102:103], v[128:129], v[84:85], v[102:103]
	v_pk_fma_f32 v[104:105], v[128:129], v[52:53], v[104:105]
	v_pk_mul_f32 v[126:127], v[126:127], v[96:97] op_sel_hi:[1,0]
	v_pk_fma_f32 v[102:103], v[130:131], v[86:87], v[102:103]
	v_pk_fma_f32 v[104:105], v[130:131], v[54:55], v[104:105]
	v_pk_mul_f32 v[128:129], v[128:129], v[96:97] op_sel_hi:[1,0]
	v_pk_fma_f32 v[102:103], v[132:133], v[88:89], v[102:103]
	v_pk_fma_f32 v[104:105], v[132:133], v[56:57], v[104:105]
	v_pk_fma_f32 v[102:103], v[134:135], v[90:91], v[102:103]
	v_pk_fma_f32 v[104:105], v[134:135], v[58:59], v[104:105]
	v_add_f32_e64 v102, v102, v103
	v_add_f32_e64 v104, v104, v105
	ds_read_b128 v[36:39], v161 offset:13824
	ds_read_b128 v[40:43], v162 offset:13840
	v_add_f32_dpp v102, v102, v102 quad_perm:[1,0,3,2] row_mask:0xf bank_mask:0xf bound_ctrl:1
	v_add_f32_dpp v104, v104, v104 quad_perm:[1,0,3,2] row_mask:0xf bank_mask:0xf bound_ctrl:1
	v_pk_mul_f32 v[130:131], v[130:131], v[96:97] op_sel_hi:[1,0]
	v_add_f32_dpp v102, v102, v102 quad_perm:[2,3,0,1] row_mask:0xf bank_mask:0xf bound_ctrl:1
	v_add_f32_dpp v104, v104, v104 quad_perm:[2,3,0,1] row_mask:0xf bank_mask:0xf bound_ctrl:1
	v_pk_mul_f32 v[132:133], v[132:133], v[96:97] op_sel_hi:[1,0]
	v_add_f32_dpp v102, v102, v102 row_half_mirror row_mask:0xf bank_mask:0xf bound_ctrl:1
	v_add_f32_dpp v104, v104, v104 row_half_mirror row_mask:0xf bank_mask:0xf bound_ctrl:1
	v_fma_f32 v105, -v96, v102, v101
	v_pk_mul_f32 v[106:107], v[96:97], v[104:105]
	v_pk_mul_f32 v[134:135], v[134:135], v[96:97] op_sel_hi:[1,0]
	v_pk_fma_f32 v[120:121], v[76:77], v[106:107], v[120:121] op_sel:[0,1,0]
	v_pk_fma_f32 v[122:123], v[78:79], v[106:107], v[122:123] op_sel:[0,1,0]
	v_fma_f32 v106, v98, v107, v106
	v_pk_fma_f32 v[124:125], v[80:81], v[106:107], v[124:125] op_sel:[0,1,0]
	v_pk_fma_f32 v[126:127], v[82:83], v[106:107], v[126:127] op_sel:[0,1,0]
	v_pk_fma_f32 v[128:129], v[84:85], v[106:107], v[128:129] op_sel:[0,1,0]
	v_pk_fma_f32 v[130:131], v[86:87], v[106:107], v[130:131] op_sel:[0,1,0]
	v_pk_fma_f32 v[132:133], v[88:89], v[106:107], v[132:133] op_sel:[0,1,0]
	v_pk_fma_f32 v[134:135], v[90:91], v[106:107], v[134:135] op_sel:[0,1,0]
	ds_write_b32 v166, v106 offset:1408
	s_waitcnt lgkmcnt(1)
	s_nop 0
	ds_read_b128 v[76:79], v161 offset:15488
	ds_read_b128 v[80:83], v162 offset:15504
	ds_read_b128 v[84:87], v161 offset:15520
	ds_read_b128 v[88:91], v162 offset:15536
	ds_read_b32 v101, v163 offset:16000
	ds_read_b128 v[96:99], v164 offset:37072
	ds_read_b128 v[52:55], v161 offset:15008
	ds_read_b128 v[56:59], v162 offset:15024
	v_pk_mul_f32 v[102:103], v[120:121], v[60:61]
	v_pk_mul_f32 v[104:105], v[120:121], v[36:37]
	v_pk_fma_f32 v[102:103], v[122:123], v[62:63], v[102:103]
	v_pk_fma_f32 v[104:105], v[122:123], v[38:39], v[104:105]
	v_pk_mul_f32 v[120:121], v[120:121], v[92:93] op_sel_hi:[1,0]
	v_pk_fma_f32 v[102:103], v[124:125], v[64:65], v[102:103]
	v_pk_fma_f32 v[104:105], v[124:125], v[40:41], v[104:105]
	v_pk_mul_f32 v[122:123], v[122:123], v[92:93] op_sel_hi:[1,0]
	v_pk_fma_f32 v[102:103], v[126:127], v[66:67], v[102:103]
	v_pk_fma_f32 v[104:105], v[126:127], v[42:43], v[104:105]
	v_pk_mul_f32 v[124:125], v[124:125], v[92:93] op_sel_hi:[1,0]
	v_pk_fma_f32 v[102:103], v[128:129], v[68:69], v[102:103]
	v_pk_fma_f32 v[104:105], v[128:129], v[44:45], v[104:105]
	v_pk_mul_f32 v[126:127], v[126:127], v[92:93] op_sel_hi:[1,0]
	v_pk_fma_f32 v[102:103], v[130:131], v[70:71], v[102:103]
	v_pk_fma_f32 v[104:105], v[130:131], v[46:47], v[104:105]
	v_pk_mul_f32 v[128:129], v[128:129], v[92:93] op_sel_hi:[1,0]
	v_pk_fma_f32 v[102:103], v[132:133], v[72:73], v[102:103]
	v_pk_fma_f32 v[104:105], v[132:133], v[48:49], v[104:105]
	v_pk_fma_f32 v[102:103], v[134:135], v[74:75], v[102:103]
	v_pk_fma_f32 v[104:105], v[134:135], v[50:51], v[104:105]
	v_add_f32_e64 v102, v102, v103
	v_add_f32_e64 v104, v104, v105
	ds_read_b128 v[36:39], v161 offset:14976
	ds_read_b128 v[40:43], v162 offset:14992
	v_add_f32_dpp v102, v102, v102 quad_perm:[1,0,3,2] row_mask:0xf bank_mask:0xf bound_ctrl:1
	v_add_f32_dpp v104, v104, v104 quad_perm:[1,0,3,2] row_mask:0xf bank_mask:0xf bound_ctrl:1
	v_pk_mul_f32 v[130:131], v[130:131], v[92:93] op_sel_hi:[1,0]
	v_add_f32_dpp v102, v102, v102 quad_perm:[2,3,0,1] row_mask:0xf bank_mask:0xf bound_ctrl:1
	v_add_f32_dpp v104, v104, v104 quad_perm:[2,3,0,1] row_mask:0xf bank_mask:0xf bound_ctrl:1
	v_pk_mul_f32 v[132:133], v[132:133], v[92:93] op_sel_hi:[1,0]
	v_add_f32_dpp v102, v102, v102 row_half_mirror row_mask:0xf bank_mask:0xf bound_ctrl:1
	v_add_f32_dpp v104, v104, v104 row_half_mirror row_mask:0xf bank_mask:0xf bound_ctrl:1
	v_fma_f32 v105, -v92, v102, v100
	v_pk_mul_f32 v[106:107], v[92:93], v[104:105]
	v_pk_mul_f32 v[134:135], v[134:135], v[92:93] op_sel_hi:[1,0]
	v_pk_fma_f32 v[120:121], v[60:61], v[106:107], v[120:121] op_sel:[0,1,0]
	v_pk_fma_f32 v[122:123], v[62:63], v[106:107], v[122:123] op_sel:[0,1,0]
	v_fma_f32 v106, v94, v107, v106
	v_pk_fma_f32 v[124:125], v[64:65], v[106:107], v[124:125] op_sel:[0,1,0]
	v_pk_fma_f32 v[126:127], v[66:67], v[106:107], v[126:127] op_sel:[0,1,0]
	v_pk_fma_f32 v[128:129], v[68:69], v[106:107], v[128:129] op_sel:[0,1,0]
	v_pk_fma_f32 v[130:131], v[70:71], v[106:107], v[130:131] op_sel:[0,1,0]
	v_pk_fma_f32 v[132:133], v[72:73], v[106:107], v[132:133] op_sel:[0,1,0]
	v_pk_fma_f32 v[134:135], v[74:75], v[106:107], v[134:135] op_sel:[0,1,0]
	ds_write_b32 v166, v106 offset:1536
	s_waitcnt lgkmcnt(1)
; __device__ __forceinline__ float red8(float v) { v = red4(v); v += dppf<0x141>(v); return v; }
; __device__ __forceinline__ f32x2 lo2(const f32x4& v) { return __builtin_shufflevector(v, v, 0, 1); }
; __device__ __forceinline__ f32x2 hi2(const f32x4& v) { return __builtin_shufflevector(v, v, 2, 3); }
; __device__ __forceinline__ f32x2 splat2(float x) { return (f32x2){x, x}; }
; __device__ __forceinline__ void gd_load(GdRegs& R, const float* vb, const float* sb, int t, int k0, int cl) {
;   const float* vt = vb + t * 288;
; #pragma unroll
;   for (int q = 0; q < 4; ++q) {
;     R.q[q] = *(const f32x4*)(vt + k0 + q * 4);
;     R.k[q] = *(const f32x4*)(vt + 128 + k0 + q * 4);
;   }
;   R.v = vt[256 + cl];
;   R.sc = *(const f32x4*)(sb + t * 4);
; }
; __device__ __forceinline__ float gd_step(f32x2 (&S)[8], const GdRegs& R) {
;   f32x2 k0a = splat2(0.f), k1a = splat2(0.f), q0a = splat2(0.f), q1a = splat2(0.f);
; #pragma unroll
;   for (int q = 0; q < 4; ++q) {
;     k0a += S[2 * q] * lo2(R.k[q]);
;     k1a += S[2 * q + 1] * hi2(R.k[q]);
;     q0a += S[2 * q] * lo2(R.q[q]);
;     q1a += S[2 * q + 1] * hi2(R.q[q]);
;   }
;   k0a += k1a; q0a += q1a;
;   const float dK = red8(k0a.x + k0a.y), dQ = red8(q0a.x + q0a.y);
;   const float vn = R.sc.y * (R.v - R.sc.x * dK);
;   const float o = R.sc.x * dQ + R.sc.z * vn;
;   const f32x2 al2 = splat2(R.sc.x), vn2 = splat2(vn);
; #pragma unroll
;   for (int q = 0; q < 4; ++q) {
;     S[2 * q] = S[2 * q] * al2 + lo2(R.k[q]) * vn2;
;     S[2 * q + 1] = S[2 * q + 1] * al2 + hi2(R.k[q]) * vn2;
;   }
;   return o;
; }
	s_nop 0
	ds_read_b128 v[60:63], v161 offset:16640
	ds_read_b128 v[64:67], v162 offset:16656
	ds_read_b128 v[68:71], v161 offset:16672
	ds_read_b128 v[72:75], v162 offset:16688
	ds_read_b32 v100, v163 offset:17152
	ds_read_b128 v[92:95], v164 offset:37088
	ds_read_b128 v[44:47], v161 offset:16160
	ds_read_b128 v[48:51], v162 offset:16176
	v_pk_mul_f32 v[102:103], v[120:121], v[76:77]
	v_pk_mul_f32 v[104:105], v[120:121], v[36:37]
	v_pk_fma_f32 v[102:103], v[122:123], v[78:79], v[102:103]
	v_pk_fma_f32 v[104:105], v[122:123], v[38:39], v[104:105]
	v_pk_mul_f32 v[120:121], v[120:121], v[96:97] op_sel_hi:[1,0]
	v_pk_fma_f32 v[102:103], v[124:125], v[80:81], v[102:103]
	v_pk_fma_f32 v[104:105], v[124:125], v[40:41], v[104:105]
	v_pk_mul_f32 v[122:123], v[122:123], v[96:97] op_sel_hi:[1,0]
	v_pk_fma_f32 v[102:103], v[126:127], v[82:83], v[102:103]
	v_pk_fma_f32 v[104:105], v[126:127], v[42:43], v[104:105]
	v_pk_mul_f32 v[124:125], v[124:125], v[96:97] op_sel_hi:[1,0]
	v_pk_fma_f32 v[102:103], v[128:129], v[84:85], v[102:103]
	v_pk_fma_f32 v[104:105], v[128:129], v[52:53], v[104:105]
	v_pk_mul_f32 v[126:127], v[126:127], v[96:97] op_sel_hi:[1,0]
	v_pk_fma_f32 v[102:103], v[130:131], v[86:87], v[102:103]
	v_pk_fma_f32 v[104:105], v[130:131], v[54:55], v[104:105]
	v_pk_mul_f32 v[128:129], v[128:129], v[96:97] op_sel_hi:[1,0]
	v_pk_fma_f32 v[102:103], v[132:133], v[88:89], v[102:103]
	v_pk_fma_f32 v[104:105], v[132:133], v[56:57], v[104:105]
	v_pk_fma_f32 v[102:103], v[134:135], v[90:91], v[102:103]
	v_pk_fma_f32 v[104:105], v[134:135], v[58:59], v[104:105]
	v_add_f32_e64 v102, v102, v103
	v_add_f32_e64 v104, v104, v105
	ds_read_b128 v[36:39], v161 offset:16128
	ds_read_b128 v[40:43], v162 offset:16144
	v_add_f32_dpp v102, v102, v102 quad_perm:[1,0,3,2] row_mask:0xf bank_mask:0xf bound_ctrl:1
	v_add_f32_dpp v104, v104, v104 quad_perm:[1,0,3,2] row_mask:0xf bank_mask:0xf bound_ctrl:1
	v_pk_mul_f32 v[130:131], v[130:131], v[96:97] op_sel_hi:[1,0]
	v_add_f32_dpp v102, v102, v102 quad_perm:[2,3,0,1] row_mask:0xf bank_mask:0xf bound_ctrl:1
	v_add_f32_dpp v104, v104, v104 quad_perm:[2,3,0,1] row_mask:0xf bank_mask:0xf bound_ctrl:1
	v_pk_mul_f32 v[132:133], v[132:133], v[96:97] op_sel_hi:[1,0]
	v_add_f32_dpp v102, v102, v102 row_half_mirror row_mask:0xf bank_mask:0xf bound_ctrl:1
	v_add_f32_dpp v104, v104, v104 row_half_mirror row_mask:0xf bank_mask:0xf bound_ctrl:1
	v_fma_f32 v105, -v96, v102, v101
	v_pk_mul_f32 v[106:107], v[96:97], v[104:105]
	v_pk_mul_f32 v[134:135], v[134:135], v[96:97] op_sel_hi:[1,0]
	v_pk_fma_f32 v[120:121], v[76:77], v[106:107], v[120:121] op_sel:[0,1,0]
	v_pk_fma_f32 v[122:123], v[78:79], v[106:107], v[122:123] op_sel:[0,1,0]
	v_fma_f32 v106, v98, v107, v106
	v_pk_fma_f32 v[124:125], v[80:81], v[106:107], v[124:125] op_sel:[0,1,0]
	v_pk_fma_f32 v[126:127], v[82:83], v[106:107], v[126:127] op_sel:[0,1,0]
	v_pk_fma_f32 v[128:129], v[84:85], v[106:107], v[128:129] op_sel:[0,1,0]
	v_pk_fma_f32 v[130:131], v[86:87], v[106:107], v[130:131] op_sel:[0,1,0]
	v_pk_fma_f32 v[132:133], v[88:89], v[106:107], v[132:133] op_sel:[0,1,0]
	v_pk_fma_f32 v[134:135], v[90:91], v[106:107], v[134:135] op_sel:[0,1,0]
	ds_write_b32 v166, v106 offset:1664
	s_waitcnt lgkmcnt(1)
	s_nop 0
	ds_read_b128 v[76:79], v161 offset:17792
	ds_read_b128 v[80:83], v162 offset:17808
	ds_read_b128 v[84:87], v161 offset:17824
	ds_read_b128 v[88:91], v162 offset:17840
	ds_read_b32 v101, v163 offset:18304
	ds_read_b128 v[96:99], v164 offset:37104
	ds_read_b128 v[52:55], v161 offset:17312
	ds_read_b128 v[56:59], v162 offset:17328
	v_pk_mul_f32 v[102:103], v[120:121], v[60:61]
	v_pk_mul_f32 v[104:105], v[120:121], v[36:37]
	v_pk_fma_f32 v[102:103], v[122:123], v[62:63], v[102:103]
	v_pk_fma_f32 v[104:105], v[122:123], v[38:39], v[104:105]
	v_pk_mul_f32 v[120:121], v[120:121], v[92:93] op_sel_hi:[1,0]
	v_pk_fma_f32 v[102:103], v[124:125], v[64:65], v[102:103]
	v_pk_fma_f32 v[104:105], v[124:125], v[40:41], v[104:105]
	v_pk_mul_f32 v[122:123], v[122:123], v[92:93] op_sel_hi:[1,0]
	v_pk_fma_f32 v[102:103], v[126:127], v[66:67], v[102:103]
	v_pk_fma_f32 v[104:105], v[126:127], v[42:43], v[104:105]
	v_pk_mul_f32 v[124:125], v[124:125], v[92:93] op_sel_hi:[1,0]
	v_pk_fma_f32 v[102:103], v[128:129], v[68:69], v[102:103]
	v_pk_fma_f32 v[104:105], v[128:129], v[44:45], v[104:105]
	v_pk_mul_f32 v[126:127], v[126:127], v[92:93] op_sel_hi:[1,0]
	v_pk_fma_f32 v[102:103], v[130:131], v[70:71], v[102:103]
	v_pk_fma_f32 v[104:105], v[130:131], v[46:47], v[104:105]
	v_pk_mul_f32 v[128:129], v[128:129], v[92:93] op_sel_hi:[1,0]
	v_pk_fma_f32 v[102:103], v[132:133], v[72:73], v[102:103]
	v_pk_fma_f32 v[104:105], v[132:133], v[48:49], v[104:105]
	v_pk_fma_f32 v[102:103], v[134:135], v[74:75], v[102:103]
	v_pk_fma_f32 v[104:105], v[134:135], v[50:51], v[104:105]
	v_add_f32_e64 v102, v102, v103
	v_add_f32_e64 v104, v104, v105
	ds_read_b128 v[36:39], v161 offset:17280
	ds_read_b128 v[40:43], v162 offset:17296
	v_add_f32_dpp v102, v102, v102 quad_perm:[1,0,3,2] row_mask:0xf bank_mask:0xf bound_ctrl:1
	v_add_f32_dpp v104, v104, v104 quad_perm:[1,0,3,2] row_mask:0xf bank_mask:0xf bound_ctrl:1
	v_pk_mul_f32 v[130:131], v[130:131], v[92:93] op_sel_hi:[1,0]
	v_add_f32_dpp v102, v102, v102 quad_perm:[2,3,0,1] row_mask:0xf bank_mask:0xf bound_ctrl:1
	v_add_f32_dpp v104, v104, v104 quad_perm:[2,3,0,1] row_mask:0xf bank_mask:0xf bound_ctrl:1
	v_pk_mul_f32 v[132:133], v[132:133], v[92:93] op_sel_hi:[1,0]
	v_add_f32_dpp v102, v102, v102 row_half_mirror row_mask:0xf bank_mask:0xf bound_ctrl:1
	v_add_f32_dpp v104, v104, v104 row_half_mirror row_mask:0xf bank_mask:0xf bound_ctrl:1
	v_fma_f32 v105, -v92, v102, v100
	v_pk_mul_f32 v[106:107], v[92:93], v[104:105]
	v_pk_mul_f32 v[134:135], v[134:135], v[92:93] op_sel_hi:[1,0]
	v_pk_fma_f32 v[120:121], v[60:61], v[106:107], v[120:121] op_sel:[0,1,0]
	v_pk_fma_f32 v[122:123], v[62:63], v[106:107], v[122:123] op_sel:[0,1,0]
	v_fma_f32 v106, v94, v107, v106
	v_pk_fma_f32 v[124:125], v[64:65], v[106:107], v[124:125] op_sel:[0,1,0]
	v_pk_fma_f32 v[126:127], v[66:67], v[106:107], v[126:127] op_sel:[0,1,0]
	v_pk_fma_f32 v[128:129], v[68:69], v[106:107], v[128:129] op_sel:[0,1,0]
	v_pk_fma_f32 v[130:131], v[70:71], v[106:107], v[130:131] op_sel:[0,1,0]
	v_pk_fma_f32 v[132:133], v[72:73], v[106:107], v[132:133] op_sel:[0,1,0]
	v_pk_fma_f32 v[134:135], v[74:75], v[106:107], v[134:135] op_sel:[0,1,0]
	ds_write_b32 v166, v106 offset:1792
	s_waitcnt lgkmcnt(1)
; __device__ __forceinline__ float red8(float v) { v = red4(v); v += dppf<0x141>(v); return v; }
; __device__ __forceinline__ f32x2 lo2(const f32x4& v) { return __builtin_shufflevector(v, v, 0, 1); }
; __device__ __forceinline__ f32x2 hi2(const f32x4& v) { return __builtin_shufflevector(v, v, 2, 3); }
; __device__ __forceinline__ f32x2 splat2(float x) { return (f32x2){x, x}; }
; __device__ __forceinline__ void rw_load(RwRegs& R, const float* vb, const float* sb, int t, int k0, int vrow0) {
;   const float* vt = vb + t * 384 + k0;
; #pragma unroll
;   for (int q = 0; q < 2; ++q) {
;     R.a[q] = *(const f32x4*)(vt + q * 4);
;     R.wr[q] = *(const f32x4*)(vt + 128 + q * 4);
;     R.w[q] = *(const f32x4*)(vt + 64 + q * 4);
;     R.b[q] = *(const f32x4*)(vt + 192 + q * 4);
;     R.k[q] = *(const f32x4*)(vt + 256 + q * 4);
;   }
;   R.v = *(const f32x2*)(vb + t * 384 + 320 + vrow0);
;   R.sc = *(const f32x4*)(sb + t * 4);
; }
; __device__ __forceinline__ f32x2 rw_step(f32x2 (&S)[2][4], const RwRegs& R) {
;   float sa[2], sy[2];
; #pragma unroll
;   for (int r = 0; r < 2; ++r) {
;     f32x2 a0 = S[r][0] * lo2(R.a[0]);
;     f32x2 a1 = S[r][1] * hi2(R.a[0]);
;     f32x2 y0 = S[r][0] * lo2(R.wr[0]);
;     f32x2 y1 = S[r][1] * hi2(R.wr[0]);
;     a0 += S[r][2] * lo2(R.a[1]);
;     a1 += S[r][3] * hi2(R.a[1]);
;     y0 += S[r][2] * lo2(R.wr[1]);
;     y1 += S[r][3] * hi2(R.wr[1]);
;     a0 += a1; y0 += y1;
;     sa[r] = a0.x + a0.y; sy[r] = y0.x + y0.y;
; __device__ __forceinline__ float gd_step(f32x2 (&S)[8], const GdRegs& R) {
;   f32x2 k0a = splat2(0.f), k1a = splat2(0.f), q0a = splat2(0.f), q1a = splat2(0.f);
; #pragma unroll
;   for (int q = 0; q < 4; ++q) {
;     k0a += S[2 * q] * lo2(R.k[q]);
;     k1a += S[2 * q + 1] * hi2(R.k[q]);
;     q0a += S[2 * q] * lo2(R.q[q]);
;     q1a += S[2 * q + 1] * hi2(R.q[q]);
;   }
;   k0a += k1a; q0a += q1a;
;   const float dK = red8(k0a.x + k0a.y), dQ = red8(q0a.x + q0a.y);
;   const float vn = R.sc.y * (R.v - R.sc.x * dK);
;   const float o = R.sc.x * dQ + R.sc.z * vn;
;   const f32x2 al2 = splat2(R.sc.x), vn2 = splat2(vn);
; #pragma unroll
;   for (int q = 0; q < 4; ++q) {
;     S[2 * q] = S[2 * q] * al2 + lo2(R.k[q]) * vn2;
;     S[2 * q + 1] = S[2 * q + 1] * al2 + hi2(R.k[q]) * vn2;
;   }
;   return o;
; }
	s_nop 0
	ds_read_b128 v[60:63], v161 offset:18944
	ds_read_b128 v[64:67], v162 offset:18960
	ds_read_b128 v[68:71], v161 offset:18976
	ds_read_b128 v[72:75], v162 offset:18992
	ds_read_b32 v100, v163 offset:19456
	ds_read_b128 v[92:95], v164 offset:37120
	ds_read_b128 v[44:47], v161 offset:18464
	ds_read_b128 v[48:51], v162 offset:18480
	v_pk_mul_f32 v[102:103], v[120:121], v[76:77]
	v_pk_mul_f32 v[104:105], v[120:121], v[36:37]
	v_pk_fma_f32 v[102:103], v[122:123], v[78:79], v[102:103]
	v_pk_fma_f32 v[104:105], v[122:123], v[38:39], v[104:105]
	v_pk_mul_f32 v[120:121], v[120:121], v[96:97] op_sel_hi:[1,0]
	v_pk_fma_f32 v[102:103], v[124:125], v[80:81], v[102:103]
	v_pk_fma_f32 v[104:105], v[124:125], v[40:41], v[104:105]
	v_pk_mul_f32 v[122:123], v[122:123], v[96:97] op_sel_hi:[1,0]
	v_pk_fma_f32 v[102:103], v[126:127], v[82:83], v[102:103]
	v_pk_fma_f32 v[104:105], v[126:127], v[42:43], v[104:105]
	v_pk_mul_f32 v[124:125], v[124:125], v[96:97] op_sel_hi:[1,0]
	v_pk_fma_f32 v[102:103], v[128:129], v[84:85], v[102:103]
	v_pk_fma_f32 v[104:105], v[128:129], v[52:53], v[104:105]
	v_pk_mul_f32 v[126:127], v[126:127], v[96:97] op_sel_hi:[1,0]
	v_pk_fma_f32 v[102:103], v[130:131], v[86:87], v[102:103]
	v_pk_fma_f32 v[104:105], v[130:131], v[54:55], v[104:105]
	v_pk_mul_f32 v[128:129], v[128:129], v[96:97] op_sel_hi:[1,0]
	v_pk_fma_f32 v[102:103], v[132:133], v[88:89], v[102:103]
	v_pk_fma_f32 v[104:105], v[132:133], v[56:57], v[104:105]
	v_pk_fma_f32 v[102:103], v[134:135], v[90:91], v[102:103]
	v_pk_fma_f32 v[104:105], v[134:135], v[58:59], v[104:105]
	v_add_f32_e64 v102, v102, v103
	v_add_f32_e64 v104, v104, v105
	ds_read_b128 v[36:39], v161 offset:18432
	ds_read_b128 v[40:43], v162 offset:18448
	v_add_f32_dpp v102, v102, v102 quad_perm:[1,0,3,2] row_mask:0xf bank_mask:0xf bound_ctrl:1
	v_add_f32_dpp v104, v104, v104 quad_perm:[1,0,3,2] row_mask:0xf bank_mask:0xf bound_ctrl:1
	v_pk_mul_f32 v[130:131], v[130:131], v[96:97] op_sel_hi:[1,0]
	v_add_f32_dpp v102, v102, v102 quad_perm:[2,3,0,1] row_mask:0xf bank_mask:0xf bound_ctrl:1
	v_add_f32_dpp v104, v104, v104 quad_perm:[2,3,0,1] row_mask:0xf bank_mask:0xf bound_ctrl:1
	v_pk_mul_f32 v[132:133], v[132:133], v[96:97] op_sel_hi:[1,0]
	v_add_f32_dpp v102, v102, v102 row_half_mirror row_mask:0xf bank_mask:0xf bound_ctrl:1
	v_add_f32_dpp v104, v104, v104 row_half_mirror row_mask:0xf bank_mask:0xf bound_ctrl:1
	v_fma_f32 v105, -v96, v102, v101
	v_pk_mul_f32 v[106:107], v[96:97], v[104:105]
	v_pk_mul_f32 v[134:135], v[134:135], v[96:97] op_sel_hi:[1,0]
	v_pk_fma_f32 v[120:121], v[76:77], v[106:107], v[120:121] op_sel:[0,1,0]
	v_pk_fma_f32 v[122:123], v[78:79], v[106:107], v[122:123] op_sel:[0,1,0]
	v_fma_f32 v106, v98, v107, v106
	v_pk_fma_f32 v[124:125], v[80:81], v[106:107], v[124:125] op_sel:[0,1,0]
	v_pk_fma_f32 v[126:127], v[82:83], v[106:107], v[126:127] op_sel:[0,1,0]
	v_pk_fma_f32 v[128:129], v[84:85], v[106:107], v[128:129] op_sel:[0,1,0]
	v_pk_fma_f32 v[130:131], v[86:87], v[106:107], v[130:131] op_sel:[0,1,0]
	v_pk_fma_f32 v[132:133], v[88:89], v[106:107], v[132:133] op_sel:[0,1,0]
	v_pk_fma_f32 v[134:135], v[90:91], v[106:107], v[134:135] op_sel:[0,1,0]
	ds_write_b32 v166, v106 offset:1920
	s_mov_b32 exec_lo, 0xf0f0f0f0
	s_mov_b32 exec_hi, 0xf0f0f0f0
	v_swap_b32 v120, v124
	v_swap_b32 v121, v125
	v_swap_b32 v122, v126
	v_swap_b32 v123, v127
	v_swap_b32 v128, v132
	v_swap_b32 v129, v133
	v_swap_b32 v130, v134
	v_swap_b32 v131, v135
	s_mov_b64 exec, -1
	s_cmp_eq_u32 s51, 0
	s_cbranch_scc1 .LBB0_193
	s_branch .LBB0_229
	.p2align 3
.Lrwf_body:
	ds_read_b128 v[68:71], v205 offset:0
	ds_read_b128 v[72:75], v205 offset:16
	ds_read_b128 v[76:79], v205 offset:512
	ds_read_b128 v[80:83], v205 offset:528
	ds_read_b128 v[84:87], v205 offset:1024
	ds_read_b128 v[88:91], v205 offset:1040
	ds_read_b64 v[92:93], v206 offset:1280
	ds_read_b64 v[94:95], v207 offset:49152
	ds_read_b128 v[96:99], v205 offset:768
	ds_read_b128 v[100:103], v205 offset:784
	ds_read_b128 v[112:115], v205 offset:256
	ds_read_b128 v[116:119], v205 offset:272
	s_waitcnt lgkmcnt(0)
	s_nop 0
	v_pk_mul_f32 v[144:145], v[8:9], v[68:69]
	v_pk_mul_f32 v[148:149], v[8:9], v[76:77]
	v_pk_mul_f32 v[146:147], v[16:17], v[68:69]
	v_pk_mul_f32 v[174:175], v[16:17], v[76:77]
	v_pk_fma_f32 v[144:145], v[10:11], v[70:71], v[144:145]
	v_pk_fma_f32 v[148:149], v[10:11], v[78:79], v[148:149]
	v_pk_fma_f32 v[146:147], v[18:19], v[70:71], v[146:147]
	v_pk_fma_f32 v[174:175], v[18:19], v[78:79], v[174:175]
	v_pk_fma_f32 v[144:145], v[4:5], v[72:73], v[144:145]
	v_pk_fma_f32 v[148:149], v[4:5], v[80:81], v[148:149]
	v_pk_fma_f32 v[146:147], v[12:13], v[72:73], v[146:147]
	v_pk_fma_f32 v[174:175], v[12:13], v[80:81], v[174:175]
	v_pk_fma_f32 v[144:145], v[6:7], v[74:75], v[144:145]
	v_pk_fma_f32 v[148:149], v[6:7], v[82:83], v[148:149]
	v_pk_fma_f32 v[146:147], v[14:15], v[74:75], v[146:147]
	v_pk_fma_f32 v[174:175], v[14:15], v[82:83], v[174:175]
	ds_read_b128 v[68:71], v205 offset:1536
	ds_read_b128 v[72:75], v205 offset:1552
	ds_read_b128 v[76:79], v205 offset:2048
	ds_read_b128 v[80:83], v205 offset:2064
	ds_read_b128 v[104:107], v205 offset:2304
	ds_read_b128 v[108:111], v205 offset:2320
	ds_read_b128 v[120:123], v205 offset:1792
	ds_read_b128 v[124:127], v205 offset:1808
	v_pk_mul_f32 v[128:129], v[92:93], v[84:85] op_sel_hi:[0,1]
	v_pk_mul_f32 v[136:137], v[92:93], v[84:85] op_sel:[1,0]
	v_add_f32_e64 v144, v144, v145
	v_add_f32_e64 v148, v148, v149
	v_add_f32_e64 v145, v146, v147
	v_add_f32_e64 v149, v174, v175
	v_pk_mul_f32 v[130:131], v[92:93], v[86:87] op_sel_hi:[0,1]
	v_pk_mul_f32 v[138:139], v[92:93], v[86:87] op_sel:[1,0]
; __device__ __forceinline__ float red8(float v) { v = red4(v); v += dppf<0x141>(v); return v; }
; __device__ __forceinline__ f32x2 lo2(const f32x4& v) { return __builtin_shufflevector(v, v, 0, 1); }
; __device__ __forceinline__ f32x2 hi2(const f32x4& v) { return __builtin_shufflevector(v, v, 2, 3); }
; __device__ __forceinline__ f32x2 splat2(float x) { return (f32x2){x, x}; }
; __device__ __forceinline__ void rw_load(RwRegs& R, const float* vb, const float* sb, int t, int k0, int vrow0) {
;   const float* vt = vb + t * 384 + k0;
; #pragma unroll
;   for (int q = 0; q < 2; ++q) {
;     R.a[q] = *(const f32x4*)(vt + q * 4);
;     R.wr[q] = *(const f32x4*)(vt + 128 + q * 4);
;     R.w[q] = *(const f32x4*)(vt + 64 + q * 4);
;     R.b[q] = *(const f32x4*)(vt + 192 + q * 4);
;     R.k[q] = *(const f32x4*)(vt + 256 + q * 4);
;   }
;   R.v = *(const f32x2*)(vb + t * 384 + 320 + vrow0);
;   R.sc = *(const f32x4*)(sb + t * 4);
; }
; __device__ __forceinline__ f32x2 rw_step(f32x2 (&S)[2][4], const RwRegs& R) {
;   float sa[2], sy[2];
; #pragma unroll
;   for (int r = 0; r < 2; ++r) {
;     f32x2 a0 = S[r][0] * lo2(R.a[0]);
;     f32x2 a1 = S[r][1] * hi2(R.a[0]);
;     f32x2 y0 = S[r][0] * lo2(R.wr[0]);
;     f32x2 y1 = S[r][1] * hi2(R.wr[0]);
;     a0 += S[r][2] * lo2(R.a[1]);
;     a1 += S[r][3] * hi2(R.a[1]);
;     y0 += S[r][2] * lo2(R.wr[1]);
;     y1 += S[r][3] * hi2(R.wr[1]);
;     a0 += a1; y0 += y1;
;     sa[r] = a0.x + a0.y; sy[r] = y0.x + y0.y;
;   }
;   sa[0] = red8(sa[0]); sa[1] = red8(sa[1]); sy[0] = red8(sy[0]); sy[1] = red8(sy[1]);
;   f32x2 yv;
; #pragma unroll
;   for (int r = 0; r < 2; ++r) {
;     const float vr = r ? R.v.y : R.v.x;
;     const f32x2 sa2 = splat2(sa[r]), vv2 = splat2(vr);
;     S[r][0] = S[r][0] * lo2(R.w[0]) + (sa2 * lo2(R.b[0]) + vv2 * lo2(R.k[0]));
;     S[r][1] = S[r][1] * hi2(R.w[0]) + (sa2 * hi2(R.b[0]) + vv2 * hi2(R.k[0]));
;     S[r][2] = S[r][2] * lo2(R.w[1]) + (sa2 * lo2(R.b[1]) + vv2 * lo2(R.k[1]));
;     S[r][3] = S[r][3] * hi2(R.w[1]) + (sa2 * hi2(R.b[1]) + vv2 * hi2(R.k[1]));
;     const float y = sy[r] + sa[r] * R.sc.x + vr * R.sc.y;
;     if (r) yv.y = y; else yv.x = y;
;   }
;   return yv;
; }
	v_add_f32_dpp v144, v144, v144 quad_perm:[1,0,3,2] row_mask:0xf bank_mask:0xf bound_ctrl:1
	v_add_f32_dpp v148, v148, v148 quad_perm:[1,0,3,2] row_mask:0xf bank_mask:0xf bound_ctrl:1
	v_add_f32_dpp v145, v145, v145 quad_perm:[1,0,3,2] row_mask:0xf bank_mask:0xf bound_ctrl:1
	v_add_f32_dpp v149, v149, v149 quad_perm:[1,0,3,2] row_mask:0xf bank_mask:0xf bound_ctrl:1
	v_pk_mul_f32 v[132:133], v[92:93], v[88:89] op_sel_hi:[0,1]
	v_pk_mul_f32 v[140:141], v[92:93], v[88:89] op_sel:[1,0]
	v_add_f32_dpp v144, v144, v144 quad_perm:[2,3,0,1] row_mask:0xf bank_mask:0xf bound_ctrl:1
	v_add_f32_dpp v148, v148, v148 quad_perm:[2,3,0,1] row_mask:0xf bank_mask:0xf bound_ctrl:1
	v_add_f32_dpp v145, v145, v145 quad_perm:[2,3,0,1] row_mask:0xf bank_mask:0xf bound_ctrl:1
	v_add_f32_dpp v149, v149, v149 quad_perm:[2,3,0,1] row_mask:0xf bank_mask:0xf bound_ctrl:1
	v_pk_mul_f32 v[134:135], v[92:93], v[90:91] op_sel_hi:[0,1]
	v_pk_mul_f32 v[142:143], v[92:93], v[90:91] op_sel:[1,0]
	v_add_f32_dpp v144, v144, v144 row_half_mirror row_mask:0xf bank_mask:0xf bound_ctrl:1
	v_add_f32_dpp v148, v148, v148 row_half_mirror row_mask:0xf bank_mask:0xf bound_ctrl:1
	v_add_f32_dpp v145, v145, v145 row_half_mirror row_mask:0xf bank_mask:0xf bound_ctrl:1
	v_add_f32_dpp v149, v149, v149 row_half_mirror row_mask:0xf bank_mask:0xf bound_ctrl:1
	v_pk_fma_f32 v[176:177], v[144:145], v[94:95], v[148:149] op_sel_hi:[1,0,1]
	v_pk_fma_f32 v[128:129], v[96:97], v[144:145], v[128:129] op_sel_hi:[1,0,1]
	v_pk_fma_f32 v[176:177], v[92:93], v[94:95], v[176:177] op_sel:[0,1,0]
	v_pk_fma_f32 v[136:137], v[96:97], v[144:145], v[136:137] op_sel:[0,1,0]
	ds_read_b128 v[84:87], v205 offset:2560
	ds_read_b128 v[88:91], v205 offset:2576
	ds_read_b64 v[92:93], v206 offset:2816
	ds_read_b64 v[94:95], v207 offset:49168
	ds_write_b64 v208, v[176:177] offset:0
	v_pk_fma_f32 v[8:9], v[8:9], v[112:113], v[128:129]
	v_pk_fma_f32 v[16:17], v[16:17], v[112:113], v[136:137]
	v_pk_fma_f32 v[130:131], v[98:99], v[144:145], v[130:131] op_sel_hi:[1,0,1]
	v_pk_fma_f32 v[138:139], v[98:99], v[144:145], v[138:139] op_sel:[0,1,0]
	v_pk_fma_f32 v[10:11], v[10:11], v[114:115], v[130:131]
	v_pk_fma_f32 v[18:19], v[18:19], v[114:115], v[138:139]
	v_pk_fma_f32 v[132:133], v[100:101], v[144:145], v[132:133] op_sel_hi:[1,0,1]
	v_pk_fma_f32 v[140:141], v[100:101], v[144:145], v[140:141] op_sel:[0,1,0]
	v_pk_fma_f32 v[4:5], v[4:5], v[116:117], v[132:133]
	v_pk_fma_f32 v[12:13], v[12:13], v[116:117], v[140:141]
	v_pk_fma_f32 v[134:135], v[102:103], v[144:145], v[134:135] op_sel_hi:[1,0,1]
	v_pk_fma_f32 v[142:143], v[102:103], v[144:145], v[142:143] op_sel:[0,1,0]
	v_pk_fma_f32 v[6:7], v[6:7], v[118:119], v[134:135]
	v_pk_fma_f32 v[14:15], v[14:15], v[118:119], v[142:143]
	s_waitcnt lgkmcnt(0)
	s_nop 0
	v_pk_mul_f32 v[144:145], v[8:9], v[68:69]
	v_pk_mul_f32 v[148:149], v[8:9], v[76:77]
	v_pk_mul_f32 v[146:147], v[16:17], v[68:69]
	v_pk_mul_f32 v[174:175], v[16:17], v[76:77]
	v_pk_fma_f32 v[144:145], v[10:11], v[70:71], v[144:145]
	v_pk_fma_f32 v[148:149], v[10:11], v[78:79], v[148:149]
	v_pk_fma_f32 v[146:147], v[18:19], v[70:71], v[146:147]
	v_pk_fma_f32 v[174:175], v[18:19], v[78:79], v[174:175]
	v_pk_fma_f32 v[144:145], v[4:5], v[72:73], v[144:145]
	v_pk_fma_f32 v[148:149], v[4:5], v[80:81], v[148:149]
	v_pk_fma_f32 v[146:147], v[12:13], v[72:73], v[146:147]
	v_pk_fma_f32 v[174:175], v[12:13], v[80:81], v[174:175]
	v_pk_fma_f32 v[144:145], v[6:7], v[74:75], v[144:145]
	v_pk_fma_f32 v[148:149], v[6:7], v[82:83], v[148:149]
	v_pk_fma_f32 v[146:147], v[14:15], v[74:75], v[146:147]
	v_pk_fma_f32 v[174:175], v[14:15], v[82:83], v[174:175]
	ds_read_b128 v[68:71], v205 offset:3072
	ds_read_b128 v[72:75], v205 offset:3088
	ds_read_b128 v[76:79], v205 offset:3584
	ds_read_b128 v[80:83], v205 offset:3600
	ds_read_b128 v[96:99], v205 offset:3840
	ds_read_b128 v[100:103], v205 offset:3856
	ds_read_b128 v[112:115], v205 offset:3328
	ds_read_b128 v[116:119], v205 offset:3344
	v_pk_mul_f32 v[128:129], v[92:93], v[84:85] op_sel_hi:[0,1]
	v_pk_mul_f32 v[136:137], v[92:93], v[84:85] op_sel:[1,0]
	v_add_f32_e64 v144, v144, v145
	v_add_f32_e64 v148, v148, v149
	v_add_f32_e64 v145, v146, v147
	v_add_f32_e64 v149, v174, v175
	v_pk_mul_f32 v[130:131], v[92:93], v[86:87] op_sel_hi:[0,1]
	v_pk_mul_f32 v[138:139], v[92:93], v[86:87] op_sel:[1,0]
	v_add_f32_dpp v144, v144, v144 quad_perm:[1,0,3,2] row_mask:0xf bank_mask:0xf bound_ctrl:1
	v_add_f32_dpp v148, v148, v148 quad_perm:[1,0,3,2] row_mask:0xf bank_mask:0xf bound_ctrl:1
	v_add_f32_dpp v145, v145, v145 quad_perm:[1,0,3,2] row_mask:0xf bank_mask:0xf bound_ctrl:1
	v_add_f32_dpp v149, v149, v149 quad_perm:[1,0,3,2] row_mask:0xf bank_mask:0xf bound_ctrl:1
	v_pk_mul_f32 v[132:133], v[92:93], v[88:89] op_sel_hi:[0,1]
	v_pk_mul_f32 v[140:141], v[92:93], v[88:89] op_sel:[1,0]
	v_add_f32_dpp v144, v144, v144 quad_perm:[2,3,0,1] row_mask:0xf bank_mask:0xf bound_ctrl:1
	v_add_f32_dpp v148, v148, v148 quad_perm:[2,3,0,1] row_mask:0xf bank_mask:0xf bound_ctrl:1
	v_add_f32_dpp v145, v145, v145 quad_perm:[2,3,0,1] row_mask:0xf bank_mask:0xf bound_ctrl:1
	v_add_f32_dpp v149, v149, v149 quad_perm:[2,3,0,1] row_mask:0xf bank_mask:0xf bound_ctrl:1
	v_pk_mul_f32 v[134:135], v[92:93], v[90:91] op_sel_hi:[0,1]
	v_pk_mul_f32 v[142:143], v[92:93], v[90:91] op_sel:[1,0]
	v_add_f32_dpp v144, v144, v144 row_half_mirror row_mask:0xf bank_mask:0xf bound_ctrl:1
	v_add_f32_dpp v148, v148, v148 row_half_mirror row_mask:0xf bank_mask:0xf bound_ctrl:1
	v_add_f32_dpp v145, v145, v145 row_half_mirror row_mask:0xf bank_mask:0xf bound_ctrl:1
	v_add_f32_dpp v149, v149, v149 row_half_mirror row_mask:0xf bank_mask:0xf bound_ctrl:1
; __device__ __forceinline__ float red8(float v) { v = red4(v); v += dppf<0x141>(v); return v; }
; __device__ __forceinline__ f32x2 lo2(const f32x4& v) { return __builtin_shufflevector(v, v, 0, 1); }
; __device__ __forceinline__ f32x2 hi2(const f32x4& v) { return __builtin_shufflevector(v, v, 2, 3); }
; __device__ __forceinline__ f32x2 splat2(float x) { return (f32x2){x, x}; }
; __device__ __forceinline__ void rw_load(RwRegs& R, const float* vb, const float* sb, int t, int k0, int vrow0) {
;   const float* vt = vb + t * 384 + k0;
; #pragma unroll
;   for (int q = 0; q < 2; ++q) {
;     R.a[q] = *(const f32x4*)(vt + q * 4);
;     R.wr[q] = *(const f32x4*)(vt + 128 + q * 4);
;     R.w[q] = *(const f32x4*)(vt + 64 + q * 4);
;     R.b[q] = *(const f32x4*)(vt + 192 + q * 4);
;     R.k[q] = *(const f32x4*)(vt + 256 + q * 4);
;   }
;   R.v = *(const f32x2*)(vb + t * 384 + 320 + vrow0);
;   R.sc = *(const f32x4*)(sb + t * 4);
; }
; __device__ __forceinline__ f32x2 rw_step(f32x2 (&S)[2][4], const RwRegs& R) {
;   float sa[2], sy[2];
; #pragma unroll
;   for (int r = 0; r < 2; ++r) {
;     f32x2 a0 = S[r][0] * lo2(R.a[0]);
;     f32x2 a1 = S[r][1] * hi2(R.a[0]);
;     f32x2 y0 = S[r][0] * lo2(R.wr[0]);
;     f32x2 y1 = S[r][1] * hi2(R.wr[0]);
;     a0 += S[r][2] * lo2(R.a[1]);
;     a1 += S[r][3] * hi2(R.a[1]);
;     y0 += S[r][2] * lo2(R.wr[1]);
;     y1 += S[r][3] * hi2(R.wr[1]);
;     a0 += a1; y0 += y1;
;     sa[r] = a0.x + a0.y; sy[r] = y0.x + y0.y;
;   }
;   sa[0] = red8(sa[0]); sa[1] = red8(sa[1]); sy[0] = red8(sy[0]); sy[1] = red8(sy[1]);
;   f32x2 yv;
; #pragma unroll
;   for (int r = 0; r < 2; ++r) {
;     const float vr = r ? R.v.y : R.v.x;
;     const f32x2 sa2 = splat2(sa[r]), vv2 = splat2(vr);
;     S[r][0] = S[r][0] * lo2(R.w[0]) + (sa2 * lo2(R.b[0]) + vv2 * lo2(R.k[0]));
;     S[r][1] = S[r][1] * hi2(R.w[0]) + (sa2 * hi2(R.b[0]) + vv2 * hi2(R.k[0]));
;     S[r][2] = S[r][2] * lo2(R.w[1]) + (sa2 * lo2(R.b[1]) + vv2 * lo2(R.k[1]));
;     S[r][3] = S[r][3] * hi2(R.w[1]) + (sa2 * hi2(R.b[1]) + vv2 * hi2(R.k[1]));
;     const float y = sy[r] + sa[r] * R.sc.x + vr * R.sc.y;
;     if (r) yv.y = y; else yv.x = y;
;   }
;   return yv;
; }
	v_pk_fma_f32 v[176:177], v[144:145], v[94:95], v[148:149] op_sel_hi:[1,0,1]
	v_pk_fma_f32 v[128:129], v[104:105], v[144:145], v[128:129] op_sel_hi:[1,0,1]
	v_pk_fma_f32 v[176:177], v[92:93], v[94:95], v[176:177] op_sel:[0,1,0]
	v_pk_fma_f32 v[136:137], v[104:105], v[144:145], v[136:137] op_sel:[0,1,0]
	ds_read_b128 v[84:87], v205 offset:4096
	ds_read_b128 v[88:91], v205 offset:4112
	ds_read_b64 v[92:93], v206 offset:4352
	ds_read_b64 v[94:95], v207 offset:49184
	ds_write_b64 v208, v[176:177] offset:256
	v_pk_fma_f32 v[8:9], v[8:9], v[120:121], v[128:129]
	v_pk_fma_f32 v[16:17], v[16:17], v[120:121], v[136:137]
	v_pk_fma_f32 v[130:131], v[106:107], v[144:145], v[130:131] op_sel_hi:[1,0,1]
	v_pk_fma_f32 v[138:139], v[106:107], v[144:145], v[138:139] op_sel:[0,1,0]
	v_pk_fma_f32 v[10:11], v[10:11], v[122:123], v[130:131]
	v_pk_fma_f32 v[18:19], v[18:19], v[122:123], v[138:139]
	v_pk_fma_f32 v[132:133], v[108:109], v[144:145], v[132:133] op_sel_hi:[1,0,1]
	v_pk_fma_f32 v[140:141], v[108:109], v[144:145], v[140:141] op_sel:[0,1,0]
	v_pk_fma_f32 v[4:5], v[4:5], v[124:125], v[132:133]
	v_pk_fma_f32 v[12:13], v[12:13], v[124:125], v[140:141]
	v_pk_fma_f32 v[134:135], v[110:111], v[144:145], v[134:135] op_sel_hi:[1,0,1]
	v_pk_fma_f32 v[142:143], v[110:111], v[144:145], v[142:143] op_sel:[0,1,0]
	v_pk_fma_f32 v[6:7], v[6:7], v[126:127], v[134:135]
	v_pk_fma_f32 v[14:15], v[14:15], v[126:127], v[142:143]
	s_waitcnt lgkmcnt(0)
	s_nop 0
	v_pk_mul_f32 v[144:145], v[8:9], v[68:69]
	v_pk_mul_f32 v[148:149], v[8:9], v[76:77]
	v_pk_mul_f32 v[146:147], v[16:17], v[68:69]
	v_pk_mul_f32 v[174:175], v[16:17], v[76:77]
	v_pk_fma_f32 v[144:145], v[10:11], v[70:71], v[144:145]
	v_pk_fma_f32 v[148:149], v[10:11], v[78:79], v[148:149]
	v_pk_fma_f32 v[146:147], v[18:19], v[70:71], v[146:147]
	v_pk_fma_f32 v[174:175], v[18:19], v[78:79], v[174:175]
	v_pk_fma_f32 v[144:145], v[4:5], v[72:73], v[144:145]
	v_pk_fma_f32 v[148:149], v[4:5], v[80:81], v[148:149]
	v_pk_fma_f32 v[146:147], v[12:13], v[72:73], v[146:147]
	v_pk_fma_f32 v[174:175], v[12:13], v[80:81], v[174:175]
	v_pk_fma_f32 v[144:145], v[6:7], v[74:75], v[144:145]
	v_pk_fma_f32 v[148:149], v[6:7], v[82:83], v[148:149]
	v_pk_fma_f32 v[146:147], v[14:15], v[74:75], v[146:147]
	v_pk_fma_f32 v[174:175], v[14:15], v[82:83], v[174:175]
	ds_read_b128 v[68:71], v205 offset:4608
	ds_read_b128 v[72:75], v205 offset:4624
	ds_read_b128 v[76:79], v205 offset:5120
	ds_read_b128 v[80:83], v205 offset:5136
	ds_read_b128 v[104:107], v205 offset:5376
	ds_read_b128 v[108:111], v205 offset:5392
	ds_read_b128 v[120:123], v205 offset:4864
	ds_read_b128 v[124:127], v205 offset:4880
	v_pk_mul_f32 v[128:129], v[92:93], v[84:85] op_sel_hi:[0,1]
	v_pk_mul_f32 v[136:137], v[92:93], v[84:85] op_sel:[1,0]
	v_add_f32_e64 v144, v144, v145
	v_add_f32_e64 v148, v148, v149
	v_add_f32_e64 v145, v146, v147
	v_add_f32_e64 v149, v174, v175
	v_pk_mul_f32 v[130:131], v[92:93], v[86:87] op_sel_hi:[0,1]
	v_pk_mul_f32 v[138:139], v[92:93], v[86:87] op_sel:[1,0]
	v_add_f32_dpp v144, v144, v144 quad_perm:[1,0,3,2] row_mask:0xf bank_mask:0xf bound_ctrl:1
	v_add_f32_dpp v148, v148, v148 quad_perm:[1,0,3,2] row_mask:0xf bank_mask:0xf bound_ctrl:1
	v_add_f32_dpp v145, v145, v145 quad_perm:[1,0,3,2] row_mask:0xf bank_mask:0xf bound_ctrl:1
	v_add_f32_dpp v149, v149, v149 quad_perm:[1,0,3,2] row_mask:0xf bank_mask:0xf bound_ctrl:1
	v_pk_mul_f32 v[132:133], v[92:93], v[88:89] op_sel_hi:[0,1]
	v_pk_mul_f32 v[140:141], v[92:93], v[88:89] op_sel:[1,0]
	v_add_f32_dpp v144, v144, v144 quad_perm:[2,3,0,1] row_mask:0xf bank_mask:0xf bound_ctrl:1
	v_add_f32_dpp v148, v148, v148 quad_perm:[2,3,0,1] row_mask:0xf bank_mask:0xf bound_ctrl:1
	v_add_f32_dpp v145, v145, v145 quad_perm:[2,3,0,1] row_mask:0xf bank_mask:0xf bound_ctrl:1
	v_add_f32_dpp v149, v149, v149 quad_perm:[2,3,0,1] row_mask:0xf bank_mask:0xf bound_ctrl:1
	v_pk_mul_f32 v[134:135], v[92:93], v[90:91] op_sel_hi:[0,1]
	v_pk_mul_f32 v[142:143], v[92:93], v[90:91] op_sel:[1,0]
	v_add_f32_dpp v144, v144, v144 row_half_mirror row_mask:0xf bank_mask:0xf bound_ctrl:1
	v_add_f32_dpp v148, v148, v148 row_half_mirror row_mask:0xf bank_mask:0xf bound_ctrl:1
	v_add_f32_dpp v145, v145, v145 row_half_mirror row_mask:0xf bank_mask:0xf bound_ctrl:1
	v_add_f32_dpp v149, v149, v149 row_half_mirror row_mask:0xf bank_mask:0xf bound_ctrl:1
	v_pk_fma_f32 v[176:177], v[144:145], v[94:95], v[148:149] op_sel_hi:[1,0,1]
	v_pk_fma_f32 v[128:129], v[96:97], v[144:145], v[128:129] op_sel_hi:[1,0,1]
	v_pk_fma_f32 v[176:177], v[92:93], v[94:95], v[176:177] op_sel:[0,1,0]
	v_pk_fma_f32 v[136:137], v[96:97], v[144:145], v[136:137] op_sel:[0,1,0]
	ds_read_b128 v[84:87], v205 offset:5632
	ds_read_b128 v[88:91], v205 offset:5648
	ds_read_b64 v[92:93], v206 offset:5888
	ds_read_b64 v[94:95], v207 offset:49200
	ds_write_b64 v208, v[176:177] offset:512
	v_pk_fma_f32 v[8:9], v[8:9], v[112:113], v[128:129]
	v_pk_fma_f32 v[16:17], v[16:17], v[112:113], v[136:137]
	v_pk_fma_f32 v[130:131], v[98:99], v[144:145], v[130:131] op_sel_hi:[1,0,1]
	v_pk_fma_f32 v[138:139], v[98:99], v[144:145], v[138:139] op_sel:[0,1,0]
	v_pk_fma_f32 v[10:11], v[10:11], v[114:115], v[130:131]
	v_pk_fma_f32 v[18:19], v[18:19], v[114:115], v[138:139]
	v_pk_fma_f32 v[132:133], v[100:101], v[144:145], v[132:133] op_sel_hi:[1,0,1]
	v_pk_fma_f32 v[140:141], v[100:101], v[144:145], v[140:141] op_sel:[0,1,0]
	v_pk_fma_f32 v[4:5], v[4:5], v[116:117], v[132:133]
	v_pk_fma_f32 v[12:13], v[12:13], v[116:117], v[140:141]
	v_pk_fma_f32 v[134:135], v[102:103], v[144:145], v[134:135] op_sel_hi:[1,0,1]
	v_pk_fma_f32 v[142:143], v[102:103], v[144:145], v[142:143] op_sel:[0,1,0]
	v_pk_fma_f32 v[6:7], v[6:7], v[118:119], v[134:135]
	v_pk_fma_f32 v[14:15], v[14:15], v[118:119], v[142:143]
	s_waitcnt lgkmcnt(0)
; __device__ __forceinline__ float red8(float v) { v = red4(v); v += dppf<0x141>(v); return v; }
; __device__ __forceinline__ f32x2 lo2(const f32x4& v) { return __builtin_shufflevector(v, v, 0, 1); }
; __device__ __forceinline__ f32x2 hi2(const f32x4& v) { return __builtin_shufflevector(v, v, 2, 3); }
; __device__ __forceinline__ f32x2 splat2(float x) { return (f32x2){x, x}; }
; __device__ __forceinline__ void rw_load(RwRegs& R, const float* vb, const float* sb, int t, int k0, int vrow0) {
;   const float* vt = vb + t * 384 + k0;
; #pragma unroll
;   for (int q = 0; q < 2; ++q) {
;     R.a[q] = *(const f32x4*)(vt + q * 4);
;     R.wr[q] = *(const f32x4*)(vt + 128 + q * 4);
;     R.w[q] = *(const f32x4*)(vt + 64 + q * 4);
;     R.b[q] = *(const f32x4*)(vt + 192 + q * 4);
;     R.k[q] = *(const f32x4*)(vt + 256 + q * 4);
;   }
;   R.v = *(const f32x2*)(vb + t * 384 + 320 + vrow0);
;   R.sc = *(const f32x4*)(sb + t * 4);
; }
; __device__ __forceinline__ f32x2 rw_step(f32x2 (&S)[2][4], const RwRegs& R) {
;   float sa[2], sy[2];
; #pragma unroll
;   for (int r = 0; r < 2; ++r) {
;     f32x2 a0 = S[r][0] * lo2(R.a[0]);
;     f32x2 a1 = S[r][1] * hi2(R.a[0]);
;     f32x2 y0 = S[r][0] * lo2(R.wr[0]);
;     f32x2 y1 = S[r][1] * hi2(R.wr[0]);
;     a0 += S[r][2] * lo2(R.a[1]);
;     a1 += S[r][3] * hi2(R.a[1]);
;     y0 += S[r][2] * lo2(R.wr[1]);
;     y1 += S[r][3] * hi2(R.wr[1]);
;     a0 += a1; y0 += y1;
;     sa[r] = a0.x + a0.y; sy[r] = y0.x + y0.y;
;   }
;   sa[0] = red8(sa[0]); sa[1] = red8(sa[1]); sy[0] = red8(sy[0]); sy[1] = red8(sy[1]);
;   f32x2 yv;
; #pragma unroll
;   for (int r = 0; r < 2; ++r) {
;     const float vr = r ? R.v.y : R.v.x;
;     const f32x2 sa2 = splat2(sa[r]), vv2 = splat2(vr);
;     S[r][0] = S[r][0] * lo2(R.w[0]) + (sa2 * lo2(R.b[0]) + vv2 * lo2(R.k[0]));
;     S[r][1] = S[r][1] * hi2(R.w[0]) + (sa2 * hi2(R.b[0]) + vv2 * hi2(R.k[0]));
;     S[r][2] = S[r][2] * lo2(R.w[1]) + (sa2 * lo2(R.b[1]) + vv2 * lo2(R.k[1]));
;     S[r][3] = S[r][3] * hi2(R.w[1]) + (sa2 * hi2(R.b[1]) + vv2 * hi2(R.k[1]));
;     const float y = sy[r] + sa[r] * R.sc.x + vr * R.sc.y;
;     if (r) yv.y = y; else yv.x = y;
;   }
;   return yv;
; }
	s_nop 0
	v_pk_mul_f32 v[144:145], v[8:9], v[68:69]
	v_pk_mul_f32 v[148:149], v[8:9], v[76:77]
	v_pk_mul_f32 v[146:147], v[16:17], v[68:69]
	v_pk_mul_f32 v[174:175], v[16:17], v[76:77]
	v_pk_fma_f32 v[144:145], v[10:11], v[70:71], v[144:145]
	v_pk_fma_f32 v[148:149], v[10:11], v[78:79], v[148:149]
	v_pk_fma_f32 v[146:147], v[18:19], v[70:71], v[146:147]
	v_pk_fma_f32 v[174:175], v[18:19], v[78:79], v[174:175]
	v_pk_fma_f32 v[144:145], v[4:5], v[72:73], v[144:145]
	v_pk_fma_f32 v[148:149], v[4:5], v[80:81], v[148:149]
	v_pk_fma_f32 v[146:147], v[12:13], v[72:73], v[146:147]
	v_pk_fma_f32 v[174:175], v[12:13], v[80:81], v[174:175]
	v_pk_fma_f32 v[144:145], v[6:7], v[74:75], v[144:145]
	v_pk_fma_f32 v[148:149], v[6:7], v[82:83], v[148:149]
	v_pk_fma_f32 v[146:147], v[14:15], v[74:75], v[146:147]
	v_pk_fma_f32 v[174:175], v[14:15], v[82:83], v[174:175]
	ds_read_b128 v[68:71], v205 offset:6144
	ds_read_b128 v[72:75], v205 offset:6160
	ds_read_b128 v[76:79], v205 offset:6656
	ds_read_b128 v[80:83], v205 offset:6672
	ds_read_b128 v[96:99], v205 offset:6912
	ds_read_b128 v[100:103], v205 offset:6928
	ds_read_b128 v[112:115], v205 offset:6400
	ds_read_b128 v[116:119], v205 offset:6416
	v_pk_mul_f32 v[128:129], v[92:93], v[84:85] op_sel_hi:[0,1]
	v_pk_mul_f32 v[136:137], v[92:93], v[84:85] op_sel:[1,0]
	v_add_f32_e64 v144, v144, v145
	v_add_f32_e64 v148, v148, v149
	v_add_f32_e64 v145, v146, v147
	v_add_f32_e64 v149, v174, v175
	v_pk_mul_f32 v[130:131], v[92:93], v[86:87] op_sel_hi:[0,1]
	v_pk_mul_f32 v[138:139], v[92:93], v[86:87] op_sel:[1,0]
	v_add_f32_dpp v144, v144, v144 quad_perm:[1,0,3,2] row_mask:0xf bank_mask:0xf bound_ctrl:1
	v_add_f32_dpp v148, v148, v148 quad_perm:[1,0,3,2] row_mask:0xf bank_mask:0xf bound_ctrl:1
	v_add_f32_dpp v145, v145, v145 quad_perm:[1,0,3,2] row_mask:0xf bank_mask:0xf bound_ctrl:1
	v_add_f32_dpp v149, v149, v149 quad_perm:[1,0,3,2] row_mask:0xf bank_mask:0xf bound_ctrl:1
	v_pk_mul_f32 v[132:133], v[92:93], v[88:89] op_sel_hi:[0,1]
	v_pk_mul_f32 v[140:141], v[92:93], v[88:89] op_sel:[1,0]
	v_add_f32_dpp v144, v144, v144 quad_perm:[2,3,0,1] row_mask:0xf bank_mask:0xf bound_ctrl:1
	v_add_f32_dpp v148, v148, v148 quad_perm:[2,3,0,1] row_mask:0xf bank_mask:0xf bound_ctrl:1
	v_add_f32_dpp v145, v145, v145 quad_perm:[2,3,0,1] row_mask:0xf bank_mask:0xf bound_ctrl:1
	v_add_f32_dpp v149, v149, v149 quad_perm:[2,3,0,1] row_mask:0xf bank_mask:0xf bound_ctrl:1
	v_pk_mul_f32 v[134:135], v[92:93], v[90:91] op_sel_hi:[0,1]
	v_pk_mul_f32 v[142:143], v[92:93], v[90:91] op_sel:[1,0]
	v_add_f32_dpp v144, v144, v144 row_half_mirror row_mask:0xf bank_mask:0xf bound_ctrl:1
	v_add_f32_dpp v148, v148, v148 row_half_mirror row_mask:0xf bank_mask:0xf bound_ctrl:1
	v_add_f32_dpp v145, v145, v145 row_half_mirror row_mask:0xf bank_mask:0xf bound_ctrl:1
	v_add_f32_dpp v149, v149, v149 row_half_mirror row_mask:0xf bank_mask:0xf bound_ctrl:1
	v_pk_fma_f32 v[176:177], v[144:145], v[94:95], v[148:149] op_sel_hi:[1,0,1]
	v_pk_fma_f32 v[128:129], v[104:105], v[144:145], v[128:129] op_sel_hi:[1,0,1]
	v_pk_fma_f32 v[176:177], v[92:93], v[94:95], v[176:177] op_sel:[0,1,0]
	v_pk_fma_f32 v[136:137], v[104:105], v[144:145], v[136:137] op_sel:[0,1,0]
	ds_read_b128 v[84:87], v205 offset:7168
	ds_read_b128 v[88:91], v205 offset:7184
	ds_read_b64 v[92:93], v206 offset:7424
	ds_read_b64 v[94:95], v207 offset:49216
	ds_write_b64 v208, v[176:177] offset:768
	v_pk_fma_f32 v[8:9], v[8:9], v[120:121], v[128:129]
	v_pk_fma_f32 v[16:17], v[16:17], v[120:121], v[136:137]
	v_pk_fma_f32 v[130:131], v[106:107], v[144:145], v[130:131] op_sel_hi:[1,0,1]
	v_pk_fma_f32 v[138:139], v[106:107], v[144:145], v[138:139] op_sel:[0,1,0]
	v_pk_fma_f32 v[10:11], v[10:11], v[122:123], v[130:131]
	v_pk_fma_f32 v[18:19], v[18:19], v[122:123], v[138:139]
	v_pk_fma_f32 v[132:133], v[108:109], v[144:145], v[132:133] op_sel_hi:[1,0,1]
	v_pk_fma_f32 v[140:141], v[108:109], v[144:145], v[140:141] op_sel:[0,1,0]
	v_pk_fma_f32 v[4:5], v[4:5], v[124:125], v[132:133]
	v_pk_fma_f32 v[12:13], v[12:13], v[124:125], v[140:141]
	v_pk_fma_f32 v[134:135], v[110:111], v[144:145], v[134:135] op_sel_hi:[1,0,1]
	v_pk_fma_f32 v[142:143], v[110:111], v[144:145], v[142:143] op_sel:[0,1,0]
	v_pk_fma_f32 v[6:7], v[6:7], v[126:127], v[134:135]
	v_pk_fma_f32 v[14:15], v[14:15], v[126:127], v[142:143]
	s_waitcnt lgkmcnt(0)
; __device__ __forceinline__ float red8(float v) { v = red4(v); v += dppf<0x141>(v); return v; }
; __device__ __forceinline__ f32x2 lo2(const f32x4& v) { return __builtin_shufflevector(v, v, 0, 1); }
; __device__ __forceinline__ f32x2 hi2(const f32x4& v) { return __builtin_shufflevector(v, v, 2, 3); }
; __device__ __forceinline__ f32x2 splat2(float x) { return (f32x2){x, x}; }
; __device__ __forceinline__ void rw_load(RwRegs& R, const float* vb, const float* sb, int t, int k0, int vrow0) {
;   const float* vt = vb + t * 384 + k0;
; #pragma unroll
;   for (int q = 0; q < 2; ++q) {
;     R.a[q] = *(const f32x4*)(vt + q * 4);
;     R.wr[q] = *(const f32x4*)(vt + 128 + q * 4);
;     R.w[q] = *(const f32x4*)(vt + 64 + q * 4);
;     R.b[q] = *(const f32x4*)(vt + 192 + q * 4);
;     R.k[q] = *(const f32x4*)(vt + 256 + q * 4);
;   }
;   R.v = *(const f32x2*)(vb + t * 384 + 320 + vrow0);
;   R.sc = *(const f32x4*)(sb + t * 4);
; }
; __device__ __forceinline__ f32x2 rw_step(f32x2 (&S)[2][4], const RwRegs& R) {
;   float sa[2], sy[2];
; #pragma unroll
;   for (int r = 0; r < 2; ++r) {
;     f32x2 a0 = S[r][0] * lo2(R.a[0]);
;     f32x2 a1 = S[r][1] * hi2(R.a[0]);
;     f32x2 y0 = S[r][0] * lo2(R.wr[0]);
;     f32x2 y1 = S[r][1] * hi2(R.wr[0]);
;     a0 += S[r][2] * lo2(R.a[1]);
;     a1 += S[r][3] * hi2(R.a[1]);
;     y0 += S[r][2] * lo2(R.wr[1]);
;     y1 += S[r][3] * hi2(R.wr[1]);
;     a0 += a1; y0 += y1;
;     sa[r] = a0.x + a0.y; sy[r] = y0.x + y0.y;
;   }
;   sa[0] = red8(sa[0]); sa[1] = red8(sa[1]); sy[0] = red8(sy[0]); sy[1] = red8(sy[1]);
;   f32x2 yv;
; #pragma unroll
;   for (int r = 0; r < 2; ++r) {
;     const float vr = r ? R.v.y : R.v.x;
;     const f32x2 sa2 = splat2(sa[r]), vv2 = splat2(vr);
;     S[r][0] = S[r][0] * lo2(R.w[0]) + (sa2 * lo2(R.b[0]) + vv2 * lo2(R.k[0]));
;     S[r][1] = S[r][1] * hi2(R.w[0]) + (sa2 * hi2(R.b[0]) + vv2 * hi2(R.k[0]));
;     S[r][2] = S[r][2] * lo2(R.w[1]) + (sa2 * lo2(R.b[1]) + vv2 * lo2(R.k[1]));
;     S[r][3] = S[r][3] * hi2(R.w[1]) + (sa2 * hi2(R.b[1]) + vv2 * hi2(R.k[1]));
;     const float y = sy[r] + sa[r] * R.sc.x + vr * R.sc.y;
;     if (r) yv.y = y; else yv.x = y;
;   }
;   return yv;
; }
	s_nop 0
	v_pk_mul_f32 v[144:145], v[8:9], v[68:69]
	v_pk_mul_f32 v[148:149], v[8:9], v[76:77]
	v_pk_mul_f32 v[146:147], v[16:17], v[68:69]
	v_pk_mul_f32 v[174:175], v[16:17], v[76:77]
	v_pk_fma_f32 v[144:145], v[10:11], v[70:71], v[144:145]
	v_pk_fma_f32 v[148:149], v[10:11], v[78:79], v[148:149]
	v_pk_fma_f32 v[146:147], v[18:19], v[70:71], v[146:147]
	v_pk_fma_f32 v[174:175], v[18:19], v[78:79], v[174:175]
	v_pk_fma_f32 v[144:145], v[4:5], v[72:73], v[144:145]
	v_pk_fma_f32 v[148:149], v[4:5], v[80:81], v[148:149]
	v_pk_fma_f32 v[146:147], v[12:13], v[72:73], v[146:147]
	v_pk_fma_f32 v[174:175], v[12:13], v[80:81], v[174:175]
	v_pk_fma_f32 v[144:145], v[6:7], v[74:75], v[144:145]
	v_pk_fma_f32 v[148:149], v[6:7], v[82:83], v[148:149]
	v_pk_fma_f32 v[146:147], v[14:15], v[74:75], v[146:147]
	v_pk_fma_f32 v[174:175], v[14:15], v[82:83], v[174:175]
	ds_read_b128 v[68:71], v205 offset:7680
	ds_read_b128 v[72:75], v205 offset:7696
	ds_read_b128 v[76:79], v205 offset:8192
	ds_read_b128 v[80:83], v205 offset:8208
	ds_read_b128 v[104:107], v205 offset:8448
	ds_read_b128 v[108:111], v205 offset:8464
	ds_read_b128 v[120:123], v205 offset:7936
	ds_read_b128 v[124:127], v205 offset:7952
	v_pk_mul_f32 v[128:129], v[92:93], v[84:85] op_sel_hi:[0,1]
	v_pk_mul_f32 v[136:137], v[92:93], v[84:85] op_sel:[1,0]
	v_add_f32_e64 v144, v144, v145
	v_add_f32_e64 v148, v148, v149
	v_add_f32_e64 v145, v146, v147
	v_add_f32_e64 v149, v174, v175
	v_pk_mul_f32 v[130:131], v[92:93], v[86:87] op_sel_hi:[0,1]
	v_pk_mul_f32 v[138:139], v[92:93], v[86:87] op_sel:[1,0]
	v_add_f32_dpp v144, v144, v144 quad_perm:[1,0,3,2] row_mask:0xf bank_mask:0xf bound_ctrl:1
	v_add_f32_dpp v148, v148, v148 quad_perm:[1,0,3,2] row_mask:0xf bank_mask:0xf bound_ctrl:1
	v_add_f32_dpp v145, v145, v145 quad_perm:[1,0,3,2] row_mask:0xf bank_mask:0xf bound_ctrl:1
	v_add_f32_dpp v149, v149, v149 quad_perm:[1,0,3,2] row_mask:0xf bank_mask:0xf bound_ctrl:1
	v_pk_mul_f32 v[132:133], v[92:93], v[88:89] op_sel_hi:[0,1]
	v_pk_mul_f32 v[140:141], v[92:93], v[88:89] op_sel:[1,0]
	v_add_f32_dpp v144, v144, v144 quad_perm:[2,3,0,1] row_mask:0xf bank_mask:0xf bound_ctrl:1
	v_add_f32_dpp v148, v148, v148 quad_perm:[2,3,0,1] row_mask:0xf bank_mask:0xf bound_ctrl:1
	v_add_f32_dpp v145, v145, v145 quad_perm:[2,3,0,1] row_mask:0xf bank_mask:0xf bound_ctrl:1
	v_add_f32_dpp v149, v149, v149 quad_perm:[2,3,0,1] row_mask:0xf bank_mask:0xf bound_ctrl:1
	v_pk_mul_f32 v[134:135], v[92:93], v[90:91] op_sel_hi:[0,1]
	v_pk_mul_f32 v[142:143], v[92:93], v[90:91] op_sel:[1,0]
	v_add_f32_dpp v144, v144, v144 row_half_mirror row_mask:0xf bank_mask:0xf bound_ctrl:1
	v_add_f32_dpp v148, v148, v148 row_half_mirror row_mask:0xf bank_mask:0xf bound_ctrl:1
	v_add_f32_dpp v145, v145, v145 row_half_mirror row_mask:0xf bank_mask:0xf bound_ctrl:1
	v_add_f32_dpp v149, v149, v149 row_half_mirror row_mask:0xf bank_mask:0xf bound_ctrl:1
	v_pk_fma_f32 v[176:177], v[144:145], v[94:95], v[148:149] op_sel_hi:[1,0,1]
	v_pk_fma_f32 v[128:129], v[96:97], v[144:145], v[128:129] op_sel_hi:[1,0,1]
	v_pk_fma_f32 v[176:177], v[92:93], v[94:95], v[176:177] op_sel:[0,1,0]
	v_pk_fma_f32 v[136:137], v[96:97], v[144:145], v[136:137] op_sel:[0,1,0]
	ds_read_b128 v[84:87], v205 offset:8704
	ds_read_b128 v[88:91], v205 offset:8720
	ds_read_b64 v[92:93], v206 offset:8960
	ds_read_b64 v[94:95], v207 offset:49232
	ds_write_b64 v208, v[176:177] offset:1024
	v_pk_fma_f32 v[8:9], v[8:9], v[112:113], v[128:129]
	v_pk_fma_f32 v[16:17], v[16:17], v[112:113], v[136:137]
	v_pk_fma_f32 v[130:131], v[98:99], v[144:145], v[130:131] op_sel_hi:[1,0,1]
	v_pk_fma_f32 v[138:139], v[98:99], v[144:145], v[138:139] op_sel:[0,1,0]
	v_pk_fma_f32 v[10:11], v[10:11], v[114:115], v[130:131]
	v_pk_fma_f32 v[18:19], v[18:19], v[114:115], v[138:139]
	v_pk_fma_f32 v[132:133], v[100:101], v[144:145], v[132:133] op_sel_hi:[1,0,1]
	v_pk_fma_f32 v[140:141], v[100:101], v[144:145], v[140:141] op_sel:[0,1,0]
	v_pk_fma_f32 v[4:5], v[4:5], v[116:117], v[132:133]
	v_pk_fma_f32 v[12:13], v[12:13], v[116:117], v[140:141]
	v_pk_fma_f32 v[134:135], v[102:103], v[144:145], v[134:135] op_sel_hi:[1,0,1]
	v_pk_fma_f32 v[142:143], v[102:103], v[144:145], v[142:143] op_sel:[0,1,0]
	v_pk_fma_f32 v[6:7], v[6:7], v[118:119], v[134:135]
	v_pk_fma_f32 v[14:15], v[14:15], v[118:119], v[142:143]
	s_waitcnt lgkmcnt(0)
; __device__ __forceinline__ float red8(float v) { v = red4(v); v += dppf<0x141>(v); return v; }
; __device__ __forceinline__ f32x2 lo2(const f32x4& v) { return __builtin_shufflevector(v, v, 0, 1); }
; __device__ __forceinline__ f32x2 hi2(const f32x4& v) { return __builtin_shufflevector(v, v, 2, 3); }
; __device__ __forceinline__ f32x2 splat2(float x) { return (f32x2){x, x}; }
; __device__ __forceinline__ void rw_load(RwRegs& R, const float* vb, const float* sb, int t, int k0, int vrow0) {
;   const float* vt = vb + t * 384 + k0;
; #pragma unroll
;   for (int q = 0; q < 2; ++q) {
;     R.a[q] = *(const f32x4*)(vt + q * 4);
;     R.wr[q] = *(const f32x4*)(vt + 128 + q * 4);
;     R.w[q] = *(const f32x4*)(vt + 64 + q * 4);
;     R.b[q] = *(const f32x4*)(vt + 192 + q * 4);
;     R.k[q] = *(const f32x4*)(vt + 256 + q * 4);
;   }
;   R.v = *(const f32x2*)(vb + t * 384 + 320 + vrow0);
;   R.sc = *(const f32x4*)(sb + t * 4);
; }
; __device__ __forceinline__ f32x2 rw_step(f32x2 (&S)[2][4], const RwRegs& R) {
;   float sa[2], sy[2];
; #pragma unroll
;   for (int r = 0; r < 2; ++r) {
;     f32x2 a0 = S[r][0] * lo2(R.a[0]);
;     f32x2 a1 = S[r][1] * hi2(R.a[0]);
;     f32x2 y0 = S[r][0] * lo2(R.wr[0]);
;     f32x2 y1 = S[r][1] * hi2(R.wr[0]);
;     a0 += S[r][2] * lo2(R.a[1]);
;     a1 += S[r][3] * hi2(R.a[1]);
;     y0 += S[r][2] * lo2(R.wr[1]);
;     y1 += S[r][3] * hi2(R.wr[1]);
;     a0 += a1; y0 += y1;
;     sa[r] = a0.x + a0.y; sy[r] = y0.x + y0.y;
;   }
;   sa[0] = red8(sa[0]); sa[1] = red8(sa[1]); sy[0] = red8(sy[0]); sy[1] = red8(sy[1]);
;   f32x2 yv;
; #pragma unroll
;   for (int r = 0; r < 2; ++r) {
;     const float vr = r ? R.v.y : R.v.x;
;     const f32x2 sa2 = splat2(sa[r]), vv2 = splat2(vr);
;     S[r][0] = S[r][0] * lo2(R.w[0]) + (sa2 * lo2(R.b[0]) + vv2 * lo2(R.k[0]));
;     S[r][1] = S[r][1] * hi2(R.w[0]) + (sa2 * hi2(R.b[0]) + vv2 * hi2(R.k[0]));
;     S[r][2] = S[r][2] * lo2(R.w[1]) + (sa2 * lo2(R.b[1]) + vv2 * lo2(R.k[1]));
;     S[r][3] = S[r][3] * hi2(R.w[1]) + (sa2 * hi2(R.b[1]) + vv2 * hi2(R.k[1]));
;     const float y = sy[r] + sa[r] * R.sc.x + vr * R.sc.y;
;     if (r) yv.y = y; else yv.x = y;
;   }
;   return yv;
; }
	s_nop 0
	v_pk_mul_f32 v[144:145], v[8:9], v[68:69]
	v_pk_mul_f32 v[148:149], v[8:9], v[76:77]
	v_pk_mul_f32 v[146:147], v[16:17], v[68:69]
	v_pk_mul_f32 v[174:175], v[16:17], v[76:77]
	v_pk_fma_f32 v[144:145], v[10:11], v[70:71], v[144:145]
	v_pk_fma_f32 v[148:149], v[10:11], v[78:79], v[148:149]
	v_pk_fma_f32 v[146:147], v[18:19], v[70:71], v[146:147]
	v_pk_fma_f32 v[174:175], v[18:19], v[78:79], v[174:175]
	v_pk_fma_f32 v[144:145], v[4:5], v[72:73], v[144:145]
	v_pk_fma_f32 v[148:149], v[4:5], v[80:81], v[148:149]
	v_pk_fma_f32 v[146:147], v[12:13], v[72:73], v[146:147]
	v_pk_fma_f32 v[174:175], v[12:13], v[80:81], v[174:175]
	v_pk_fma_f32 v[144:145], v[6:7], v[74:75], v[144:145]
	v_pk_fma_f32 v[148:149], v[6:7], v[82:83], v[148:149]
	v_pk_fma_f32 v[146:147], v[14:15], v[74:75], v[146:147]
	v_pk_fma_f32 v[174:175], v[14:15], v[82:83], v[174:175]
	ds_read_b128 v[68:71], v205 offset:9216
	ds_read_b128 v[72:75], v205 offset:9232
	ds_read_b128 v[76:79], v205 offset:9728
	ds_read_b128 v[80:83], v205 offset:9744
	ds_read_b128 v[96:99], v205 offset:9984
	ds_read_b128 v[100:103], v205 offset:10000
	ds_read_b128 v[112:115], v205 offset:9472
	ds_read_b128 v[116:119], v205 offset:9488
	v_pk_mul_f32 v[128:129], v[92:93], v[84:85] op_sel_hi:[0,1]
	v_pk_mul_f32 v[136:137], v[92:93], v[84:85] op_sel:[1,0]
	v_add_f32_e64 v144, v144, v145
	v_add_f32_e64 v148, v148, v149
	v_add_f32_e64 v145, v146, v147
	v_add_f32_e64 v149, v174, v175
	v_pk_mul_f32 v[130:131], v[92:93], v[86:87] op_sel_hi:[0,1]
	v_pk_mul_f32 v[138:139], v[92:93], v[86:87] op_sel:[1,0]
	v_add_f32_dpp v144, v144, v144 quad_perm:[1,0,3,2] row_mask:0xf bank_mask:0xf bound_ctrl:1
	v_add_f32_dpp v148, v148, v148 quad_perm:[1,0,3,2] row_mask:0xf bank_mask:0xf bound_ctrl:1
	v_add_f32_dpp v145, v145, v145 quad_perm:[1,0,3,2] row_mask:0xf bank_mask:0xf bound_ctrl:1
	v_add_f32_dpp v149, v149, v149 quad_perm:[1,0,3,2] row_mask:0xf bank_mask:0xf bound_ctrl:1
	v_pk_mul_f32 v[132:133], v[92:93], v[88:89] op_sel_hi:[0,1]
	v_pk_mul_f32 v[140:141], v[92:93], v[88:89] op_sel:[1,0]
	v_add_f32_dpp v144, v144, v144 quad_perm:[2,3,0,1] row_mask:0xf bank_mask:0xf bound_ctrl:1
	v_add_f32_dpp v148, v148, v148 quad_perm:[2,3,0,1] row_mask:0xf bank_mask:0xf bound_ctrl:1
	v_add_f32_dpp v145, v145, v145 quad_perm:[2,3,0,1] row_mask:0xf bank_mask:0xf bound_ctrl:1
	v_add_f32_dpp v149, v149, v149 quad_perm:[2,3,0,1] row_mask:0xf bank_mask:0xf bound_ctrl:1
	v_pk_mul_f32 v[134:135], v[92:93], v[90:91] op_sel_hi:[0,1]
	v_pk_mul_f32 v[142:143], v[92:93], v[90:91] op_sel:[1,0]
	v_add_f32_dpp v144, v144, v144 row_half_mirror row_mask:0xf bank_mask:0xf bound_ctrl:1
	v_add_f32_dpp v148, v148, v148 row_half_mirror row_mask:0xf bank_mask:0xf bound_ctrl:1
	v_add_f32_dpp v145, v145, v145 row_half_mirror row_mask:0xf bank_mask:0xf bound_ctrl:1
	v_add_f32_dpp v149, v149, v149 row_half_mirror row_mask:0xf bank_mask:0xf bound_ctrl:1
	v_pk_fma_f32 v[176:177], v[144:145], v[94:95], v[148:149] op_sel_hi:[1,0,1]
	v_pk_fma_f32 v[128:129], v[104:105], v[144:145], v[128:129] op_sel_hi:[1,0,1]
	v_pk_fma_f32 v[176:177], v[92:93], v[94:95], v[176:177] op_sel:[0,1,0]
	v_pk_fma_f32 v[136:137], v[104:105], v[144:145], v[136:137] op_sel:[0,1,0]
	ds_read_b128 v[84:87], v205 offset:10240
	ds_read_b128 v[88:91], v205 offset:10256
	ds_read_b64 v[92:93], v206 offset:10496
	ds_read_b64 v[94:95], v207 offset:49248
	ds_write_b64 v208, v[176:177] offset:1280
	v_pk_fma_f32 v[8:9], v[8:9], v[120:121], v[128:129]
	v_pk_fma_f32 v[16:17], v[16:17], v[120:121], v[136:137]
	v_pk_fma_f32 v[130:131], v[106:107], v[144:145], v[130:131] op_sel_hi:[1,0,1]
	v_pk_fma_f32 v[138:139], v[106:107], v[144:145], v[138:139] op_sel:[0,1,0]
	v_pk_fma_f32 v[10:11], v[10:11], v[122:123], v[130:131]
	v_pk_fma_f32 v[18:19], v[18:19], v[122:123], v[138:139]
	v_pk_fma_f32 v[132:133], v[108:109], v[144:145], v[132:133] op_sel_hi:[1,0,1]
	v_pk_fma_f32 v[140:141], v[108:109], v[144:145], v[140:141] op_sel:[0,1,0]
	v_pk_fma_f32 v[4:5], v[4:5], v[124:125], v[132:133]
	v_pk_fma_f32 v[12:13], v[12:13], v[124:125], v[140:141]
	v_pk_fma_f32 v[134:135], v[110:111], v[144:145], v[134:135] op_sel_hi:[1,0,1]
	v_pk_fma_f32 v[142:143], v[110:111], v[144:145], v[142:143] op_sel:[0,1,0]
	v_pk_fma_f32 v[6:7], v[6:7], v[126:127], v[134:135]
	v_pk_fma_f32 v[14:15], v[14:15], v[126:127], v[142:143]
	s_waitcnt lgkmcnt(0)
; __device__ __forceinline__ float red8(float v) { v = red4(v); v += dppf<0x141>(v); return v; }
; __device__ __forceinline__ f32x2 lo2(const f32x4& v) { return __builtin_shufflevector(v, v, 0, 1); }
; __device__ __forceinline__ f32x2 hi2(const f32x4& v) { return __builtin_shufflevector(v, v, 2, 3); }
; __device__ __forceinline__ f32x2 splat2(float x) { return (f32x2){x, x}; }
; __device__ __forceinline__ void rw_load(RwRegs& R, const float* vb, const float* sb, int t, int k0, int vrow0) {
;   const float* vt = vb + t * 384 + k0;
; #pragma unroll
;   for (int q = 0; q < 2; ++q) {
;     R.a[q] = *(const f32x4*)(vt + q * 4);
;     R.wr[q] = *(const f32x4*)(vt + 128 + q * 4);
;     R.w[q] = *(const f32x4*)(vt + 64 + q * 4);
;     R.b[q] = *(const f32x4*)(vt + 192 + q * 4);
;     R.k[q] = *(const f32x4*)(vt + 256 + q * 4);
;   }
;   R.v = *(const f32x2*)(vb + t * 384 + 320 + vrow0);
;   R.sc = *(const f32x4*)(sb + t * 4);
; }
; __device__ __forceinline__ f32x2 rw_step(f32x2 (&S)[2][4], const RwRegs& R) {
;   float sa[2], sy[2];
; #pragma unroll
;   for (int r = 0; r < 2; ++r) {
;     f32x2 a0 = S[r][0] * lo2(R.a[0]);
;     f32x2 a1 = S[r][1] * hi2(R.a[0]);
;     f32x2 y0 = S[r][0] * lo2(R.wr[0]);
;     f32x2 y1 = S[r][1] * hi2(R.wr[0]);
;     a0 += S[r][2] * lo2(R.a[1]);
;     a1 += S[r][3] * hi2(R.a[1]);
;     y0 += S[r][2] * lo2(R.wr[1]);
;     y1 += S[r][3] * hi2(R.wr[1]);
;     a0 += a1; y0 += y1;
;     sa[r] = a0.x + a0.y; sy[r] = y0.x + y0.y;
;   }
;   sa[0] = red8(sa[0]); sa[1] = red8(sa[1]); sy[0] = red8(sy[0]); sy[1] = red8(sy[1]);
;   f32x2 yv;
; #pragma unroll
;   for (int r = 0; r < 2; ++r) {
;     const float vr = r ? R.v.y : R.v.x;
;     const f32x2 sa2 = splat2(sa[r]), vv2 = splat2(vr);
;     S[r][0] = S[r][0] * lo2(R.w[0]) + (sa2 * lo2(R.b[0]) + vv2 * lo2(R.k[0]));
;     S[r][1] = S[r][1] * hi2(R.w[0]) + (sa2 * hi2(R.b[0]) + vv2 * hi2(R.k[0]));
;     S[r][2] = S[r][2] * lo2(R.w[1]) + (sa2 * lo2(R.b[1]) + vv2 * lo2(R.k[1]));
;     S[r][3] = S[r][3] * hi2(R.w[1]) + (sa2 * hi2(R.b[1]) + vv2 * hi2(R.k[1]));
;     const float y = sy[r] + sa[r] * R.sc.x + vr * R.sc.y;
;     if (r) yv.y = y; else yv.x = y;
;   }
;   return yv;
; }
	s_nop 0
	v_pk_mul_f32 v[144:145], v[8:9], v[68:69]
	v_pk_mul_f32 v[148:149], v[8:9], v[76:77]
	v_pk_mul_f32 v[146:147], v[16:17], v[68:69]
	v_pk_mul_f32 v[174:175], v[16:17], v[76:77]
	v_pk_fma_f32 v[144:145], v[10:11], v[70:71], v[144:145]
	v_pk_fma_f32 v[148:149], v[10:11], v[78:79], v[148:149]
	v_pk_fma_f32 v[146:147], v[18:19], v[70:71], v[146:147]
	v_pk_fma_f32 v[174:175], v[18:19], v[78:79], v[174:175]
	v_pk_fma_f32 v[144:145], v[4:5], v[72:73], v[144:145]
	v_pk_fma_f32 v[148:149], v[4:5], v[80:81], v[148:149]
	v_pk_fma_f32 v[146:147], v[12:13], v[72:73], v[146:147]
	v_pk_fma_f32 v[174:175], v[12:13], v[80:81], v[174:175]
	v_pk_fma_f32 v[144:145], v[6:7], v[74:75], v[144:145]
	v_pk_fma_f32 v[148:149], v[6:7], v[82:83], v[148:149]
	v_pk_fma_f32 v[146:147], v[14:15], v[74:75], v[146:147]
	v_pk_fma_f32 v[174:175], v[14:15], v[82:83], v[174:175]
	ds_read_b128 v[68:71], v205 offset:10752
	ds_read_b128 v[72:75], v205 offset:10768
	ds_read_b128 v[76:79], v205 offset:11264
	ds_read_b128 v[80:83], v205 offset:11280
	ds_read_b128 v[104:107], v205 offset:11520
	ds_read_b128 v[108:111], v205 offset:11536
	ds_read_b128 v[120:123], v205 offset:11008
	ds_read_b128 v[124:127], v205 offset:11024
	v_pk_mul_f32 v[128:129], v[92:93], v[84:85] op_sel_hi:[0,1]
	v_pk_mul_f32 v[136:137], v[92:93], v[84:85] op_sel:[1,0]
	v_add_f32_e64 v144, v144, v145
	v_add_f32_e64 v148, v148, v149
	v_add_f32_e64 v145, v146, v147
	v_add_f32_e64 v149, v174, v175
	v_pk_mul_f32 v[130:131], v[92:93], v[86:87] op_sel_hi:[0,1]
	v_pk_mul_f32 v[138:139], v[92:93], v[86:87] op_sel:[1,0]
	v_add_f32_dpp v144, v144, v144 quad_perm:[1,0,3,2] row_mask:0xf bank_mask:0xf bound_ctrl:1
	v_add_f32_dpp v148, v148, v148 quad_perm:[1,0,3,2] row_mask:0xf bank_mask:0xf bound_ctrl:1
	v_add_f32_dpp v145, v145, v145 quad_perm:[1,0,3,2] row_mask:0xf bank_mask:0xf bound_ctrl:1
	v_add_f32_dpp v149, v149, v149 quad_perm:[1,0,3,2] row_mask:0xf bank_mask:0xf bound_ctrl:1
	v_pk_mul_f32 v[132:133], v[92:93], v[88:89] op_sel_hi:[0,1]
	v_pk_mul_f32 v[140:141], v[92:93], v[88:89] op_sel:[1,0]
	v_add_f32_dpp v144, v144, v144 quad_perm:[2,3,0,1] row_mask:0xf bank_mask:0xf bound_ctrl:1
	v_add_f32_dpp v148, v148, v148 quad_perm:[2,3,0,1] row_mask:0xf bank_mask:0xf bound_ctrl:1
	v_add_f32_dpp v145, v145, v145 quad_perm:[2,3,0,1] row_mask:0xf bank_mask:0xf bound_ctrl:1
	v_add_f32_dpp v149, v149, v149 quad_perm:[2,3,0,1] row_mask:0xf bank_mask:0xf bound_ctrl:1
	v_pk_mul_f32 v[134:135], v[92:93], v[90:91] op_sel_hi:[0,1]
	v_pk_mul_f32 v[142:143], v[92:93], v[90:91] op_sel:[1,0]
	v_add_f32_dpp v144, v144, v144 row_half_mirror row_mask:0xf bank_mask:0xf bound_ctrl:1
	v_add_f32_dpp v148, v148, v148 row_half_mirror row_mask:0xf bank_mask:0xf bound_ctrl:1
	v_add_f32_dpp v145, v145, v145 row_half_mirror row_mask:0xf bank_mask:0xf bound_ctrl:1
	v_add_f32_dpp v149, v149, v149 row_half_mirror row_mask:0xf bank_mask:0xf bound_ctrl:1
	v_pk_fma_f32 v[176:177], v[144:145], v[94:95], v[148:149] op_sel_hi:[1,0,1]
	v_pk_fma_f32 v[128:129], v[96:97], v[144:145], v[128:129] op_sel_hi:[1,0,1]
	v_pk_fma_f32 v[176:177], v[92:93], v[94:95], v[176:177] op_sel:[0,1,0]
	v_pk_fma_f32 v[136:137], v[96:97], v[144:145], v[136:137] op_sel:[0,1,0]
	ds_read_b128 v[84:87], v205 offset:11776
	ds_read_b128 v[88:91], v205 offset:11792
	ds_read_b64 v[92:93], v206 offset:12032
	ds_read_b64 v[94:95], v207 offset:49264
	ds_write_b64 v208, v[176:177] offset:1536
	v_pk_fma_f32 v[8:9], v[8:9], v[112:113], v[128:129]
	v_pk_fma_f32 v[16:17], v[16:17], v[112:113], v[136:137]
	v_pk_fma_f32 v[130:131], v[98:99], v[144:145], v[130:131] op_sel_hi:[1,0,1]
	v_pk_fma_f32 v[138:139], v[98:99], v[144:145], v[138:139] op_sel:[0,1,0]
	v_pk_fma_f32 v[10:11], v[10:11], v[114:115], v[130:131]
	v_pk_fma_f32 v[18:19], v[18:19], v[114:115], v[138:139]
	v_pk_fma_f32 v[132:133], v[100:101], v[144:145], v[132:133] op_sel_hi:[1,0,1]
	v_pk_fma_f32 v[140:141], v[100:101], v[144:145], v[140:141] op_sel:[0,1,0]
	v_pk_fma_f32 v[4:5], v[4:5], v[116:117], v[132:133]
	v_pk_fma_f32 v[12:13], v[12:13], v[116:117], v[140:141]
	v_pk_fma_f32 v[134:135], v[102:103], v[144:145], v[134:135] op_sel_hi:[1,0,1]
	v_pk_fma_f32 v[142:143], v[102:103], v[144:145], v[142:143] op_sel:[0,1,0]
	v_pk_fma_f32 v[6:7], v[6:7], v[118:119], v[134:135]
	v_pk_fma_f32 v[14:15], v[14:15], v[118:119], v[142:143]
	s_waitcnt lgkmcnt(0)
; __device__ __forceinline__ float red8(float v) { v = red4(v); v += dppf<0x141>(v); return v; }
; __device__ __forceinline__ f32x2 lo2(const f32x4& v) { return __builtin_shufflevector(v, v, 0, 1); }
; __device__ __forceinline__ f32x2 hi2(const f32x4& v) { return __builtin_shufflevector(v, v, 2, 3); }
; __device__ __forceinline__ f32x2 splat2(float x) { return (f32x2){x, x}; }
; __device__ __forceinline__ void rw_load(RwRegs& R, const float* vb, const float* sb, int t, int k0, int vrow0) {
;   const float* vt = vb + t * 384 + k0;
; #pragma unroll
;   for (int q = 0; q < 2; ++q) {
;     R.a[q] = *(const f32x4*)(vt + q * 4);
;     R.wr[q] = *(const f32x4*)(vt + 128 + q * 4);
;     R.w[q] = *(const f32x4*)(vt + 64 + q * 4);
;     R.b[q] = *(const f32x4*)(vt + 192 + q * 4);
;     R.k[q] = *(const f32x4*)(vt + 256 + q * 4);
;   }
;   R.v = *(const f32x2*)(vb + t * 384 + 320 + vrow0);
;   R.sc = *(const f32x4*)(sb + t * 4);
; }
; __device__ __forceinline__ f32x2 rw_step(f32x2 (&S)[2][4], const RwRegs& R) {
;   float sa[2], sy[2];
; #pragma unroll
;   for (int r = 0; r < 2; ++r) {
;     f32x2 a0 = S[r][0] * lo2(R.a[0]);
;     f32x2 a1 = S[r][1] * hi2(R.a[0]);
;     f32x2 y0 = S[r][0] * lo2(R.wr[0]);
;     f32x2 y1 = S[r][1] * hi2(R.wr[0]);
;     a0 += S[r][2] * lo2(R.a[1]);
;     a1 += S[r][3] * hi2(R.a[1]);
;     y0 += S[r][2] * lo2(R.wr[1]);
;     y1 += S[r][3] * hi2(R.wr[1]);
;     a0 += a1; y0 += y1;
;     sa[r] = a0.x + a0.y; sy[r] = y0.x + y0.y;
;   }
;   sa[0] = red8(sa[0]); sa[1] = red8(sa[1]); sy[0] = red8(sy[0]); sy[1] = red8(sy[1]);
;   f32x2 yv;
; #pragma unroll
;   for (int r = 0; r < 2; ++r) {
;     const float vr = r ? R.v.y : R.v.x;
;     const f32x2 sa2 = splat2(sa[r]), vv2 = splat2(vr);
;     S[r][0] = S[r][0] * lo2(R.w[0]) + (sa2 * lo2(R.b[0]) + vv2 * lo2(R.k[0]));
;     S[r][1] = S[r][1] * hi2(R.w[0]) + (sa2 * hi2(R.b[0]) + vv2 * hi2(R.k[0]));
;     S[r][2] = S[r][2] * lo2(R.w[1]) + (sa2 * lo2(R.b[1]) + vv2 * lo2(R.k[1]));
;     S[r][3] = S[r][3] * hi2(R.w[1]) + (sa2 * hi2(R.b[1]) + vv2 * hi2(R.k[1]));
;     const float y = sy[r] + sa[r] * R.sc.x + vr * R.sc.y;
;     if (r) yv.y = y; else yv.x = y;
;   }
;   return yv;
; }
	s_nop 0
	v_pk_mul_f32 v[144:145], v[8:9], v[68:69]
	v_pk_mul_f32 v[148:149], v[8:9], v[76:77]
	v_pk_mul_f32 v[146:147], v[16:17], v[68:69]
	v_pk_mul_f32 v[174:175], v[16:17], v[76:77]
	v_pk_fma_f32 v[144:145], v[10:11], v[70:71], v[144:145]
	v_pk_fma_f32 v[148:149], v[10:11], v[78:79], v[148:149]
	v_pk_fma_f32 v[146:147], v[18:19], v[70:71], v[146:147]
	v_pk_fma_f32 v[174:175], v[18:19], v[78:79], v[174:175]
	v_pk_fma_f32 v[144:145], v[4:5], v[72:73], v[144:145]
	v_pk_fma_f32 v[148:149], v[4:5], v[80:81], v[148:149]
	v_pk_fma_f32 v[146:147], v[12:13], v[72:73], v[146:147]
	v_pk_fma_f32 v[174:175], v[12:13], v[80:81], v[174:175]
	v_pk_fma_f32 v[144:145], v[6:7], v[74:75], v[144:145]
	v_pk_fma_f32 v[148:149], v[6:7], v[82:83], v[148:149]
	v_pk_fma_f32 v[146:147], v[14:15], v[74:75], v[146:147]
	v_pk_fma_f32 v[174:175], v[14:15], v[82:83], v[174:175]
	ds_read_b128 v[68:71], v205 offset:12288
	ds_read_b128 v[72:75], v205 offset:12304
	ds_read_b128 v[76:79], v205 offset:12800
	ds_read_b128 v[80:83], v205 offset:12816
	ds_read_b128 v[96:99], v205 offset:13056
	ds_read_b128 v[100:103], v205 offset:13072
	ds_read_b128 v[112:115], v205 offset:12544
	ds_read_b128 v[116:119], v205 offset:12560
	v_pk_mul_f32 v[128:129], v[92:93], v[84:85] op_sel_hi:[0,1]
	v_pk_mul_f32 v[136:137], v[92:93], v[84:85] op_sel:[1,0]
	v_add_f32_e64 v144, v144, v145
	v_add_f32_e64 v148, v148, v149
	v_add_f32_e64 v145, v146, v147
	v_add_f32_e64 v149, v174, v175
	v_pk_mul_f32 v[130:131], v[92:93], v[86:87] op_sel_hi:[0,1]
	v_pk_mul_f32 v[138:139], v[92:93], v[86:87] op_sel:[1,0]
	v_add_f32_dpp v144, v144, v144 quad_perm:[1,0,3,2] row_mask:0xf bank_mask:0xf bound_ctrl:1
	v_add_f32_dpp v148, v148, v148 quad_perm:[1,0,3,2] row_mask:0xf bank_mask:0xf bound_ctrl:1
	v_add_f32_dpp v145, v145, v145 quad_perm:[1,0,3,2] row_mask:0xf bank_mask:0xf bound_ctrl:1
	v_add_f32_dpp v149, v149, v149 quad_perm:[1,0,3,2] row_mask:0xf bank_mask:0xf bound_ctrl:1
	v_pk_mul_f32 v[132:133], v[92:93], v[88:89] op_sel_hi:[0,1]
	v_pk_mul_f32 v[140:141], v[92:93], v[88:89] op_sel:[1,0]
	v_add_f32_dpp v144, v144, v144 quad_perm:[2,3,0,1] row_mask:0xf bank_mask:0xf bound_ctrl:1
	v_add_f32_dpp v148, v148, v148 quad_perm:[2,3,0,1] row_mask:0xf bank_mask:0xf bound_ctrl:1
	v_add_f32_dpp v145, v145, v145 quad_perm:[2,3,0,1] row_mask:0xf bank_mask:0xf bound_ctrl:1
	v_add_f32_dpp v149, v149, v149 quad_perm:[2,3,0,1] row_mask:0xf bank_mask:0xf bound_ctrl:1
	v_pk_mul_f32 v[134:135], v[92:93], v[90:91] op_sel_hi:[0,1]
	v_pk_mul_f32 v[142:143], v[92:93], v[90:91] op_sel:[1,0]
	v_add_f32_dpp v144, v144, v144 row_half_mirror row_mask:0xf bank_mask:0xf bound_ctrl:1
	v_add_f32_dpp v148, v148, v148 row_half_mirror row_mask:0xf bank_mask:0xf bound_ctrl:1
	v_add_f32_dpp v145, v145, v145 row_half_mirror row_mask:0xf bank_mask:0xf bound_ctrl:1
	v_add_f32_dpp v149, v149, v149 row_half_mirror row_mask:0xf bank_mask:0xf bound_ctrl:1
	v_pk_fma_f32 v[176:177], v[144:145], v[94:95], v[148:149] op_sel_hi:[1,0,1]
	v_pk_fma_f32 v[128:129], v[104:105], v[144:145], v[128:129] op_sel_hi:[1,0,1]
	v_pk_fma_f32 v[176:177], v[92:93], v[94:95], v[176:177] op_sel:[0,1,0]
	v_pk_fma_f32 v[136:137], v[104:105], v[144:145], v[136:137] op_sel:[0,1,0]
	ds_read_b128 v[84:87], v205 offset:13312
	ds_read_b128 v[88:91], v205 offset:13328
	ds_read_b64 v[92:93], v206 offset:13568
	ds_read_b64 v[94:95], v207 offset:49280
	ds_write_b64 v208, v[176:177] offset:1792
	v_pk_fma_f32 v[8:9], v[8:9], v[120:121], v[128:129]
	v_pk_fma_f32 v[16:17], v[16:17], v[120:121], v[136:137]
	v_pk_fma_f32 v[130:131], v[106:107], v[144:145], v[130:131] op_sel_hi:[1,0,1]
	v_pk_fma_f32 v[138:139], v[106:107], v[144:145], v[138:139] op_sel:[0,1,0]
	v_pk_fma_f32 v[10:11], v[10:11], v[122:123], v[130:131]
	v_pk_fma_f32 v[18:19], v[18:19], v[122:123], v[138:139]
	v_pk_fma_f32 v[132:133], v[108:109], v[144:145], v[132:133] op_sel_hi:[1,0,1]
	v_pk_fma_f32 v[140:141], v[108:109], v[144:145], v[140:141] op_sel:[0,1,0]
	v_pk_fma_f32 v[4:5], v[4:5], v[124:125], v[132:133]
	v_pk_fma_f32 v[12:13], v[12:13], v[124:125], v[140:141]
	v_pk_fma_f32 v[134:135], v[110:111], v[144:145], v[134:135] op_sel_hi:[1,0,1]
	v_pk_fma_f32 v[142:143], v[110:111], v[144:145], v[142:143] op_sel:[0,1,0]
	v_pk_fma_f32 v[6:7], v[6:7], v[126:127], v[134:135]
	v_pk_fma_f32 v[14:15], v[14:15], v[126:127], v[142:143]
	s_waitcnt lgkmcnt(0)
; __device__ __forceinline__ float red8(float v) { v = red4(v); v += dppf<0x141>(v); return v; }
; __device__ __forceinline__ f32x2 lo2(const f32x4& v) { return __builtin_shufflevector(v, v, 0, 1); }
; __device__ __forceinline__ f32x2 hi2(const f32x4& v) { return __builtin_shufflevector(v, v, 2, 3); }
; __device__ __forceinline__ f32x2 splat2(float x) { return (f32x2){x, x}; }
; __device__ __forceinline__ void rw_load(RwRegs& R, const float* vb, const float* sb, int t, int k0, int vrow0) {
;   const float* vt = vb + t * 384 + k0;
; #pragma unroll
;   for (int q = 0; q < 2; ++q) {
;     R.a[q] = *(const f32x4*)(vt + q * 4);
;     R.wr[q] = *(const f32x4*)(vt + 128 + q * 4);
;     R.w[q] = *(const f32x4*)(vt + 64 + q * 4);
;     R.b[q] = *(const f32x4*)(vt + 192 + q * 4);
;     R.k[q] = *(const f32x4*)(vt + 256 + q * 4);
;   }
;   R.v = *(const f32x2*)(vb + t * 384 + 320 + vrow0);
;   R.sc = *(const f32x4*)(sb + t * 4);
; }
; __device__ __forceinline__ f32x2 rw_step(f32x2 (&S)[2][4], const RwRegs& R) {
;   float sa[2], sy[2];
; #pragma unroll
;   for (int r = 0; r < 2; ++r) {
;     f32x2 a0 = S[r][0] * lo2(R.a[0]);
;     f32x2 a1 = S[r][1] * hi2(R.a[0]);
;     f32x2 y0 = S[r][0] * lo2(R.wr[0]);
;     f32x2 y1 = S[r][1] * hi2(R.wr[0]);
;     a0 += S[r][2] * lo2(R.a[1]);
;     a1 += S[r][3] * hi2(R.a[1]);
;     y0 += S[r][2] * lo2(R.wr[1]);
;     y1 += S[r][3] * hi2(R.wr[1]);
;     a0 += a1; y0 += y1;
;     sa[r] = a0.x + a0.y; sy[r] = y0.x + y0.y;
;   }
;   sa[0] = red8(sa[0]); sa[1] = red8(sa[1]); sy[0] = red8(sy[0]); sy[1] = red8(sy[1]);
;   f32x2 yv;
; #pragma unroll
;   for (int r = 0; r < 2; ++r) {
;     const float vr = r ? R.v.y : R.v.x;
;     const f32x2 sa2 = splat2(sa[r]), vv2 = splat2(vr);
;     S[r][0] = S[r][0] * lo2(R.w[0]) + (sa2 * lo2(R.b[0]) + vv2 * lo2(R.k[0]));
;     S[r][1] = S[r][1] * hi2(R.w[0]) + (sa2 * hi2(R.b[0]) + vv2 * hi2(R.k[0]));
;     S[r][2] = S[r][2] * lo2(R.w[1]) + (sa2 * lo2(R.b[1]) + vv2 * lo2(R.k[1]));
;     S[r][3] = S[r][3] * hi2(R.w[1]) + (sa2 * hi2(R.b[1]) + vv2 * hi2(R.k[1]));
;     const float y = sy[r] + sa[r] * R.sc.x + vr * R.sc.y;
;     if (r) yv.y = y; else yv.x = y;
;   }
;   return yv;
; }
	s_nop 0
	v_pk_mul_f32 v[144:145], v[8:9], v[68:69]
	v_pk_mul_f32 v[148:149], v[8:9], v[76:77]
	v_pk_mul_f32 v[146:147], v[16:17], v[68:69]
	v_pk_mul_f32 v[174:175], v[16:17], v[76:77]
	v_pk_fma_f32 v[144:145], v[10:11], v[70:71], v[144:145]
	v_pk_fma_f32 v[148:149], v[10:11], v[78:79], v[148:149]
	v_pk_fma_f32 v[146:147], v[18:19], v[70:71], v[146:147]
	v_pk_fma_f32 v[174:175], v[18:19], v[78:79], v[174:175]
	v_pk_fma_f32 v[144:145], v[4:5], v[72:73], v[144:145]
	v_pk_fma_f32 v[148:149], v[4:5], v[80:81], v[148:149]
	v_pk_fma_f32 v[146:147], v[12:13], v[72:73], v[146:147]
	v_pk_fma_f32 v[174:175], v[12:13], v[80:81], v[174:175]
	v_pk_fma_f32 v[144:145], v[6:7], v[74:75], v[144:145]
	v_pk_fma_f32 v[148:149], v[6:7], v[82:83], v[148:149]
	v_pk_fma_f32 v[146:147], v[14:15], v[74:75], v[146:147]
	v_pk_fma_f32 v[174:175], v[14:15], v[82:83], v[174:175]
	ds_read_b128 v[68:71], v205 offset:13824
	ds_read_b128 v[72:75], v205 offset:13840
	ds_read_b128 v[76:79], v205 offset:14336
	ds_read_b128 v[80:83], v205 offset:14352
	ds_read_b128 v[104:107], v205 offset:14592
	ds_read_b128 v[108:111], v205 offset:14608
	ds_read_b128 v[120:123], v205 offset:14080
	ds_read_b128 v[124:127], v205 offset:14096
	v_pk_mul_f32 v[128:129], v[92:93], v[84:85] op_sel_hi:[0,1]
	v_pk_mul_f32 v[136:137], v[92:93], v[84:85] op_sel:[1,0]
	v_add_f32_e64 v144, v144, v145
	v_add_f32_e64 v148, v148, v149
	v_add_f32_e64 v145, v146, v147
	v_add_f32_e64 v149, v174, v175
	v_pk_mul_f32 v[130:131], v[92:93], v[86:87] op_sel_hi:[0,1]
	v_pk_mul_f32 v[138:139], v[92:93], v[86:87] op_sel:[1,0]
	v_add_f32_dpp v144, v144, v144 quad_perm:[1,0,3,2] row_mask:0xf bank_mask:0xf bound_ctrl:1
	v_add_f32_dpp v148, v148, v148 quad_perm:[1,0,3,2] row_mask:0xf bank_mask:0xf bound_ctrl:1
	v_add_f32_dpp v145, v145, v145 quad_perm:[1,0,3,2] row_mask:0xf bank_mask:0xf bound_ctrl:1
	v_add_f32_dpp v149, v149, v149 quad_perm:[1,0,3,2] row_mask:0xf bank_mask:0xf bound_ctrl:1
	v_pk_mul_f32 v[132:133], v[92:93], v[88:89] op_sel_hi:[0,1]
	v_pk_mul_f32 v[140:141], v[92:93], v[88:89] op_sel:[1,0]
	v_add_f32_dpp v144, v144, v144 quad_perm:[2,3,0,1] row_mask:0xf bank_mask:0xf bound_ctrl:1
	v_add_f32_dpp v148, v148, v148 quad_perm:[2,3,0,1] row_mask:0xf bank_mask:0xf bound_ctrl:1
	v_add_f32_dpp v145, v145, v145 quad_perm:[2,3,0,1] row_mask:0xf bank_mask:0xf bound_ctrl:1
	v_add_f32_dpp v149, v149, v149 quad_perm:[2,3,0,1] row_mask:0xf bank_mask:0xf bound_ctrl:1
	v_pk_mul_f32 v[134:135], v[92:93], v[90:91] op_sel_hi:[0,1]
	v_pk_mul_f32 v[142:143], v[92:93], v[90:91] op_sel:[1,0]
	v_add_f32_dpp v144, v144, v144 row_half_mirror row_mask:0xf bank_mask:0xf bound_ctrl:1
	v_add_f32_dpp v148, v148, v148 row_half_mirror row_mask:0xf bank_mask:0xf bound_ctrl:1
	v_add_f32_dpp v145, v145, v145 row_half_mirror row_mask:0xf bank_mask:0xf bound_ctrl:1
	v_add_f32_dpp v149, v149, v149 row_half_mirror row_mask:0xf bank_mask:0xf bound_ctrl:1
	v_pk_fma_f32 v[176:177], v[144:145], v[94:95], v[148:149] op_sel_hi:[1,0,1]
	v_pk_fma_f32 v[128:129], v[96:97], v[144:145], v[128:129] op_sel_hi:[1,0,1]
	v_pk_fma_f32 v[176:177], v[92:93], v[94:95], v[176:177] op_sel:[0,1,0]
	v_pk_fma_f32 v[136:137], v[96:97], v[144:145], v[136:137] op_sel:[0,1,0]
	ds_read_b128 v[84:87], v205 offset:14848
	ds_read_b128 v[88:91], v205 offset:14864
	ds_read_b64 v[92:93], v206 offset:15104
	ds_read_b64 v[94:95], v207 offset:49296
	ds_write_b64 v208, v[176:177] offset:2048
	v_pk_fma_f32 v[8:9], v[8:9], v[112:113], v[128:129]
	v_pk_fma_f32 v[16:17], v[16:17], v[112:113], v[136:137]
	v_pk_fma_f32 v[130:131], v[98:99], v[144:145], v[130:131] op_sel_hi:[1,0,1]
	v_pk_fma_f32 v[138:139], v[98:99], v[144:145], v[138:139] op_sel:[0,1,0]
	v_pk_fma_f32 v[10:11], v[10:11], v[114:115], v[130:131]
	v_pk_fma_f32 v[18:19], v[18:19], v[114:115], v[138:139]
	v_pk_fma_f32 v[132:133], v[100:101], v[144:145], v[132:133] op_sel_hi:[1,0,1]
	v_pk_fma_f32 v[140:141], v[100:101], v[144:145], v[140:141] op_sel:[0,1,0]
	v_pk_fma_f32 v[4:5], v[4:5], v[116:117], v[132:133]
	v_pk_fma_f32 v[12:13], v[12:13], v[116:117], v[140:141]
	v_pk_fma_f32 v[134:135], v[102:103], v[144:145], v[134:135] op_sel_hi:[1,0,1]
	v_pk_fma_f32 v[142:143], v[102:103], v[144:145], v[142:143] op_sel:[0,1,0]
	v_pk_fma_f32 v[6:7], v[6:7], v[118:119], v[134:135]
	v_pk_fma_f32 v[14:15], v[14:15], v[118:119], v[142:143]
	s_waitcnt lgkmcnt(0)
; __device__ __forceinline__ float red8(float v) { v = red4(v); v += dppf<0x141>(v); return v; }
; __device__ __forceinline__ f32x2 lo2(const f32x4& v) { return __builtin_shufflevector(v, v, 0, 1); }
; __device__ __forceinline__ f32x2 hi2(const f32x4& v) { return __builtin_shufflevector(v, v, 2, 3); }
; __device__ __forceinline__ f32x2 splat2(float x) { return (f32x2){x, x}; }
; __device__ __forceinline__ void rw_load(RwRegs& R, const float* vb, const float* sb, int t, int k0, int vrow0) {
;   const float* vt = vb + t * 384 + k0;
; #pragma unroll
;   for (int q = 0; q < 2; ++q) {
;     R.a[q] = *(const f32x4*)(vt + q * 4);
;     R.wr[q] = *(const f32x4*)(vt + 128 + q * 4);
;     R.w[q] = *(const f32x4*)(vt + 64 + q * 4);
;     R.b[q] = *(const f32x4*)(vt + 192 + q * 4);
;     R.k[q] = *(const f32x4*)(vt + 256 + q * 4);
;   }
;   R.v = *(const f32x2*)(vb + t * 384 + 320 + vrow0);
;   R.sc = *(const f32x4*)(sb + t * 4);
; }
; __device__ __forceinline__ f32x2 rw_step(f32x2 (&S)[2][4], const RwRegs& R) {
;   float sa[2], sy[2];
; #pragma unroll
;   for (int r = 0; r < 2; ++r) {
;     f32x2 a0 = S[r][0] * lo2(R.a[0]);
;     f32x2 a1 = S[r][1] * hi2(R.a[0]);
;     f32x2 y0 = S[r][0] * lo2(R.wr[0]);
;     f32x2 y1 = S[r][1] * hi2(R.wr[0]);
;     a0 += S[r][2] * lo2(R.a[1]);
;     a1 += S[r][3] * hi2(R.a[1]);
;     y0 += S[r][2] * lo2(R.wr[1]);
;     y1 += S[r][3] * hi2(R.wr[1]);
;     a0 += a1; y0 += y1;
;     sa[r] = a0.x + a0.y; sy[r] = y0.x + y0.y;
;   }
;   sa[0] = red8(sa[0]); sa[1] = red8(sa[1]); sy[0] = red8(sy[0]); sy[1] = red8(sy[1]);
;   f32x2 yv;
; #pragma unroll
;   for (int r = 0; r < 2; ++r) {
;     const float vr = r ? R.v.y : R.v.x;
;     const f32x2 sa2 = splat2(sa[r]), vv2 = splat2(vr);
;     S[r][0] = S[r][0] * lo2(R.w[0]) + (sa2 * lo2(R.b[0]) + vv2 * lo2(R.k[0]));
;     S[r][1] = S[r][1] * hi2(R.w[0]) + (sa2 * hi2(R.b[0]) + vv2 * hi2(R.k[0]));
;     S[r][2] = S[r][2] * lo2(R.w[1]) + (sa2 * lo2(R.b[1]) + vv2 * lo2(R.k[1]));
;     S[r][3] = S[r][3] * hi2(R.w[1]) + (sa2 * hi2(R.b[1]) + vv2 * hi2(R.k[1]));
;     const float y = sy[r] + sa[r] * R.sc.x + vr * R.sc.y;
;     if (r) yv.y = y; else yv.x = y;
;   }
;   return yv;
; }
	s_nop 0
	v_pk_mul_f32 v[144:145], v[8:9], v[68:69]
	v_pk_mul_f32 v[148:149], v[8:9], v[76:77]
	v_pk_mul_f32 v[146:147], v[16:17], v[68:69]
	v_pk_mul_f32 v[174:175], v[16:17], v[76:77]
	v_pk_fma_f32 v[144:145], v[10:11], v[70:71], v[144:145]
	v_pk_fma_f32 v[148:149], v[10:11], v[78:79], v[148:149]
	v_pk_fma_f32 v[146:147], v[18:19], v[70:71], v[146:147]
	v_pk_fma_f32 v[174:175], v[18:19], v[78:79], v[174:175]
	v_pk_fma_f32 v[144:145], v[4:5], v[72:73], v[144:145]
	v_pk_fma_f32 v[148:149], v[4:5], v[80:81], v[148:149]
	v_pk_fma_f32 v[146:147], v[12:13], v[72:73], v[146:147]
	v_pk_fma_f32 v[174:175], v[12:13], v[80:81], v[174:175]
	v_pk_fma_f32 v[144:145], v[6:7], v[74:75], v[144:145]
	v_pk_fma_f32 v[148:149], v[6:7], v[82:83], v[148:149]
	v_pk_fma_f32 v[146:147], v[14:15], v[74:75], v[146:147]
	v_pk_fma_f32 v[174:175], v[14:15], v[82:83], v[174:175]
	ds_read_b128 v[68:71], v205 offset:15360
	ds_read_b128 v[72:75], v205 offset:15376
	ds_read_b128 v[76:79], v205 offset:15872
	ds_read_b128 v[80:83], v205 offset:15888
	ds_read_b128 v[96:99], v205 offset:16128
	ds_read_b128 v[100:103], v205 offset:16144
	ds_read_b128 v[112:115], v205 offset:15616
	ds_read_b128 v[116:119], v205 offset:15632
	v_pk_mul_f32 v[128:129], v[92:93], v[84:85] op_sel_hi:[0,1]
	v_pk_mul_f32 v[136:137], v[92:93], v[84:85] op_sel:[1,0]
	v_add_f32_e64 v144, v144, v145
	v_add_f32_e64 v148, v148, v149
	v_add_f32_e64 v145, v146, v147
	v_add_f32_e64 v149, v174, v175
	v_pk_mul_f32 v[130:131], v[92:93], v[86:87] op_sel_hi:[0,1]
	v_pk_mul_f32 v[138:139], v[92:93], v[86:87] op_sel:[1,0]
	v_add_f32_dpp v144, v144, v144 quad_perm:[1,0,3,2] row_mask:0xf bank_mask:0xf bound_ctrl:1
	v_add_f32_dpp v148, v148, v148 quad_perm:[1,0,3,2] row_mask:0xf bank_mask:0xf bound_ctrl:1
	v_add_f32_dpp v145, v145, v145 quad_perm:[1,0,3,2] row_mask:0xf bank_mask:0xf bound_ctrl:1
	v_add_f32_dpp v149, v149, v149 quad_perm:[1,0,3,2] row_mask:0xf bank_mask:0xf bound_ctrl:1
	v_pk_mul_f32 v[132:133], v[92:93], v[88:89] op_sel_hi:[0,1]
	v_pk_mul_f32 v[140:141], v[92:93], v[88:89] op_sel:[1,0]
	v_add_f32_dpp v144, v144, v144 quad_perm:[2,3,0,1] row_mask:0xf bank_mask:0xf bound_ctrl:1
	v_add_f32_dpp v148, v148, v148 quad_perm:[2,3,0,1] row_mask:0xf bank_mask:0xf bound_ctrl:1
	v_add_f32_dpp v145, v145, v145 quad_perm:[2,3,0,1] row_mask:0xf bank_mask:0xf bound_ctrl:1
	v_add_f32_dpp v149, v149, v149 quad_perm:[2,3,0,1] row_mask:0xf bank_mask:0xf bound_ctrl:1
	v_pk_mul_f32 v[134:135], v[92:93], v[90:91] op_sel_hi:[0,1]
	v_pk_mul_f32 v[142:143], v[92:93], v[90:91] op_sel:[1,0]
	v_add_f32_dpp v144, v144, v144 row_half_mirror row_mask:0xf bank_mask:0xf bound_ctrl:1
	v_add_f32_dpp v148, v148, v148 row_half_mirror row_mask:0xf bank_mask:0xf bound_ctrl:1
	v_add_f32_dpp v145, v145, v145 row_half_mirror row_mask:0xf bank_mask:0xf bound_ctrl:1
	v_add_f32_dpp v149, v149, v149 row_half_mirror row_mask:0xf bank_mask:0xf bound_ctrl:1
	v_pk_fma_f32 v[176:177], v[144:145], v[94:95], v[148:149] op_sel_hi:[1,0,1]
	v_pk_fma_f32 v[128:129], v[104:105], v[144:145], v[128:129] op_sel_hi:[1,0,1]
	v_pk_fma_f32 v[176:177], v[92:93], v[94:95], v[176:177] op_sel:[0,1,0]
	v_pk_fma_f32 v[136:137], v[104:105], v[144:145], v[136:137] op_sel:[0,1,0]
	ds_read_b128 v[84:87], v205 offset:16384
	ds_read_b128 v[88:91], v205 offset:16400
	ds_read_b64 v[92:93], v206 offset:16640
	ds_read_b64 v[94:95], v207 offset:49312
	ds_write_b64 v208, v[176:177] offset:2304
	v_pk_fma_f32 v[8:9], v[8:9], v[120:121], v[128:129]
	v_pk_fma_f32 v[16:17], v[16:17], v[120:121], v[136:137]
	v_pk_fma_f32 v[130:131], v[106:107], v[144:145], v[130:131] op_sel_hi:[1,0,1]
	v_pk_fma_f32 v[138:139], v[106:107], v[144:145], v[138:139] op_sel:[0,1,0]
	v_pk_fma_f32 v[10:11], v[10:11], v[122:123], v[130:131]
	v_pk_fma_f32 v[18:19], v[18:19], v[122:123], v[138:139]
	v_pk_fma_f32 v[132:133], v[108:109], v[144:145], v[132:133] op_sel_hi:[1,0,1]
	v_pk_fma_f32 v[140:141], v[108:109], v[144:145], v[140:141] op_sel:[0,1,0]
	v_pk_fma_f32 v[4:5], v[4:5], v[124:125], v[132:133]
	v_pk_fma_f32 v[12:13], v[12:13], v[124:125], v[140:141]
	v_pk_fma_f32 v[134:135], v[110:111], v[144:145], v[134:135] op_sel_hi:[1,0,1]
	v_pk_fma_f32 v[142:143], v[110:111], v[144:145], v[142:143] op_sel:[0,1,0]
	v_pk_fma_f32 v[6:7], v[6:7], v[126:127], v[134:135]
	v_pk_fma_f32 v[14:15], v[14:15], v[126:127], v[142:143]
	s_waitcnt lgkmcnt(0)
; __device__ __forceinline__ float red8(float v) { v = red4(v); v += dppf<0x141>(v); return v; }
; __device__ __forceinline__ f32x2 lo2(const f32x4& v) { return __builtin_shufflevector(v, v, 0, 1); }
; __device__ __forceinline__ f32x2 hi2(const f32x4& v) { return __builtin_shufflevector(v, v, 2, 3); }
; __device__ __forceinline__ f32x2 splat2(float x) { return (f32x2){x, x}; }
; __device__ __forceinline__ void rw_load(RwRegs& R, const float* vb, const float* sb, int t, int k0, int vrow0) {
;   const float* vt = vb + t * 384 + k0;
; #pragma unroll
;   for (int q = 0; q < 2; ++q) {
;     R.a[q] = *(const f32x4*)(vt + q * 4);
;     R.wr[q] = *(const f32x4*)(vt + 128 + q * 4);
;     R.w[q] = *(const f32x4*)(vt + 64 + q * 4);
;     R.b[q] = *(const f32x4*)(vt + 192 + q * 4);
;     R.k[q] = *(const f32x4*)(vt + 256 + q * 4);
;   }
;   R.v = *(const f32x2*)(vb + t * 384 + 320 + vrow0);
;   R.sc = *(const f32x4*)(sb + t * 4);
; }
; __device__ __forceinline__ f32x2 rw_step(f32x2 (&S)[2][4], const RwRegs& R) {
;   float sa[2], sy[2];
; #pragma unroll
;   for (int r = 0; r < 2; ++r) {
;     f32x2 a0 = S[r][0] * lo2(R.a[0]);
;     f32x2 a1 = S[r][1] * hi2(R.a[0]);
;     f32x2 y0 = S[r][0] * lo2(R.wr[0]);
;     f32x2 y1 = S[r][1] * hi2(R.wr[0]);
;     a0 += S[r][2] * lo2(R.a[1]);
;     a1 += S[r][3] * hi2(R.a[1]);
;     y0 += S[r][2] * lo2(R.wr[1]);
;     y1 += S[r][3] * hi2(R.wr[1]);
;     a0 += a1; y0 += y1;
;     sa[r] = a0.x + a0.y; sy[r] = y0.x + y0.y;
;   }
;   sa[0] = red8(sa[0]); sa[1] = red8(sa[1]); sy[0] = red8(sy[0]); sy[1] = red8(sy[1]);
;   f32x2 yv;
; #pragma unroll
;   for (int r = 0; r < 2; ++r) {
;     const float vr = r ? R.v.y : R.v.x;
;     const f32x2 sa2 = splat2(sa[r]), vv2 = splat2(vr);
;     S[r][0] = S[r][0] * lo2(R.w[0]) + (sa2 * lo2(R.b[0]) + vv2 * lo2(R.k[0]));
;     S[r][1] = S[r][1] * hi2(R.w[0]) + (sa2 * hi2(R.b[0]) + vv2 * hi2(R.k[0]));
;     S[r][2] = S[r][2] * lo2(R.w[1]) + (sa2 * lo2(R.b[1]) + vv2 * lo2(R.k[1]));
;     S[r][3] = S[r][3] * hi2(R.w[1]) + (sa2 * hi2(R.b[1]) + vv2 * hi2(R.k[1]));
;     const float y = sy[r] + sa[r] * R.sc.x + vr * R.sc.y;
;     if (r) yv.y = y; else yv.x = y;
;   }
;   return yv;
; }
	s_nop 0
	v_pk_mul_f32 v[144:145], v[8:9], v[68:69]
	v_pk_mul_f32 v[148:149], v[8:9], v[76:77]
	v_pk_mul_f32 v[146:147], v[16:17], v[68:69]
	v_pk_mul_f32 v[174:175], v[16:17], v[76:77]
	v_pk_fma_f32 v[144:145], v[10:11], v[70:71], v[144:145]
	v_pk_fma_f32 v[148:149], v[10:11], v[78:79], v[148:149]
	v_pk_fma_f32 v[146:147], v[18:19], v[70:71], v[146:147]
	v_pk_fma_f32 v[174:175], v[18:19], v[78:79], v[174:175]
	v_pk_fma_f32 v[144:145], v[4:5], v[72:73], v[144:145]
	v_pk_fma_f32 v[148:149], v[4:5], v[80:81], v[148:149]
	v_pk_fma_f32 v[146:147], v[12:13], v[72:73], v[146:147]
	v_pk_fma_f32 v[174:175], v[12:13], v[80:81], v[174:175]
	v_pk_fma_f32 v[144:145], v[6:7], v[74:75], v[144:145]
	v_pk_fma_f32 v[148:149], v[6:7], v[82:83], v[148:149]
	v_pk_fma_f32 v[146:147], v[14:15], v[74:75], v[146:147]
	v_pk_fma_f32 v[174:175], v[14:15], v[82:83], v[174:175]
	ds_read_b128 v[68:71], v205 offset:16896
	ds_read_b128 v[72:75], v205 offset:16912
	ds_read_b128 v[76:79], v205 offset:17408
	ds_read_b128 v[80:83], v205 offset:17424
	ds_read_b128 v[104:107], v205 offset:17664
	ds_read_b128 v[108:111], v205 offset:17680
	ds_read_b128 v[120:123], v205 offset:17152
	ds_read_b128 v[124:127], v205 offset:17168
	v_pk_mul_f32 v[128:129], v[92:93], v[84:85] op_sel_hi:[0,1]
	v_pk_mul_f32 v[136:137], v[92:93], v[84:85] op_sel:[1,0]
	v_add_f32_e64 v144, v144, v145
	v_add_f32_e64 v148, v148, v149
	v_add_f32_e64 v145, v146, v147
	v_add_f32_e64 v149, v174, v175
	v_pk_mul_f32 v[130:131], v[92:93], v[86:87] op_sel_hi:[0,1]
	v_pk_mul_f32 v[138:139], v[92:93], v[86:87] op_sel:[1,0]
	v_add_f32_dpp v144, v144, v144 quad_perm:[1,0,3,2] row_mask:0xf bank_mask:0xf bound_ctrl:1
	v_add_f32_dpp v148, v148, v148 quad_perm:[1,0,3,2] row_mask:0xf bank_mask:0xf bound_ctrl:1
	v_add_f32_dpp v145, v145, v145 quad_perm:[1,0,3,2] row_mask:0xf bank_mask:0xf bound_ctrl:1
	v_add_f32_dpp v149, v149, v149 quad_perm:[1,0,3,2] row_mask:0xf bank_mask:0xf bound_ctrl:1
	v_pk_mul_f32 v[132:133], v[92:93], v[88:89] op_sel_hi:[0,1]
	v_pk_mul_f32 v[140:141], v[92:93], v[88:89] op_sel:[1,0]
	v_add_f32_dpp v144, v144, v144 quad_perm:[2,3,0,1] row_mask:0xf bank_mask:0xf bound_ctrl:1
	v_add_f32_dpp v148, v148, v148 quad_perm:[2,3,0,1] row_mask:0xf bank_mask:0xf bound_ctrl:1
	v_add_f32_dpp v145, v145, v145 quad_perm:[2,3,0,1] row_mask:0xf bank_mask:0xf bound_ctrl:1
	v_add_f32_dpp v149, v149, v149 quad_perm:[2,3,0,1] row_mask:0xf bank_mask:0xf bound_ctrl:1
	v_pk_mul_f32 v[134:135], v[92:93], v[90:91] op_sel_hi:[0,1]
	v_pk_mul_f32 v[142:143], v[92:93], v[90:91] op_sel:[1,0]
	v_add_f32_dpp v144, v144, v144 row_half_mirror row_mask:0xf bank_mask:0xf bound_ctrl:1
	v_add_f32_dpp v148, v148, v148 row_half_mirror row_mask:0xf bank_mask:0xf bound_ctrl:1
	v_add_f32_dpp v145, v145, v145 row_half_mirror row_mask:0xf bank_mask:0xf bound_ctrl:1
	v_add_f32_dpp v149, v149, v149 row_half_mirror row_mask:0xf bank_mask:0xf bound_ctrl:1
	v_pk_fma_f32 v[176:177], v[144:145], v[94:95], v[148:149] op_sel_hi:[1,0,1]
	v_pk_fma_f32 v[128:129], v[96:97], v[144:145], v[128:129] op_sel_hi:[1,0,1]
	v_pk_fma_f32 v[176:177], v[92:93], v[94:95], v[176:177] op_sel:[0,1,0]
	v_pk_fma_f32 v[136:137], v[96:97], v[144:145], v[136:137] op_sel:[0,1,0]
	ds_read_b128 v[84:87], v205 offset:17920
	ds_read_b128 v[88:91], v205 offset:17936
	ds_read_b64 v[92:93], v206 offset:18176
	ds_read_b64 v[94:95], v207 offset:49328
	ds_write_b64 v208, v[176:177] offset:2560
	v_pk_fma_f32 v[8:9], v[8:9], v[112:113], v[128:129]
	v_pk_fma_f32 v[16:17], v[16:17], v[112:113], v[136:137]
	v_pk_fma_f32 v[130:131], v[98:99], v[144:145], v[130:131] op_sel_hi:[1,0,1]
	v_pk_fma_f32 v[138:139], v[98:99], v[144:145], v[138:139] op_sel:[0,1,0]
	v_pk_fma_f32 v[10:11], v[10:11], v[114:115], v[130:131]
	v_pk_fma_f32 v[18:19], v[18:19], v[114:115], v[138:139]
	v_pk_fma_f32 v[132:133], v[100:101], v[144:145], v[132:133] op_sel_hi:[1,0,1]
	v_pk_fma_f32 v[140:141], v[100:101], v[144:145], v[140:141] op_sel:[0,1,0]
	v_pk_fma_f32 v[4:5], v[4:5], v[116:117], v[132:133]
	v_pk_fma_f32 v[12:13], v[12:13], v[116:117], v[140:141]
	v_pk_fma_f32 v[134:135], v[102:103], v[144:145], v[134:135] op_sel_hi:[1,0,1]
	v_pk_fma_f32 v[142:143], v[102:103], v[144:145], v[142:143] op_sel:[0,1,0]
	v_pk_fma_f32 v[6:7], v[6:7], v[118:119], v[134:135]
	v_pk_fma_f32 v[14:15], v[14:15], v[118:119], v[142:143]
	s_waitcnt lgkmcnt(0)
; __device__ __forceinline__ float red8(float v) { v = red4(v); v += dppf<0x141>(v); return v; }
; __device__ __forceinline__ f32x2 lo2(const f32x4& v) { return __builtin_shufflevector(v, v, 0, 1); }
; __device__ __forceinline__ f32x2 hi2(const f32x4& v) { return __builtin_shufflevector(v, v, 2, 3); }
; __device__ __forceinline__ f32x2 splat2(float x) { return (f32x2){x, x}; }
; __device__ __forceinline__ void rw_load(RwRegs& R, const float* vb, const float* sb, int t, int k0, int vrow0) {
;   const float* vt = vb + t * 384 + k0;
; #pragma unroll
;   for (int q = 0; q < 2; ++q) {
;     R.a[q] = *(const f32x4*)(vt + q * 4);
;     R.wr[q] = *(const f32x4*)(vt + 128 + q * 4);
;     R.w[q] = *(const f32x4*)(vt + 64 + q * 4);
;     R.b[q] = *(const f32x4*)(vt + 192 + q * 4);
;     R.k[q] = *(const f32x4*)(vt + 256 + q * 4);
;   }
;   R.v = *(const f32x2*)(vb + t * 384 + 320 + vrow0);
;   R.sc = *(const f32x4*)(sb + t * 4);
; }
; __device__ __forceinline__ f32x2 rw_step(f32x2 (&S)[2][4], const RwRegs& R) {
;   float sa[2], sy[2];
; #pragma unroll
;   for (int r = 0; r < 2; ++r) {
;     f32x2 a0 = S[r][0] * lo2(R.a[0]);
;     f32x2 a1 = S[r][1] * hi2(R.a[0]);
;     f32x2 y0 = S[r][0] * lo2(R.wr[0]);
;     f32x2 y1 = S[r][1] * hi2(R.wr[0]);
;     a0 += S[r][2] * lo2(R.a[1]);
;     a1 += S[r][3] * hi2(R.a[1]);
;     y0 += S[r][2] * lo2(R.wr[1]);
;     y1 += S[r][3] * hi2(R.wr[1]);
;     a0 += a1; y0 += y1;
;     sa[r] = a0.x + a0.y; sy[r] = y0.x + y0.y;
;   }
;   sa[0] = red8(sa[0]); sa[1] = red8(sa[1]); sy[0] = red8(sy[0]); sy[1] = red8(sy[1]);
;   f32x2 yv;
; #pragma unroll
;   for (int r = 0; r < 2; ++r) {
;     const float vr = r ? R.v.y : R.v.x;
;     const f32x2 sa2 = splat2(sa[r]), vv2 = splat2(vr);
;     S[r][0] = S[r][0] * lo2(R.w[0]) + (sa2 * lo2(R.b[0]) + vv2 * lo2(R.k[0]));
;     S[r][1] = S[r][1] * hi2(R.w[0]) + (sa2 * hi2(R.b[0]) + vv2 * hi2(R.k[0]));
;     S[r][2] = S[r][2] * lo2(R.w[1]) + (sa2 * lo2(R.b[1]) + vv2 * lo2(R.k[1]));
;     S[r][3] = S[r][3] * hi2(R.w[1]) + (sa2 * hi2(R.b[1]) + vv2 * hi2(R.k[1]));
;     const float y = sy[r] + sa[r] * R.sc.x + vr * R.sc.y;
;     if (r) yv.y = y; else yv.x = y;
;   }
;   return yv;
; }
	s_nop 0
	v_pk_mul_f32 v[144:145], v[8:9], v[68:69]
	v_pk_mul_f32 v[148:149], v[8:9], v[76:77]
	v_pk_mul_f32 v[146:147], v[16:17], v[68:69]
	v_pk_mul_f32 v[174:175], v[16:17], v[76:77]
	v_pk_fma_f32 v[144:145], v[10:11], v[70:71], v[144:145]
	v_pk_fma_f32 v[148:149], v[10:11], v[78:79], v[148:149]
	v_pk_fma_f32 v[146:147], v[18:19], v[70:71], v[146:147]
	v_pk_fma_f32 v[174:175], v[18:19], v[78:79], v[174:175]
	v_pk_fma_f32 v[144:145], v[4:5], v[72:73], v[144:145]
	v_pk_fma_f32 v[148:149], v[4:5], v[80:81], v[148:149]
	v_pk_fma_f32 v[146:147], v[12:13], v[72:73], v[146:147]
	v_pk_fma_f32 v[174:175], v[12:13], v[80:81], v[174:175]
	v_pk_fma_f32 v[144:145], v[6:7], v[74:75], v[144:145]
	v_pk_fma_f32 v[148:149], v[6:7], v[82:83], v[148:149]
	v_pk_fma_f32 v[146:147], v[14:15], v[74:75], v[146:147]
	v_pk_fma_f32 v[174:175], v[14:15], v[82:83], v[174:175]
	ds_read_b128 v[68:71], v205 offset:18432
	ds_read_b128 v[72:75], v205 offset:18448
	ds_read_b128 v[76:79], v205 offset:18944
	ds_read_b128 v[80:83], v205 offset:18960
	ds_read_b128 v[96:99], v205 offset:19200
	ds_read_b128 v[100:103], v205 offset:19216
	ds_read_b128 v[112:115], v205 offset:18688
	ds_read_b128 v[116:119], v205 offset:18704
	v_pk_mul_f32 v[128:129], v[92:93], v[84:85] op_sel_hi:[0,1]
	v_pk_mul_f32 v[136:137], v[92:93], v[84:85] op_sel:[1,0]
	v_add_f32_e64 v144, v144, v145
	v_add_f32_e64 v148, v148, v149
	v_add_f32_e64 v145, v146, v147
	v_add_f32_e64 v149, v174, v175
	v_pk_mul_f32 v[130:131], v[92:93], v[86:87] op_sel_hi:[0,1]
	v_pk_mul_f32 v[138:139], v[92:93], v[86:87] op_sel:[1,0]
	v_add_f32_dpp v144, v144, v144 quad_perm:[1,0,3,2] row_mask:0xf bank_mask:0xf bound_ctrl:1
	v_add_f32_dpp v148, v148, v148 quad_perm:[1,0,3,2] row_mask:0xf bank_mask:0xf bound_ctrl:1
	v_add_f32_dpp v145, v145, v145 quad_perm:[1,0,3,2] row_mask:0xf bank_mask:0xf bound_ctrl:1
	v_add_f32_dpp v149, v149, v149 quad_perm:[1,0,3,2] row_mask:0xf bank_mask:0xf bound_ctrl:1
	v_pk_mul_f32 v[132:133], v[92:93], v[88:89] op_sel_hi:[0,1]
	v_pk_mul_f32 v[140:141], v[92:93], v[88:89] op_sel:[1,0]
	v_add_f32_dpp v144, v144, v144 quad_perm:[2,3,0,1] row_mask:0xf bank_mask:0xf bound_ctrl:1
	v_add_f32_dpp v148, v148, v148 quad_perm:[2,3,0,1] row_mask:0xf bank_mask:0xf bound_ctrl:1
	v_add_f32_dpp v145, v145, v145 quad_perm:[2,3,0,1] row_mask:0xf bank_mask:0xf bound_ctrl:1
	v_add_f32_dpp v149, v149, v149 quad_perm:[2,3,0,1] row_mask:0xf bank_mask:0xf bound_ctrl:1
	v_pk_mul_f32 v[134:135], v[92:93], v[90:91] op_sel_hi:[0,1]
	v_pk_mul_f32 v[142:143], v[92:93], v[90:91] op_sel:[1,0]
	v_add_f32_dpp v144, v144, v144 row_half_mirror row_mask:0xf bank_mask:0xf bound_ctrl:1
	v_add_f32_dpp v148, v148, v148 row_half_mirror row_mask:0xf bank_mask:0xf bound_ctrl:1
	v_add_f32_dpp v145, v145, v145 row_half_mirror row_mask:0xf bank_mask:0xf bound_ctrl:1
	v_add_f32_dpp v149, v149, v149 row_half_mirror row_mask:0xf bank_mask:0xf bound_ctrl:1
	v_pk_fma_f32 v[176:177], v[144:145], v[94:95], v[148:149] op_sel_hi:[1,0,1]
	v_pk_fma_f32 v[128:129], v[104:105], v[144:145], v[128:129] op_sel_hi:[1,0,1]
	v_pk_fma_f32 v[176:177], v[92:93], v[94:95], v[176:177] op_sel:[0,1,0]
	v_pk_fma_f32 v[136:137], v[104:105], v[144:145], v[136:137] op_sel:[0,1,0]
	ds_read_b128 v[84:87], v205 offset:19456
	ds_read_b128 v[88:91], v205 offset:19472
	ds_read_b64 v[92:93], v206 offset:19712
	ds_read_b64 v[94:95], v207 offset:49344
	ds_write_b64 v208, v[176:177] offset:2816
	v_pk_fma_f32 v[8:9], v[8:9], v[120:121], v[128:129]
	v_pk_fma_f32 v[16:17], v[16:17], v[120:121], v[136:137]
	v_pk_fma_f32 v[130:131], v[106:107], v[144:145], v[130:131] op_sel_hi:[1,0,1]
	v_pk_fma_f32 v[138:139], v[106:107], v[144:145], v[138:139] op_sel:[0,1,0]
	v_pk_fma_f32 v[10:11], v[10:11], v[122:123], v[130:131]
	v_pk_fma_f32 v[18:19], v[18:19], v[122:123], v[138:139]
	v_pk_fma_f32 v[132:133], v[108:109], v[144:145], v[132:133] op_sel_hi:[1,0,1]
	v_pk_fma_f32 v[140:141], v[108:109], v[144:145], v[140:141] op_sel:[0,1,0]
	v_pk_fma_f32 v[4:5], v[4:5], v[124:125], v[132:133]
	v_pk_fma_f32 v[12:13], v[12:13], v[124:125], v[140:141]
	v_pk_fma_f32 v[134:135], v[110:111], v[144:145], v[134:135] op_sel_hi:[1,0,1]
	v_pk_fma_f32 v[142:143], v[110:111], v[144:145], v[142:143] op_sel:[0,1,0]
	v_pk_fma_f32 v[6:7], v[6:7], v[126:127], v[134:135]
	v_pk_fma_f32 v[14:15], v[14:15], v[126:127], v[142:143]
	s_waitcnt lgkmcnt(0)
; __device__ __forceinline__ float red8(float v) { v = red4(v); v += dppf<0x141>(v); return v; }
; __device__ __forceinline__ f32x2 lo2(const f32x4& v) { return __builtin_shufflevector(v, v, 0, 1); }
; __device__ __forceinline__ f32x2 hi2(const f32x4& v) { return __builtin_shufflevector(v, v, 2, 3); }
; __device__ __forceinline__ f32x2 splat2(float x) { return (f32x2){x, x}; }
; __device__ __forceinline__ void rw_load(RwRegs& R, const float* vb, const float* sb, int t, int k0, int vrow0) {
;   const float* vt = vb + t * 384 + k0;
; #pragma unroll
;   for (int q = 0; q < 2; ++q) {
;     R.a[q] = *(const f32x4*)(vt + q * 4);
;     R.wr[q] = *(const f32x4*)(vt + 128 + q * 4);
;     R.w[q] = *(const f32x4*)(vt + 64 + q * 4);
;     R.b[q] = *(const f32x4*)(vt + 192 + q * 4);
;     R.k[q] = *(const f32x4*)(vt + 256 + q * 4);
;   }
;   R.v = *(const f32x2*)(vb + t * 384 + 320 + vrow0);
;   R.sc = *(const f32x4*)(sb + t * 4);
; }
; __device__ __forceinline__ f32x2 rw_step(f32x2 (&S)[2][4], const RwRegs& R) {
;   float sa[2], sy[2];
; #pragma unroll
;   for (int r = 0; r < 2; ++r) {
;     f32x2 a0 = S[r][0] * lo2(R.a[0]);
;     f32x2 a1 = S[r][1] * hi2(R.a[0]);
;     f32x2 y0 = S[r][0] * lo2(R.wr[0]);
;     f32x2 y1 = S[r][1] * hi2(R.wr[0]);
;     a0 += S[r][2] * lo2(R.a[1]);
;     a1 += S[r][3] * hi2(R.a[1]);
;     y0 += S[r][2] * lo2(R.wr[1]);
;     y1 += S[r][3] * hi2(R.wr[1]);
;     a0 += a1; y0 += y1;
;     sa[r] = a0.x + a0.y; sy[r] = y0.x + y0.y;
;   }
;   sa[0] = red8(sa[0]); sa[1] = red8(sa[1]); sy[0] = red8(sy[0]); sy[1] = red8(sy[1]);
;   f32x2 yv;
; #pragma unroll
;   for (int r = 0; r < 2; ++r) {
;     const float vr = r ? R.v.y : R.v.x;
;     const f32x2 sa2 = splat2(sa[r]), vv2 = splat2(vr);
;     S[r][0] = S[r][0] * lo2(R.w[0]) + (sa2 * lo2(R.b[0]) + vv2 * lo2(R.k[0]));
;     S[r][1] = S[r][1] * hi2(R.w[0]) + (sa2 * hi2(R.b[0]) + vv2 * hi2(R.k[0]));
;     S[r][2] = S[r][2] * lo2(R.w[1]) + (sa2 * lo2(R.b[1]) + vv2 * lo2(R.k[1]));
;     S[r][3] = S[r][3] * hi2(R.w[1]) + (sa2 * hi2(R.b[1]) + vv2 * hi2(R.k[1]));
;     const float y = sy[r] + sa[r] * R.sc.x + vr * R.sc.y;
;     if (r) yv.y = y; else yv.x = y;
;   }
;   return yv;
; }
	s_nop 0
	v_pk_mul_f32 v[144:145], v[8:9], v[68:69]
	v_pk_mul_f32 v[148:149], v[8:9], v[76:77]
	v_pk_mul_f32 v[146:147], v[16:17], v[68:69]
	v_pk_mul_f32 v[174:175], v[16:17], v[76:77]
	v_pk_fma_f32 v[144:145], v[10:11], v[70:71], v[144:145]
	v_pk_fma_f32 v[148:149], v[10:11], v[78:79], v[148:149]
	v_pk_fma_f32 v[146:147], v[18:19], v[70:71], v[146:147]
	v_pk_fma_f32 v[174:175], v[18:19], v[78:79], v[174:175]
	v_pk_fma_f32 v[144:145], v[4:5], v[72:73], v[144:145]
	v_pk_fma_f32 v[148:149], v[4:5], v[80:81], v[148:149]
	v_pk_fma_f32 v[146:147], v[12:13], v[72:73], v[146:147]
	v_pk_fma_f32 v[174:175], v[12:13], v[80:81], v[174:175]
	v_pk_fma_f32 v[144:145], v[6:7], v[74:75], v[144:145]
	v_pk_fma_f32 v[148:149], v[6:7], v[82:83], v[148:149]
	v_pk_fma_f32 v[146:147], v[14:15], v[74:75], v[146:147]
	v_pk_fma_f32 v[174:175], v[14:15], v[82:83], v[174:175]
	ds_read_b128 v[68:71], v205 offset:19968
	ds_read_b128 v[72:75], v205 offset:19984
	ds_read_b128 v[76:79], v205 offset:20480
	ds_read_b128 v[80:83], v205 offset:20496
	ds_read_b128 v[104:107], v205 offset:20736
	ds_read_b128 v[108:111], v205 offset:20752
	ds_read_b128 v[120:123], v205 offset:20224
	ds_read_b128 v[124:127], v205 offset:20240
	v_pk_mul_f32 v[128:129], v[92:93], v[84:85] op_sel_hi:[0,1]
	v_pk_mul_f32 v[136:137], v[92:93], v[84:85] op_sel:[1,0]
	v_add_f32_e64 v144, v144, v145
	v_add_f32_e64 v148, v148, v149
	v_add_f32_e64 v145, v146, v147
	v_add_f32_e64 v149, v174, v175
	v_pk_mul_f32 v[130:131], v[92:93], v[86:87] op_sel_hi:[0,1]
	v_pk_mul_f32 v[138:139], v[92:93], v[86:87] op_sel:[1,0]
	v_add_f32_dpp v144, v144, v144 quad_perm:[1,0,3,2] row_mask:0xf bank_mask:0xf bound_ctrl:1
	v_add_f32_dpp v148, v148, v148 quad_perm:[1,0,3,2] row_mask:0xf bank_mask:0xf bound_ctrl:1
	v_add_f32_dpp v145, v145, v145 quad_perm:[1,0,3,2] row_mask:0xf bank_mask:0xf bound_ctrl:1
	v_add_f32_dpp v149, v149, v149 quad_perm:[1,0,3,2] row_mask:0xf bank_mask:0xf bound_ctrl:1
	v_pk_mul_f32 v[132:133], v[92:93], v[88:89] op_sel_hi:[0,1]
	v_pk_mul_f32 v[140:141], v[92:93], v[88:89] op_sel:[1,0]
	v_add_f32_dpp v144, v144, v144 quad_perm:[2,3,0,1] row_mask:0xf bank_mask:0xf bound_ctrl:1
	v_add_f32_dpp v148, v148, v148 quad_perm:[2,3,0,1] row_mask:0xf bank_mask:0xf bound_ctrl:1
	v_add_f32_dpp v145, v145, v145 quad_perm:[2,3,0,1] row_mask:0xf bank_mask:0xf bound_ctrl:1
	v_add_f32_dpp v149, v149, v149 quad_perm:[2,3,0,1] row_mask:0xf bank_mask:0xf bound_ctrl:1
	v_pk_mul_f32 v[134:135], v[92:93], v[90:91] op_sel_hi:[0,1]
	v_pk_mul_f32 v[142:143], v[92:93], v[90:91] op_sel:[1,0]
	v_add_f32_dpp v144, v144, v144 row_half_mirror row_mask:0xf bank_mask:0xf bound_ctrl:1
	v_add_f32_dpp v148, v148, v148 row_half_mirror row_mask:0xf bank_mask:0xf bound_ctrl:1
	v_add_f32_dpp v145, v145, v145 row_half_mirror row_mask:0xf bank_mask:0xf bound_ctrl:1
	v_add_f32_dpp v149, v149, v149 row_half_mirror row_mask:0xf bank_mask:0xf bound_ctrl:1
	v_pk_fma_f32 v[176:177], v[144:145], v[94:95], v[148:149] op_sel_hi:[1,0,1]
	v_pk_fma_f32 v[128:129], v[96:97], v[144:145], v[128:129] op_sel_hi:[1,0,1]
	v_pk_fma_f32 v[176:177], v[92:93], v[94:95], v[176:177] op_sel:[0,1,0]
	v_pk_fma_f32 v[136:137], v[96:97], v[144:145], v[136:137] op_sel:[0,1,0]
	ds_read_b128 v[84:87], v205 offset:20992
	ds_read_b128 v[88:91], v205 offset:21008
	ds_read_b64 v[92:93], v206 offset:21248
	ds_read_b64 v[94:95], v207 offset:49360
	ds_write_b64 v208, v[176:177] offset:3072
	v_pk_fma_f32 v[8:9], v[8:9], v[112:113], v[128:129]
	v_pk_fma_f32 v[16:17], v[16:17], v[112:113], v[136:137]
	v_pk_fma_f32 v[130:131], v[98:99], v[144:145], v[130:131] op_sel_hi:[1,0,1]
	v_pk_fma_f32 v[138:139], v[98:99], v[144:145], v[138:139] op_sel:[0,1,0]
	v_pk_fma_f32 v[10:11], v[10:11], v[114:115], v[130:131]
	v_pk_fma_f32 v[18:19], v[18:19], v[114:115], v[138:139]
	v_pk_fma_f32 v[132:133], v[100:101], v[144:145], v[132:133] op_sel_hi:[1,0,1]
	v_pk_fma_f32 v[140:141], v[100:101], v[144:145], v[140:141] op_sel:[0,1,0]
	v_pk_fma_f32 v[4:5], v[4:5], v[116:117], v[132:133]
	v_pk_fma_f32 v[12:13], v[12:13], v[116:117], v[140:141]
	v_pk_fma_f32 v[134:135], v[102:103], v[144:145], v[134:135] op_sel_hi:[1,0,1]
	v_pk_fma_f32 v[142:143], v[102:103], v[144:145], v[142:143] op_sel:[0,1,0]
	v_pk_fma_f32 v[6:7], v[6:7], v[118:119], v[134:135]
	v_pk_fma_f32 v[14:15], v[14:15], v[118:119], v[142:143]
	s_waitcnt lgkmcnt(0)
; __device__ __forceinline__ float red8(float v) { v = red4(v); v += dppf<0x141>(v); return v; }
; __device__ __forceinline__ f32x2 lo2(const f32x4& v) { return __builtin_shufflevector(v, v, 0, 1); }
; __device__ __forceinline__ f32x2 hi2(const f32x4& v) { return __builtin_shufflevector(v, v, 2, 3); }
; __device__ __forceinline__ f32x2 splat2(float x) { return (f32x2){x, x}; }
; __device__ __forceinline__ void rw_load(RwRegs& R, const float* vb, const float* sb, int t, int k0, int vrow0) {
;   const float* vt = vb + t * 384 + k0;
; #pragma unroll
;   for (int q = 0; q < 2; ++q) {
;     R.a[q] = *(const f32x4*)(vt + q * 4);
;     R.wr[q] = *(const f32x4*)(vt + 128 + q * 4);
;     R.w[q] = *(const f32x4*)(vt + 64 + q * 4);
;     R.b[q] = *(const f32x4*)(vt + 192 + q * 4);
;     R.k[q] = *(const f32x4*)(vt + 256 + q * 4);
;   }
;   R.v = *(const f32x2*)(vb + t * 384 + 320 + vrow0);
;   R.sc = *(const f32x4*)(sb + t * 4);
; }
; __device__ __forceinline__ f32x2 rw_step(f32x2 (&S)[2][4], const RwRegs& R) {
;   float sa[2], sy[2];
; #pragma unroll
;   for (int r = 0; r < 2; ++r) {
;     f32x2 a0 = S[r][0] * lo2(R.a[0]);
;     f32x2 a1 = S[r][1] * hi2(R.a[0]);
;     f32x2 y0 = S[r][0] * lo2(R.wr[0]);
;     f32x2 y1 = S[r][1] * hi2(R.wr[0]);
;     a0 += S[r][2] * lo2(R.a[1]);
;     a1 += S[r][3] * hi2(R.a[1]);
;     y0 += S[r][2] * lo2(R.wr[1]);
;     y1 += S[r][3] * hi2(R.wr[1]);
;     a0 += a1; y0 += y1;
;     sa[r] = a0.x + a0.y; sy[r] = y0.x + y0.y;
;   }
;   sa[0] = red8(sa[0]); sa[1] = red8(sa[1]); sy[0] = red8(sy[0]); sy[1] = red8(sy[1]);
;   f32x2 yv;
; #pragma unroll
;   for (int r = 0; r < 2; ++r) {
;     const float vr = r ? R.v.y : R.v.x;
;     const f32x2 sa2 = splat2(sa[r]), vv2 = splat2(vr);
;     S[r][0] = S[r][0] * lo2(R.w[0]) + (sa2 * lo2(R.b[0]) + vv2 * lo2(R.k[0]));
;     S[r][1] = S[r][1] * hi2(R.w[0]) + (sa2 * hi2(R.b[0]) + vv2 * hi2(R.k[0]));
;     S[r][2] = S[r][2] * lo2(R.w[1]) + (sa2 * lo2(R.b[1]) + vv2 * lo2(R.k[1]));
;     S[r][3] = S[r][3] * hi2(R.w[1]) + (sa2 * hi2(R.b[1]) + vv2 * hi2(R.k[1]));
;     const float y = sy[r] + sa[r] * R.sc.x + vr * R.sc.y;
;     if (r) yv.y = y; else yv.x = y;
;   }
;   return yv;
; }
	s_nop 0
	v_pk_mul_f32 v[144:145], v[8:9], v[68:69]
	v_pk_mul_f32 v[148:149], v[8:9], v[76:77]
	v_pk_mul_f32 v[146:147], v[16:17], v[68:69]
	v_pk_mul_f32 v[174:175], v[16:17], v[76:77]
	v_pk_fma_f32 v[144:145], v[10:11], v[70:71], v[144:145]
	v_pk_fma_f32 v[148:149], v[10:11], v[78:79], v[148:149]
	v_pk_fma_f32 v[146:147], v[18:19], v[70:71], v[146:147]
	v_pk_fma_f32 v[174:175], v[18:19], v[78:79], v[174:175]
	v_pk_fma_f32 v[144:145], v[4:5], v[72:73], v[144:145]
	v_pk_fma_f32 v[148:149], v[4:5], v[80:81], v[148:149]
	v_pk_fma_f32 v[146:147], v[12:13], v[72:73], v[146:147]
	v_pk_fma_f32 v[174:175], v[12:13], v[80:81], v[174:175]
	v_pk_fma_f32 v[144:145], v[6:7], v[74:75], v[144:145]
	v_pk_fma_f32 v[148:149], v[6:7], v[82:83], v[148:149]
	v_pk_fma_f32 v[146:147], v[14:15], v[74:75], v[146:147]
	v_pk_fma_f32 v[174:175], v[14:15], v[82:83], v[174:175]
	ds_read_b128 v[68:71], v205 offset:21504
	ds_read_b128 v[72:75], v205 offset:21520
	ds_read_b128 v[76:79], v205 offset:22016
	ds_read_b128 v[80:83], v205 offset:22032
	ds_read_b128 v[96:99], v205 offset:22272
	ds_read_b128 v[100:103], v205 offset:22288
	ds_read_b128 v[112:115], v205 offset:21760
	ds_read_b128 v[116:119], v205 offset:21776
	v_pk_mul_f32 v[128:129], v[92:93], v[84:85] op_sel_hi:[0,1]
	v_pk_mul_f32 v[136:137], v[92:93], v[84:85] op_sel:[1,0]
	v_add_f32_e64 v144, v144, v145
	v_add_f32_e64 v148, v148, v149
	v_add_f32_e64 v145, v146, v147
	v_add_f32_e64 v149, v174, v175
	v_pk_mul_f32 v[130:131], v[92:93], v[86:87] op_sel_hi:[0,1]
	v_pk_mul_f32 v[138:139], v[92:93], v[86:87] op_sel:[1,0]
	v_add_f32_dpp v144, v144, v144 quad_perm:[1,0,3,2] row_mask:0xf bank_mask:0xf bound_ctrl:1
	v_add_f32_dpp v148, v148, v148 quad_perm:[1,0,3,2] row_mask:0xf bank_mask:0xf bound_ctrl:1
	v_add_f32_dpp v145, v145, v145 quad_perm:[1,0,3,2] row_mask:0xf bank_mask:0xf bound_ctrl:1
	v_add_f32_dpp v149, v149, v149 quad_perm:[1,0,3,2] row_mask:0xf bank_mask:0xf bound_ctrl:1
	v_pk_mul_f32 v[132:133], v[92:93], v[88:89] op_sel_hi:[0,1]
	v_pk_mul_f32 v[140:141], v[92:93], v[88:89] op_sel:[1,0]
	v_add_f32_dpp v144, v144, v144 quad_perm:[2,3,0,1] row_mask:0xf bank_mask:0xf bound_ctrl:1
	v_add_f32_dpp v148, v148, v148 quad_perm:[2,3,0,1] row_mask:0xf bank_mask:0xf bound_ctrl:1
	v_add_f32_dpp v145, v145, v145 quad_perm:[2,3,0,1] row_mask:0xf bank_mask:0xf bound_ctrl:1
	v_add_f32_dpp v149, v149, v149 quad_perm:[2,3,0,1] row_mask:0xf bank_mask:0xf bound_ctrl:1
	v_pk_mul_f32 v[134:135], v[92:93], v[90:91] op_sel_hi:[0,1]
	v_pk_mul_f32 v[142:143], v[92:93], v[90:91] op_sel:[1,0]
	v_add_f32_dpp v144, v144, v144 row_half_mirror row_mask:0xf bank_mask:0xf bound_ctrl:1
	v_add_f32_dpp v148, v148, v148 row_half_mirror row_mask:0xf bank_mask:0xf bound_ctrl:1
	v_add_f32_dpp v145, v145, v145 row_half_mirror row_mask:0xf bank_mask:0xf bound_ctrl:1
	v_add_f32_dpp v149, v149, v149 row_half_mirror row_mask:0xf bank_mask:0xf bound_ctrl:1
	v_pk_fma_f32 v[176:177], v[144:145], v[94:95], v[148:149] op_sel_hi:[1,0,1]
	v_pk_fma_f32 v[128:129], v[104:105], v[144:145], v[128:129] op_sel_hi:[1,0,1]
	v_pk_fma_f32 v[176:177], v[92:93], v[94:95], v[176:177] op_sel:[0,1,0]
	v_pk_fma_f32 v[136:137], v[104:105], v[144:145], v[136:137] op_sel:[0,1,0]
	ds_read_b128 v[84:87], v205 offset:22528
	ds_read_b128 v[88:91], v205 offset:22544
	ds_read_b64 v[92:93], v206 offset:22784
	ds_read_b64 v[94:95], v207 offset:49376
	ds_write_b64 v208, v[176:177] offset:3328
	v_pk_fma_f32 v[8:9], v[8:9], v[120:121], v[128:129]
	v_pk_fma_f32 v[16:17], v[16:17], v[120:121], v[136:137]
	v_pk_fma_f32 v[130:131], v[106:107], v[144:145], v[130:131] op_sel_hi:[1,0,1]
	v_pk_fma_f32 v[138:139], v[106:107], v[144:145], v[138:139] op_sel:[0,1,0]
	v_pk_fma_f32 v[10:11], v[10:11], v[122:123], v[130:131]
	v_pk_fma_f32 v[18:19], v[18:19], v[122:123], v[138:139]
	v_pk_fma_f32 v[132:133], v[108:109], v[144:145], v[132:133] op_sel_hi:[1,0,1]
	v_pk_fma_f32 v[140:141], v[108:109], v[144:145], v[140:141] op_sel:[0,1,0]
	v_pk_fma_f32 v[4:5], v[4:5], v[124:125], v[132:133]
	v_pk_fma_f32 v[12:13], v[12:13], v[124:125], v[140:141]
	v_pk_fma_f32 v[134:135], v[110:111], v[144:145], v[134:135] op_sel_hi:[1,0,1]
	v_pk_fma_f32 v[142:143], v[110:111], v[144:145], v[142:143] op_sel:[0,1,0]
	v_pk_fma_f32 v[6:7], v[6:7], v[126:127], v[134:135]
	v_pk_fma_f32 v[14:15], v[14:15], v[126:127], v[142:143]
	s_waitcnt lgkmcnt(0)
; __device__ __forceinline__ float red8(float v) { v = red4(v); v += dppf<0x141>(v); return v; }
; __device__ __forceinline__ f32x2 lo2(const f32x4& v) { return __builtin_shufflevector(v, v, 0, 1); }
; __device__ __forceinline__ f32x2 hi2(const f32x4& v) { return __builtin_shufflevector(v, v, 2, 3); }
; __device__ __forceinline__ f32x2 splat2(float x) { return (f32x2){x, x}; }
; __device__ __forceinline__ void rw_load(RwRegs& R, const float* vb, const float* sb, int t, int k0, int vrow0) {
;   const float* vt = vb + t * 384 + k0;
; #pragma unroll
;   for (int q = 0; q < 2; ++q) {
;     R.a[q] = *(const f32x4*)(vt + q * 4);
;     R.wr[q] = *(const f32x4*)(vt + 128 + q * 4);
;     R.w[q] = *(const f32x4*)(vt + 64 + q * 4);
;     R.b[q] = *(const f32x4*)(vt + 192 + q * 4);
;     R.k[q] = *(const f32x4*)(vt + 256 + q * 4);
;   }
;   R.v = *(const f32x2*)(vb + t * 384 + 320 + vrow0);
;   R.sc = *(const f32x4*)(sb + t * 4);
; }
; __device__ __forceinline__ f32x2 rw_step(f32x2 (&S)[2][4], const RwRegs& R) {
;   float sa[2], sy[2];
; #pragma unroll
;   for (int r = 0; r < 2; ++r) {
;     f32x2 a0 = S[r][0] * lo2(R.a[0]);
;     f32x2 a1 = S[r][1] * hi2(R.a[0]);
;     f32x2 y0 = S[r][0] * lo2(R.wr[0]);
;     f32x2 y1 = S[r][1] * hi2(R.wr[0]);
;     a0 += S[r][2] * lo2(R.a[1]);
;     a1 += S[r][3] * hi2(R.a[1]);
;     y0 += S[r][2] * lo2(R.wr[1]);
;     y1 += S[r][3] * hi2(R.wr[1]);
;     a0 += a1; y0 += y1;
;     sa[r] = a0.x + a0.y; sy[r] = y0.x + y0.y;
;   }
;   sa[0] = red8(sa[0]); sa[1] = red8(sa[1]); sy[0] = red8(sy[0]); sy[1] = red8(sy[1]);
;   f32x2 yv;
; #pragma unroll
;   for (int r = 0; r < 2; ++r) {
;     const float vr = r ? R.v.y : R.v.x;
;     const f32x2 sa2 = splat2(sa[r]), vv2 = splat2(vr);
;     S[r][0] = S[r][0] * lo2(R.w[0]) + (sa2 * lo2(R.b[0]) + vv2 * lo2(R.k[0]));
;     S[r][1] = S[r][1] * hi2(R.w[0]) + (sa2 * hi2(R.b[0]) + vv2 * hi2(R.k[0]));
;     S[r][2] = S[r][2] * lo2(R.w[1]) + (sa2 * lo2(R.b[1]) + vv2 * lo2(R.k[1]));
;     S[r][3] = S[r][3] * hi2(R.w[1]) + (sa2 * hi2(R.b[1]) + vv2 * hi2(R.k[1]));
;     const float y = sy[r] + sa[r] * R.sc.x + vr * R.sc.y;
;     if (r) yv.y = y; else yv.x = y;
;   }
;   return yv;
; }
	s_nop 0
	v_pk_mul_f32 v[144:145], v[8:9], v[68:69]
	v_pk_mul_f32 v[148:149], v[8:9], v[76:77]
	v_pk_mul_f32 v[146:147], v[16:17], v[68:69]
	v_pk_mul_f32 v[174:175], v[16:17], v[76:77]
	v_pk_fma_f32 v[144:145], v[10:11], v[70:71], v[144:145]
	v_pk_fma_f32 v[148:149], v[10:11], v[78:79], v[148:149]
	v_pk_fma_f32 v[146:147], v[18:19], v[70:71], v[146:147]
	v_pk_fma_f32 v[174:175], v[18:19], v[78:79], v[174:175]
	v_pk_fma_f32 v[144:145], v[4:5], v[72:73], v[144:145]
	v_pk_fma_f32 v[148:149], v[4:5], v[80:81], v[148:149]
	v_pk_fma_f32 v[146:147], v[12:13], v[72:73], v[146:147]
	v_pk_fma_f32 v[174:175], v[12:13], v[80:81], v[174:175]
	v_pk_fma_f32 v[144:145], v[6:7], v[74:75], v[144:145]
	v_pk_fma_f32 v[148:149], v[6:7], v[82:83], v[148:149]
	v_pk_fma_f32 v[146:147], v[14:15], v[74:75], v[146:147]
	v_pk_fma_f32 v[174:175], v[14:15], v[82:83], v[174:175]
	ds_read_b128 v[68:71], v205 offset:23040
	ds_read_b128 v[72:75], v205 offset:23056
	ds_read_b128 v[76:79], v205 offset:23552
	ds_read_b128 v[80:83], v205 offset:23568
	ds_read_b128 v[104:107], v205 offset:23808
	ds_read_b128 v[108:111], v205 offset:23824
	ds_read_b128 v[120:123], v205 offset:23296
	ds_read_b128 v[124:127], v205 offset:23312
	v_pk_mul_f32 v[128:129], v[92:93], v[84:85] op_sel_hi:[0,1]
	v_pk_mul_f32 v[136:137], v[92:93], v[84:85] op_sel:[1,0]
	v_add_f32_e64 v144, v144, v145
	v_add_f32_e64 v148, v148, v149
	v_add_f32_e64 v145, v146, v147
	v_add_f32_e64 v149, v174, v175
	v_pk_mul_f32 v[130:131], v[92:93], v[86:87] op_sel_hi:[0,1]
	v_pk_mul_f32 v[138:139], v[92:93], v[86:87] op_sel:[1,0]
	v_add_f32_dpp v144, v144, v144 quad_perm:[1,0,3,2] row_mask:0xf bank_mask:0xf bound_ctrl:1
	v_add_f32_dpp v148, v148, v148 quad_perm:[1,0,3,2] row_mask:0xf bank_mask:0xf bound_ctrl:1
	v_add_f32_dpp v145, v145, v145 quad_perm:[1,0,3,2] row_mask:0xf bank_mask:0xf bound_ctrl:1
	v_add_f32_dpp v149, v149, v149 quad_perm:[1,0,3,2] row_mask:0xf bank_mask:0xf bound_ctrl:1
	v_pk_mul_f32 v[132:133], v[92:93], v[88:89] op_sel_hi:[0,1]
	v_pk_mul_f32 v[140:141], v[92:93], v[88:89] op_sel:[1,0]
	v_add_f32_dpp v144, v144, v144 quad_perm:[2,3,0,1] row_mask:0xf bank_mask:0xf bound_ctrl:1
	v_add_f32_dpp v148, v148, v148 quad_perm:[2,3,0,1] row_mask:0xf bank_mask:0xf bound_ctrl:1
	v_add_f32_dpp v145, v145, v145 quad_perm:[2,3,0,1] row_mask:0xf bank_mask:0xf bound_ctrl:1
	v_add_f32_dpp v149, v149, v149 quad_perm:[2,3,0,1] row_mask:0xf bank_mask:0xf bound_ctrl:1
	v_pk_mul_f32 v[134:135], v[92:93], v[90:91] op_sel_hi:[0,1]
	v_pk_mul_f32 v[142:143], v[92:93], v[90:91] op_sel:[1,0]
	v_add_f32_dpp v144, v144, v144 row_half_mirror row_mask:0xf bank_mask:0xf bound_ctrl:1
	v_add_f32_dpp v148, v148, v148 row_half_mirror row_mask:0xf bank_mask:0xf bound_ctrl:1
	v_add_f32_dpp v145, v145, v145 row_half_mirror row_mask:0xf bank_mask:0xf bound_ctrl:1
	v_add_f32_dpp v149, v149, v149 row_half_mirror row_mask:0xf bank_mask:0xf bound_ctrl:1
	v_pk_fma_f32 v[176:177], v[144:145], v[94:95], v[148:149] op_sel_hi:[1,0,1]
	v_pk_fma_f32 v[128:129], v[96:97], v[144:145], v[128:129] op_sel_hi:[1,0,1]
	v_pk_fma_f32 v[176:177], v[92:93], v[94:95], v[176:177] op_sel:[0,1,0]
	v_pk_fma_f32 v[136:137], v[96:97], v[144:145], v[136:137] op_sel:[0,1,0]
	ds_read_b128 v[84:87], v205 offset:24064
	ds_read_b128 v[88:91], v205 offset:24080
	ds_read_b64 v[92:93], v206 offset:24320
	ds_read_b64 v[94:95], v207 offset:49392
	ds_write_b64 v208, v[176:177] offset:3584
	v_pk_fma_f32 v[8:9], v[8:9], v[112:113], v[128:129]
	v_pk_fma_f32 v[16:17], v[16:17], v[112:113], v[136:137]
	v_pk_fma_f32 v[130:131], v[98:99], v[144:145], v[130:131] op_sel_hi:[1,0,1]
	v_pk_fma_f32 v[138:139], v[98:99], v[144:145], v[138:139] op_sel:[0,1,0]
	v_pk_fma_f32 v[10:11], v[10:11], v[114:115], v[130:131]
	v_pk_fma_f32 v[18:19], v[18:19], v[114:115], v[138:139]
	v_pk_fma_f32 v[132:133], v[100:101], v[144:145], v[132:133] op_sel_hi:[1,0,1]
	v_pk_fma_f32 v[140:141], v[100:101], v[144:145], v[140:141] op_sel:[0,1,0]
	v_pk_fma_f32 v[4:5], v[4:5], v[116:117], v[132:133]
	v_pk_fma_f32 v[12:13], v[12:13], v[116:117], v[140:141]
	v_pk_fma_f32 v[134:135], v[102:103], v[144:145], v[134:135] op_sel_hi:[1,0,1]
	v_pk_fma_f32 v[142:143], v[102:103], v[144:145], v[142:143] op_sel:[0,1,0]
	v_pk_fma_f32 v[6:7], v[6:7], v[118:119], v[134:135]
	v_pk_fma_f32 v[14:15], v[14:15], v[118:119], v[142:143]
	s_waitcnt lgkmcnt(0)
; __device__ __forceinline__ void rw_load(RwRegs& R, const float* vb, const float* sb, int t, int k0, int vrow0) {
;   const float* vt = vb + t * 384 + k0;
; #pragma unroll
;   for (int q = 0; q < 2; ++q) {
;     R.a[q] = *(const f32x4*)(vt + q * 4);
;     R.wr[q] = *(const f32x4*)(vt + 128 + q * 4);
;     R.w[q] = *(const f32x4*)(vt + 64 + q * 4);
;     R.b[q] = *(const f32x4*)(vt + 192 + q * 4);
;     R.k[q] = *(const f32x4*)(vt + 256 + q * 4);
;   }
;   R.v = *(const f32x2*)(vb + t * 384 + 320 + vrow0);
;   R.sc = *(const f32x4*)(sb + t * 4);
; }
; __device__ __forceinline__ f32x2 rw_step(f32x2 (&S)[2][4], const RwRegs& R) {
;   float sa[2], sy[2];
; #pragma unroll
;   for (int r = 0; r < 2; ++r) {
;     f32x2 a0 = S[r][0] * lo2(R.a[0]);
;     f32x2 a1 = S[r][1] * hi2(R.a[0]);
;     f32x2 y0 = S[r][0] * lo2(R.wr[0]);
;     f32x2 y1 = S[r][1] * hi2(R.wr[0]);
;     a0 += S[r][2] * lo2(R.a[1]);
;     a1 += S[r][3] * hi2(R.a[1]);
;     y0 += S[r][2] * lo2(R.wr[1]);
;     y1 += S[r][3] * hi2(R.wr[1]);
;     a0 += a1; y0 += y1;
;     sa[r] = a0.x + a0.y; sy[r] = y0.x + y0.y;
;   }
;   sa[0] = red8(sa[0]); sa[1] = red8(sa[1]); sy[0] = red8(sy[0]); sy[1] = red8(sy[1]);
;   f32x2 yv;
; #pragma unroll
;   for (int r = 0; r < 2; ++r) {
;     const float vr = r ? R.v.y : R.v.x;
;     const f32x2 sa2 = splat2(sa[r]), vv2 = splat2(vr);
;     S[r][0] = S[r][0] * lo2(R.w[0]) + (sa2 * lo2(R.b[0]) + vv2 * lo2(R.k[0]));
;     S[r][1] = S[r][1] * hi2(R.w[0]) + (sa2 * hi2(R.b[0]) + vv2 * hi2(R.k[0]));
;     S[r][2] = S[r][2] * lo2(R.w[1]) + (sa2 * lo2(R.b[1]) + vv2 * lo2(R.k[1]));
;     S[r][3] = S[r][3] * hi2(R.w[1]) + (sa2 * hi2(R.b[1]) + vv2 * hi2(R.k[1]));
;     const float y = sy[r] + sa[r] * R.sc.x + vr * R.sc.y;
;     if (r) yv.y = y; else yv.x = y;
;   }
;   return yv;
; }
; __device__ __forceinline__ void scan_rwkv(const Params& p, int l, int seq, int h, char* smem, const unsigned* wflags, unsigned wexpect) {
;     ...
;     for (int t = 0; t < nsteps; t += 2) {
;       rw_load(RB, vb, sb, min(t + 1, 15), k0, vrow0);
;       const f32x2 y0v = rw_step(S, RA);
;       *(f32x2*)((part == 0) ? (yb + t * 64 + vrow0) : ydummy) = y0v;
;       SCAN_INTERLEAVE(13, 4);
;       if (t + 1 < nsteps) {
;         rw_load(RA, vb, sb, min(t + 2, 15), k0, vrow0);
;         const f32x2 y1v = rw_step(S, RB);
;         *(f32x2*)((part == 0) ? (yb + (t + 1) * 64 + vrow0) : ydummy) = y1v;
	s_nop 0
	v_pk_mul_f32 v[144:145], v[8:9], v[68:69]
	v_pk_mul_f32 v[148:149], v[8:9], v[76:77]
	v_pk_mul_f32 v[146:147], v[16:17], v[68:69]
	v_pk_mul_f32 v[174:175], v[16:17], v[76:77]
	v_pk_fma_f32 v[144:145], v[10:11], v[70:71], v[144:145]
	v_pk_fma_f32 v[148:149], v[10:11], v[78:79], v[148:149]
	v_pk_fma_f32 v[146:147], v[18:19], v[70:71], v[146:147]
	v_pk_fma_f32 v[174:175], v[18:19], v[78:79], v[174:175]
	v_pk_fma_f32 v[144:145], v[4:5], v[72:73], v[144:145]
	v_pk_fma_f32 v[148:149], v[4:5], v[80:81], v[148:149]
	v_pk_fma_f32 v[146:147], v[12:13], v[72:73], v[146:147]
	v_pk_fma_f32 v[174:175], v[12:13], v[80:81], v[174:175]
	v_pk_fma_f32 v[144:145], v[6:7], v[74:75], v[144:145]
	v_pk_fma_f32 v[148:149], v[6:7], v[82:83], v[148:149]
	v_pk_fma_f32 v[146:147], v[14:15], v[74:75], v[146:147]
	v_pk_fma_f32 v[174:175], v[14:15], v[82:83], v[174:175]
	ds_read_b128 v[68:71], v205 offset:24576
	ds_read_b128 v[72:75], v205 offset:24592
	ds_read_b128 v[76:79], v205 offset:25088
	ds_read_b128 v[80:83], v205 offset:25104
	ds_read_b128 v[96:99], v205 offset:25344
	ds_read_b128 v[100:103], v205 offset:25360
	ds_read_b128 v[112:115], v205 offset:24832
	ds_read_b128 v[116:119], v205 offset:24848
	v_pk_mul_f32 v[128:129], v[92:93], v[84:85] op_sel_hi:[0,1]
	v_pk_mul_f32 v[136:137], v[92:93], v[84:85] op_sel:[1,0]
	v_add_f32_e64 v144, v144, v145
	v_add_f32_e64 v148, v148, v149
	v_add_f32_e64 v145, v146, v147
	v_add_f32_e64 v149, v174, v175
	v_pk_mul_f32 v[130:131], v[92:93], v[86:87] op_sel_hi:[0,1]
	v_pk_mul_f32 v[138:139], v[92:93], v[86:87] op_sel:[1,0]
	v_add_f32_dpp v144, v144, v144 quad_perm:[1,0,3,2] row_mask:0xf bank_mask:0xf bound_ctrl:1
	v_add_f32_dpp v148, v148, v148 quad_perm:[1,0,3,2] row_mask:0xf bank_mask:0xf bound_ctrl:1
	v_add_f32_dpp v145, v145, v145 quad_perm:[1,0,3,2] row_mask:0xf bank_mask:0xf bound_ctrl:1
	v_add_f32_dpp v149, v149, v149 quad_perm:[1,0,3,2] row_mask:0xf bank_mask:0xf bound_ctrl:1
	v_pk_mul_f32 v[132:133], v[92:93], v[88:89] op_sel_hi:[0,1]
	v_pk_mul_f32 v[140:141], v[92:93], v[88:89] op_sel:[1,0]
	v_add_f32_dpp v144, v144, v144 quad_perm:[2,3,0,1] row_mask:0xf bank_mask:0xf bound_ctrl:1
	v_add_f32_dpp v148, v148, v148 quad_perm:[2,3,0,1] row_mask:0xf bank_mask:0xf bound_ctrl:1
	v_add_f32_dpp v145, v145, v145 quad_perm:[2,3,0,1] row_mask:0xf bank_mask:0xf bound_ctrl:1
	v_add_f32_dpp v149, v149, v149 quad_perm:[2,3,0,1] row_mask:0xf bank_mask:0xf bound_ctrl:1
	v_pk_mul_f32 v[134:135], v[92:93], v[90:91] op_sel_hi:[0,1]
	v_pk_mul_f32 v[142:143], v[92:93], v[90:91] op_sel:[1,0]
	v_add_f32_dpp v144, v144, v144 row_half_mirror row_mask:0xf bank_mask:0xf bound_ctrl:1
	v_add_f32_dpp v148, v148, v148 row_half_mirror row_mask:0xf bank_mask:0xf bound_ctrl:1
	v_add_f32_dpp v145, v145, v145 row_half_mirror row_mask:0xf bank_mask:0xf bound_ctrl:1
	v_add_f32_dpp v149, v149, v149 row_half_mirror row_mask:0xf bank_mask:0xf bound_ctrl:1
	v_pk_fma_f32 v[176:177], v[144:145], v[94:95], v[148:149] op_sel_hi:[1,0,1]
	v_pk_fma_f32 v[128:129], v[104:105], v[144:145], v[128:129] op_sel_hi:[1,0,1]
	v_pk_fma_f32 v[176:177], v[92:93], v[94:95], v[176:177] op_sel:[0,1,0]
	v_pk_fma_f32 v[136:137], v[104:105], v[144:145], v[136:137] op_sel:[0,1,0]
	ds_read_b128 v[84:87], v205 offset:25600
	ds_read_b128 v[88:91], v205 offset:25616
	ds_read_b64 v[92:93], v206 offset:25856
	ds_read_b64 v[94:95], v207 offset:49408
	ds_write_b64 v208, v[176:177] offset:3840
	v_pk_fma_f32 v[8:9], v[8:9], v[120:121], v[128:129]
	v_pk_fma_f32 v[16:17], v[16:17], v[120:121], v[136:137]
	v_pk_fma_f32 v[130:131], v[106:107], v[144:145], v[130:131] op_sel_hi:[1,0,1]
	v_pk_fma_f32 v[138:139], v[106:107], v[144:145], v[138:139] op_sel:[0,1,0]
	v_pk_fma_f32 v[10:11], v[10:11], v[122:123], v[130:131]
	v_pk_fma_f32 v[18:19], v[18:19], v[122:123], v[138:139]
	v_pk_fma_f32 v[132:133], v[108:109], v[144:145], v[132:133] op_sel_hi:[1,0,1]
	v_pk_fma_f32 v[140:141], v[108:109], v[144:145], v[140:141] op_sel:[0,1,0]
	v_pk_fma_f32 v[4:5], v[4:5], v[124:125], v[132:133]
	v_pk_fma_f32 v[12:13], v[12:13], v[124:125], v[140:141]
	v_pk_fma_f32 v[134:135], v[110:111], v[144:145], v[134:135] op_sel_hi:[1,0,1]
	v_pk_fma_f32 v[142:143], v[110:111], v[144:145], v[142:143] op_sel:[0,1,0]
	v_pk_fma_f32 v[6:7], v[6:7], v[126:127], v[134:135]
	v_pk_fma_f32 v[14:15], v[14:15], v[126:127], v[142:143]
	s_cmp_eq_u32 s39, 0
	s_cbranch_scc1 .LBB0_283
	s_branch .LBB0_301
	.p2align 3
; __device__ __forceinline__ float red8(float v) { v = red4(v); v += dppf<0x141>(v); return v; }
; __device__ __forceinline__ f32x2 lo2(const f32x4& v) { return __builtin_shufflevector(v, v, 0, 1); }
; __device__ __forceinline__ f32x2 hi2(const f32x4& v) { return __builtin_shufflevector(v, v, 2, 3); }
; __device__ __forceinline__ f32x2 splat2(float x) { return (f32x2){x, x}; }
; __device__ __forceinline__ void ss_load(SsRegs& R, const float* vb, const float* sb, int t, int n0, int prow0) {
;   const float* vt = vb + t * 320;
; #pragma unroll
;   for (int q = 0; q < 4; ++q) {
;     R.B[q] = *(const f32x4*)(vt + n0 + q * 4);
;     R.C[q] = *(const f32x4*)(vt + 128 + n0 + q * 4);
;   }
;   R.x = *(const f32x2*)(vt + 256 + prow0);
;   R.sc = *(const f32x2*)(sb + t * 2);
; }
; __device__ __forceinline__ f32x2 ss_step(f32x2 (&S)[2][8], const SsRegs& R) {
;   const f32x2 dA2 = splat2(R.sc.y);
;   f32x2 out;
; #pragma unroll
;   for (int r = 0; r < 2; ++r) {
;     const f32x2 xdt2 = splat2((r ? R.x.y : R.x.x) * R.sc.x);
;     f32x2 y0 = splat2(0.f), y1 = splat2(0.f);
; #pragma unroll
;     for (int q = 0; q < 4; ++q) {
;       S[r][2 * q] = S[r][2 * q] * dA2 + xdt2 * lo2(R.B[q]);
;       S[r][2 * q + 1] = S[r][2 * q + 1] * dA2 + xdt2 * hi2(R.B[q]);
;       y0 += S[r][2 * q] * lo2(R.C[q]);
;       y1 += S[r][2 * q + 1] * hi2(R.C[q]);
;     }
;     y0 += y1;
;     const float y = red8(y0.x + y0.y);
;     if (r) out.y = y; else out.x = y;
;   }
;   return out;
; }
.Lssf_body:
	s_mov_b32 exec_lo, 0xf0f0f0f0
	s_mov_b32 exec_hi, 0xf0f0f0f0
	v_swap_b32 v28, v12
	v_swap_b32 v29, v13
	v_swap_b32 v30, v14
	v_swap_b32 v31, v15
	v_swap_b32 v8, v4
	v_swap_b32 v9, v5
	v_swap_b32 v10, v6
	v_swap_b32 v11, v7
	v_swap_b32 v24, v32
	v_swap_b32 v25, v33
	v_swap_b32 v26, v34
	v_swap_b32 v27, v35
	v_swap_b32 v20, v16
	v_swap_b32 v21, v17
	v_swap_b32 v22, v18
	v_swap_b32 v23, v19
	s_mov_b64 exec, -1
	s_nop 0
	ds_read_b64 v[108:109], v152 offset:1024
	ds_read_b64 v[110:111], v153 offset:40960
	ds_read_b128 v[60:63], v150 offset:0
	ds_read_b128 v[84:87], v150 offset:512
	ds_read_b128 v[64:67], v151 offset:16
	ds_read_b128 v[88:91], v151 offset:528
	ds_read_b128 v[68:71], v150 offset:32
	ds_read_b128 v[92:95], v150 offset:544
	ds_read_b128 v[76:79], v151 offset:48
	ds_read_b128 v[100:103], v151 offset:560
	s_waitcnt lgkmcnt(0)
	s_nop 0
	ds_read_b64 v[112:113], v152 offset:2304
	ds_read_b64 v[114:115], v153 offset:40968
	ds_read_b128 v[72:75], v150 offset:1312
	ds_read_b128 v[96:99], v150 offset:1824
	ds_read_b128 v[80:83], v151 offset:1328
	ds_read_b128 v[104:107], v151 offset:1840
	v_pk_mul_f32 v[156:157], v[108:109], v[110:111] op_sel_hi:[1,0]
	v_pk_mul_f32 v[116:117], v[156:157], v[60:61] op_sel_hi:[0,1]
	v_pk_mul_f32 v[118:119], v[156:157], v[60:61] op_sel:[1,0]
	v_pk_fma_f32 v[28:29], v[28:29], v[110:111], v[116:117] op_sel:[0,1,0]
	v_pk_fma_f32 v[24:25], v[24:25], v[110:111], v[118:119] op_sel:[0,1,0]
	v_pk_mul_f32 v[188:189], v[28:29], v[84:85]
	v_pk_mul_f32 v[190:191], v[24:25], v[84:85]
	v_pk_mul_f32 v[120:121], v[156:157], v[62:63] op_sel_hi:[0,1]
	v_pk_mul_f32 v[122:123], v[156:157], v[62:63] op_sel:[1,0]
	v_pk_fma_f32 v[30:31], v[30:31], v[110:111], v[120:121] op_sel:[0,1,0]
	v_pk_fma_f32 v[26:27], v[26:27], v[110:111], v[122:123] op_sel:[0,1,0]
	v_pk_fma_f32 v[188:189], v[30:31], v[86:87], v[188:189]
	v_pk_fma_f32 v[190:191], v[26:27], v[86:87], v[190:191]
	v_pk_mul_f32 v[116:117], v[156:157], v[64:65] op_sel_hi:[0,1]
	v_pk_mul_f32 v[118:119], v[156:157], v[64:65] op_sel:[1,0]
	v_pk_fma_f32 v[12:13], v[12:13], v[110:111], v[116:117] op_sel:[0,1,0]
	v_pk_fma_f32 v[32:33], v[32:33], v[110:111], v[118:119] op_sel:[0,1,0]
	v_pk_fma_f32 v[188:189], v[12:13], v[88:89], v[188:189]
	v_pk_fma_f32 v[190:191], v[32:33], v[88:89], v[190:191]
	v_pk_mul_f32 v[120:121], v[156:157], v[66:67] op_sel_hi:[0,1]
	v_pk_mul_f32 v[122:123], v[156:157], v[66:67] op_sel:[1,0]
	v_pk_fma_f32 v[14:15], v[14:15], v[110:111], v[120:121] op_sel:[0,1,0]
	v_pk_fma_f32 v[34:35], v[34:35], v[110:111], v[122:123] op_sel:[0,1,0]
	v_pk_fma_f32 v[188:189], v[14:15], v[90:91], v[188:189]
	v_pk_fma_f32 v[190:191], v[34:35], v[90:91], v[190:191]
	ds_read_b128 v[60:63], v150 offset:1280
	ds_read_b128 v[84:87], v150 offset:1792
	ds_read_b128 v[64:67], v151 offset:1296
	ds_read_b128 v[88:91], v151 offset:1808
	v_pk_mul_f32 v[116:117], v[156:157], v[68:69] op_sel_hi:[0,1]
	v_pk_mul_f32 v[118:119], v[156:157], v[68:69] op_sel:[1,0]
	v_pk_fma_f32 v[8:9], v[8:9], v[110:111], v[116:117] op_sel:[0,1,0]
	v_pk_fma_f32 v[20:21], v[20:21], v[110:111], v[118:119] op_sel:[0,1,0]
	v_pk_fma_f32 v[188:189], v[8:9], v[92:93], v[188:189]
	v_pk_fma_f32 v[190:191], v[20:21], v[92:93], v[190:191]
	v_pk_mul_f32 v[120:121], v[156:157], v[70:71] op_sel_hi:[0,1]
	v_pk_mul_f32 v[122:123], v[156:157], v[70:71] op_sel:[1,0]
	v_pk_fma_f32 v[10:11], v[10:11], v[110:111], v[120:121] op_sel:[0,1,0]
	v_pk_fma_f32 v[22:23], v[22:23], v[110:111], v[122:123] op_sel:[0,1,0]
	v_pk_fma_f32 v[188:189], v[10:11], v[94:95], v[188:189]
	v_pk_fma_f32 v[190:191], v[22:23], v[94:95], v[190:191]
	v_pk_mul_f32 v[116:117], v[156:157], v[76:77] op_sel_hi:[0,1]
	v_pk_mul_f32 v[118:119], v[156:157], v[76:77] op_sel:[1,0]
	v_pk_fma_f32 v[4:5], v[4:5], v[110:111], v[116:117] op_sel:[0,1,0]
	v_pk_fma_f32 v[16:17], v[16:17], v[110:111], v[118:119] op_sel:[0,1,0]
	v_pk_fma_f32 v[188:189], v[4:5], v[100:101], v[188:189]
	v_pk_fma_f32 v[190:191], v[16:17], v[100:101], v[190:191]
	v_pk_mul_f32 v[120:121], v[156:157], v[78:79] op_sel_hi:[0,1]
	v_pk_mul_f32 v[122:123], v[156:157], v[78:79] op_sel:[1,0]
	v_pk_fma_f32 v[6:7], v[6:7], v[110:111], v[120:121] op_sel:[0,1,0]
	v_pk_fma_f32 v[18:19], v[18:19], v[110:111], v[122:123] op_sel:[0,1,0]
	v_pk_fma_f32 v[188:189], v[6:7], v[102:103], v[188:189]
	v_pk_fma_f32 v[190:191], v[18:19], v[102:103], v[190:191]
	v_add_f32_e64 v192, v188, v189
	v_add_f32_e64 v193, v190, v191
	s_waitcnt lgkmcnt(0)
; __device__ __forceinline__ float red8(float v) { v = red4(v); v += dppf<0x141>(v); return v; }
; __device__ __forceinline__ f32x2 lo2(const f32x4& v) { return __builtin_shufflevector(v, v, 0, 1); }
; __device__ __forceinline__ f32x2 hi2(const f32x4& v) { return __builtin_shufflevector(v, v, 2, 3); }
; __device__ __forceinline__ f32x2 splat2(float x) { return (f32x2){x, x}; }
; __device__ __forceinline__ void ss_load(SsRegs& R, const float* vb, const float* sb, int t, int n0, int prow0) {
;   const float* vt = vb + t * 320;
; #pragma unroll
;   for (int q = 0; q < 4; ++q) {
;     R.B[q] = *(const f32x4*)(vt + n0 + q * 4);
;     R.C[q] = *(const f32x4*)(vt + 128 + n0 + q * 4);
;   }
;   R.x = *(const f32x2*)(vt + 256 + prow0);
;   R.sc = *(const f32x2*)(sb + t * 2);
; }
; __device__ __forceinline__ f32x2 ss_step(f32x2 (&S)[2][8], const SsRegs& R) {
;   const f32x2 dA2 = splat2(R.sc.y);
;   f32x2 out;
; #pragma unroll
;   for (int r = 0; r < 2; ++r) {
;     const f32x2 xdt2 = splat2((r ? R.x.y : R.x.x) * R.sc.x);
;     f32x2 y0 = splat2(0.f), y1 = splat2(0.f);
; #pragma unroll
;     for (int q = 0; q < 4; ++q) {
;       S[r][2 * q] = S[r][2 * q] * dA2 + xdt2 * lo2(R.B[q]);
;       S[r][2 * q + 1] = S[r][2 * q + 1] * dA2 + xdt2 * hi2(R.B[q]);
;       y0 += S[r][2 * q] * lo2(R.C[q]);
;       y1 += S[r][2 * q + 1] * hi2(R.C[q]);
;     }
;     y0 += y1;
;     const float y = red8(y0.x + y0.y);
;     if (r) out.y = y; else out.x = y;
;   }
;   return out;
; }
	s_nop 0
	ds_read_b64 v[108:109], v152 offset:3584
	ds_read_b64 v[110:111], v153 offset:40976
	ds_read_b128 v[68:71], v150 offset:2592
	ds_read_b128 v[92:95], v150 offset:3104
	ds_read_b128 v[76:79], v151 offset:2608
	ds_read_b128 v[100:103], v151 offset:3120
	v_pk_mul_f32 v[156:157], v[112:113], v[114:115] op_sel_hi:[1,0]
	v_pk_mul_f32 v[116:117], v[156:157], v[60:61] op_sel_hi:[0,1]
	v_pk_mul_f32 v[118:119], v[156:157], v[60:61] op_sel:[1,0]
	v_pk_fma_f32 v[28:29], v[28:29], v[114:115], v[116:117] op_sel:[0,1,0]
	v_pk_fma_f32 v[24:25], v[24:25], v[114:115], v[118:119] op_sel:[0,1,0]
	v_pk_mul_f32 v[188:189], v[28:29], v[84:85]
	v_pk_mul_f32 v[190:191], v[24:25], v[84:85]
	v_add_f32_dpp v192, v192, v192 quad_perm:[1,0,3,2] row_mask:0xf bank_mask:0xf bound_ctrl:1
	v_add_f32_dpp v193, v193, v193 quad_perm:[1,0,3,2] row_mask:0xf bank_mask:0xf bound_ctrl:1
	v_pk_mul_f32 v[120:121], v[156:157], v[62:63] op_sel_hi:[0,1]
	v_pk_mul_f32 v[122:123], v[156:157], v[62:63] op_sel:[1,0]
	v_pk_fma_f32 v[30:31], v[30:31], v[114:115], v[120:121] op_sel:[0,1,0]
	v_pk_fma_f32 v[26:27], v[26:27], v[114:115], v[122:123] op_sel:[0,1,0]
	v_pk_fma_f32 v[188:189], v[30:31], v[86:87], v[188:189]
	v_pk_fma_f32 v[190:191], v[26:27], v[86:87], v[190:191]
	v_add_f32_dpp v192, v192, v192 quad_perm:[2,3,0,1] row_mask:0xf bank_mask:0xf bound_ctrl:1
	v_add_f32_dpp v193, v193, v193 quad_perm:[2,3,0,1] row_mask:0xf bank_mask:0xf bound_ctrl:1
	v_pk_mul_f32 v[116:117], v[156:157], v[64:65] op_sel_hi:[0,1]
	v_pk_mul_f32 v[118:119], v[156:157], v[64:65] op_sel:[1,0]
	v_pk_fma_f32 v[12:13], v[12:13], v[114:115], v[116:117] op_sel:[0,1,0]
	v_pk_fma_f32 v[32:33], v[32:33], v[114:115], v[118:119] op_sel:[0,1,0]
	v_pk_fma_f32 v[188:189], v[12:13], v[88:89], v[188:189]
	v_pk_fma_f32 v[190:191], v[32:33], v[88:89], v[190:191]
	v_add_f32_dpp v192, v192, v192 row_half_mirror row_mask:0xf bank_mask:0xf bound_ctrl:1
	v_add_f32_dpp v193, v193, v193 row_half_mirror row_mask:0xf bank_mask:0xf bound_ctrl:1
	v_pk_mul_f32 v[120:121], v[156:157], v[66:67] op_sel_hi:[0,1]
	v_pk_mul_f32 v[122:123], v[156:157], v[66:67] op_sel:[1,0]
	v_pk_fma_f32 v[14:15], v[14:15], v[114:115], v[120:121] op_sel:[0,1,0]
	v_pk_fma_f32 v[34:35], v[34:35], v[114:115], v[122:123] op_sel:[0,1,0]
	v_pk_fma_f32 v[188:189], v[14:15], v[90:91], v[188:189]
	v_pk_fma_f32 v[190:191], v[34:35], v[90:91], v[190:191]
	ds_read_b128 v[60:63], v150 offset:2560
	ds_read_b128 v[84:87], v150 offset:3072
	ds_read_b128 v[64:67], v151 offset:2576
	ds_read_b128 v[88:91], v151 offset:3088
	ds_write_b64 v154, v[192:193] offset:0
	v_pk_mul_f32 v[116:117], v[156:157], v[72:73] op_sel_hi:[0,1]
	v_pk_mul_f32 v[118:119], v[156:157], v[72:73] op_sel:[1,0]
	v_pk_fma_f32 v[8:9], v[8:9], v[114:115], v[116:117] op_sel:[0,1,0]
	v_pk_fma_f32 v[20:21], v[20:21], v[114:115], v[118:119] op_sel:[0,1,0]
	v_pk_fma_f32 v[188:189], v[8:9], v[96:97], v[188:189]
	v_pk_fma_f32 v[190:191], v[20:21], v[96:97], v[190:191]
	v_pk_mul_f32 v[120:121], v[156:157], v[74:75] op_sel_hi:[0,1]
	v_pk_mul_f32 v[122:123], v[156:157], v[74:75] op_sel:[1,0]
	v_pk_fma_f32 v[10:11], v[10:11], v[114:115], v[120:121] op_sel:[0,1,0]
	v_pk_fma_f32 v[22:23], v[22:23], v[114:115], v[122:123] op_sel:[0,1,0]
	v_pk_fma_f32 v[188:189], v[10:11], v[98:99], v[188:189]
	v_pk_fma_f32 v[190:191], v[22:23], v[98:99], v[190:191]
	v_pk_mul_f32 v[116:117], v[156:157], v[80:81] op_sel_hi:[0,1]
	v_pk_mul_f32 v[118:119], v[156:157], v[80:81] op_sel:[1,0]
	v_pk_fma_f32 v[4:5], v[4:5], v[114:115], v[116:117] op_sel:[0,1,0]
	v_pk_fma_f32 v[16:17], v[16:17], v[114:115], v[118:119] op_sel:[0,1,0]
	v_pk_fma_f32 v[188:189], v[4:5], v[104:105], v[188:189]
	v_pk_fma_f32 v[190:191], v[16:17], v[104:105], v[190:191]
	v_pk_mul_f32 v[120:121], v[156:157], v[82:83] op_sel_hi:[0,1]
	v_pk_mul_f32 v[122:123], v[156:157], v[82:83] op_sel:[1,0]
	v_pk_fma_f32 v[6:7], v[6:7], v[114:115], v[120:121] op_sel:[0,1,0]
	v_pk_fma_f32 v[18:19], v[18:19], v[114:115], v[122:123] op_sel:[0,1,0]
	v_pk_fma_f32 v[188:189], v[6:7], v[106:107], v[188:189]
	v_pk_fma_f32 v[190:191], v[18:19], v[106:107], v[190:191]
	v_add_f32_e64 v192, v188, v189
	v_add_f32_e64 v193, v190, v191
	s_waitcnt lgkmcnt(0)
	s_nop 0
	ds_read_b64 v[112:113], v152 offset:4864
	ds_read_b64 v[114:115], v153 offset:40984
	ds_read_b128 v[72:75], v150 offset:3872
	ds_read_b128 v[96:99], v150 offset:4384
	ds_read_b128 v[80:83], v151 offset:3888
	ds_read_b128 v[104:107], v151 offset:4400
	v_pk_mul_f32 v[156:157], v[108:109], v[110:111] op_sel_hi:[1,0]
	v_pk_mul_f32 v[116:117], v[156:157], v[60:61] op_sel_hi:[0,1]
	v_pk_mul_f32 v[118:119], v[156:157], v[60:61] op_sel:[1,0]
	v_pk_fma_f32 v[28:29], v[28:29], v[110:111], v[116:117] op_sel:[0,1,0]
	v_pk_fma_f32 v[24:25], v[24:25], v[110:111], v[118:119] op_sel:[0,1,0]
	v_pk_mul_f32 v[188:189], v[28:29], v[84:85]
	v_pk_mul_f32 v[190:191], v[24:25], v[84:85]
	v_add_f32_dpp v192, v192, v192 quad_perm:[1,0,3,2] row_mask:0xf bank_mask:0xf bound_ctrl:1
	v_add_f32_dpp v193, v193, v193 quad_perm:[1,0,3,2] row_mask:0xf bank_mask:0xf bound_ctrl:1
	v_pk_mul_f32 v[120:121], v[156:157], v[62:63] op_sel_hi:[0,1]
	v_pk_mul_f32 v[122:123], v[156:157], v[62:63] op_sel:[1,0]
	v_pk_fma_f32 v[30:31], v[30:31], v[110:111], v[120:121] op_sel:[0,1,0]
	v_pk_fma_f32 v[26:27], v[26:27], v[110:111], v[122:123] op_sel:[0,1,0]
	v_pk_fma_f32 v[188:189], v[30:31], v[86:87], v[188:189]
	v_pk_fma_f32 v[190:191], v[26:27], v[86:87], v[190:191]
	v_add_f32_dpp v192, v192, v192 quad_perm:[2,3,0,1] row_mask:0xf bank_mask:0xf bound_ctrl:1
	v_add_f32_dpp v193, v193, v193 quad_perm:[2,3,0,1] row_mask:0xf bank_mask:0xf bound_ctrl:1
	v_pk_mul_f32 v[116:117], v[156:157], v[64:65] op_sel_hi:[0,1]
; __device__ __forceinline__ float red8(float v) { v = red4(v); v += dppf<0x141>(v); return v; }
; __device__ __forceinline__ f32x2 lo2(const f32x4& v) { return __builtin_shufflevector(v, v, 0, 1); }
; __device__ __forceinline__ f32x2 hi2(const f32x4& v) { return __builtin_shufflevector(v, v, 2, 3); }
; __device__ __forceinline__ f32x2 splat2(float x) { return (f32x2){x, x}; }
; __device__ __forceinline__ void ss_load(SsRegs& R, const float* vb, const float* sb, int t, int n0, int prow0) {
;   const float* vt = vb + t * 320;
; #pragma unroll
;   for (int q = 0; q < 4; ++q) {
;     R.B[q] = *(const f32x4*)(vt + n0 + q * 4);
;     R.C[q] = *(const f32x4*)(vt + 128 + n0 + q * 4);
;   }
;   R.x = *(const f32x2*)(vt + 256 + prow0);
;   R.sc = *(const f32x2*)(sb + t * 2);
; }
; __device__ __forceinline__ f32x2 ss_step(f32x2 (&S)[2][8], const SsRegs& R) {
;   const f32x2 dA2 = splat2(R.sc.y);
;   f32x2 out;
; #pragma unroll
;   for (int r = 0; r < 2; ++r) {
;     const f32x2 xdt2 = splat2((r ? R.x.y : R.x.x) * R.sc.x);
;     f32x2 y0 = splat2(0.f), y1 = splat2(0.f);
; #pragma unroll
;     for (int q = 0; q < 4; ++q) {
;       S[r][2 * q] = S[r][2 * q] * dA2 + xdt2 * lo2(R.B[q]);
;       S[r][2 * q + 1] = S[r][2 * q + 1] * dA2 + xdt2 * hi2(R.B[q]);
;       y0 += S[r][2 * q] * lo2(R.C[q]);
;       y1 += S[r][2 * q + 1] * hi2(R.C[q]);
;     }
;     y0 += y1;
;     const float y = red8(y0.x + y0.y);
;     if (r) out.y = y; else out.x = y;
;   }
;   return out;
; }
	v_pk_mul_f32 v[118:119], v[156:157], v[64:65] op_sel:[1,0]
	v_pk_fma_f32 v[12:13], v[12:13], v[110:111], v[116:117] op_sel:[0,1,0]
	v_pk_fma_f32 v[32:33], v[32:33], v[110:111], v[118:119] op_sel:[0,1,0]
	v_pk_fma_f32 v[188:189], v[12:13], v[88:89], v[188:189]
	v_pk_fma_f32 v[190:191], v[32:33], v[88:89], v[190:191]
	v_add_f32_dpp v192, v192, v192 row_half_mirror row_mask:0xf bank_mask:0xf bound_ctrl:1
	v_add_f32_dpp v193, v193, v193 row_half_mirror row_mask:0xf bank_mask:0xf bound_ctrl:1
	v_pk_mul_f32 v[120:121], v[156:157], v[66:67] op_sel_hi:[0,1]
	v_pk_mul_f32 v[122:123], v[156:157], v[66:67] op_sel:[1,0]
	v_pk_fma_f32 v[14:15], v[14:15], v[110:111], v[120:121] op_sel:[0,1,0]
	v_pk_fma_f32 v[34:35], v[34:35], v[110:111], v[122:123] op_sel:[0,1,0]
	v_pk_fma_f32 v[188:189], v[14:15], v[90:91], v[188:189]
	v_pk_fma_f32 v[190:191], v[34:35], v[90:91], v[190:191]
	ds_read_b128 v[60:63], v150 offset:3840
	ds_read_b128 v[84:87], v150 offset:4352
	ds_read_b128 v[64:67], v151 offset:3856
	ds_read_b128 v[88:91], v151 offset:4368
	ds_write_b64 v154, v[192:193] offset:256
	v_pk_mul_f32 v[116:117], v[156:157], v[68:69] op_sel_hi:[0,1]
	v_pk_mul_f32 v[118:119], v[156:157], v[68:69] op_sel:[1,0]
	v_pk_fma_f32 v[8:9], v[8:9], v[110:111], v[116:117] op_sel:[0,1,0]
	v_pk_fma_f32 v[20:21], v[20:21], v[110:111], v[118:119] op_sel:[0,1,0]
	v_pk_fma_f32 v[188:189], v[8:9], v[92:93], v[188:189]
	v_pk_fma_f32 v[190:191], v[20:21], v[92:93], v[190:191]
	v_pk_mul_f32 v[120:121], v[156:157], v[70:71] op_sel_hi:[0,1]
	v_pk_mul_f32 v[122:123], v[156:157], v[70:71] op_sel:[1,0]
	v_pk_fma_f32 v[10:11], v[10:11], v[110:111], v[120:121] op_sel:[0,1,0]
	v_pk_fma_f32 v[22:23], v[22:23], v[110:111], v[122:123] op_sel:[0,1,0]
	v_pk_fma_f32 v[188:189], v[10:11], v[94:95], v[188:189]
	v_pk_fma_f32 v[190:191], v[22:23], v[94:95], v[190:191]
	v_pk_mul_f32 v[116:117], v[156:157], v[76:77] op_sel_hi:[0,1]
	v_pk_mul_f32 v[118:119], v[156:157], v[76:77] op_sel:[1,0]
	v_pk_fma_f32 v[4:5], v[4:5], v[110:111], v[116:117] op_sel:[0,1,0]
	v_pk_fma_f32 v[16:17], v[16:17], v[110:111], v[118:119] op_sel:[0,1,0]
	v_pk_fma_f32 v[188:189], v[4:5], v[100:101], v[188:189]
	v_pk_fma_f32 v[190:191], v[16:17], v[100:101], v[190:191]
	v_pk_mul_f32 v[120:121], v[156:157], v[78:79] op_sel_hi:[0,1]
	v_pk_mul_f32 v[122:123], v[156:157], v[78:79] op_sel:[1,0]
	v_pk_fma_f32 v[6:7], v[6:7], v[110:111], v[120:121] op_sel:[0,1,0]
	v_pk_fma_f32 v[18:19], v[18:19], v[110:111], v[122:123] op_sel:[0,1,0]
	v_pk_fma_f32 v[188:189], v[6:7], v[102:103], v[188:189]
	v_pk_fma_f32 v[190:191], v[18:19], v[102:103], v[190:191]
	v_add_f32_e64 v192, v188, v189
	v_add_f32_e64 v193, v190, v191
	s_waitcnt lgkmcnt(0)
	s_nop 0
	ds_read_b64 v[108:109], v152 offset:6144
	ds_read_b64 v[110:111], v153 offset:40992
	ds_read_b128 v[68:71], v150 offset:5152
	ds_read_b128 v[92:95], v150 offset:5664
	ds_read_b128 v[76:79], v151 offset:5168
	ds_read_b128 v[100:103], v151 offset:5680
	v_pk_mul_f32 v[156:157], v[112:113], v[114:115] op_sel_hi:[1,0]
	v_pk_mul_f32 v[116:117], v[156:157], v[60:61] op_sel_hi:[0,1]
	v_pk_mul_f32 v[118:119], v[156:157], v[60:61] op_sel:[1,0]
	v_pk_fma_f32 v[28:29], v[28:29], v[114:115], v[116:117] op_sel:[0,1,0]
	v_pk_fma_f32 v[24:25], v[24:25], v[114:115], v[118:119] op_sel:[0,1,0]
	v_pk_mul_f32 v[188:189], v[28:29], v[84:85]
	v_pk_mul_f32 v[190:191], v[24:25], v[84:85]
	v_add_f32_dpp v192, v192, v192 quad_perm:[1,0,3,2] row_mask:0xf bank_mask:0xf bound_ctrl:1
	v_add_f32_dpp v193, v193, v193 quad_perm:[1,0,3,2] row_mask:0xf bank_mask:0xf bound_ctrl:1
	v_pk_mul_f32 v[120:121], v[156:157], v[62:63] op_sel_hi:[0,1]
	v_pk_mul_f32 v[122:123], v[156:157], v[62:63] op_sel:[1,0]
	v_pk_fma_f32 v[30:31], v[30:31], v[114:115], v[120:121] op_sel:[0,1,0]
	v_pk_fma_f32 v[26:27], v[26:27], v[114:115], v[122:123] op_sel:[0,1,0]
	v_pk_fma_f32 v[188:189], v[30:31], v[86:87], v[188:189]
	v_pk_fma_f32 v[190:191], v[26:27], v[86:87], v[190:191]
	v_add_f32_dpp v192, v192, v192 quad_perm:[2,3,0,1] row_mask:0xf bank_mask:0xf bound_ctrl:1
	v_add_f32_dpp v193, v193, v193 quad_perm:[2,3,0,1] row_mask:0xf bank_mask:0xf bound_ctrl:1
	v_pk_mul_f32 v[116:117], v[156:157], v[64:65] op_sel_hi:[0,1]
	v_pk_mul_f32 v[118:119], v[156:157], v[64:65] op_sel:[1,0]
	v_pk_fma_f32 v[12:13], v[12:13], v[114:115], v[116:117] op_sel:[0,1,0]
	v_pk_fma_f32 v[32:33], v[32:33], v[114:115], v[118:119] op_sel:[0,1,0]
	v_pk_fma_f32 v[188:189], v[12:13], v[88:89], v[188:189]
	v_pk_fma_f32 v[190:191], v[32:33], v[88:89], v[190:191]
	v_add_f32_dpp v192, v192, v192 row_half_mirror row_mask:0xf bank_mask:0xf bound_ctrl:1
	v_add_f32_dpp v193, v193, v193 row_half_mirror row_mask:0xf bank_mask:0xf bound_ctrl:1
	v_pk_mul_f32 v[120:121], v[156:157], v[66:67] op_sel_hi:[0,1]
	v_pk_mul_f32 v[122:123], v[156:157], v[66:67] op_sel:[1,0]
	v_pk_fma_f32 v[14:15], v[14:15], v[114:115], v[120:121] op_sel:[0,1,0]
	v_pk_fma_f32 v[34:35], v[34:35], v[114:115], v[122:123] op_sel:[0,1,0]
	v_pk_fma_f32 v[188:189], v[14:15], v[90:91], v[188:189]
	v_pk_fma_f32 v[190:191], v[34:35], v[90:91], v[190:191]
	ds_read_b128 v[60:63], v150 offset:5120
	ds_read_b128 v[84:87], v150 offset:5632
	ds_read_b128 v[64:67], v151 offset:5136
	ds_read_b128 v[88:91], v151 offset:5648
	ds_write_b64 v154, v[192:193] offset:512
	v_pk_mul_f32 v[116:117], v[156:157], v[72:73] op_sel_hi:[0,1]
	v_pk_mul_f32 v[118:119], v[156:157], v[72:73] op_sel:[1,0]
	v_pk_fma_f32 v[8:9], v[8:9], v[114:115], v[116:117] op_sel:[0,1,0]
	v_pk_fma_f32 v[20:21], v[20:21], v[114:115], v[118:119] op_sel:[0,1,0]
	v_pk_fma_f32 v[188:189], v[8:9], v[96:97], v[188:189]
	v_pk_fma_f32 v[190:191], v[20:21], v[96:97], v[190:191]
	v_pk_mul_f32 v[120:121], v[156:157], v[74:75] op_sel_hi:[0,1]
	v_pk_mul_f32 v[122:123], v[156:157], v[74:75] op_sel:[1,0]
	v_pk_fma_f32 v[10:11], v[10:11], v[114:115], v[120:121] op_sel:[0,1,0]
	v_pk_fma_f32 v[22:23], v[22:23], v[114:115], v[122:123] op_sel:[0,1,0]
	v_pk_fma_f32 v[188:189], v[10:11], v[98:99], v[188:189]
	v_pk_fma_f32 v[190:191], v[22:23], v[98:99], v[190:191]
	v_pk_mul_f32 v[116:117], v[156:157], v[80:81] op_sel_hi:[0,1]
	v_pk_mul_f32 v[118:119], v[156:157], v[80:81] op_sel:[1,0]
	v_pk_fma_f32 v[4:5], v[4:5], v[114:115], v[116:117] op_sel:[0,1,0]
	v_pk_fma_f32 v[16:17], v[16:17], v[114:115], v[118:119] op_sel:[0,1,0]
	v_pk_fma_f32 v[188:189], v[4:5], v[104:105], v[188:189]
	v_pk_fma_f32 v[190:191], v[16:17], v[104:105], v[190:191]
	v_pk_mul_f32 v[120:121], v[156:157], v[82:83] op_sel_hi:[0,1]
	v_pk_mul_f32 v[122:123], v[156:157], v[82:83] op_sel:[1,0]
	v_pk_fma_f32 v[6:7], v[6:7], v[114:115], v[120:121] op_sel:[0,1,0]
	v_pk_fma_f32 v[18:19], v[18:19], v[114:115], v[122:123] op_sel:[0,1,0]
	v_pk_fma_f32 v[188:189], v[6:7], v[106:107], v[188:189]
	v_pk_fma_f32 v[190:191], v[18:19], v[106:107], v[190:191]
	v_add_f32_e64 v192, v188, v189
	v_add_f32_e64 v193, v190, v191
	s_waitcnt lgkmcnt(0)
; __device__ __forceinline__ float red8(float v) { v = red4(v); v += dppf<0x141>(v); return v; }
; __device__ __forceinline__ f32x2 lo2(const f32x4& v) { return __builtin_shufflevector(v, v, 0, 1); }
; __device__ __forceinline__ f32x2 hi2(const f32x4& v) { return __builtin_shufflevector(v, v, 2, 3); }
; __device__ __forceinline__ f32x2 splat2(float x) { return (f32x2){x, x}; }
; __device__ __forceinline__ void ss_load(SsRegs& R, const float* vb, const float* sb, int t, int n0, int prow0) {
;   const float* vt = vb + t * 320;
; #pragma unroll
;   for (int q = 0; q < 4; ++q) {
;     R.B[q] = *(const f32x4*)(vt + n0 + q * 4);
;     R.C[q] = *(const f32x4*)(vt + 128 + n0 + q * 4);
;   }
;   R.x = *(const f32x2*)(vt + 256 + prow0);
;   R.sc = *(const f32x2*)(sb + t * 2);
; }
; __device__ __forceinline__ f32x2 ss_step(f32x2 (&S)[2][8], const SsRegs& R) {
;   const f32x2 dA2 = splat2(R.sc.y);
;   f32x2 out;
; #pragma unroll
;   for (int r = 0; r < 2; ++r) {
;     const f32x2 xdt2 = splat2((r ? R.x.y : R.x.x) * R.sc.x);
;     f32x2 y0 = splat2(0.f), y1 = splat2(0.f);
; #pragma unroll
;     for (int q = 0; q < 4; ++q) {
;       S[r][2 * q] = S[r][2 * q] * dA2 + xdt2 * lo2(R.B[q]);
;       S[r][2 * q + 1] = S[r][2 * q + 1] * dA2 + xdt2 * hi2(R.B[q]);
;       y0 += S[r][2 * q] * lo2(R.C[q]);
;       y1 += S[r][2 * q + 1] * hi2(R.C[q]);
;     }
;     y0 += y1;
;     const float y = red8(y0.x + y0.y);
;     if (r) out.y = y; else out.x = y;
;   }
;   return out;
; }
	s_nop 0
	ds_read_b64 v[112:113], v152 offset:7424
	ds_read_b64 v[114:115], v153 offset:41000
	ds_read_b128 v[72:75], v150 offset:6432
	ds_read_b128 v[96:99], v150 offset:6944
	ds_read_b128 v[80:83], v151 offset:6448
	ds_read_b128 v[104:107], v151 offset:6960
	v_pk_mul_f32 v[156:157], v[108:109], v[110:111] op_sel_hi:[1,0]
	v_pk_mul_f32 v[116:117], v[156:157], v[60:61] op_sel_hi:[0,1]
	v_pk_mul_f32 v[118:119], v[156:157], v[60:61] op_sel:[1,0]
	v_pk_fma_f32 v[28:29], v[28:29], v[110:111], v[116:117] op_sel:[0,1,0]
	v_pk_fma_f32 v[24:25], v[24:25], v[110:111], v[118:119] op_sel:[0,1,0]
	v_pk_mul_f32 v[188:189], v[28:29], v[84:85]
	v_pk_mul_f32 v[190:191], v[24:25], v[84:85]
	v_add_f32_dpp v192, v192, v192 quad_perm:[1,0,3,2] row_mask:0xf bank_mask:0xf bound_ctrl:1
	v_add_f32_dpp v193, v193, v193 quad_perm:[1,0,3,2] row_mask:0xf bank_mask:0xf bound_ctrl:1
	v_pk_mul_f32 v[120:121], v[156:157], v[62:63] op_sel_hi:[0,1]
	v_pk_mul_f32 v[122:123], v[156:157], v[62:63] op_sel:[1,0]
	v_pk_fma_f32 v[30:31], v[30:31], v[110:111], v[120:121] op_sel:[0,1,0]
	v_pk_fma_f32 v[26:27], v[26:27], v[110:111], v[122:123] op_sel:[0,1,0]
	v_pk_fma_f32 v[188:189], v[30:31], v[86:87], v[188:189]
	v_pk_fma_f32 v[190:191], v[26:27], v[86:87], v[190:191]
	v_add_f32_dpp v192, v192, v192 quad_perm:[2,3,0,1] row_mask:0xf bank_mask:0xf bound_ctrl:1
	v_add_f32_dpp v193, v193, v193 quad_perm:[2,3,0,1] row_mask:0xf bank_mask:0xf bound_ctrl:1
	v_pk_mul_f32 v[116:117], v[156:157], v[64:65] op_sel_hi:[0,1]
	v_pk_mul_f32 v[118:119], v[156:157], v[64:65] op_sel:[1,0]
	v_pk_fma_f32 v[12:13], v[12:13], v[110:111], v[116:117] op_sel:[0,1,0]
	v_pk_fma_f32 v[32:33], v[32:33], v[110:111], v[118:119] op_sel:[0,1,0]
	v_pk_fma_f32 v[188:189], v[12:13], v[88:89], v[188:189]
	v_pk_fma_f32 v[190:191], v[32:33], v[88:89], v[190:191]
	v_add_f32_dpp v192, v192, v192 row_half_mirror row_mask:0xf bank_mask:0xf bound_ctrl:1
	v_add_f32_dpp v193, v193, v193 row_half_mirror row_mask:0xf bank_mask:0xf bound_ctrl:1
	v_pk_mul_f32 v[120:121], v[156:157], v[66:67] op_sel_hi:[0,1]
	v_pk_mul_f32 v[122:123], v[156:157], v[66:67] op_sel:[1,0]
	v_pk_fma_f32 v[14:15], v[14:15], v[110:111], v[120:121] op_sel:[0,1,0]
	v_pk_fma_f32 v[34:35], v[34:35], v[110:111], v[122:123] op_sel:[0,1,0]
	v_pk_fma_f32 v[188:189], v[14:15], v[90:91], v[188:189]
	v_pk_fma_f32 v[190:191], v[34:35], v[90:91], v[190:191]
	ds_read_b128 v[60:63], v150 offset:6400
	ds_read_b128 v[84:87], v150 offset:6912
	ds_read_b128 v[64:67], v151 offset:6416
	ds_read_b128 v[88:91], v151 offset:6928
	ds_write_b64 v154, v[192:193] offset:768
	v_pk_mul_f32 v[116:117], v[156:157], v[68:69] op_sel_hi:[0,1]
	v_pk_mul_f32 v[118:119], v[156:157], v[68:69] op_sel:[1,0]
	v_pk_fma_f32 v[8:9], v[8:9], v[110:111], v[116:117] op_sel:[0,1,0]
	v_pk_fma_f32 v[20:21], v[20:21], v[110:111], v[118:119] op_sel:[0,1,0]
	v_pk_fma_f32 v[188:189], v[8:9], v[92:93], v[188:189]
	v_pk_fma_f32 v[190:191], v[20:21], v[92:93], v[190:191]
	v_pk_mul_f32 v[120:121], v[156:157], v[70:71] op_sel_hi:[0,1]
	v_pk_mul_f32 v[122:123], v[156:157], v[70:71] op_sel:[1,0]
	v_pk_fma_f32 v[10:11], v[10:11], v[110:111], v[120:121] op_sel:[0,1,0]
	v_pk_fma_f32 v[22:23], v[22:23], v[110:111], v[122:123] op_sel:[0,1,0]
	v_pk_fma_f32 v[188:189], v[10:11], v[94:95], v[188:189]
	v_pk_fma_f32 v[190:191], v[22:23], v[94:95], v[190:191]
	v_pk_mul_f32 v[116:117], v[156:157], v[76:77] op_sel_hi:[0,1]
	v_pk_mul_f32 v[118:119], v[156:157], v[76:77] op_sel:[1,0]
	v_pk_fma_f32 v[4:5], v[4:5], v[110:111], v[116:117] op_sel:[0,1,0]
	v_pk_fma_f32 v[16:17], v[16:17], v[110:111], v[118:119] op_sel:[0,1,0]
	v_pk_fma_f32 v[188:189], v[4:5], v[100:101], v[188:189]
	v_pk_fma_f32 v[190:191], v[16:17], v[100:101], v[190:191]
	v_pk_mul_f32 v[120:121], v[156:157], v[78:79] op_sel_hi:[0,1]
	v_pk_mul_f32 v[122:123], v[156:157], v[78:79] op_sel:[1,0]
	v_pk_fma_f32 v[6:7], v[6:7], v[110:111], v[120:121] op_sel:[0,1,0]
	v_pk_fma_f32 v[18:19], v[18:19], v[110:111], v[122:123] op_sel:[0,1,0]
	v_pk_fma_f32 v[188:189], v[6:7], v[102:103], v[188:189]
	v_pk_fma_f32 v[190:191], v[18:19], v[102:103], v[190:191]
	v_add_f32_e64 v192, v188, v189
	v_add_f32_e64 v193, v190, v191
	s_waitcnt lgkmcnt(0)
	s_nop 0
	ds_read_b64 v[108:109], v152 offset:8704
	ds_read_b64 v[110:111], v153 offset:41008
	ds_read_b128 v[68:71], v150 offset:7712
	ds_read_b128 v[92:95], v150 offset:8224
	ds_read_b128 v[76:79], v151 offset:7728
	ds_read_b128 v[100:103], v151 offset:8240
	v_pk_mul_f32 v[156:157], v[112:113], v[114:115] op_sel_hi:[1,0]
	v_pk_mul_f32 v[116:117], v[156:157], v[60:61] op_sel_hi:[0,1]
	v_pk_mul_f32 v[118:119], v[156:157], v[60:61] op_sel:[1,0]
	v_pk_fma_f32 v[28:29], v[28:29], v[114:115], v[116:117] op_sel:[0,1,0]
	v_pk_fma_f32 v[24:25], v[24:25], v[114:115], v[118:119] op_sel:[0,1,0]
	v_pk_mul_f32 v[188:189], v[28:29], v[84:85]
	v_pk_mul_f32 v[190:191], v[24:25], v[84:85]
	v_add_f32_dpp v192, v192, v192 quad_perm:[1,0,3,2] row_mask:0xf bank_mask:0xf bound_ctrl:1
	v_add_f32_dpp v193, v193, v193 quad_perm:[1,0,3,2] row_mask:0xf bank_mask:0xf bound_ctrl:1
	v_pk_mul_f32 v[120:121], v[156:157], v[62:63] op_sel_hi:[0,1]
	v_pk_mul_f32 v[122:123], v[156:157], v[62:63] op_sel:[1,0]
	v_pk_fma_f32 v[30:31], v[30:31], v[114:115], v[120:121] op_sel:[0,1,0]
	v_pk_fma_f32 v[26:27], v[26:27], v[114:115], v[122:123] op_sel:[0,1,0]
	v_pk_fma_f32 v[188:189], v[30:31], v[86:87], v[188:189]
	v_pk_fma_f32 v[190:191], v[26:27], v[86:87], v[190:191]
	v_add_f32_dpp v192, v192, v192 quad_perm:[2,3,0,1] row_mask:0xf bank_mask:0xf bound_ctrl:1
	v_add_f32_dpp v193, v193, v193 quad_perm:[2,3,0,1] row_mask:0xf bank_mask:0xf bound_ctrl:1
	v_pk_mul_f32 v[116:117], v[156:157], v[64:65] op_sel_hi:[0,1]
; __device__ __forceinline__ float red8(float v) { v = red4(v); v += dppf<0x141>(v); return v; }
; __device__ __forceinline__ f32x2 lo2(const f32x4& v) { return __builtin_shufflevector(v, v, 0, 1); }
; __device__ __forceinline__ f32x2 hi2(const f32x4& v) { return __builtin_shufflevector(v, v, 2, 3); }
; __device__ __forceinline__ f32x2 splat2(float x) { return (f32x2){x, x}; }
; __device__ __forceinline__ void ss_load(SsRegs& R, const float* vb, const float* sb, int t, int n0, int prow0) {
;   const float* vt = vb + t * 320;
; #pragma unroll
;   for (int q = 0; q < 4; ++q) {
;     R.B[q] = *(const f32x4*)(vt + n0 + q * 4);
;     R.C[q] = *(const f32x4*)(vt + 128 + n0 + q * 4);
;   }
;   R.x = *(const f32x2*)(vt + 256 + prow0);
;   R.sc = *(const f32x2*)(sb + t * 2);
; }
; __device__ __forceinline__ f32x2 ss_step(f32x2 (&S)[2][8], const SsRegs& R) {
;   const f32x2 dA2 = splat2(R.sc.y);
;   f32x2 out;
; #pragma unroll
;   for (int r = 0; r < 2; ++r) {
;     const f32x2 xdt2 = splat2((r ? R.x.y : R.x.x) * R.sc.x);
;     f32x2 y0 = splat2(0.f), y1 = splat2(0.f);
; #pragma unroll
;     for (int q = 0; q < 4; ++q) {
;       S[r][2 * q] = S[r][2 * q] * dA2 + xdt2 * lo2(R.B[q]);
;       S[r][2 * q + 1] = S[r][2 * q + 1] * dA2 + xdt2 * hi2(R.B[q]);
;       y0 += S[r][2 * q] * lo2(R.C[q]);
;       y1 += S[r][2 * q + 1] * hi2(R.C[q]);
;     }
;     y0 += y1;
;     const float y = red8(y0.x + y0.y);
;     if (r) out.y = y; else out.x = y;
;   }
;   return out;
; }
	v_pk_mul_f32 v[118:119], v[156:157], v[64:65] op_sel:[1,0]
	v_pk_fma_f32 v[12:13], v[12:13], v[114:115], v[116:117] op_sel:[0,1,0]
	v_pk_fma_f32 v[32:33], v[32:33], v[114:115], v[118:119] op_sel:[0,1,0]
	v_pk_fma_f32 v[188:189], v[12:13], v[88:89], v[188:189]
	v_pk_fma_f32 v[190:191], v[32:33], v[88:89], v[190:191]
	v_add_f32_dpp v192, v192, v192 row_half_mirror row_mask:0xf bank_mask:0xf bound_ctrl:1
	v_add_f32_dpp v193, v193, v193 row_half_mirror row_mask:0xf bank_mask:0xf bound_ctrl:1
	v_pk_mul_f32 v[120:121], v[156:157], v[66:67] op_sel_hi:[0,1]
	v_pk_mul_f32 v[122:123], v[156:157], v[66:67] op_sel:[1,0]
	v_pk_fma_f32 v[14:15], v[14:15], v[114:115], v[120:121] op_sel:[0,1,0]
	v_pk_fma_f32 v[34:35], v[34:35], v[114:115], v[122:123] op_sel:[0,1,0]
	v_pk_fma_f32 v[188:189], v[14:15], v[90:91], v[188:189]
	v_pk_fma_f32 v[190:191], v[34:35], v[90:91], v[190:191]
	ds_read_b128 v[60:63], v150 offset:7680
	ds_read_b128 v[84:87], v150 offset:8192
	ds_read_b128 v[64:67], v151 offset:7696
	ds_read_b128 v[88:91], v151 offset:8208
	ds_write_b64 v154, v[192:193] offset:1024
	v_pk_mul_f32 v[116:117], v[156:157], v[72:73] op_sel_hi:[0,1]
	v_pk_mul_f32 v[118:119], v[156:157], v[72:73] op_sel:[1,0]
	v_pk_fma_f32 v[8:9], v[8:9], v[114:115], v[116:117] op_sel:[0,1,0]
	v_pk_fma_f32 v[20:21], v[20:21], v[114:115], v[118:119] op_sel:[0,1,0]
	v_pk_fma_f32 v[188:189], v[8:9], v[96:97], v[188:189]
	v_pk_fma_f32 v[190:191], v[20:21], v[96:97], v[190:191]
	v_pk_mul_f32 v[120:121], v[156:157], v[74:75] op_sel_hi:[0,1]
	v_pk_mul_f32 v[122:123], v[156:157], v[74:75] op_sel:[1,0]
	v_pk_fma_f32 v[10:11], v[10:11], v[114:115], v[120:121] op_sel:[0,1,0]
	v_pk_fma_f32 v[22:23], v[22:23], v[114:115], v[122:123] op_sel:[0,1,0]
	v_pk_fma_f32 v[188:189], v[10:11], v[98:99], v[188:189]
	v_pk_fma_f32 v[190:191], v[22:23], v[98:99], v[190:191]
	v_pk_mul_f32 v[116:117], v[156:157], v[80:81] op_sel_hi:[0,1]
	v_pk_mul_f32 v[118:119], v[156:157], v[80:81] op_sel:[1,0]
	v_pk_fma_f32 v[4:5], v[4:5], v[114:115], v[116:117] op_sel:[0,1,0]
	v_pk_fma_f32 v[16:17], v[16:17], v[114:115], v[118:119] op_sel:[0,1,0]
	v_pk_fma_f32 v[188:189], v[4:5], v[104:105], v[188:189]
	v_pk_fma_f32 v[190:191], v[16:17], v[104:105], v[190:191]
	v_pk_mul_f32 v[120:121], v[156:157], v[82:83] op_sel_hi:[0,1]
	v_pk_mul_f32 v[122:123], v[156:157], v[82:83] op_sel:[1,0]
	v_pk_fma_f32 v[6:7], v[6:7], v[114:115], v[120:121] op_sel:[0,1,0]
	v_pk_fma_f32 v[18:19], v[18:19], v[114:115], v[122:123] op_sel:[0,1,0]
	v_pk_fma_f32 v[188:189], v[6:7], v[106:107], v[188:189]
	v_pk_fma_f32 v[190:191], v[18:19], v[106:107], v[190:191]
	v_add_f32_e64 v192, v188, v189
	v_add_f32_e64 v193, v190, v191
	s_waitcnt lgkmcnt(0)
	s_nop 0
	ds_read_b64 v[112:113], v152 offset:9984
	ds_read_b64 v[114:115], v153 offset:41016
	ds_read_b128 v[72:75], v150 offset:8992
	ds_read_b128 v[96:99], v150 offset:9504
	ds_read_b128 v[80:83], v151 offset:9008
	ds_read_b128 v[104:107], v151 offset:9520
	v_pk_mul_f32 v[156:157], v[108:109], v[110:111] op_sel_hi:[1,0]
	v_pk_mul_f32 v[116:117], v[156:157], v[60:61] op_sel_hi:[0,1]
	v_pk_mul_f32 v[118:119], v[156:157], v[60:61] op_sel:[1,0]
	v_pk_fma_f32 v[28:29], v[28:29], v[110:111], v[116:117] op_sel:[0,1,0]
	v_pk_fma_f32 v[24:25], v[24:25], v[110:111], v[118:119] op_sel:[0,1,0]
	v_pk_mul_f32 v[188:189], v[28:29], v[84:85]
	v_pk_mul_f32 v[190:191], v[24:25], v[84:85]
	v_add_f32_dpp v192, v192, v192 quad_perm:[1,0,3,2] row_mask:0xf bank_mask:0xf bound_ctrl:1
	v_add_f32_dpp v193, v193, v193 quad_perm:[1,0,3,2] row_mask:0xf bank_mask:0xf bound_ctrl:1
	v_pk_mul_f32 v[120:121], v[156:157], v[62:63] op_sel_hi:[0,1]
	v_pk_mul_f32 v[122:123], v[156:157], v[62:63] op_sel:[1,0]
	v_pk_fma_f32 v[30:31], v[30:31], v[110:111], v[120:121] op_sel:[0,1,0]
	v_pk_fma_f32 v[26:27], v[26:27], v[110:111], v[122:123] op_sel:[0,1,0]
	v_pk_fma_f32 v[188:189], v[30:31], v[86:87], v[188:189]
	v_pk_fma_f32 v[190:191], v[26:27], v[86:87], v[190:191]
	v_add_f32_dpp v192, v192, v192 quad_perm:[2,3,0,1] row_mask:0xf bank_mask:0xf bound_ctrl:1
	v_add_f32_dpp v193, v193, v193 quad_perm:[2,3,0,1] row_mask:0xf bank_mask:0xf bound_ctrl:1
	v_pk_mul_f32 v[116:117], v[156:157], v[64:65] op_sel_hi:[0,1]
	v_pk_mul_f32 v[118:119], v[156:157], v[64:65] op_sel:[1,0]
	v_pk_fma_f32 v[12:13], v[12:13], v[110:111], v[116:117] op_sel:[0,1,0]
	v_pk_fma_f32 v[32:33], v[32:33], v[110:111], v[118:119] op_sel:[0,1,0]
	v_pk_fma_f32 v[188:189], v[12:13], v[88:89], v[188:189]
	v_pk_fma_f32 v[190:191], v[32:33], v[88:89], v[190:191]
	v_add_f32_dpp v192, v192, v192 row_half_mirror row_mask:0xf bank_mask:0xf bound_ctrl:1
	v_add_f32_dpp v193, v193, v193 row_half_mirror row_mask:0xf bank_mask:0xf bound_ctrl:1
	v_pk_mul_f32 v[120:121], v[156:157], v[66:67] op_sel_hi:[0,1]
	v_pk_mul_f32 v[122:123], v[156:157], v[66:67] op_sel:[1,0]
	v_pk_fma_f32 v[14:15], v[14:15], v[110:111], v[120:121] op_sel:[0,1,0]
	v_pk_fma_f32 v[34:35], v[34:35], v[110:111], v[122:123] op_sel:[0,1,0]
	v_pk_fma_f32 v[188:189], v[14:15], v[90:91], v[188:189]
	v_pk_fma_f32 v[190:191], v[34:35], v[90:91], v[190:191]
	ds_read_b128 v[60:63], v150 offset:8960
	ds_read_b128 v[84:87], v150 offset:9472
	ds_read_b128 v[64:67], v151 offset:8976
	ds_read_b128 v[88:91], v151 offset:9488
	ds_write_b64 v154, v[192:193] offset:1280
	v_pk_mul_f32 v[116:117], v[156:157], v[68:69] op_sel_hi:[0,1]
	v_pk_mul_f32 v[118:119], v[156:157], v[68:69] op_sel:[1,0]
	v_pk_fma_f32 v[8:9], v[8:9], v[110:111], v[116:117] op_sel:[0,1,0]
	v_pk_fma_f32 v[20:21], v[20:21], v[110:111], v[118:119] op_sel:[0,1,0]
	v_pk_fma_f32 v[188:189], v[8:9], v[92:93], v[188:189]
	v_pk_fma_f32 v[190:191], v[20:21], v[92:93], v[190:191]
	v_pk_mul_f32 v[120:121], v[156:157], v[70:71] op_sel_hi:[0,1]
	v_pk_mul_f32 v[122:123], v[156:157], v[70:71] op_sel:[1,0]
	v_pk_fma_f32 v[10:11], v[10:11], v[110:111], v[120:121] op_sel:[0,1,0]
	v_pk_fma_f32 v[22:23], v[22:23], v[110:111], v[122:123] op_sel:[0,1,0]
	v_pk_fma_f32 v[188:189], v[10:11], v[94:95], v[188:189]
	v_pk_fma_f32 v[190:191], v[22:23], v[94:95], v[190:191]
	v_pk_mul_f32 v[116:117], v[156:157], v[76:77] op_sel_hi:[0,1]
	v_pk_mul_f32 v[118:119], v[156:157], v[76:77] op_sel:[1,0]
	v_pk_fma_f32 v[4:5], v[4:5], v[110:111], v[116:117] op_sel:[0,1,0]
	v_pk_fma_f32 v[16:17], v[16:17], v[110:111], v[118:119] op_sel:[0,1,0]
	v_pk_fma_f32 v[188:189], v[4:5], v[100:101], v[188:189]
	v_pk_fma_f32 v[190:191], v[16:17], v[100:101], v[190:191]
	v_pk_mul_f32 v[120:121], v[156:157], v[78:79] op_sel_hi:[0,1]
	v_pk_mul_f32 v[122:123], v[156:157], v[78:79] op_sel:[1,0]
	v_pk_fma_f32 v[6:7], v[6:7], v[110:111], v[120:121] op_sel:[0,1,0]
	v_pk_fma_f32 v[18:19], v[18:19], v[110:111], v[122:123] op_sel:[0,1,0]
	v_pk_fma_f32 v[188:189], v[6:7], v[102:103], v[188:189]
	v_pk_fma_f32 v[190:191], v[18:19], v[102:103], v[190:191]
	v_add_f32_e64 v192, v188, v189
	v_add_f32_e64 v193, v190, v191
	s_waitcnt lgkmcnt(0)
; __device__ __forceinline__ float red8(float v) { v = red4(v); v += dppf<0x141>(v); return v; }
; __device__ __forceinline__ f32x2 lo2(const f32x4& v) { return __builtin_shufflevector(v, v, 0, 1); }
; __device__ __forceinline__ f32x2 hi2(const f32x4& v) { return __builtin_shufflevector(v, v, 2, 3); }
; __device__ __forceinline__ f32x2 splat2(float x) { return (f32x2){x, x}; }
; __device__ __forceinline__ void ss_load(SsRegs& R, const float* vb, const float* sb, int t, int n0, int prow0) {
;   const float* vt = vb + t * 320;
; #pragma unroll
;   for (int q = 0; q < 4; ++q) {
;     R.B[q] = *(const f32x4*)(vt + n0 + q * 4);
;     R.C[q] = *(const f32x4*)(vt + 128 + n0 + q * 4);
;   }
;   R.x = *(const f32x2*)(vt + 256 + prow0);
;   R.sc = *(const f32x2*)(sb + t * 2);
; }
; __device__ __forceinline__ f32x2 ss_step(f32x2 (&S)[2][8], const SsRegs& R) {
;   const f32x2 dA2 = splat2(R.sc.y);
;   f32x2 out;
; #pragma unroll
;   for (int r = 0; r < 2; ++r) {
;     const f32x2 xdt2 = splat2((r ? R.x.y : R.x.x) * R.sc.x);
;     f32x2 y0 = splat2(0.f), y1 = splat2(0.f);
; #pragma unroll
;     for (int q = 0; q < 4; ++q) {
;       S[r][2 * q] = S[r][2 * q] * dA2 + xdt2 * lo2(R.B[q]);
;       S[r][2 * q + 1] = S[r][2 * q + 1] * dA2 + xdt2 * hi2(R.B[q]);
;       y0 += S[r][2 * q] * lo2(R.C[q]);
;       y1 += S[r][2 * q + 1] * hi2(R.C[q]);
;     }
;     y0 += y1;
;     const float y = red8(y0.x + y0.y);
;     if (r) out.y = y; else out.x = y;
;   }
;   return out;
; }
	s_nop 0
	ds_read_b64 v[108:109], v152 offset:11264
	ds_read_b64 v[110:111], v153 offset:41024
	ds_read_b128 v[68:71], v150 offset:10272
	ds_read_b128 v[92:95], v150 offset:10784
	ds_read_b128 v[76:79], v151 offset:10288
	ds_read_b128 v[100:103], v151 offset:10800
	v_pk_mul_f32 v[156:157], v[112:113], v[114:115] op_sel_hi:[1,0]
	v_pk_mul_f32 v[116:117], v[156:157], v[60:61] op_sel_hi:[0,1]
	v_pk_mul_f32 v[118:119], v[156:157], v[60:61] op_sel:[1,0]
	v_pk_fma_f32 v[28:29], v[28:29], v[114:115], v[116:117] op_sel:[0,1,0]
	v_pk_fma_f32 v[24:25], v[24:25], v[114:115], v[118:119] op_sel:[0,1,0]
	v_pk_mul_f32 v[188:189], v[28:29], v[84:85]
	v_pk_mul_f32 v[190:191], v[24:25], v[84:85]
	v_add_f32_dpp v192, v192, v192 quad_perm:[1,0,3,2] row_mask:0xf bank_mask:0xf bound_ctrl:1
	v_add_f32_dpp v193, v193, v193 quad_perm:[1,0,3,2] row_mask:0xf bank_mask:0xf bound_ctrl:1
	v_pk_mul_f32 v[120:121], v[156:157], v[62:63] op_sel_hi:[0,1]
	v_pk_mul_f32 v[122:123], v[156:157], v[62:63] op_sel:[1,0]
	v_pk_fma_f32 v[30:31], v[30:31], v[114:115], v[120:121] op_sel:[0,1,0]
	v_pk_fma_f32 v[26:27], v[26:27], v[114:115], v[122:123] op_sel:[0,1,0]
	v_pk_fma_f32 v[188:189], v[30:31], v[86:87], v[188:189]
	v_pk_fma_f32 v[190:191], v[26:27], v[86:87], v[190:191]
	v_add_f32_dpp v192, v192, v192 quad_perm:[2,3,0,1] row_mask:0xf bank_mask:0xf bound_ctrl:1
	v_add_f32_dpp v193, v193, v193 quad_perm:[2,3,0,1] row_mask:0xf bank_mask:0xf bound_ctrl:1
	v_pk_mul_f32 v[116:117], v[156:157], v[64:65] op_sel_hi:[0,1]
	v_pk_mul_f32 v[118:119], v[156:157], v[64:65] op_sel:[1,0]
	v_pk_fma_f32 v[12:13], v[12:13], v[114:115], v[116:117] op_sel:[0,1,0]
	v_pk_fma_f32 v[32:33], v[32:33], v[114:115], v[118:119] op_sel:[0,1,0]
	v_pk_fma_f32 v[188:189], v[12:13], v[88:89], v[188:189]
	v_pk_fma_f32 v[190:191], v[32:33], v[88:89], v[190:191]
	v_add_f32_dpp v192, v192, v192 row_half_mirror row_mask:0xf bank_mask:0xf bound_ctrl:1
	v_add_f32_dpp v193, v193, v193 row_half_mirror row_mask:0xf bank_mask:0xf bound_ctrl:1
	v_pk_mul_f32 v[120:121], v[156:157], v[66:67] op_sel_hi:[0,1]
	v_pk_mul_f32 v[122:123], v[156:157], v[66:67] op_sel:[1,0]
	v_pk_fma_f32 v[14:15], v[14:15], v[114:115], v[120:121] op_sel:[0,1,0]
	v_pk_fma_f32 v[34:35], v[34:35], v[114:115], v[122:123] op_sel:[0,1,0]
	v_pk_fma_f32 v[188:189], v[14:15], v[90:91], v[188:189]
	v_pk_fma_f32 v[190:191], v[34:35], v[90:91], v[190:191]
	ds_read_b128 v[60:63], v150 offset:10240
	ds_read_b128 v[84:87], v150 offset:10752
	ds_read_b128 v[64:67], v151 offset:10256
	ds_read_b128 v[88:91], v151 offset:10768
	ds_write_b64 v154, v[192:193] offset:1536
	v_pk_mul_f32 v[116:117], v[156:157], v[72:73] op_sel_hi:[0,1]
	v_pk_mul_f32 v[118:119], v[156:157], v[72:73] op_sel:[1,0]
	v_pk_fma_f32 v[8:9], v[8:9], v[114:115], v[116:117] op_sel:[0,1,0]
	v_pk_fma_f32 v[20:21], v[20:21], v[114:115], v[118:119] op_sel:[0,1,0]
	v_pk_fma_f32 v[188:189], v[8:9], v[96:97], v[188:189]
	v_pk_fma_f32 v[190:191], v[20:21], v[96:97], v[190:191]
	v_pk_mul_f32 v[120:121], v[156:157], v[74:75] op_sel_hi:[0,1]
	v_pk_mul_f32 v[122:123], v[156:157], v[74:75] op_sel:[1,0]
	v_pk_fma_f32 v[10:11], v[10:11], v[114:115], v[120:121] op_sel:[0,1,0]
	v_pk_fma_f32 v[22:23], v[22:23], v[114:115], v[122:123] op_sel:[0,1,0]
	v_pk_fma_f32 v[188:189], v[10:11], v[98:99], v[188:189]
	v_pk_fma_f32 v[190:191], v[22:23], v[98:99], v[190:191]
	v_pk_mul_f32 v[116:117], v[156:157], v[80:81] op_sel_hi:[0,1]
	v_pk_mul_f32 v[118:119], v[156:157], v[80:81] op_sel:[1,0]
	v_pk_fma_f32 v[4:5], v[4:5], v[114:115], v[116:117] op_sel:[0,1,0]
	v_pk_fma_f32 v[16:17], v[16:17], v[114:115], v[118:119] op_sel:[0,1,0]
	v_pk_fma_f32 v[188:189], v[4:5], v[104:105], v[188:189]
	v_pk_fma_f32 v[190:191], v[16:17], v[104:105], v[190:191]
	v_pk_mul_f32 v[120:121], v[156:157], v[82:83] op_sel_hi:[0,1]
	v_pk_mul_f32 v[122:123], v[156:157], v[82:83] op_sel:[1,0]
	v_pk_fma_f32 v[6:7], v[6:7], v[114:115], v[120:121] op_sel:[0,1,0]
	v_pk_fma_f32 v[18:19], v[18:19], v[114:115], v[122:123] op_sel:[0,1,0]
	v_pk_fma_f32 v[188:189], v[6:7], v[106:107], v[188:189]
	v_pk_fma_f32 v[190:191], v[18:19], v[106:107], v[190:191]
	v_add_f32_e64 v192, v188, v189
	v_add_f32_e64 v193, v190, v191
	s_waitcnt lgkmcnt(0)
	s_nop 0
	ds_read_b64 v[112:113], v152 offset:12544
	ds_read_b64 v[114:115], v153 offset:41032
	ds_read_b128 v[72:75], v150 offset:11552
	ds_read_b128 v[96:99], v150 offset:12064
	ds_read_b128 v[80:83], v151 offset:11568
	ds_read_b128 v[104:107], v151 offset:12080
	v_pk_mul_f32 v[156:157], v[108:109], v[110:111] op_sel_hi:[1,0]
	v_pk_mul_f32 v[116:117], v[156:157], v[60:61] op_sel_hi:[0,1]
	v_pk_mul_f32 v[118:119], v[156:157], v[60:61] op_sel:[1,0]
	v_pk_fma_f32 v[28:29], v[28:29], v[110:111], v[116:117] op_sel:[0,1,0]
	v_pk_fma_f32 v[24:25], v[24:25], v[110:111], v[118:119] op_sel:[0,1,0]
	v_pk_mul_f32 v[188:189], v[28:29], v[84:85]
	v_pk_mul_f32 v[190:191], v[24:25], v[84:85]
	v_add_f32_dpp v192, v192, v192 quad_perm:[1,0,3,2] row_mask:0xf bank_mask:0xf bound_ctrl:1
	v_add_f32_dpp v193, v193, v193 quad_perm:[1,0,3,2] row_mask:0xf bank_mask:0xf bound_ctrl:1
	v_pk_mul_f32 v[120:121], v[156:157], v[62:63] op_sel_hi:[0,1]
	v_pk_mul_f32 v[122:123], v[156:157], v[62:63] op_sel:[1,0]
	v_pk_fma_f32 v[30:31], v[30:31], v[110:111], v[120:121] op_sel:[0,1,0]
	v_pk_fma_f32 v[26:27], v[26:27], v[110:111], v[122:123] op_sel:[0,1,0]
	v_pk_fma_f32 v[188:189], v[30:31], v[86:87], v[188:189]
	v_pk_fma_f32 v[190:191], v[26:27], v[86:87], v[190:191]
	v_add_f32_dpp v192, v192, v192 quad_perm:[2,3,0,1] row_mask:0xf bank_mask:0xf bound_ctrl:1
	v_add_f32_dpp v193, v193, v193 quad_perm:[2,3,0,1] row_mask:0xf bank_mask:0xf bound_ctrl:1
; __device__ __forceinline__ float red8(float v) { v = red4(v); v += dppf<0x141>(v); return v; }
; __device__ __forceinline__ f32x2 lo2(const f32x4& v) { return __builtin_shufflevector(v, v, 0, 1); }
; __device__ __forceinline__ f32x2 hi2(const f32x4& v) { return __builtin_shufflevector(v, v, 2, 3); }
; __device__ __forceinline__ f32x2 splat2(float x) { return (f32x2){x, x}; }
; #define SCAN_INTERLEAVE(nds, nvalu)                                   \
;   _Pragma("unroll") for (int i_ = 0; i_ < (nds); ++i_) {               \
;     __builtin_amdgcn_sched_group_barrier(0x100, 1, 0);                 \
;     __builtin_amdgcn_sched_group_barrier(0x002, (nvalu), 0);           \
;   }
; __device__ __forceinline__ f32x2 ss_step(f32x2 (&S)[2][8], const SsRegs& R) {
;   const f32x2 dA2 = splat2(R.sc.y);
;   f32x2 out;
; #pragma unroll
;   for (int r = 0; r < 2; ++r) {
;     const f32x2 xdt2 = splat2((r ? R.x.y : R.x.x) * R.sc.x);
;     f32x2 y0 = splat2(0.f), y1 = splat2(0.f);
; #pragma unroll
;     for (int q = 0; q < 4; ++q) {
;       S[r][2 * q] = S[r][2 * q] * dA2 + xdt2 * lo2(R.B[q]);
;       S[r][2 * q + 1] = S[r][2 * q + 1] * dA2 + xdt2 * hi2(R.B[q]);
;       y0 += S[r][2 * q] * lo2(R.C[q]);
;       y1 += S[r][2 * q + 1] * hi2(R.C[q]);
;     }
;     y0 += y1;
;     const float y = red8(y0.x + y0.y);
;     if (r) out.y = y; else out.x = y;
;   }
;   return out;
; }
; __device__ __forceinline__ void scan_ssm(const Params& p, int l, int seq, int h, char* smem, const unsigned* wflags, unsigned wexpect) {
;     ...
;     for (int t = 0; t < nsteps; t += 2) {
;       ss_load(RB, vb, sb, min(t + 1, 15), n0, prow0);
;       const f32x2 y0v = ss_step(S, RA);
;       *(f32x2*)((part == 0) ? (yb + t * 64 + prow0) : ydummy) = y0v;
;       SCAN_INTERLEAVE(10, 5);
;       if (t + 1 < nsteps) {
;         ss_load(RA, vb, sb, min(t + 2, 15), n0, prow0);
;         const f32x2 y1v = ss_step(S, RB);
;         *(f32x2*)((part == 0) ? (yb + (t + 1) * 64 + prow0) : ydummy) = y1v;
;         SCAN_INTERLEAVE(10, 5);
;       }
	v_pk_mul_f32 v[116:117], v[156:157], v[64:65] op_sel_hi:[0,1]
	v_pk_mul_f32 v[118:119], v[156:157], v[64:65] op_sel:[1,0]
	v_pk_fma_f32 v[12:13], v[12:13], v[110:111], v[116:117] op_sel:[0,1,0]
	v_pk_fma_f32 v[32:33], v[32:33], v[110:111], v[118:119] op_sel:[0,1,0]
	v_pk_fma_f32 v[188:189], v[12:13], v[88:89], v[188:189]
	v_pk_fma_f32 v[190:191], v[32:33], v[88:89], v[190:191]
	v_add_f32_dpp v192, v192, v192 row_half_mirror row_mask:0xf bank_mask:0xf bound_ctrl:1
	v_add_f32_dpp v193, v193, v193 row_half_mirror row_mask:0xf bank_mask:0xf bound_ctrl:1
	v_pk_mul_f32 v[120:121], v[156:157], v[66:67] op_sel_hi:[0,1]
	v_pk_mul_f32 v[122:123], v[156:157], v[66:67] op_sel:[1,0]
	v_pk_fma_f32 v[14:15], v[14:15], v[110:111], v[120:121] op_sel:[0,1,0]
	v_pk_fma_f32 v[34:35], v[34:35], v[110:111], v[122:123] op_sel:[0,1,0]
	v_pk_fma_f32 v[188:189], v[14:15], v[90:91], v[188:189]
	v_pk_fma_f32 v[190:191], v[34:35], v[90:91], v[190:191]
	ds_read_b128 v[60:63], v150 offset:11520
	ds_read_b128 v[84:87], v150 offset:12032
	ds_read_b128 v[64:67], v151 offset:11536
	ds_read_b128 v[88:91], v151 offset:12048
	ds_write_b64 v154, v[192:193] offset:1792
	v_pk_mul_f32 v[116:117], v[156:157], v[68:69] op_sel_hi:[0,1]
	v_pk_mul_f32 v[118:119], v[156:157], v[68:69] op_sel:[1,0]
	v_pk_fma_f32 v[8:9], v[8:9], v[110:111], v[116:117] op_sel:[0,1,0]
	v_pk_fma_f32 v[20:21], v[20:21], v[110:111], v[118:119] op_sel:[0,1,0]
	v_pk_fma_f32 v[188:189], v[8:9], v[92:93], v[188:189]
	v_pk_fma_f32 v[190:191], v[20:21], v[92:93], v[190:191]
	v_pk_mul_f32 v[120:121], v[156:157], v[70:71] op_sel_hi:[0,1]
	v_pk_mul_f32 v[122:123], v[156:157], v[70:71] op_sel:[1,0]
	v_pk_fma_f32 v[10:11], v[10:11], v[110:111], v[120:121] op_sel:[0,1,0]
	v_pk_fma_f32 v[22:23], v[22:23], v[110:111], v[122:123] op_sel:[0,1,0]
	v_pk_fma_f32 v[188:189], v[10:11], v[94:95], v[188:189]
	v_pk_fma_f32 v[190:191], v[22:23], v[94:95], v[190:191]
	v_pk_mul_f32 v[116:117], v[156:157], v[76:77] op_sel_hi:[0,1]
	v_pk_mul_f32 v[118:119], v[156:157], v[76:77] op_sel:[1,0]
	v_pk_fma_f32 v[4:5], v[4:5], v[110:111], v[116:117] op_sel:[0,1,0]
	v_pk_fma_f32 v[16:17], v[16:17], v[110:111], v[118:119] op_sel:[0,1,0]
	v_pk_fma_f32 v[188:189], v[4:5], v[100:101], v[188:189]
	v_pk_fma_f32 v[190:191], v[16:17], v[100:101], v[190:191]
	v_pk_mul_f32 v[120:121], v[156:157], v[78:79] op_sel_hi:[0,1]
	v_pk_mul_f32 v[122:123], v[156:157], v[78:79] op_sel:[1,0]
	v_pk_fma_f32 v[6:7], v[6:7], v[110:111], v[120:121] op_sel:[0,1,0]
	v_pk_fma_f32 v[18:19], v[18:19], v[110:111], v[122:123] op_sel:[0,1,0]
	v_pk_fma_f32 v[188:189], v[6:7], v[102:103], v[188:189]
	v_pk_fma_f32 v[190:191], v[18:19], v[102:103], v[190:191]
	v_add_f32_e64 v192, v188, v189
	v_add_f32_e64 v193, v190, v191
	s_waitcnt lgkmcnt(0)
	s_nop 0
	ds_read_b64 v[108:109], v152 offset:13824
	ds_read_b64 v[110:111], v153 offset:41040
	ds_read_b128 v[68:71], v150 offset:12832
	ds_read_b128 v[92:95], v150 offset:13344
	ds_read_b128 v[76:79], v151 offset:12848
	ds_read_b128 v[100:103], v151 offset:13360
	v_pk_mul_f32 v[156:157], v[112:113], v[114:115] op_sel_hi:[1,0]
	v_pk_mul_f32 v[116:117], v[156:157], v[60:61] op_sel_hi:[0,1]
	v_pk_mul_f32 v[118:119], v[156:157], v[60:61] op_sel:[1,0]
	v_pk_fma_f32 v[28:29], v[28:29], v[114:115], v[116:117] op_sel:[0,1,0]
	v_pk_fma_f32 v[24:25], v[24:25], v[114:115], v[118:119] op_sel:[0,1,0]
	v_pk_mul_f32 v[188:189], v[28:29], v[84:85]
	v_pk_mul_f32 v[190:191], v[24:25], v[84:85]
	v_add_f32_dpp v192, v192, v192 quad_perm:[1,0,3,2] row_mask:0xf bank_mask:0xf bound_ctrl:1
	v_add_f32_dpp v193, v193, v193 quad_perm:[1,0,3,2] row_mask:0xf bank_mask:0xf bound_ctrl:1
	v_pk_mul_f32 v[120:121], v[156:157], v[62:63] op_sel_hi:[0,1]
	v_pk_mul_f32 v[122:123], v[156:157], v[62:63] op_sel:[1,0]
	v_pk_fma_f32 v[30:31], v[30:31], v[114:115], v[120:121] op_sel:[0,1,0]
	v_pk_fma_f32 v[26:27], v[26:27], v[114:115], v[122:123] op_sel:[0,1,0]
	v_pk_fma_f32 v[188:189], v[30:31], v[86:87], v[188:189]
	v_pk_fma_f32 v[190:191], v[26:27], v[86:87], v[190:191]
	v_add_f32_dpp v192, v192, v192 quad_perm:[2,3,0,1] row_mask:0xf bank_mask:0xf bound_ctrl:1
	v_add_f32_dpp v193, v193, v193 quad_perm:[2,3,0,1] row_mask:0xf bank_mask:0xf bound_ctrl:1
	v_pk_mul_f32 v[116:117], v[156:157], v[64:65] op_sel_hi:[0,1]
	v_pk_mul_f32 v[118:119], v[156:157], v[64:65] op_sel:[1,0]
	v_pk_fma_f32 v[12:13], v[12:13], v[114:115], v[116:117] op_sel:[0,1,0]
	v_pk_fma_f32 v[32:33], v[32:33], v[114:115], v[118:119] op_sel:[0,1,0]
	v_pk_fma_f32 v[188:189], v[12:13], v[88:89], v[188:189]
	v_pk_fma_f32 v[190:191], v[32:33], v[88:89], v[190:191]
	v_add_f32_dpp v192, v192, v192 row_half_mirror row_mask:0xf bank_mask:0xf bound_ctrl:1
	v_add_f32_dpp v193, v193, v193 row_half_mirror row_mask:0xf bank_mask:0xf bound_ctrl:1
	v_pk_mul_f32 v[120:121], v[156:157], v[66:67] op_sel_hi:[0,1]
	v_pk_mul_f32 v[122:123], v[156:157], v[66:67] op_sel:[1,0]
	v_pk_fma_f32 v[14:15], v[14:15], v[114:115], v[120:121] op_sel:[0,1,0]
	v_pk_fma_f32 v[34:35], v[34:35], v[114:115], v[122:123] op_sel:[0,1,0]
	v_pk_fma_f32 v[188:189], v[14:15], v[90:91], v[188:189]
	v_pk_fma_f32 v[190:191], v[34:35], v[90:91], v[190:191]
	ds_read_b128 v[60:63], v150 offset:12800
	ds_read_b128 v[84:87], v150 offset:13312
	ds_read_b128 v[64:67], v151 offset:12816
	ds_read_b128 v[88:91], v151 offset:13328
	ds_write_b64 v154, v[192:193] offset:2048
	v_pk_mul_f32 v[116:117], v[156:157], v[72:73] op_sel_hi:[0,1]
	v_pk_mul_f32 v[118:119], v[156:157], v[72:73] op_sel:[1,0]
	v_pk_fma_f32 v[8:9], v[8:9], v[114:115], v[116:117] op_sel:[0,1,0]
	v_pk_fma_f32 v[20:21], v[20:21], v[114:115], v[118:119] op_sel:[0,1,0]
	v_pk_fma_f32 v[188:189], v[8:9], v[96:97], v[188:189]
	v_pk_fma_f32 v[190:191], v[20:21], v[96:97], v[190:191]
	v_pk_mul_f32 v[120:121], v[156:157], v[74:75] op_sel_hi:[0,1]
	v_pk_mul_f32 v[122:123], v[156:157], v[74:75] op_sel:[1,0]
	v_pk_fma_f32 v[10:11], v[10:11], v[114:115], v[120:121] op_sel:[0,1,0]
	v_pk_fma_f32 v[22:23], v[22:23], v[114:115], v[122:123] op_sel:[0,1,0]
	v_pk_fma_f32 v[188:189], v[10:11], v[98:99], v[188:189]
	v_pk_fma_f32 v[190:191], v[22:23], v[98:99], v[190:191]
	v_pk_mul_f32 v[116:117], v[156:157], v[80:81] op_sel_hi:[0,1]
	v_pk_mul_f32 v[118:119], v[156:157], v[80:81] op_sel:[1,0]
	v_pk_fma_f32 v[4:5], v[4:5], v[114:115], v[116:117] op_sel:[0,1,0]
	v_pk_fma_f32 v[16:17], v[16:17], v[114:115], v[118:119] op_sel:[0,1,0]
	v_pk_fma_f32 v[188:189], v[4:5], v[104:105], v[188:189]
	v_pk_fma_f32 v[190:191], v[16:17], v[104:105], v[190:191]
	v_pk_mul_f32 v[120:121], v[156:157], v[82:83] op_sel_hi:[0,1]
	v_pk_mul_f32 v[122:123], v[156:157], v[82:83] op_sel:[1,0]
	v_pk_fma_f32 v[6:7], v[6:7], v[114:115], v[120:121] op_sel:[0,1,0]
	v_pk_fma_f32 v[18:19], v[18:19], v[114:115], v[122:123] op_sel:[0,1,0]
	v_pk_fma_f32 v[188:189], v[6:7], v[106:107], v[188:189]
	v_pk_fma_f32 v[190:191], v[18:19], v[106:107], v[190:191]
	v_add_f32_e64 v192, v188, v189
	v_add_f32_e64 v193, v190, v191
	s_waitcnt lgkmcnt(0)
; __device__ __forceinline__ float red8(float v) { v = red4(v); v += dppf<0x141>(v); return v; }
; __device__ __forceinline__ f32x2 lo2(const f32x4& v) { return __builtin_shufflevector(v, v, 0, 1); }
; __device__ __forceinline__ f32x2 hi2(const f32x4& v) { return __builtin_shufflevector(v, v, 2, 3); }
; __device__ __forceinline__ f32x2 splat2(float x) { return (f32x2){x, x}; }
; #define SCAN_INTERLEAVE(nds, nvalu)                                   \
;   _Pragma("unroll") for (int i_ = 0; i_ < (nds); ++i_) {               \
;     __builtin_amdgcn_sched_group_barrier(0x100, 1, 0);                 \
;     __builtin_amdgcn_sched_group_barrier(0x002, (nvalu), 0);           \
;   }
; __device__ __forceinline__ f32x2 ss_step(f32x2 (&S)[2][8], const SsRegs& R) {
;   const f32x2 dA2 = splat2(R.sc.y);
;   f32x2 out;
; #pragma unroll
;   for (int r = 0; r < 2; ++r) {
;     const f32x2 xdt2 = splat2((r ? R.x.y : R.x.x) * R.sc.x);
;     f32x2 y0 = splat2(0.f), y1 = splat2(0.f);
; #pragma unroll
;     for (int q = 0; q < 4; ++q) {
;       S[r][2 * q] = S[r][2 * q] * dA2 + xdt2 * lo2(R.B[q]);
;       S[r][2 * q + 1] = S[r][2 * q + 1] * dA2 + xdt2 * hi2(R.B[q]);
;       y0 += S[r][2 * q] * lo2(R.C[q]);
;       y1 += S[r][2 * q + 1] * hi2(R.C[q]);
;     }
;     y0 += y1;
;     const float y = red8(y0.x + y0.y);
;     if (r) out.y = y; else out.x = y;
;   }
;   return out;
; }
; __device__ __forceinline__ void scan_ssm(const Params& p, int l, int seq, int h, char* smem, const unsigned* wflags, unsigned wexpect) {
;     ...
;     for (int t = 0; t < nsteps; t += 2) {
;       ss_load(RB, vb, sb, min(t + 1, 15), n0, prow0);
;       const f32x2 y0v = ss_step(S, RA);
;       *(f32x2*)((part == 0) ? (yb + t * 64 + prow0) : ydummy) = y0v;
;       SCAN_INTERLEAVE(10, 5);
;       if (t + 1 < nsteps) {
;         ss_load(RA, vb, sb, min(t + 2, 15), n0, prow0);
;         const f32x2 y1v = ss_step(S, RB);
;         *(f32x2*)((part == 0) ? (yb + (t + 1) * 64 + prow0) : ydummy) = y1v;
;         SCAN_INTERLEAVE(10, 5);
;       }
	s_nop 0
	ds_read_b64 v[112:113], v152 offset:15104
	ds_read_b64 v[114:115], v153 offset:41048
	ds_read_b128 v[72:75], v150 offset:14112
	ds_read_b128 v[96:99], v150 offset:14624
	ds_read_b128 v[80:83], v151 offset:14128
	ds_read_b128 v[104:107], v151 offset:14640
	v_pk_mul_f32 v[156:157], v[108:109], v[110:111] op_sel_hi:[1,0]
	v_pk_mul_f32 v[116:117], v[156:157], v[60:61] op_sel_hi:[0,1]
	v_pk_mul_f32 v[118:119], v[156:157], v[60:61] op_sel:[1,0]
	v_pk_fma_f32 v[28:29], v[28:29], v[110:111], v[116:117] op_sel:[0,1,0]
	v_pk_fma_f32 v[24:25], v[24:25], v[110:111], v[118:119] op_sel:[0,1,0]
	v_pk_mul_f32 v[188:189], v[28:29], v[84:85]
	v_pk_mul_f32 v[190:191], v[24:25], v[84:85]
	v_add_f32_dpp v192, v192, v192 quad_perm:[1,0,3,2] row_mask:0xf bank_mask:0xf bound_ctrl:1
	v_add_f32_dpp v193, v193, v193 quad_perm:[1,0,3,2] row_mask:0xf bank_mask:0xf bound_ctrl:1
	v_pk_mul_f32 v[120:121], v[156:157], v[62:63] op_sel_hi:[0,1]
	v_pk_mul_f32 v[122:123], v[156:157], v[62:63] op_sel:[1,0]
	v_pk_fma_f32 v[30:31], v[30:31], v[110:111], v[120:121] op_sel:[0,1,0]
	v_pk_fma_f32 v[26:27], v[26:27], v[110:111], v[122:123] op_sel:[0,1,0]
	v_pk_fma_f32 v[188:189], v[30:31], v[86:87], v[188:189]
	v_pk_fma_f32 v[190:191], v[26:27], v[86:87], v[190:191]
	v_add_f32_dpp v192, v192, v192 quad_perm:[2,3,0,1] row_mask:0xf bank_mask:0xf bound_ctrl:1
	v_add_f32_dpp v193, v193, v193 quad_perm:[2,3,0,1] row_mask:0xf bank_mask:0xf bound_ctrl:1
	v_pk_mul_f32 v[116:117], v[156:157], v[64:65] op_sel_hi:[0,1]
	v_pk_mul_f32 v[118:119], v[156:157], v[64:65] op_sel:[1,0]
	v_pk_fma_f32 v[12:13], v[12:13], v[110:111], v[116:117] op_sel:[0,1,0]
	v_pk_fma_f32 v[32:33], v[32:33], v[110:111], v[118:119] op_sel:[0,1,0]
	v_pk_fma_f32 v[188:189], v[12:13], v[88:89], v[188:189]
	v_pk_fma_f32 v[190:191], v[32:33], v[88:89], v[190:191]
	v_add_f32_dpp v192, v192, v192 row_half_mirror row_mask:0xf bank_mask:0xf bound_ctrl:1
	v_add_f32_dpp v193, v193, v193 row_half_mirror row_mask:0xf bank_mask:0xf bound_ctrl:1
	v_pk_mul_f32 v[120:121], v[156:157], v[66:67] op_sel_hi:[0,1]
	v_pk_mul_f32 v[122:123], v[156:157], v[66:67] op_sel:[1,0]
	v_pk_fma_f32 v[14:15], v[14:15], v[110:111], v[120:121] op_sel:[0,1,0]
	v_pk_fma_f32 v[34:35], v[34:35], v[110:111], v[122:123] op_sel:[0,1,0]
	v_pk_fma_f32 v[188:189], v[14:15], v[90:91], v[188:189]
	v_pk_fma_f32 v[190:191], v[34:35], v[90:91], v[190:191]
	ds_read_b128 v[60:63], v150 offset:14080
	ds_read_b128 v[84:87], v150 offset:14592
	ds_read_b128 v[64:67], v151 offset:14096
	ds_read_b128 v[88:91], v151 offset:14608
	ds_write_b64 v154, v[192:193] offset:2304
	v_pk_mul_f32 v[116:117], v[156:157], v[68:69] op_sel_hi:[0,1]
	v_pk_mul_f32 v[118:119], v[156:157], v[68:69] op_sel:[1,0]
	v_pk_fma_f32 v[8:9], v[8:9], v[110:111], v[116:117] op_sel:[0,1,0]
	v_pk_fma_f32 v[20:21], v[20:21], v[110:111], v[118:119] op_sel:[0,1,0]
	v_pk_fma_f32 v[188:189], v[8:9], v[92:93], v[188:189]
	v_pk_fma_f32 v[190:191], v[20:21], v[92:93], v[190:191]
	v_pk_mul_f32 v[120:121], v[156:157], v[70:71] op_sel_hi:[0,1]
	v_pk_mul_f32 v[122:123], v[156:157], v[70:71] op_sel:[1,0]
	v_pk_fma_f32 v[10:11], v[10:11], v[110:111], v[120:121] op_sel:[0,1,0]
	v_pk_fma_f32 v[22:23], v[22:23], v[110:111], v[122:123] op_sel:[0,1,0]
	v_pk_fma_f32 v[188:189], v[10:11], v[94:95], v[188:189]
	v_pk_fma_f32 v[190:191], v[22:23], v[94:95], v[190:191]
	v_pk_mul_f32 v[116:117], v[156:157], v[76:77] op_sel_hi:[0,1]
	v_pk_mul_f32 v[118:119], v[156:157], v[76:77] op_sel:[1,0]
	v_pk_fma_f32 v[4:5], v[4:5], v[110:111], v[116:117] op_sel:[0,1,0]
	v_pk_fma_f32 v[16:17], v[16:17], v[110:111], v[118:119] op_sel:[0,1,0]
	v_pk_fma_f32 v[188:189], v[4:5], v[100:101], v[188:189]
	v_pk_fma_f32 v[190:191], v[16:17], v[100:101], v[190:191]
	v_pk_mul_f32 v[120:121], v[156:157], v[78:79] op_sel_hi:[0,1]
	v_pk_mul_f32 v[122:123], v[156:157], v[78:79] op_sel:[1,0]
	v_pk_fma_f32 v[6:7], v[6:7], v[110:111], v[120:121] op_sel:[0,1,0]
	v_pk_fma_f32 v[18:19], v[18:19], v[110:111], v[122:123] op_sel:[0,1,0]
	v_pk_fma_f32 v[188:189], v[6:7], v[102:103], v[188:189]
	v_pk_fma_f32 v[190:191], v[18:19], v[102:103], v[190:191]
	v_add_f32_e64 v192, v188, v189
	v_add_f32_e64 v193, v190, v191
	s_waitcnt lgkmcnt(0)
	s_nop 0
	ds_read_b64 v[108:109], v152 offset:16384
	ds_read_b64 v[110:111], v153 offset:41056
	ds_read_b128 v[68:71], v150 offset:15392
	ds_read_b128 v[92:95], v150 offset:15904
	ds_read_b128 v[76:79], v151 offset:15408
	ds_read_b128 v[100:103], v151 offset:15920
	v_pk_mul_f32 v[156:157], v[112:113], v[114:115] op_sel_hi:[1,0]
	v_pk_mul_f32 v[116:117], v[156:157], v[60:61] op_sel_hi:[0,1]
	v_pk_mul_f32 v[118:119], v[156:157], v[60:61] op_sel:[1,0]
	v_pk_fma_f32 v[28:29], v[28:29], v[114:115], v[116:117] op_sel:[0,1,0]
	v_pk_fma_f32 v[24:25], v[24:25], v[114:115], v[118:119] op_sel:[0,1,0]
	v_pk_mul_f32 v[188:189], v[28:29], v[84:85]
	v_pk_mul_f32 v[190:191], v[24:25], v[84:85]
	v_add_f32_dpp v192, v192, v192 quad_perm:[1,0,3,2] row_mask:0xf bank_mask:0xf bound_ctrl:1
	v_add_f32_dpp v193, v193, v193 quad_perm:[1,0,3,2] row_mask:0xf bank_mask:0xf bound_ctrl:1
	v_pk_mul_f32 v[120:121], v[156:157], v[62:63] op_sel_hi:[0,1]
	v_pk_mul_f32 v[122:123], v[156:157], v[62:63] op_sel:[1,0]
	v_pk_fma_f32 v[30:31], v[30:31], v[114:115], v[120:121] op_sel:[0,1,0]
	v_pk_fma_f32 v[26:27], v[26:27], v[114:115], v[122:123] op_sel:[0,1,0]
	v_pk_fma_f32 v[188:189], v[30:31], v[86:87], v[188:189]
	v_pk_fma_f32 v[190:191], v[26:27], v[86:87], v[190:191]
	v_add_f32_dpp v192, v192, v192 quad_perm:[2,3,0,1] row_mask:0xf bank_mask:0xf bound_ctrl:1
	v_add_f32_dpp v193, v193, v193 quad_perm:[2,3,0,1] row_mask:0xf bank_mask:0xf bound_ctrl:1
; __device__ __forceinline__ float red8(float v) { v = red4(v); v += dppf<0x141>(v); return v; }
; __device__ __forceinline__ f32x2 lo2(const f32x4& v) { return __builtin_shufflevector(v, v, 0, 1); }
; __device__ __forceinline__ f32x2 hi2(const f32x4& v) { return __builtin_shufflevector(v, v, 2, 3); }
; __device__ __forceinline__ f32x2 splat2(float x) { return (f32x2){x, x}; }
; #define SCAN_INTERLEAVE(nds, nvalu)                                   \
;   _Pragma("unroll") for (int i_ = 0; i_ < (nds); ++i_) {               \
;     __builtin_amdgcn_sched_group_barrier(0x100, 1, 0);                 \
;     __builtin_amdgcn_sched_group_barrier(0x002, (nvalu), 0);           \
;   }
; __device__ __forceinline__ f32x2 ss_step(f32x2 (&S)[2][8], const SsRegs& R) {
;   const f32x2 dA2 = splat2(R.sc.y);
;   f32x2 out;
; #pragma unroll
;   for (int r = 0; r < 2; ++r) {
;     const f32x2 xdt2 = splat2((r ? R.x.y : R.x.x) * R.sc.x);
;     f32x2 y0 = splat2(0.f), y1 = splat2(0.f);
; #pragma unroll
;     for (int q = 0; q < 4; ++q) {
;       S[r][2 * q] = S[r][2 * q] * dA2 + xdt2 * lo2(R.B[q]);
;       S[r][2 * q + 1] = S[r][2 * q + 1] * dA2 + xdt2 * hi2(R.B[q]);
;       y0 += S[r][2 * q] * lo2(R.C[q]);
;       y1 += S[r][2 * q + 1] * hi2(R.C[q]);
;     }
;     y0 += y1;
;     const float y = red8(y0.x + y0.y);
;     if (r) out.y = y; else out.x = y;
;   }
;   return out;
; }
; __device__ __forceinline__ void scan_ssm(const Params& p, int l, int seq, int h, char* smem, const unsigned* wflags, unsigned wexpect) {
;     ...
;     for (int t = 0; t < nsteps; t += 2) {
;       ss_load(RB, vb, sb, min(t + 1, 15), n0, prow0);
;       const f32x2 y0v = ss_step(S, RA);
;       *(f32x2*)((part == 0) ? (yb + t * 64 + prow0) : ydummy) = y0v;
;       SCAN_INTERLEAVE(10, 5);
;       if (t + 1 < nsteps) {
;         ss_load(RA, vb, sb, min(t + 2, 15), n0, prow0);
;         const f32x2 y1v = ss_step(S, RB);
;         *(f32x2*)((part == 0) ? (yb + (t + 1) * 64 + prow0) : ydummy) = y1v;
;         SCAN_INTERLEAVE(10, 5);
;       }
	v_pk_mul_f32 v[116:117], v[156:157], v[64:65] op_sel_hi:[0,1]
	v_pk_mul_f32 v[118:119], v[156:157], v[64:65] op_sel:[1,0]
	v_pk_fma_f32 v[12:13], v[12:13], v[114:115], v[116:117] op_sel:[0,1,0]
	v_pk_fma_f32 v[32:33], v[32:33], v[114:115], v[118:119] op_sel:[0,1,0]
	v_pk_fma_f32 v[188:189], v[12:13], v[88:89], v[188:189]
	v_pk_fma_f32 v[190:191], v[32:33], v[88:89], v[190:191]
	v_add_f32_dpp v192, v192, v192 row_half_mirror row_mask:0xf bank_mask:0xf bound_ctrl:1
	v_add_f32_dpp v193, v193, v193 row_half_mirror row_mask:0xf bank_mask:0xf bound_ctrl:1
	v_pk_mul_f32 v[120:121], v[156:157], v[66:67] op_sel_hi:[0,1]
	v_pk_mul_f32 v[122:123], v[156:157], v[66:67] op_sel:[1,0]
	v_pk_fma_f32 v[14:15], v[14:15], v[114:115], v[120:121] op_sel:[0,1,0]
	v_pk_fma_f32 v[34:35], v[34:35], v[114:115], v[122:123] op_sel:[0,1,0]
	v_pk_fma_f32 v[188:189], v[14:15], v[90:91], v[188:189]
	v_pk_fma_f32 v[190:191], v[34:35], v[90:91], v[190:191]
	ds_read_b128 v[60:63], v150 offset:15360
	ds_read_b128 v[84:87], v150 offset:15872
	ds_read_b128 v[64:67], v151 offset:15376
	ds_read_b128 v[88:91], v151 offset:15888
	ds_write_b64 v154, v[192:193] offset:2560
	v_pk_mul_f32 v[116:117], v[156:157], v[72:73] op_sel_hi:[0,1]
	v_pk_mul_f32 v[118:119], v[156:157], v[72:73] op_sel:[1,0]
	v_pk_fma_f32 v[8:9], v[8:9], v[114:115], v[116:117] op_sel:[0,1,0]
	v_pk_fma_f32 v[20:21], v[20:21], v[114:115], v[118:119] op_sel:[0,1,0]
	v_pk_fma_f32 v[188:189], v[8:9], v[96:97], v[188:189]
	v_pk_fma_f32 v[190:191], v[20:21], v[96:97], v[190:191]
	v_pk_mul_f32 v[120:121], v[156:157], v[74:75] op_sel_hi:[0,1]
	v_pk_mul_f32 v[122:123], v[156:157], v[74:75] op_sel:[1,0]
	v_pk_fma_f32 v[10:11], v[10:11], v[114:115], v[120:121] op_sel:[0,1,0]
	v_pk_fma_f32 v[22:23], v[22:23], v[114:115], v[122:123] op_sel:[0,1,0]
	v_pk_fma_f32 v[188:189], v[10:11], v[98:99], v[188:189]
	v_pk_fma_f32 v[190:191], v[22:23], v[98:99], v[190:191]
	v_pk_mul_f32 v[116:117], v[156:157], v[80:81] op_sel_hi:[0,1]
	v_pk_mul_f32 v[118:119], v[156:157], v[80:81] op_sel:[1,0]
	v_pk_fma_f32 v[4:5], v[4:5], v[114:115], v[116:117] op_sel:[0,1,0]
	v_pk_fma_f32 v[16:17], v[16:17], v[114:115], v[118:119] op_sel:[0,1,0]
	v_pk_fma_f32 v[188:189], v[4:5], v[104:105], v[188:189]
	v_pk_fma_f32 v[190:191], v[16:17], v[104:105], v[190:191]
	v_pk_mul_f32 v[120:121], v[156:157], v[82:83] op_sel_hi:[0,1]
	v_pk_mul_f32 v[122:123], v[156:157], v[82:83] op_sel:[1,0]
	v_pk_fma_f32 v[6:7], v[6:7], v[114:115], v[120:121] op_sel:[0,1,0]
	v_pk_fma_f32 v[18:19], v[18:19], v[114:115], v[122:123] op_sel:[0,1,0]
	v_pk_fma_f32 v[188:189], v[6:7], v[106:107], v[188:189]
	v_pk_fma_f32 v[190:191], v[18:19], v[106:107], v[190:191]
	v_add_f32_e64 v192, v188, v189
	v_add_f32_e64 v193, v190, v191
	s_waitcnt lgkmcnt(0)
	s_nop 0
	ds_read_b64 v[112:113], v152 offset:17664
	ds_read_b64 v[114:115], v153 offset:41064
	ds_read_b128 v[72:75], v150 offset:16672
	ds_read_b128 v[96:99], v150 offset:17184
	ds_read_b128 v[80:83], v151 offset:16688
	ds_read_b128 v[104:107], v151 offset:17200
	v_pk_mul_f32 v[156:157], v[108:109], v[110:111] op_sel_hi:[1,0]
	v_pk_mul_f32 v[116:117], v[156:157], v[60:61] op_sel_hi:[0,1]
	v_pk_mul_f32 v[118:119], v[156:157], v[60:61] op_sel:[1,0]
	v_pk_fma_f32 v[28:29], v[28:29], v[110:111], v[116:117] op_sel:[0,1,0]
	v_pk_fma_f32 v[24:25], v[24:25], v[110:111], v[118:119] op_sel:[0,1,0]
	v_pk_mul_f32 v[188:189], v[28:29], v[84:85]
	v_pk_mul_f32 v[190:191], v[24:25], v[84:85]
	v_add_f32_dpp v192, v192, v192 quad_perm:[1,0,3,2] row_mask:0xf bank_mask:0xf bound_ctrl:1
	v_add_f32_dpp v193, v193, v193 quad_perm:[1,0,3,2] row_mask:0xf bank_mask:0xf bound_ctrl:1
	v_pk_mul_f32 v[120:121], v[156:157], v[62:63] op_sel_hi:[0,1]
	v_pk_mul_f32 v[122:123], v[156:157], v[62:63] op_sel:[1,0]
	v_pk_fma_f32 v[30:31], v[30:31], v[110:111], v[120:121] op_sel:[0,1,0]
	v_pk_fma_f32 v[26:27], v[26:27], v[110:111], v[122:123] op_sel:[0,1,0]
	v_pk_fma_f32 v[188:189], v[30:31], v[86:87], v[188:189]
	v_pk_fma_f32 v[190:191], v[26:27], v[86:87], v[190:191]
	v_add_f32_dpp v192, v192, v192 quad_perm:[2,3,0,1] row_mask:0xf bank_mask:0xf bound_ctrl:1
	v_add_f32_dpp v193, v193, v193 quad_perm:[2,3,0,1] row_mask:0xf bank_mask:0xf bound_ctrl:1
	v_pk_mul_f32 v[116:117], v[156:157], v[64:65] op_sel_hi:[0,1]
	v_pk_mul_f32 v[118:119], v[156:157], v[64:65] op_sel:[1,0]
	v_pk_fma_f32 v[12:13], v[12:13], v[110:111], v[116:117] op_sel:[0,1,0]
	v_pk_fma_f32 v[32:33], v[32:33], v[110:111], v[118:119] op_sel:[0,1,0]
	v_pk_fma_f32 v[188:189], v[12:13], v[88:89], v[188:189]
	v_pk_fma_f32 v[190:191], v[32:33], v[88:89], v[190:191]
	v_add_f32_dpp v192, v192, v192 row_half_mirror row_mask:0xf bank_mask:0xf bound_ctrl:1
	v_add_f32_dpp v193, v193, v193 row_half_mirror row_mask:0xf bank_mask:0xf bound_ctrl:1
	v_pk_mul_f32 v[120:121], v[156:157], v[66:67] op_sel_hi:[0,1]
	v_pk_mul_f32 v[122:123], v[156:157], v[66:67] op_sel:[1,0]
	v_pk_fma_f32 v[14:15], v[14:15], v[110:111], v[120:121] op_sel:[0,1,0]
	v_pk_fma_f32 v[34:35], v[34:35], v[110:111], v[122:123] op_sel:[0,1,0]
	v_pk_fma_f32 v[188:189], v[14:15], v[90:91], v[188:189]
	v_pk_fma_f32 v[190:191], v[34:35], v[90:91], v[190:191]
	ds_read_b128 v[60:63], v150 offset:16640
	ds_read_b128 v[84:87], v150 offset:17152
	ds_read_b128 v[64:67], v151 offset:16656
	ds_read_b128 v[88:91], v151 offset:17168
	ds_write_b64 v154, v[192:193] offset:2816
	v_pk_mul_f32 v[116:117], v[156:157], v[68:69] op_sel_hi:[0,1]
	v_pk_mul_f32 v[118:119], v[156:157], v[68:69] op_sel:[1,0]
	v_pk_fma_f32 v[8:9], v[8:9], v[110:111], v[116:117] op_sel:[0,1,0]
	v_pk_fma_f32 v[20:21], v[20:21], v[110:111], v[118:119] op_sel:[0,1,0]
	v_pk_fma_f32 v[188:189], v[8:9], v[92:93], v[188:189]
	v_pk_fma_f32 v[190:191], v[20:21], v[92:93], v[190:191]
	v_pk_mul_f32 v[120:121], v[156:157], v[70:71] op_sel_hi:[0,1]
	v_pk_mul_f32 v[122:123], v[156:157], v[70:71] op_sel:[1,0]
	v_pk_fma_f32 v[10:11], v[10:11], v[110:111], v[120:121] op_sel:[0,1,0]
	v_pk_fma_f32 v[22:23], v[22:23], v[110:111], v[122:123] op_sel:[0,1,0]
	v_pk_fma_f32 v[188:189], v[10:11], v[94:95], v[188:189]
	v_pk_fma_f32 v[190:191], v[22:23], v[94:95], v[190:191]
	v_pk_mul_f32 v[116:117], v[156:157], v[76:77] op_sel_hi:[0,1]
	v_pk_mul_f32 v[118:119], v[156:157], v[76:77] op_sel:[1,0]
	v_pk_fma_f32 v[4:5], v[4:5], v[110:111], v[116:117] op_sel:[0,1,0]
	v_pk_fma_f32 v[16:17], v[16:17], v[110:111], v[118:119] op_sel:[0,1,0]
	v_pk_fma_f32 v[188:189], v[4:5], v[100:101], v[188:189]
	v_pk_fma_f32 v[190:191], v[16:17], v[100:101], v[190:191]
	v_pk_mul_f32 v[120:121], v[156:157], v[78:79] op_sel_hi:[0,1]
	v_pk_mul_f32 v[122:123], v[156:157], v[78:79] op_sel:[1,0]
	v_pk_fma_f32 v[6:7], v[6:7], v[110:111], v[120:121] op_sel:[0,1,0]
	v_pk_fma_f32 v[18:19], v[18:19], v[110:111], v[122:123] op_sel:[0,1,0]
	v_pk_fma_f32 v[188:189], v[6:7], v[102:103], v[188:189]
	v_pk_fma_f32 v[190:191], v[18:19], v[102:103], v[190:191]
	v_add_f32_e64 v192, v188, v189
	v_add_f32_e64 v193, v190, v191
	s_waitcnt lgkmcnt(0)
; __device__ __forceinline__ float red8(float v) { v = red4(v); v += dppf<0x141>(v); return v; }
; __device__ __forceinline__ f32x2 lo2(const f32x4& v) { return __builtin_shufflevector(v, v, 0, 1); }
; __device__ __forceinline__ f32x2 hi2(const f32x4& v) { return __builtin_shufflevector(v, v, 2, 3); }
; __device__ __forceinline__ f32x2 splat2(float x) { return (f32x2){x, x}; }
; #define SCAN_INTERLEAVE(nds, nvalu)                                   \
;   _Pragma("unroll") for (int i_ = 0; i_ < (nds); ++i_) {               \
;     __builtin_amdgcn_sched_group_barrier(0x100, 1, 0);                 \
;     __builtin_amdgcn_sched_group_barrier(0x002, (nvalu), 0);           \
;   }
; __device__ __forceinline__ f32x2 ss_step(f32x2 (&S)[2][8], const SsRegs& R) {
;   const f32x2 dA2 = splat2(R.sc.y);
;   f32x2 out;
; #pragma unroll
;   for (int r = 0; r < 2; ++r) {
;     const f32x2 xdt2 = splat2((r ? R.x.y : R.x.x) * R.sc.x);
;     f32x2 y0 = splat2(0.f), y1 = splat2(0.f);
; #pragma unroll
;     for (int q = 0; q < 4; ++q) {
;       S[r][2 * q] = S[r][2 * q] * dA2 + xdt2 * lo2(R.B[q]);
;       S[r][2 * q + 1] = S[r][2 * q + 1] * dA2 + xdt2 * hi2(R.B[q]);
;       y0 += S[r][2 * q] * lo2(R.C[q]);
;       y1 += S[r][2 * q + 1] * hi2(R.C[q]);
;     }
;     y0 += y1;
;     const float y = red8(y0.x + y0.y);
;     if (r) out.y = y; else out.x = y;
;   }
;   return out;
; }
; __device__ __forceinline__ void scan_ssm(const Params& p, int l, int seq, int h, char* smem, const unsigned* wflags, unsigned wexpect) {
;     ...
;     for (int t = 0; t < nsteps; t += 2) {
;       ss_load(RB, vb, sb, min(t + 1, 15), n0, prow0);
;       const f32x2 y0v = ss_step(S, RA);
;       *(f32x2*)((part == 0) ? (yb + t * 64 + prow0) : ydummy) = y0v;
;       SCAN_INTERLEAVE(10, 5);
;       if (t + 1 < nsteps) {
;         ss_load(RA, vb, sb, min(t + 2, 15), n0, prow0);
;         const f32x2 y1v = ss_step(S, RB);
;         *(f32x2*)((part == 0) ? (yb + (t + 1) * 64 + prow0) : ydummy) = y1v;
;         SCAN_INTERLEAVE(10, 5);
;       }
	s_nop 0
	ds_read_b64 v[108:109], v152 offset:18944
	ds_read_b64 v[110:111], v153 offset:41072
	ds_read_b128 v[68:71], v150 offset:17952
	ds_read_b128 v[92:95], v150 offset:18464
	ds_read_b128 v[76:79], v151 offset:17968
	ds_read_b128 v[100:103], v151 offset:18480
	v_pk_mul_f32 v[156:157], v[112:113], v[114:115] op_sel_hi:[1,0]
	v_pk_mul_f32 v[116:117], v[156:157], v[60:61] op_sel_hi:[0,1]
	v_pk_mul_f32 v[118:119], v[156:157], v[60:61] op_sel:[1,0]
	v_pk_fma_f32 v[28:29], v[28:29], v[114:115], v[116:117] op_sel:[0,1,0]
	v_pk_fma_f32 v[24:25], v[24:25], v[114:115], v[118:119] op_sel:[0,1,0]
	v_pk_mul_f32 v[188:189], v[28:29], v[84:85]
	v_pk_mul_f32 v[190:191], v[24:25], v[84:85]
	v_add_f32_dpp v192, v192, v192 quad_perm:[1,0,3,2] row_mask:0xf bank_mask:0xf bound_ctrl:1
	v_add_f32_dpp v193, v193, v193 quad_perm:[1,0,3,2] row_mask:0xf bank_mask:0xf bound_ctrl:1
	v_pk_mul_f32 v[120:121], v[156:157], v[62:63] op_sel_hi:[0,1]
	v_pk_mul_f32 v[122:123], v[156:157], v[62:63] op_sel:[1,0]
	v_pk_fma_f32 v[30:31], v[30:31], v[114:115], v[120:121] op_sel:[0,1,0]
	v_pk_fma_f32 v[26:27], v[26:27], v[114:115], v[122:123] op_sel:[0,1,0]
	v_pk_fma_f32 v[188:189], v[30:31], v[86:87], v[188:189]
	v_pk_fma_f32 v[190:191], v[26:27], v[86:87], v[190:191]
	v_add_f32_dpp v192, v192, v192 quad_perm:[2,3,0,1] row_mask:0xf bank_mask:0xf bound_ctrl:1
	v_add_f32_dpp v193, v193, v193 quad_perm:[2,3,0,1] row_mask:0xf bank_mask:0xf bound_ctrl:1
	v_pk_mul_f32 v[116:117], v[156:157], v[64:65] op_sel_hi:[0,1]
	v_pk_mul_f32 v[118:119], v[156:157], v[64:65] op_sel:[1,0]
	v_pk_fma_f32 v[12:13], v[12:13], v[114:115], v[116:117] op_sel:[0,1,0]
	v_pk_fma_f32 v[32:33], v[32:33], v[114:115], v[118:119] op_sel:[0,1,0]
	v_pk_fma_f32 v[188:189], v[12:13], v[88:89], v[188:189]
	v_pk_fma_f32 v[190:191], v[32:33], v[88:89], v[190:191]
	v_add_f32_dpp v192, v192, v192 row_half_mirror row_mask:0xf bank_mask:0xf bound_ctrl:1
	v_add_f32_dpp v193, v193, v193 row_half_mirror row_mask:0xf bank_mask:0xf bound_ctrl:1
	v_pk_mul_f32 v[120:121], v[156:157], v[66:67] op_sel_hi:[0,1]
	v_pk_mul_f32 v[122:123], v[156:157], v[66:67] op_sel:[1,0]
	v_pk_fma_f32 v[14:15], v[14:15], v[114:115], v[120:121] op_sel:[0,1,0]
	v_pk_fma_f32 v[34:35], v[34:35], v[114:115], v[122:123] op_sel:[0,1,0]
	v_pk_fma_f32 v[188:189], v[14:15], v[90:91], v[188:189]
	v_pk_fma_f32 v[190:191], v[34:35], v[90:91], v[190:191]
	ds_read_b128 v[60:63], v150 offset:17920
	ds_read_b128 v[84:87], v150 offset:18432
	ds_read_b128 v[64:67], v151 offset:17936
	ds_read_b128 v[88:91], v151 offset:18448
	ds_write_b64 v154, v[192:193] offset:3072
	v_pk_mul_f32 v[116:117], v[156:157], v[72:73] op_sel_hi:[0,1]
	v_pk_mul_f32 v[118:119], v[156:157], v[72:73] op_sel:[1,0]
	v_pk_fma_f32 v[8:9], v[8:9], v[114:115], v[116:117] op_sel:[0,1,0]
	v_pk_fma_f32 v[20:21], v[20:21], v[114:115], v[118:119] op_sel:[0,1,0]
	v_pk_fma_f32 v[188:189], v[8:9], v[96:97], v[188:189]
	v_pk_fma_f32 v[190:191], v[20:21], v[96:97], v[190:191]
	v_pk_mul_f32 v[120:121], v[156:157], v[74:75] op_sel_hi:[0,1]
	v_pk_mul_f32 v[122:123], v[156:157], v[74:75] op_sel:[1,0]
	v_pk_fma_f32 v[10:11], v[10:11], v[114:115], v[120:121] op_sel:[0,1,0]
	v_pk_fma_f32 v[22:23], v[22:23], v[114:115], v[122:123] op_sel:[0,1,0]
	v_pk_fma_f32 v[188:189], v[10:11], v[98:99], v[188:189]
	v_pk_fma_f32 v[190:191], v[22:23], v[98:99], v[190:191]
	v_pk_mul_f32 v[116:117], v[156:157], v[80:81] op_sel_hi:[0,1]
	v_pk_mul_f32 v[118:119], v[156:157], v[80:81] op_sel:[1,0]
	v_pk_fma_f32 v[4:5], v[4:5], v[114:115], v[116:117] op_sel:[0,1,0]
	v_pk_fma_f32 v[16:17], v[16:17], v[114:115], v[118:119] op_sel:[0,1,0]
	v_pk_fma_f32 v[188:189], v[4:5], v[104:105], v[188:189]
	v_pk_fma_f32 v[190:191], v[16:17], v[104:105], v[190:191]
	v_pk_mul_f32 v[120:121], v[156:157], v[82:83] op_sel_hi:[0,1]
	v_pk_mul_f32 v[122:123], v[156:157], v[82:83] op_sel:[1,0]
	v_pk_fma_f32 v[6:7], v[6:7], v[114:115], v[120:121] op_sel:[0,1,0]
	v_pk_fma_f32 v[18:19], v[18:19], v[114:115], v[122:123] op_sel:[0,1,0]
	v_pk_fma_f32 v[188:189], v[6:7], v[106:107], v[188:189]
	v_pk_fma_f32 v[190:191], v[18:19], v[106:107], v[190:191]
	v_add_f32_e64 v192, v188, v189
	v_add_f32_e64 v193, v190, v191
	s_waitcnt lgkmcnt(0)
	s_nop 0
	ds_read_b64 v[112:113], v152 offset:20224
	ds_read_b64 v[114:115], v153 offset:41080
	ds_read_b128 v[72:75], v150 offset:19232
	ds_read_b128 v[96:99], v150 offset:19744
	ds_read_b128 v[80:83], v151 offset:19248
	ds_read_b128 v[104:107], v151 offset:19760
	v_pk_mul_f32 v[156:157], v[108:109], v[110:111] op_sel_hi:[1,0]
	v_pk_mul_f32 v[116:117], v[156:157], v[60:61] op_sel_hi:[0,1]
	v_pk_mul_f32 v[118:119], v[156:157], v[60:61] op_sel:[1,0]
	v_pk_fma_f32 v[28:29], v[28:29], v[110:111], v[116:117] op_sel:[0,1,0]
	v_pk_fma_f32 v[24:25], v[24:25], v[110:111], v[118:119] op_sel:[0,1,0]
	v_pk_mul_f32 v[188:189], v[28:29], v[84:85]
	v_pk_mul_f32 v[190:191], v[24:25], v[84:85]
	v_add_f32_dpp v192, v192, v192 quad_perm:[1,0,3,2] row_mask:0xf bank_mask:0xf bound_ctrl:1
	v_add_f32_dpp v193, v193, v193 quad_perm:[1,0,3,2] row_mask:0xf bank_mask:0xf bound_ctrl:1
	v_pk_mul_f32 v[120:121], v[156:157], v[62:63] op_sel_hi:[0,1]
	v_pk_mul_f32 v[122:123], v[156:157], v[62:63] op_sel:[1,0]
	v_pk_fma_f32 v[30:31], v[30:31], v[110:111], v[120:121] op_sel:[0,1,0]
	v_pk_fma_f32 v[26:27], v[26:27], v[110:111], v[122:123] op_sel:[0,1,0]
	v_pk_fma_f32 v[188:189], v[30:31], v[86:87], v[188:189]
	v_pk_fma_f32 v[190:191], v[26:27], v[86:87], v[190:191]
	v_add_f32_dpp v192, v192, v192 quad_perm:[2,3,0,1] row_mask:0xf bank_mask:0xf bound_ctrl:1
	v_add_f32_dpp v193, v193, v193 quad_perm:[2,3,0,1] row_mask:0xf bank_mask:0xf bound_ctrl:1
; __device__ __forceinline__ float red8(float v) { v = red4(v); v += dppf<0x141>(v); return v; }
; __device__ __forceinline__ f32x2 lo2(const f32x4& v) { return __builtin_shufflevector(v, v, 0, 1); }
; __device__ __forceinline__ f32x2 hi2(const f32x4& v) { return __builtin_shufflevector(v, v, 2, 3); }
; __device__ __forceinline__ f32x2 splat2(float x) { return (f32x2){x, x}; }
; #define SCAN_INTERLEAVE(nds, nvalu)                                   \
;   _Pragma("unroll") for (int i_ = 0; i_ < (nds); ++i_) {               \
;     __builtin_amdgcn_sched_group_barrier(0x100, 1, 0);                 \
;     __builtin_amdgcn_sched_group_barrier(0x002, (nvalu), 0);           \
;   }
; __device__ __forceinline__ f32x2 ss_step(f32x2 (&S)[2][8], const SsRegs& R) {
;   const f32x2 dA2 = splat2(R.sc.y);
;   f32x2 out;
; #pragma unroll
;   for (int r = 0; r < 2; ++r) {
;     const f32x2 xdt2 = splat2((r ? R.x.y : R.x.x) * R.sc.x);
;     f32x2 y0 = splat2(0.f), y1 = splat2(0.f);
; #pragma unroll
;     for (int q = 0; q < 4; ++q) {
;       S[r][2 * q] = S[r][2 * q] * dA2 + xdt2 * lo2(R.B[q]);
;       S[r][2 * q + 1] = S[r][2 * q + 1] * dA2 + xdt2 * hi2(R.B[q]);
;       y0 += S[r][2 * q] * lo2(R.C[q]);
;       y1 += S[r][2 * q + 1] * hi2(R.C[q]);
;     }
;     y0 += y1;
;     const float y = red8(y0.x + y0.y);
;     if (r) out.y = y; else out.x = y;
;   }
;   return out;
; }
; __device__ __forceinline__ void scan_ssm(const Params& p, int l, int seq, int h, char* smem, const unsigned* wflags, unsigned wexpect) {
;     ...
;     for (int t = 0; t < nsteps; t += 2) {
;       ss_load(RB, vb, sb, min(t + 1, 15), n0, prow0);
;       const f32x2 y0v = ss_step(S, RA);
;       *(f32x2*)((part == 0) ? (yb + t * 64 + prow0) : ydummy) = y0v;
;       SCAN_INTERLEAVE(10, 5);
;       if (t + 1 < nsteps) {
;         ss_load(RA, vb, sb, min(t + 2, 15), n0, prow0);
;         const f32x2 y1v = ss_step(S, RB);
;         *(f32x2*)((part == 0) ? (yb + (t + 1) * 64 + prow0) : ydummy) = y1v;
;         SCAN_INTERLEAVE(10, 5);
;       }
	v_pk_mul_f32 v[116:117], v[156:157], v[64:65] op_sel_hi:[0,1]
	v_pk_mul_f32 v[118:119], v[156:157], v[64:65] op_sel:[1,0]
	v_pk_fma_f32 v[12:13], v[12:13], v[110:111], v[116:117] op_sel:[0,1,0]
	v_pk_fma_f32 v[32:33], v[32:33], v[110:111], v[118:119] op_sel:[0,1,0]
	v_pk_fma_f32 v[188:189], v[12:13], v[88:89], v[188:189]
	v_pk_fma_f32 v[190:191], v[32:33], v[88:89], v[190:191]
	v_add_f32_dpp v192, v192, v192 row_half_mirror row_mask:0xf bank_mask:0xf bound_ctrl:1
	v_add_f32_dpp v193, v193, v193 row_half_mirror row_mask:0xf bank_mask:0xf bound_ctrl:1
	v_pk_mul_f32 v[120:121], v[156:157], v[66:67] op_sel_hi:[0,1]
	v_pk_mul_f32 v[122:123], v[156:157], v[66:67] op_sel:[1,0]
	v_pk_fma_f32 v[14:15], v[14:15], v[110:111], v[120:121] op_sel:[0,1,0]
	v_pk_fma_f32 v[34:35], v[34:35], v[110:111], v[122:123] op_sel:[0,1,0]
	v_pk_fma_f32 v[188:189], v[14:15], v[90:91], v[188:189]
	v_pk_fma_f32 v[190:191], v[34:35], v[90:91], v[190:191]
	ds_read_b128 v[60:63], v150 offset:19200
	ds_read_b128 v[84:87], v150 offset:19712
	ds_read_b128 v[64:67], v151 offset:19216
	ds_read_b128 v[88:91], v151 offset:19728
	ds_write_b64 v154, v[192:193] offset:3328
	v_pk_mul_f32 v[116:117], v[156:157], v[68:69] op_sel_hi:[0,1]
	v_pk_mul_f32 v[118:119], v[156:157], v[68:69] op_sel:[1,0]
	v_pk_fma_f32 v[8:9], v[8:9], v[110:111], v[116:117] op_sel:[0,1,0]
	v_pk_fma_f32 v[20:21], v[20:21], v[110:111], v[118:119] op_sel:[0,1,0]
	v_pk_fma_f32 v[188:189], v[8:9], v[92:93], v[188:189]
	v_pk_fma_f32 v[190:191], v[20:21], v[92:93], v[190:191]
	v_pk_mul_f32 v[120:121], v[156:157], v[70:71] op_sel_hi:[0,1]
	v_pk_mul_f32 v[122:123], v[156:157], v[70:71] op_sel:[1,0]
	v_pk_fma_f32 v[10:11], v[10:11], v[110:111], v[120:121] op_sel:[0,1,0]
	v_pk_fma_f32 v[22:23], v[22:23], v[110:111], v[122:123] op_sel:[0,1,0]
	v_pk_fma_f32 v[188:189], v[10:11], v[94:95], v[188:189]
	v_pk_fma_f32 v[190:191], v[22:23], v[94:95], v[190:191]
	v_pk_mul_f32 v[116:117], v[156:157], v[76:77] op_sel_hi:[0,1]
	v_pk_mul_f32 v[118:119], v[156:157], v[76:77] op_sel:[1,0]
	v_pk_fma_f32 v[4:5], v[4:5], v[110:111], v[116:117] op_sel:[0,1,0]
	v_pk_fma_f32 v[16:17], v[16:17], v[110:111], v[118:119] op_sel:[0,1,0]
	v_pk_fma_f32 v[188:189], v[4:5], v[100:101], v[188:189]
	v_pk_fma_f32 v[190:191], v[16:17], v[100:101], v[190:191]
	v_pk_mul_f32 v[120:121], v[156:157], v[78:79] op_sel_hi:[0,1]
	v_pk_mul_f32 v[122:123], v[156:157], v[78:79] op_sel:[1,0]
	v_pk_fma_f32 v[6:7], v[6:7], v[110:111], v[120:121] op_sel:[0,1,0]
	v_pk_fma_f32 v[18:19], v[18:19], v[110:111], v[122:123] op_sel:[0,1,0]
	v_pk_fma_f32 v[188:189], v[6:7], v[102:103], v[188:189]
	v_pk_fma_f32 v[190:191], v[18:19], v[102:103], v[190:191]
	v_add_f32_e64 v192, v188, v189
	v_add_f32_e64 v193, v190, v191
	s_waitcnt lgkmcnt(0)
; __device__ __forceinline__ float red8(float v) { v = red4(v); v += dppf<0x141>(v); return v; }
; __device__ __forceinline__ f32x2 lo2(const f32x4& v) { return __builtin_shufflevector(v, v, 0, 1); }
; __device__ __forceinline__ f32x2 hi2(const f32x4& v) { return __builtin_shufflevector(v, v, 2, 3); }
; __device__ __forceinline__ f32x2 splat2(float x) { return (f32x2){x, x}; }
; #define SCAN_INTERLEAVE(nds, nvalu)                                   \
;   _Pragma("unroll") for (int i_ = 0; i_ < (nds); ++i_) {               \
;     __builtin_amdgcn_sched_group_barrier(0x100, 1, 0);                 \
;     __builtin_amdgcn_sched_group_barrier(0x002, (nvalu), 0);           \
;   }
; __device__ __forceinline__ f32x2 ss_step(f32x2 (&S)[2][8], const SsRegs& R) {
;   const f32x2 dA2 = splat2(R.sc.y);
;   f32x2 out;
; #pragma unroll
;   for (int r = 0; r < 2; ++r) {
;     const f32x2 xdt2 = splat2((r ? R.x.y : R.x.x) * R.sc.x);
;     f32x2 y0 = splat2(0.f), y1 = splat2(0.f);
; #pragma unroll
;     for (int q = 0; q < 4; ++q) {
;       S[r][2 * q] = S[r][2 * q] * dA2 + xdt2 * lo2(R.B[q]);
;       S[r][2 * q + 1] = S[r][2 * q + 1] * dA2 + xdt2 * hi2(R.B[q]);
;       y0 += S[r][2 * q] * lo2(R.C[q]);
;       y1 += S[r][2 * q + 1] * hi2(R.C[q]);
;     }
;     y0 += y1;
;     const float y = red8(y0.x + y0.y);
;     if (r) out.y = y; else out.x = y;
;   }
;   return out;
; }
; __device__ __forceinline__ void scan_ssm(const Params& p, int l, int seq, int h, char* smem, const unsigned* wflags, unsigned wexpect) {
;     ...
;     for (int t = 0; t < nsteps; t += 2) {
;       ss_load(RB, vb, sb, min(t + 1, 15), n0, prow0);
;       const f32x2 y0v = ss_step(S, RA);
;       *(f32x2*)((part == 0) ? (yb + t * 64 + prow0) : ydummy) = y0v;
;       SCAN_INTERLEAVE(10, 5);
;       if (t + 1 < nsteps) {
;         ss_load(RA, vb, sb, min(t + 2, 15), n0, prow0);
;         const f32x2 y1v = ss_step(S, RB);
;         *(f32x2*)((part == 0) ? (yb + (t + 1) * 64 + prow0) : ydummy) = y1v;
;         SCAN_INTERLEAVE(10, 5);
;       }
;     }
	s_nop 0
	ds_read_b64 v[108:109], v152 offset:21504
	ds_read_b64 v[110:111], v153 offset:41088
	ds_read_b128 v[68:71], v150 offset:20512
	ds_read_b128 v[92:95], v150 offset:21024
	ds_read_b128 v[76:79], v151 offset:20528
	ds_read_b128 v[100:103], v151 offset:21040
	v_pk_mul_f32 v[156:157], v[112:113], v[114:115] op_sel_hi:[1,0]
	v_pk_mul_f32 v[116:117], v[156:157], v[60:61] op_sel_hi:[0,1]
	v_pk_mul_f32 v[118:119], v[156:157], v[60:61] op_sel:[1,0]
	v_pk_fma_f32 v[28:29], v[28:29], v[114:115], v[116:117] op_sel:[0,1,0]
	v_pk_fma_f32 v[24:25], v[24:25], v[114:115], v[118:119] op_sel:[0,1,0]
	v_pk_mul_f32 v[188:189], v[28:29], v[84:85]
	v_pk_mul_f32 v[190:191], v[24:25], v[84:85]
	v_add_f32_dpp v192, v192, v192 quad_perm:[1,0,3,2] row_mask:0xf bank_mask:0xf bound_ctrl:1
	v_add_f32_dpp v193, v193, v193 quad_perm:[1,0,3,2] row_mask:0xf bank_mask:0xf bound_ctrl:1
	v_pk_mul_f32 v[120:121], v[156:157], v[62:63] op_sel_hi:[0,1]
	v_pk_mul_f32 v[122:123], v[156:157], v[62:63] op_sel:[1,0]
	v_pk_fma_f32 v[30:31], v[30:31], v[114:115], v[120:121] op_sel:[0,1,0]
	v_pk_fma_f32 v[26:27], v[26:27], v[114:115], v[122:123] op_sel:[0,1,0]
	v_pk_fma_f32 v[188:189], v[30:31], v[86:87], v[188:189]
	v_pk_fma_f32 v[190:191], v[26:27], v[86:87], v[190:191]
	v_add_f32_dpp v192, v192, v192 quad_perm:[2,3,0,1] row_mask:0xf bank_mask:0xf bound_ctrl:1
	v_add_f32_dpp v193, v193, v193 quad_perm:[2,3,0,1] row_mask:0xf bank_mask:0xf bound_ctrl:1
	v_pk_mul_f32 v[116:117], v[156:157], v[64:65] op_sel_hi:[0,1]
	v_pk_mul_f32 v[118:119], v[156:157], v[64:65] op_sel:[1,0]
	v_pk_fma_f32 v[12:13], v[12:13], v[114:115], v[116:117] op_sel:[0,1,0]
	v_pk_fma_f32 v[32:33], v[32:33], v[114:115], v[118:119] op_sel:[0,1,0]
	v_pk_fma_f32 v[188:189], v[12:13], v[88:89], v[188:189]
	v_pk_fma_f32 v[190:191], v[32:33], v[88:89], v[190:191]
	v_add_f32_dpp v192, v192, v192 row_half_mirror row_mask:0xf bank_mask:0xf bound_ctrl:1
	v_add_f32_dpp v193, v193, v193 row_half_mirror row_mask:0xf bank_mask:0xf bound_ctrl:1
	v_pk_mul_f32 v[120:121], v[156:157], v[66:67] op_sel_hi:[0,1]
	v_pk_mul_f32 v[122:123], v[156:157], v[66:67] op_sel:[1,0]
	v_pk_fma_f32 v[14:15], v[14:15], v[114:115], v[120:121] op_sel:[0,1,0]
	v_pk_fma_f32 v[34:35], v[34:35], v[114:115], v[122:123] op_sel:[0,1,0]
	v_pk_fma_f32 v[188:189], v[14:15], v[90:91], v[188:189]
	v_pk_fma_f32 v[190:191], v[34:35], v[90:91], v[190:191]
	ds_read_b128 v[60:63], v150 offset:20480
	ds_read_b128 v[84:87], v150 offset:20992
	ds_read_b128 v[64:67], v151 offset:20496
	ds_read_b128 v[88:91], v151 offset:21008
	ds_write_b64 v154, v[192:193] offset:3584
	v_pk_mul_f32 v[116:117], v[156:157], v[72:73] op_sel_hi:[0,1]
	v_pk_mul_f32 v[118:119], v[156:157], v[72:73] op_sel:[1,0]
	v_pk_fma_f32 v[8:9], v[8:9], v[114:115], v[116:117] op_sel:[0,1,0]
	v_pk_fma_f32 v[20:21], v[20:21], v[114:115], v[118:119] op_sel:[0,1,0]
	v_pk_fma_f32 v[188:189], v[8:9], v[96:97], v[188:189]
	v_pk_fma_f32 v[190:191], v[20:21], v[96:97], v[190:191]
	v_pk_mul_f32 v[120:121], v[156:157], v[74:75] op_sel_hi:[0,1]
	v_pk_mul_f32 v[122:123], v[156:157], v[74:75] op_sel:[1,0]
	v_pk_fma_f32 v[10:11], v[10:11], v[114:115], v[120:121] op_sel:[0,1,0]
	v_pk_fma_f32 v[22:23], v[22:23], v[114:115], v[122:123] op_sel:[0,1,0]
	v_pk_fma_f32 v[188:189], v[10:11], v[98:99], v[188:189]
	v_pk_fma_f32 v[190:191], v[22:23], v[98:99], v[190:191]
	v_pk_mul_f32 v[116:117], v[156:157], v[80:81] op_sel_hi:[0,1]
	v_pk_mul_f32 v[118:119], v[156:157], v[80:81] op_sel:[1,0]
	v_pk_fma_f32 v[4:5], v[4:5], v[114:115], v[116:117] op_sel:[0,1,0]
	v_pk_fma_f32 v[16:17], v[16:17], v[114:115], v[118:119] op_sel:[0,1,0]
	v_pk_fma_f32 v[188:189], v[4:5], v[104:105], v[188:189]
	v_pk_fma_f32 v[190:191], v[16:17], v[104:105], v[190:191]
	v_pk_mul_f32 v[120:121], v[156:157], v[82:83] op_sel_hi:[0,1]
	v_pk_mul_f32 v[122:123], v[156:157], v[82:83] op_sel:[1,0]
	v_pk_fma_f32 v[6:7], v[6:7], v[114:115], v[120:121] op_sel:[0,1,0]
	v_pk_fma_f32 v[18:19], v[18:19], v[114:115], v[122:123] op_sel:[0,1,0]
	v_pk_fma_f32 v[188:189], v[6:7], v[106:107], v[188:189]
	v_pk_fma_f32 v[190:191], v[18:19], v[106:107], v[190:191]
	v_add_f32_e64 v192, v188, v189
	v_add_f32_e64 v193, v190, v191
	s_nop 0
	s_nop 0
	v_add_f32_dpp v192, v192, v192 quad_perm:[1,0,3,2] row_mask:0xf bank_mask:0xf bound_ctrl:1
	v_add_f32_dpp v193, v193, v193 quad_perm:[1,0,3,2] row_mask:0xf bank_mask:0xf bound_ctrl:1
	s_nop 0
	s_nop 0
	v_add_f32_dpp v192, v192, v192 quad_perm:[2,3,0,1] row_mask:0xf bank_mask:0xf bound_ctrl:1
	v_add_f32_dpp v193, v193, v193 quad_perm:[2,3,0,1] row_mask:0xf bank_mask:0xf bound_ctrl:1
	s_nop 0
	s_nop 0
	v_add_f32_dpp v192, v192, v192 row_half_mirror row_mask:0xf bank_mask:0xf bound_ctrl:1
	v_add_f32_dpp v193, v193, v193 row_half_mirror row_mask:0xf bank_mask:0xf bound_ctrl:1
	ds_write_b64 v154, v[192:193] offset:3840
	s_mov_b32 exec_lo, 0xf0f0f0f0
	s_mov_b32 exec_hi, 0xf0f0f0f0
	v_swap_b32 v28, v12
	v_swap_b32 v29, v13
	v_swap_b32 v30, v14
	v_swap_b32 v31, v15
	v_swap_b32 v8, v4
	v_swap_b32 v9, v5
	v_swap_b32 v10, v6
	v_swap_b32 v11, v7
	v_swap_b32 v24, v32
	v_swap_b32 v25, v33
	v_swap_b32 v26, v34
	v_swap_b32 v27, v35
	v_swap_b32 v20, v16
	v_swap_b32 v21, v17
	v_swap_b32 v22, v18
	v_swap_b32 v23, v19
	s_mov_b64 exec, -1
	s_cmp_eq_u32 s50, 0
	s_cbranch_scc1 .LBB0_648
	s_branch .LBB0_684
